# attention: 32-bit K/V load offsets with SGPR tile bases (address tail 4 instr to 1)
# speedup vs baseline: 1.2188x; 1.0055x over previous
.LBB0_246:
	s_lshl_b32 s1, s71, 2
	s_and_b32 s22, s1, 0xffffff00
	s_lshr_b32 s0, s71, 3
	s_bfe_u32 s56, s71, 0x30003
	s_or_b32 s24, s22, s72
	s_cmp_lt_i32 s24, 0x8000
	s_movk_i32 s22, 0xfff
	s_cselect_b32 s75, s22, 0x1fff
	s_bfe_u32 s0, s0, 0x10002
	s_andn2_b32 s74, s1, s75
	s_mul_i32 s0, s0, 0x1800000
	s_add_u32 s0, s96, s0
	s_addc_u32 s1, s97, 0
	s_lshl_b32 s22, s71, 4
	s_and_b32 s22, s22, 0x180
	s_add_u32 s22, s0, s22
	v_or_b32_e32 v162, s24, v167
	s_addc_u32 s23, s1, 0
	v_ashrrev_i32_e32 v163, 31, v162
	v_lshl_add_u64 v[12:13], s[22:23], 0, v[158:159]
	v_lshlrev_b64 v[0:1], 9, v[162:163]
	v_lshl_add_u64 v[8:9], v[12:13], 0, v[0:1]
	global_load_dwordx4 v[0:3], v[8:9], off
	v_or_b32_e32 v160, 8, v162
	v_ashrrev_i32_e32 v161, 31, v160
	s_add_u32 s68, s22, 0x3000000
	s_addc_u32 s69, s23, 0
	s_lshl_b32 s98, s74, 9
	s_add_u32 s100, s68, s98
	s_addc_u32 s101, s69, 0
	s_add_u32 s98, s100, 0x3000000
	s_addc_u32 s99, s101, 0
	s_sub_i32 s76, s24, s74
	s_sub_i32 s0, s76, 64
	s_waitcnt vmcnt(7)
	v_add_u32_e32 v20, s0, v172
	v_min_i32_e32 v21, s75, v20
	s_waitcnt vmcnt(6)
	v_add_u32_e32 v24, s0, v173
	v_min_i32_e32 v25, s75, v24
	s_waitcnt vmcnt(5)
	v_add_u32_e32 v28, s0, v182
	v_min_i32_e32 v29, s75, v28
	s_waitcnt vmcnt(2)
	v_add_u32_e32 v40, s0, v166
	v_min_i32_e32 v32, s75, v40
	v_add_u32_e32 v41, 16, v40
	s_movk_i32 s1, 0xffef
	v_min_i32_e32 v41, s75, v41
	v_or_b32_e32 v128, 32, v166
	v_add_u32_e32 v56, s0, v128
	v_add_u32_e32 v149, s76, v155
	v_add_u32_e32 v150, s76, v172
	v_add_u32_e32 v151, s76, v173
	v_add_u32_e32 v252, s76, v182
	v_or_b32_e32 v251, s76, v167
	v_subrev_u32_e32 v250, s76, v251
	v_or_b32_e32 v144, 8, v251
	v_subrev_u32_e32 v249, s76, v144
	v_add_u32_e32 v196, 0x60, v155
	v_add_u32_e32 v168, 0x60, v172
	v_add_u32_e32 v193, 0x60, v173
	v_add_u32_e32 v194, 0x60, v182
	v_add_u32_e32 v186, s76, v206
	s_waitcnt vmcnt(0)
	v_lshlrev_b32_e32 v4, 16, v0
	v_and_b32_e32 v5, 0xffff0000, v0
	v_lshlrev_b32_e32 v0, 16, v1
	v_and_b32_e32 v1, 0xffff0000, v1
	v_pk_mul_f32 v[4:5], v[4:5], s[58:59] op_sel_hi:[1,0]
	v_pk_mul_f32 v[0:1], v[0:1], s[58:59] op_sel_hi:[1,0]
	v_cvt_pk_bf16_f32 v4, v4, v5
	v_cvt_pk_bf16_f32 v5, v0, v1
	v_lshlrev_b32_e32 v0, 16, v2
	v_and_b32_e32 v1, 0xffff0000, v2
	v_pk_mul_f32 v[0:1], v[0:1], s[58:59] op_sel_hi:[1,0]
	s_nop 0
	v_cvt_pk_bf16_f32 v6, v0, v1
	v_lshlrev_b32_e32 v0, 16, v3
	v_and_b32_e32 v1, 0xffff0000, v3
	v_pk_mul_f32 v[0:1], v[0:1], s[58:59] op_sel_hi:[1,0]
	s_nop 0
	v_cvt_pk_bf16_f32 v7, v0, v1
	global_load_dwordx4 v[0:3], v[8:9], off offset:64
	s_waitcnt vmcnt(0)
	v_lshlrev_b32_e32 v8, 16, v0
	v_and_b32_e32 v9, 0xffff0000, v0
	v_lshlrev_b32_e32 v0, 16, v1
	v_and_b32_e32 v1, 0xffff0000, v1
	v_pk_mul_f32 v[8:9], v[8:9], s[58:59] op_sel_hi:[1,0]
	v_pk_mul_f32 v[0:1], v[0:1], s[58:59] op_sel_hi:[1,0]
	v_cvt_pk_bf16_f32 v8, v8, v9
	v_cvt_pk_bf16_f32 v9, v0, v1
	v_lshlrev_b32_e32 v0, 16, v2
	v_and_b32_e32 v1, 0xffff0000, v2
	v_pk_mul_f32 v[0:1], v[0:1], s[58:59] op_sel_hi:[1,0]
	s_nop 0
	v_cvt_pk_bf16_f32 v10, v0, v1
	v_lshlrev_b32_e32 v0, 16, v3
	v_and_b32_e32 v1, 0xffff0000, v3
	v_pk_mul_f32 v[0:1], v[0:1], s[58:59] op_sel_hi:[1,0]
	s_nop 0
	v_cvt_pk_bf16_f32 v11, v0, v1
	v_lshlrev_b64 v[0:1], 9, v[160:161]
	v_lshl_add_u64 v[16:17], v[12:13], 0, v[0:1]
	global_load_dwordx4 v[0:3], v[16:17], off
	s_waitcnt vmcnt(0)
	v_lshlrev_b32_e32 v12, 16, v0
	v_and_b32_e32 v13, 0xffff0000, v0
	v_lshlrev_b32_e32 v0, 16, v1
	v_and_b32_e32 v1, 0xffff0000, v1
	v_pk_mul_f32 v[12:13], v[12:13], s[58:59] op_sel_hi:[1,0]
	v_pk_mul_f32 v[0:1], v[0:1], s[58:59] op_sel_hi:[1,0]
	v_cvt_pk_bf16_f32 v12, v12, v13
	v_cvt_pk_bf16_f32 v13, v0, v1
	v_lshlrev_b32_e32 v0, 16, v2
	v_and_b32_e32 v1, 0xffff0000, v2
	v_pk_mul_f32 v[0:1], v[0:1], s[58:59] op_sel_hi:[1,0]
	s_nop 0
	v_cvt_pk_bf16_f32 v14, v0, v1
	v_lshlrev_b32_e32 v0, 16, v3
	v_and_b32_e32 v1, 0xffff0000, v3
	v_pk_mul_f32 v[0:1], v[0:1], s[58:59] op_sel_hi:[1,0]
	s_nop 0
	v_cvt_pk_bf16_f32 v15, v0, v1
	global_load_dwordx4 v[0:3], v[16:17], off offset:64
	s_waitcnt vmcnt(0)
	v_lshlrev_b32_e32 v16, 16, v0
	v_and_b32_e32 v17, 0xffff0000, v0
	v_pk_mul_f32 v[16:17], v[16:17], s[58:59] op_sel_hi:[1,0]
	s_nop 0
	v_cvt_pk_bf16_f32 v0, v16, v17
	v_lshlrev_b32_e32 v16, 16, v1
	v_and_b32_e32 v17, 0xffff0000, v1
	v_pk_mul_f32 v[16:17], v[16:17], s[58:59] op_sel_hi:[1,0]
	s_nop 0
	v_cvt_pk_bf16_f32 v1, v16, v17
	v_lshlrev_b32_e32 v16, 16, v2
	v_and_b32_e32 v17, 0xffff0000, v2
	v_pk_mul_f32 v[16:17], v[16:17], s[58:59] op_sel_hi:[1,0]
	s_nop 0
	v_cvt_pk_bf16_f32 v2, v16, v17
	v_lshlrev_b32_e32 v16, 16, v3
	v_and_b32_e32 v17, 0xffff0000, v3
	v_pk_mul_f32 v[16:17], v[16:17], s[58:59] op_sel_hi:[1,0]
	s_nop 0
	v_cvt_pk_bf16_f32 v3, v16, v17
	v_lshl_add_u64 v[16:17], s[22:23], 0, v[152:153]
	s_mov_b64 s[22:23], 0x6000000
	v_lshl_add_u64 v[164:165], v[16:17], 0, s[22:23]
	v_add_u32_e32 v16, s0, v155
	s_sub_i32 s22, 0x80, s76
	s_nop 0
	v_med3_i32 v16, v16, 0, s75
	v_cmp_lt_i32_e32 vcc, -1, v20
	s_nop 1
	v_cndmask_b32_e32 v20, 0, v21, vcc
	v_cmp_lt_i32_e32 vcc, -1, v24
	s_nop 1
	v_cndmask_b32_e32 v24, 0, v25, vcc
	v_cmp_lt_i32_e32 vcc, -1, v28
	s_nop 1
	v_cndmask_b32_e32 v28, 0, v29, vcc
	v_lshl_add_u32 v16, v16, 9, v152
	global_load_dwordx4 v[16:19], v16, s[98:99]
	v_lshl_add_u32 v20, v20, 9, v152
	v_cmp_lt_i32_e32 vcc, -1, v40
	global_load_dwordx4 v[20:23], v20, s[98:99]
	v_lshl_add_u32 v24, v24, 9, v152
	v_cndmask_b32_e32 v32, 0, v32, vcc
	v_cmp_lt_i32_e32 vcc, s1, v40
	global_load_dwordx4 v[24:27], v24, s[98:99]
	v_lshl_add_u32 v28, v28, 9, v152
	v_cndmask_b32_e32 v40, 0, v41, vcc
	global_load_dwordx4 v[28:31], v28, s[98:99]
	v_lshl_add_u32 v36, v32, 9, v158
	v_lshl_add_u32 v40, v40, 9, v158
	s_sub_i32 s1, s76, 32
	global_load_dwordx4 v[32:35], v36, s[100:101]
	s_nop 0
	global_load_dwordx4 v[36:39], v36, s[100:101] offset:64
	s_nop 0
	global_load_dwordx4 v[48:51], v40, s[100:101]
	global_load_dwordx4 v[52:55], v40, s[100:101] offset:64
	v_add_u32_e32 v40, s1, v155
	v_med3_i32 v40, v40, 0, s75
	v_lshl_add_u32 v40, v40, 9, v152
	global_load_dwordx4 v[76:79], v40, s[98:99]
	v_add_u32_e32 v40, s1, v172
	v_med3_i32 v40, v40, 0, s75
	v_lshl_add_u32 v40, v40, 9, v152
	global_load_dwordx4 v[84:87], v40, s[98:99]
	v_add_u32_e32 v40, s1, v173
	v_med3_i32 v40, v40, 0, s75
	v_lshl_add_u32 v40, v40, 9, v152
	global_load_dwordx4 v[88:91], v40, s[98:99]
	v_add_u32_e32 v40, s1, v182
	s_min_i32 s1, s0, 0
	s_sub_i32 s1, 0, s1
	v_med3_i32 v40, v40, 0, s75
	v_lshl_add_u32 v40, v40, 9, v152
	global_load_dwordx4 v[92:95], v40, s[98:99]
	v_min_i32_e32 v40, s75, v56
	v_cmp_lt_i32_e32 vcc, -1, v56
	v_add_u32_e32 v56, 16, v56
	s_nop 0
	v_cndmask_b32_e32 v40, 0, v40, vcc
	v_med3_i32 v56, v56, 0, s75
	v_lshl_add_u32 v44, v40, 9, v158
	v_lshl_add_u32 v60, v56, 9, v158
	global_load_dwordx4 v[40:43], v44, s[100:101]
	s_nop 0
	global_load_dwordx4 v[44:47], v44, s[100:101] offset:64
	s_nop 0
	global_load_dwordx4 v[56:59], v60, s[100:101]
	s_nop 0
	global_load_dwordx4 v[60:63], v60, s[100:101] offset:64
	s_waitcnt vmcnt(15)
	ds_write_b128 v241, v[16:19]
	s_waitcnt vmcnt(14)
	ds_write_b128 v242, v[20:23]
	s_waitcnt vmcnt(13)
	ds_write_b128 v243, v[24:27]
	s_waitcnt vmcnt(12)
	ds_write_b128 v244, v[28:31]
	v_or_b32_e32 v24, 16, v166
	v_add_u32_e32 v24, s76, v24
	v_med3_i32 v16, v149, 0, s75
	v_lshl_add_u32 v16, v16, 9, v152
	global_load_dwordx4 v[64:67], v16, s[98:99]
	s_sub_i32 s0, s75, s0
	v_med3_i32 v16, v150, 0, s75
	v_lshl_add_u32 v16, v16, 9, v152
	global_load_dwordx4 v[68:71], v16, s[98:99]
	v_max_i32_e32 v147, s1, v250
	v_max_i32_e32 v148, s1, v249
	v_med3_i32 v16, v151, 0, s75
	v_lshl_add_u32 v16, v16, 9, v152
	global_load_dwordx4 v[72:75], v16, s[98:99]
	v_med3_i32 v16, v252, 0, s75
	v_lshl_add_u32 v16, v16, 9, v152
	global_load_dwordx4 v[80:83], v16, s[98:99]
	v_add_u32_e32 v16, s76, v166
	v_med3_i32 v16, v16, 0, s75
	v_med3_i32 v24, v24, 0, s75
	v_lshl_add_u32 v20, v16, 9, v158
	v_lshl_add_u32 v28, v24, 9, v158
	global_load_dwordx4 v[16:19], v20, s[100:101]
	s_nop 0
	global_load_dwordx4 v[20:23], v20, s[100:101] offset:64
	s_nop 0
	global_load_dwordx4 v[24:27], v28, s[100:101]
	s_nop 0
	global_load_dwordx4 v[28:31], v28, s[100:101] offset:64
	ds_read_b64_tr_b16 v[98:99], v169 offset:2304
	ds_read_b64_tr_b16 v[96:97], v169
	ds_read_b64_tr_b16 v[100:101], v169 offset:32
	ds_read_b64_tr_b16 v[102:103], v169 offset:2336
	ds_read_b64_tr_b16 v[116:117], v169 offset:64
	ds_read_b64_tr_b16 v[118:119], v169 offset:2368
	ds_read_b64_tr_b16 v[134:135], v169 offset:96
	ds_read_b64_tr_b16 v[136:137], v169 offset:2400
	s_waitcnt vmcnt(15)
	ds_write_b128 v241, v[76:79] offset:4608
	s_waitcnt vmcnt(14)
	ds_write_b128 v242, v[84:87] offset:4608
	s_waitcnt vmcnt(13)
	ds_write_b128 v243, v[88:91] offset:4608
	s_waitcnt vmcnt(12)
	ds_write_b128 v244, v[92:95] offset:4608
	v_mfma_f32_16x16x32_bf16 v[76:79], v[32:35], v[4:7], 0
	v_mfma_f32_16x16x32_bf16 v[32:35], v[32:35], v[12:15], 0
	v_mfma_f32_16x16x32_bf16 v[76:79], v[36:39], v[8:11], v[76:79]
	v_mfma_f32_16x16x32_bf16 v[84:87], v[48:51], v[4:7], 0
	v_mfma_f32_16x16x32_bf16 v[32:35], v[36:39], v[0:3], v[32:35]
	v_mfma_f32_16x16x32_bf16 v[36:39], v[48:51], v[12:15], 0
	v_add_u32_e32 v48, s22, v251
	v_min3_i32 v48, v48, s0, v245
	v_sub_u32_e32 v49, v154, v147
	v_sub_u32_e32 v146, v48, v147
	v_add_u32_e32 v48, s22, v144
	v_min3_i32 v48, v48, s0, v245
	v_add_u32_e32 v51, 1, v49
	v_sub_u32_e32 v145, v48, v148
	v_max_f32_e32 v48, v76, v76
	v_cmp_gt_u32_e64 s[0:1], v51, v146
	v_cmp_gt_u32_e32 vcc, v49, v146
	v_max_f32_e32 v48, 0xf149f2ca, v48
	v_cndmask_b32_e64 v51, v77, v246, s[0:1]
	v_cndmask_b32_e32 v48, v48, v246, vcc
	v_mfma_f32_16x16x32_bf16 v[84:87], v[52:55], v[8:11], v[84:87]
	v_max_f32_e32 v48, v48, v51
	v_add_u32_e32 v51, 2, v49
	v_cmp_gt_u32_e64 s[22:23], v51, v146
	v_mfma_f32_16x16x32_bf16 v[36:39], v[52:55], v[0:3], v[36:39]
	v_add_u32_e32 v52, 3, v49
	v_cmp_gt_u32_e64 s[24:25], v52, v146
	v_cndmask_b32_e64 v51, v78, v246, s[22:23]
	v_sub_u32_e32 v50, v154, v148
	v_cndmask_b32_e64 v52, v79, v246, s[24:25]
	v_max3_f32 v48, v48, v51, v52
	v_add_u32_e32 v51, 16, v49
	v_add_u32_e32 v52, 17, v49
	v_cmp_gt_u32_e64 s[26:27], v51, v146
	v_cmp_gt_u32_e64 s[28:29], v52, v146
	v_cmp_gt_u32_e64 s[38:39], v50, v145
	v_cndmask_b32_e64 v51, v84, v246, s[26:27]
	v_cndmask_b32_e64 v52, v85, v246, s[28:29]
	v_max3_f32 v48, v48, v51, v52
	v_add_u32_e32 v51, 18, v49
	v_add_u32_e32 v49, 19, v49
	v_cmp_gt_u32_e64 s[30:31], v51, v146
	v_cmp_gt_u32_e64 s[34:35], v49, v146
	v_add_u32_e32 v52, 3, v50
	v_cndmask_b32_e64 v51, v86, v246, s[30:31]
	v_cndmask_b32_e64 v49, v87, v246, s[34:35]
	v_max3_f32 v48, v48, v51, v49
	v_add_u32_e32 v51, 1, v50
	v_max_f32_e32 v49, v32, v32
	v_cmp_gt_u32_e64 s[40:41], v51, v145
	v_max_f32_e32 v49, 0xf149f2ca, v49
	v_cndmask_b32_e64 v49, v49, v246, s[38:39]
	v_cndmask_b32_e64 v51, v33, v246, s[40:41]
	v_max_f32_e32 v49, v49, v51
	v_add_u32_e32 v51, 2, v50
	v_cmp_gt_u32_e64 s[42:43], v51, v145
	v_cmp_gt_u32_e64 s[44:45], v52, v145
	s_nop 0
	v_cndmask_b32_e64 v51, v34, v246, s[42:43]
	v_cndmask_b32_e64 v52, v35, v246, s[44:45]
	v_max3_f32 v49, v49, v51, v52
	v_add_u32_e32 v51, 16, v50
	v_add_u32_e32 v52, 17, v50
	v_cmp_gt_u32_e64 s[46:47], v51, v145
	v_cmp_gt_u32_e64 s[48:49], v52, v145
	s_nop 0
	v_cndmask_b32_e64 v51, v36, v246, s[46:47]
	v_cndmask_b32_e64 v52, v37, v246, s[48:49]
	v_max3_f32 v49, v49, v51, v52
	v_add_u32_e32 v51, 18, v50
	v_add_u32_e32 v50, 19, v50
	v_cmp_gt_u32_e64 s[50:51], v51, v145
	v_cmp_gt_u32_e64 s[52:53], v50, v145
	s_nop 0
	v_cndmask_b32_e64 v51, v38, v246, s[50:51]
	v_cndmask_b32_e64 v50, v39, v246, s[52:53]
	v_max3_f32 v49, v49, v51, v50
	v_mov_b32_e32 v50, v48
	v_mov_b32_e32 v51, v48
	s_nop 1
	v_permlane32_swap_b32_e32 v50, v51
	v_max3_f32 v48, v48, v50, v51
	v_mov_b32_e32 v50, v49
	v_mov_b32_e32 v51, v49
	s_nop 1
	v_permlane32_swap_b32_e32 v50, v51
	v_max3_f32 v49, v49, v50, v51
	v_mov_b32_e32 v50, v48
	v_mov_b32_e32 v51, v48
	s_nop 1
	v_permlane16_swap_b32_e32 v50, v51
	v_max_f32_e32 v48, v48, v50
	v_mov_b32_e32 v50, v49
	v_mov_b32_e32 v88, v49
	s_nop 1
	v_permlane16_swap_b32_e32 v50, v88
	v_max3_f32 v129, v48, v51, s73
	v_sub_f32_e32 v48, 0xf149f2ca, v129
	v_max_f32_e32 v49, v49, v50
	v_exp_f32_e32 v50, v48
	v_sub_f32_e32 v48, v76, v129
	v_exp_f32_e32 v48, v48
	v_sub_f32_e32 v52, v77, v129
	v_max3_f32 v131, v49, v88, s73
	v_exp_f32_e32 v52, v52
	v_sub_f32_e32 v36, v36, v131
	v_sub_f32_e32 v53, v78, v129
	v_exp_f32_e32 v36, v36
	v_exp_f32_e32 v53, v53
	v_sub_f32_e32 v54, v79, v129
	v_cndmask_b32_e64 v51, v48, 0, vcc
	v_exp_f32_e32 v54, v54
	v_sub_f32_e32 v55, v84, v129
	v_add_f32_e32 v48, 0, v51
	v_cndmask_b32_e64 v52, v52, 0, s[0:1]
	v_exp_f32_e32 v55, v55
	v_sub_f32_e32 v76, v85, v129
	v_add_f32_e32 v48, v52, v48
	v_exp_f32_e32 v76, v76
	v_sub_f32_e32 v77, v86, v129
	v_cvt_pk_bf16_f32 v52, v51, v52
	v_cndmask_b32_e64 v51, v36, 0, s[46:47]
	v_sub_f32_e32 v36, v37, v131
	v_cndmask_b32_e64 v53, v53, 0, s[22:23]
	v_exp_f32_e32 v77, v77
	v_sub_f32_e32 v78, v87, v129
	v_exp_f32_e32 v36, v36
	v_add_f32_e32 v48, v53, v48
	v_cndmask_b32_e64 v54, v54, 0, s[24:25]
	v_exp_f32_e32 v78, v78
	v_add_f32_e32 v48, v54, v48
	v_cndmask_b32_e64 v55, v55, 0, s[26:27]
	v_sub_f32_e32 v32, v32, v131
	v_add_f32_e32 v48, v55, v48
	v_cndmask_b32_e64 v76, v76, 0, s[28:29]
	v_exp_f32_e32 v32, v32
	v_sub_f32_e32 v33, v33, v131
	v_add_f32_e32 v48, v76, v48
	v_cndmask_b32_e64 v77, v77, 0, s[30:31]
	v_cvt_pk_bf16_f32 v53, v53, v54
	v_cvt_pk_bf16_f32 v54, v55, v76
	v_exp_f32_e32 v33, v33
	v_sub_f32_e32 v34, v34, v131
	v_cndmask_b32_e64 v76, v36, 0, s[48:49]
	v_sub_f32_e32 v36, v38, v131
	v_add_f32_e32 v48, v77, v48
	v_cndmask_b32_e64 v78, v78, 0, s[34:35]
	v_exp_f32_e32 v34, v34
	v_sub_f32_e32 v35, v35, v131
	v_exp_f32_e32 v36, v36
	v_add_f32_e32 v130, v78, v48
	v_exp_f32_e32 v35, v35
	v_mul_f32_e32 v48, 0, v50
	v_fmac_f32_e32 v130, 0, v50
	v_cndmask_b32_e64 v50, v32, 0, s[38:39]
	v_add_f32_e32 v32, 0, v50
	v_cndmask_b32_e64 v33, v33, 0, s[40:41]
	v_cvt_pk_bf16_f32 v55, v77, v78
	v_add_f32_e32 v32, v33, v32
	v_cndmask_b32_e64 v34, v34, 0, s[42:43]
	v_cndmask_b32_e64 v77, v36, 0, s[50:51]
	v_sub_f32_e32 v36, v39, v131
	v_sub_f32_e32 v49, 0xf149f2ca, v131
	v_add_f32_e32 v32, v34, v32
	v_cndmask_b32_e64 v35, v35, 0, s[44:45]
	v_exp_f32_e32 v36, v36
	v_exp_f32_e32 v49, v49
	v_add_f32_e32 v32, v35, v32
	v_add_f32_e32 v32, v51, v32
	v_add_f32_e32 v32, v76, v32
	v_add_f32_e32 v32, v77, v32
	v_cndmask_b32_e64 v39, v36, 0, s[52:53]
	v_add_f32_e32 v132, v39, v32
	v_mul_f32_e32 v32, 0, v49
	v_fmac_f32_e32 v132, 0, v49
	v_cvt_pk_bf16_f32 v36, v50, v33
	v_cvt_pk_bf16_f32 v37, v34, v35
	v_cvt_pk_bf16_f32 v38, v51, v76
	v_cvt_pk_bf16_f32 v39, v77, v39
	v_mov_b32_e32 v49, v48
	v_mov_b32_e32 v50, v48
	v_mov_b32_e32 v51, v48
	v_mov_b32_e32 v33, v32
	v_mov_b32_e32 v34, v32
	v_mov_b32_e32 v35, v32
	s_waitcnt lgkmcnt(6)
	v_mfma_f32_16x16x32_bf16 v[112:115], v[116:119], v[52:55], v[48:51]
	v_mfma_f32_16x16x32_bf16 v[124:127], v[96:99], v[36:39], v[32:35]
	v_mfma_f32_16x16x32_bf16 v[108:111], v[100:103], v[36:39], v[32:35]
	v_mfma_f32_16x16x32_bf16 v[116:119], v[116:119], v[36:39], v[32:35]
	s_waitcnt lgkmcnt(4)
	v_mfma_f32_16x16x32_bf16 v[88:91], v[134:137], v[36:39], v[32:35]
	s_nop 2
	v_add_u32_e32 v32, 32, v155
	v_add_u32_e32 v32, s76, v32
	v_mfma_f32_16x16x32_bf16 v[120:123], v[96:99], v[52:55], v[48:51]
	s_nop 0
	v_med3_i32 v32, v32, 0, s75
	v_lshl_add_u32 v32, v32, 9, v152
	global_load_dwordx4 v[76:79], v32, s[98:99]
	v_add_u32_e32 v32, 32, v172
	v_add_u32_e32 v32, s76, v32
	v_mfma_f32_16x16x32_bf16 v[104:107], v[100:103], v[52:55], v[48:51]
	s_nop 0
	v_med3_i32 v32, v32, 0, s75
	v_lshl_add_u32 v32, v32, 9, v152
	global_load_dwordx4 v[84:87], v32, s[98:99]
	v_add_u32_e32 v32, 32, v173
	v_add_u32_e32 v32, s76, v32
	v_mfma_f32_16x16x32_bf16 v[96:99], v[134:137], v[52:55], v[48:51]
	s_nop 0
	v_med3_i32 v32, v32, 0, s75
	v_lshl_add_u32 v32, v32, 9, v152
	global_load_dwordx4 v[92:95], v32, s[98:99]
	v_add_u32_e32 v32, 32, v182
	v_add_u32_e32 v32, s76, v32
	v_or_b32_e32 v48, 48, v166
	v_add_u32_e32 v48, s76, v48
	v_med3_i32 v32, v32, 0, s75
	v_lshl_add_u32 v32, v32, 9, v152
	global_load_dwordx4 v[100:103], v32, s[98:99]
	v_add_u32_e32 v32, s76, v128
	s_nop 0
	v_med3_i32 v32, v32, 0, s75
	v_med3_i32 v48, v48, 0, s75
	v_lshl_add_u32 v36, v32, 9, v158
	v_lshl_add_u32 v52, v48, 9, v158
	global_load_dwordx4 v[32:35], v36, s[100:101]
	s_nop 0
	global_load_dwordx4 v[36:39], v36, s[100:101] offset:64
	s_nop 0
	global_load_dwordx4 v[48:51], v52, s[100:101]
	s_nop 0
	global_load_dwordx4 v[52:55], v52, s[100:101] offset:64
	ds_read_b64_tr_b16 v[136:137], v169 offset:6912
	ds_read_b64_tr_b16 v[134:135], v169 offset:4608
	ds_read_b64_tr_b16 v[138:139], v169 offset:4640
	ds_read_b64_tr_b16 v[140:141], v169 offset:6944
	ds_read_b64_tr_b16 v[176:177], v169 offset:4672
	ds_read_b64_tr_b16 v[178:179], v169 offset:6976
	ds_read_b64_tr_b16 v[188:189], v169 offset:4704
	ds_read_b64_tr_b16 v[190:191], v169 offset:7008
	s_waitcnt vmcnt(15)
	ds_write_b128 v241, v[64:67]
	s_waitcnt vmcnt(14)
	ds_write_b128 v242, v[68:71]
	s_waitcnt vmcnt(13)
	ds_write_b128 v243, v[72:75]
	s_waitcnt vmcnt(12)
	ds_write_b128 v244, v[80:83]
	v_mfma_f32_16x16x32_bf16 v[64:67], v[40:43], v[4:7], 0
	v_mfma_f32_16x16x32_bf16 v[40:43], v[40:43], v[12:15], 0
	v_mfma_f32_16x16x32_bf16 v[64:67], v[44:47], v[8:11], v[64:67]
	v_mfma_f32_16x16x32_bf16 v[68:71], v[56:59], v[4:7], 0
	v_mfma_f32_16x16x32_bf16 v[40:43], v[44:47], v[0:3], v[40:43]
	v_mfma_f32_16x16x32_bf16 v[44:47], v[56:59], v[12:15], 0
	v_sub_u32_e32 v56, v187, v147
	v_add_u32_e32 v59, 1, v56
	s_nop 2
	v_max_f32_e32 v58, v64, v64
	v_cmp_gt_u32_e64 s[0:1], v59, v146
	v_cmp_gt_u32_e32 vcc, v56, v146
	v_max_f32_e32 v58, 0xf149f2ca, v58
	v_cndmask_b32_e64 v59, v65, v246, s[0:1]
	v_cndmask_b32_e32 v58, v58, v246, vcc
	v_mfma_f32_16x16x32_bf16 v[68:71], v[60:63], v[8:11], v[68:71]
	v_max_f32_e32 v58, v58, v59
	v_add_u32_e32 v59, 2, v56
	v_cmp_gt_u32_e64 s[22:23], v59, v146
	v_mfma_f32_16x16x32_bf16 v[44:47], v[60:63], v[0:3], v[44:47]
	v_add_u32_e32 v60, 3, v56
	v_cmp_gt_u32_e64 s[24:25], v60, v146
	v_cndmask_b32_e64 v59, v66, v246, s[22:23]
	v_sub_u32_e32 v57, v187, v148
	v_cndmask_b32_e64 v60, v67, v246, s[24:25]
	v_max3_f32 v58, v58, v59, v60
	v_add_u32_e32 v59, 16, v56
	v_add_u32_e32 v60, 17, v56
	v_cmp_gt_u32_e64 s[26:27], v59, v146
	v_cmp_gt_u32_e64 s[28:29], v60, v146
	v_cmp_gt_u32_e64 s[38:39], v57, v145
	v_cndmask_b32_e64 v59, v68, v246, s[26:27]
	v_cndmask_b32_e64 v60, v69, v246, s[28:29]
	v_max3_f32 v58, v58, v59, v60
	v_add_u32_e32 v59, 18, v56
	v_add_u32_e32 v56, 19, v56
	v_cmp_gt_u32_e64 s[30:31], v59, v146
	v_cmp_gt_u32_e64 s[34:35], v56, v146
	v_add_u32_e32 v60, 3, v57
	v_cndmask_b32_e64 v59, v70, v246, s[30:31]
	v_cndmask_b32_e64 v56, v71, v246, s[34:35]
	v_max3_f32 v56, v58, v59, v56
	v_add_u32_e32 v59, 1, v57
	v_max_f32_e32 v58, v40, v40
	v_cmp_gt_u32_e64 s[40:41], v59, v145
	v_max_f32_e32 v58, 0xf149f2ca, v58
	v_cndmask_b32_e64 v58, v58, v246, s[38:39]
	v_cndmask_b32_e64 v59, v41, v246, s[40:41]
	v_max_f32_e32 v58, v58, v59
	v_add_u32_e32 v59, 2, v57
	v_cmp_gt_u32_e64 s[42:43], v59, v145
	v_cmp_gt_u32_e64 s[44:45], v60, v145
	s_nop 0
	v_cndmask_b32_e64 v59, v42, v246, s[42:43]
	v_cndmask_b32_e64 v60, v43, v246, s[44:45]
	v_max3_f32 v58, v58, v59, v60
	v_add_u32_e32 v59, 16, v57
	v_add_u32_e32 v60, 17, v57
	v_cmp_gt_u32_e64 s[46:47], v59, v145
	v_cmp_gt_u32_e64 s[48:49], v60, v145
	s_nop 0
	v_cndmask_b32_e64 v59, v44, v246, s[46:47]
	v_cndmask_b32_e64 v60, v45, v246, s[48:49]
	v_max3_f32 v58, v58, v59, v60
	v_add_u32_e32 v59, 18, v57
	v_add_u32_e32 v57, 19, v57
	v_cmp_gt_u32_e64 s[50:51], v59, v145
	v_cmp_gt_u32_e64 s[52:53], v57, v145
	s_nop 0
	v_cndmask_b32_e64 v59, v46, v246, s[50:51]
	v_cndmask_b32_e64 v57, v47, v246, s[52:53]
	v_max3_f32 v57, v58, v59, v57
	v_mov_b32_e32 v58, v56
	v_mov_b32_e32 v59, v56
	s_nop 1
	v_permlane32_swap_b32_e32 v58, v59
	v_max3_f32 v56, v56, v58, v59
	v_mov_b32_e32 v58, v57
	v_mov_b32_e32 v59, v57
	s_nop 1
	v_permlane32_swap_b32_e32 v58, v59
	v_max3_f32 v57, v57, v58, v59
	v_mov_b32_e32 v58, v56
	v_mov_b32_e32 v59, v56
	s_nop 1
	v_permlane16_swap_b32_e32 v58, v59
	v_max_f32_e32 v56, v56, v58
	v_mov_b32_e32 v58, v57
	v_mov_b32_e32 v61, v57
	v_max3_f32 v128, v129, v56, v59
	s_nop 0
	v_permlane16_swap_b32_e32 v58, v61
	v_sub_f32_e32 v56, v129, v128
	v_exp_f32_e32 v60, v56
	v_sub_f32_e32 v56, v64, v128
	v_max_f32_e32 v62, v57, v58
	v_exp_f32_e32 v56, v56
	v_sub_f32_e32 v58, v65, v128
	v_exp_f32_e32 v58, v58
	v_sub_f32_e32 v59, v66, v128
	v_exp_f32_e32 v59, v59
	v_sub_f32_e32 v63, v67, v128
	v_exp_f32_e32 v63, v63
	v_sub_f32_e32 v64, v68, v128
	v_cndmask_b32_e64 v56, v56, 0, vcc
	v_exp_f32_e32 v64, v64
	v_sub_f32_e32 v65, v69, v128
	v_add_f32_e32 v57, 0, v56
	v_cndmask_b32_e64 v58, v58, 0, s[0:1]
	v_exp_f32_e32 v65, v65
	v_sub_f32_e32 v66, v70, v128
	v_add_f32_e32 v57, v58, v57
	v_cndmask_b32_e64 v59, v59, 0, s[22:23]
	v_exp_f32_e32 v66, v66
	v_sub_f32_e32 v67, v71, v128
	v_add_f32_e32 v57, v59, v57
	v_cndmask_b32_e64 v63, v63, 0, s[24:25]
	v_exp_f32_e32 v67, v67
	v_add_f32_e32 v57, v63, v57
	v_cndmask_b32_e64 v64, v64, 0, s[26:27]
	v_add_f32_e32 v57, v64, v57
	v_cndmask_b32_e64 v65, v65, 0, s[28:29]
	v_add_f32_e32 v57, v65, v57
	v_cndmask_b32_e64 v66, v66, 0, s[30:31]
	v_add_f32_e32 v57, v66, v57
	v_cndmask_b32_e64 v67, v67, 0, s[34:35]
	v_add_f32_e32 v129, v67, v57
	v_fmac_f32_e32 v129, v130, v60
	v_max3_f32 v130, v131, v62, v61
	v_sub_f32_e32 v40, v40, v130
	v_exp_f32_e32 v40, v40
	v_sub_f32_e32 v41, v41, v130
	v_exp_f32_e32 v41, v41
	v_sub_f32_e32 v42, v42, v130
	v_exp_f32_e32 v42, v42
	v_sub_f32_e32 v43, v43, v130
	v_exp_f32_e32 v43, v43
	v_sub_f32_e32 v44, v44, v130
	v_sub_f32_e32 v61, v131, v130
	v_cndmask_b32_e64 v40, v40, 0, s[38:39]
	v_exp_f32_e32 v44, v44
	v_sub_f32_e32 v45, v45, v130
	v_exp_f32_e32 v62, v61
	v_add_f32_e32 v61, 0, v40
	v_cndmask_b32_e64 v41, v41, 0, s[40:41]
	v_exp_f32_e32 v45, v45
	v_sub_f32_e32 v46, v46, v130
	v_add_f32_e32 v61, v41, v61
	v_cndmask_b32_e64 v42, v42, 0, s[42:43]
	v_exp_f32_e32 v46, v46
	v_sub_f32_e32 v47, v47, v130
	v_add_f32_e32 v61, v42, v61
	v_cndmask_b32_e64 v43, v43, 0, s[44:45]
	v_exp_f32_e32 v47, v47
	v_add_f32_e32 v61, v43, v61
	v_cndmask_b32_e64 v44, v44, 0, s[46:47]
	v_add_f32_e32 v61, v44, v61
	v_cndmask_b32_e64 v45, v45, 0, s[48:49]
	v_add_f32_e32 v61, v45, v61
	v_cndmask_b32_e64 v46, v46, 0, s[50:51]
	v_add_f32_e32 v61, v46, v61
	v_cndmask_b32_e64 v47, v47, 0, s[52:53]
	v_cvt_pk_bf16_f32 v56, v56, v58
	v_cvt_pk_bf16_f32 v57, v59, v63
	v_cvt_pk_bf16_f32 v58, v64, v65
	v_cvt_pk_bf16_f32 v59, v66, v67
	v_add_f32_e32 v131, v47, v61
	v_cvt_pk_bf16_f32 v40, v40, v41
	v_cvt_pk_bf16_f32 v41, v42, v43
	v_cvt_pk_bf16_f32 v42, v44, v45
	v_cvt_pk_bf16_f32 v43, v46, v47
	v_pk_mul_f32 v[46:47], v[122:123], v[60:61] op_sel_hi:[1,0]
	v_pk_mul_f32 v[44:45], v[120:121], v[60:61] op_sel_hi:[1,0]
	v_fmac_f32_e32 v131, v132, v62
	s_waitcnt lgkmcnt(10)
	v_mfma_f32_16x16x32_bf16 v[64:67], v[134:137], v[56:59], v[44:47]
	s_nop 2
	v_mul_f32_e64 v46, v126, v62
	v_mul_f32_e64 v47, v127, v62
	v_pk_mul_f32 v[44:45], v[124:125], v[62:63] op_sel_hi:[1,0]
	s_nop 1
	v_mfma_f32_16x16x32_bf16 v[68:71], v[134:137], v[40:43], v[44:47]
	s_nop 2
	v_mul_f32_e64 v46, v106, v60
	v_mul_f32_e64 v47, v107, v60
	v_pk_mul_f32 v[44:45], v[104:105], v[60:61] op_sel_hi:[1,0]
	s_waitcnt lgkmcnt(8)
	s_nop 0
	v_mfma_f32_16x16x32_bf16 v[104:107], v[138:141], v[56:59], v[44:47]
	s_nop 2
	v_mul_f32_e64 v46, v110, v62
	v_mul_f32_e64 v47, v111, v62
	v_pk_mul_f32 v[44:45], v[108:109], v[62:63] op_sel_hi:[1,0]
	s_nop 1
	v_mfma_f32_16x16x32_bf16 v[108:111], v[138:141], v[40:43], v[44:47]
	s_nop 2
	v_mul_f32_e64 v46, v114, v60
	v_mul_f32_e64 v47, v115, v60
	v_pk_mul_f32 v[44:45], v[112:113], v[60:61] op_sel_hi:[1,0]
	s_waitcnt lgkmcnt(6)
	s_nop 0
	v_mfma_f32_16x16x32_bf16 v[112:115], v[176:179], v[56:59], v[44:47]
	s_nop 2
	v_mul_f32_e64 v46, v118, v62
	v_mul_f32_e64 v47, v119, v62
	v_pk_mul_f32 v[44:45], v[116:117], v[62:63] op_sel_hi:[1,0]
	s_nop 1
	v_mfma_f32_16x16x32_bf16 v[116:119], v[176:179], v[40:43], v[44:47]
	s_nop 2
	v_mul_f32_e64 v46, v98, v60
	v_mul_f32_e64 v47, v99, v60
	v_pk_mul_f32 v[44:45], v[96:97], v[60:61] op_sel_hi:[1,0]
	s_waitcnt lgkmcnt(4)
	s_nop 0
	v_mfma_f32_16x16x32_bf16 v[120:123], v[188:191], v[56:59], v[44:47]
	v_or_b32_e32 v56, 0x50, v166
	v_add_u32_e32 v56, s76, v56
	s_nop 0
	v_pk_mul_f32 v[46:47], v[90:91], v[62:63] op_sel_hi:[1,0]
	v_pk_mul_f32 v[44:45], v[88:89], v[62:63] op_sel_hi:[1,0]
	s_nop 1
	v_mfma_f32_16x16x32_bf16 v[124:127], v[188:191], v[40:43], v[44:47]
	v_add_u32_e32 v40, 64, v155
	v_add_u32_e32 v40, s76, v40
	v_med3_i32 v40, v40, 0, s75
	v_lshl_add_u32 v40, v40, 9, v152
	global_load_dwordx4 v[72:75], v40, s[98:99]
	v_add_u32_e32 v40, 64, v172
	v_add_u32_e32 v40, s76, v40
	v_med3_i32 v40, v40, 0, s75
	v_lshl_add_u32 v40, v40, 9, v152
	global_load_dwordx4 v[80:83], v40, s[98:99]
	v_add_u32_e32 v40, 64, v173
	v_add_u32_e32 v40, s76, v40
	v_med3_i32 v40, v40, 0, s75
	v_lshl_add_u32 v40, v40, 9, v152
	global_load_dwordx4 v[88:91], v40, s[98:99]
	v_add_u32_e32 v40, 64, v182
	v_add_u32_e32 v40, s76, v40
	v_med3_i32 v40, v40, 0, s75
	v_lshl_add_u32 v40, v40, 9, v152
	global_load_dwordx4 v[96:99], v40, s[98:99]
	v_or_b32_e32 v40, 64, v166
	v_add_u32_e32 v40, s76, v40
	v_med3_i32 v40, v40, 0, s75
	v_med3_i32 v56, v56, 0, s75
	v_lshl_add_u32 v44, v40, 9, v158
	v_lshl_add_u32 v60, v56, 9, v158
	global_load_dwordx4 v[40:43], v44, s[100:101]
	s_nop 0
	global_load_dwordx4 v[44:47], v44, s[100:101] offset:64
	s_nop 0
	global_load_dwordx4 v[56:59], v60, s[100:101]
	s_nop 0
	global_load_dwordx4 v[60:63], v60, s[100:101] offset:64
	ds_read_b64_tr_b16 v[136:137], v169 offset:2304
	ds_read_b64_tr_b16 v[134:135], v169
	ds_read_b64_tr_b16 v[138:139], v169 offset:32
	ds_read_b64_tr_b16 v[140:141], v169 offset:2336
	ds_read_b64_tr_b16 v[176:177], v169 offset:64
	ds_read_b64_tr_b16 v[178:179], v169 offset:2368
	ds_read_b64_tr_b16 v[188:189], v169 offset:96
	ds_read_b64_tr_b16 v[190:191], v169 offset:2400
	s_waitcnt vmcnt(15)
	ds_write_b128 v241, v[76:79] offset:4608
	s_waitcnt vmcnt(14)
	ds_write_b128 v242, v[84:87] offset:4608
	s_waitcnt vmcnt(13)
	ds_write_b128 v243, v[92:95] offset:4608
	s_waitcnt vmcnt(12)
	ds_write_b128 v244, v[100:103] offset:4608
	v_mfma_f32_16x16x32_bf16 v[76:79], v[16:19], v[4:7], 0
	v_mfma_f32_16x16x32_bf16 v[16:19], v[16:19], v[12:15], 0
	v_mfma_f32_16x16x32_bf16 v[76:79], v[20:23], v[8:11], v[76:79]
	v_mfma_f32_16x16x32_bf16 v[84:87], v[24:27], v[4:7], 0
	v_mfma_f32_16x16x32_bf16 v[16:19], v[20:23], v[0:3], v[16:19]
	v_mfma_f32_16x16x32_bf16 v[20:23], v[24:27], v[12:15], 0
	v_sub_u32_e32 v24, v192, v147
	v_add_u32_e32 v27, 1, v24
	s_nop 2
	v_max_f32_e32 v26, v76, v76
	v_cmp_gt_u32_e64 s[0:1], v27, v146
	v_cmp_gt_u32_e32 vcc, v24, v146
	v_max_f32_e32 v26, 0xf149f2ca, v26
	v_cndmask_b32_e64 v27, v77, v246, s[0:1]
	v_cndmask_b32_e32 v26, v26, v246, vcc
	v_mfma_f32_16x16x32_bf16 v[84:87], v[28:31], v[8:11], v[84:87]
	v_max_f32_e32 v26, v26, v27
	v_add_u32_e32 v27, 2, v24
	v_cmp_gt_u32_e64 s[22:23], v27, v146
	v_mfma_f32_16x16x32_bf16 v[20:23], v[28:31], v[0:3], v[20:23]
	v_add_u32_e32 v28, 3, v24
	v_cmp_gt_u32_e64 s[24:25], v28, v146
	v_cndmask_b32_e64 v27, v78, v246, s[22:23]
	v_sub_u32_e32 v25, v192, v148
	v_cndmask_b32_e64 v28, v79, v246, s[24:25]
	v_max3_f32 v26, v26, v27, v28
	v_add_u32_e32 v27, 16, v24
	v_add_u32_e32 v28, 17, v24
	v_cmp_gt_u32_e64 s[26:27], v27, v146
	v_cmp_gt_u32_e64 s[28:29], v28, v146
	v_cmp_gt_u32_e64 s[38:39], v25, v145
	v_cndmask_b32_e64 v27, v84, v246, s[26:27]
	v_cndmask_b32_e64 v28, v85, v246, s[28:29]
	v_max3_f32 v26, v26, v27, v28
	v_add_u32_e32 v27, 18, v24
	v_add_u32_e32 v24, 19, v24
	v_cmp_gt_u32_e64 s[30:31], v27, v146
	v_cmp_gt_u32_e64 s[34:35], v24, v146
	v_add_u32_e32 v28, 3, v25
	v_cndmask_b32_e64 v27, v86, v246, s[30:31]
	v_cndmask_b32_e64 v24, v87, v246, s[34:35]
	v_max3_f32 v24, v26, v27, v24
	v_add_u32_e32 v27, 1, v25
	v_max_f32_e32 v26, v16, v16
	v_cmp_gt_u32_e64 s[40:41], v27, v145
	v_max_f32_e32 v26, 0xf149f2ca, v26
	v_cndmask_b32_e64 v26, v26, v246, s[38:39]
	v_cndmask_b32_e64 v27, v17, v246, s[40:41]
	v_max_f32_e32 v26, v26, v27
	v_add_u32_e32 v27, 2, v25
	v_cmp_gt_u32_e64 s[42:43], v27, v145
	v_cmp_gt_u32_e64 s[44:45], v28, v145
	s_nop 0
	v_cndmask_b32_e64 v27, v18, v246, s[42:43]
	v_cndmask_b32_e64 v28, v19, v246, s[44:45]
	v_max3_f32 v26, v26, v27, v28
	v_add_u32_e32 v27, 16, v25
	v_add_u32_e32 v28, 17, v25
	v_cmp_gt_u32_e64 s[46:47], v27, v145
	v_cmp_gt_u32_e64 s[48:49], v28, v145
	s_nop 0
	v_cndmask_b32_e64 v27, v20, v246, s[46:47]
	v_cndmask_b32_e64 v28, v21, v246, s[48:49]
	v_max3_f32 v26, v26, v27, v28
	v_add_u32_e32 v27, 18, v25
	v_add_u32_e32 v25, 19, v25
	v_cmp_gt_u32_e64 s[50:51], v27, v145
	v_cmp_gt_u32_e64 s[52:53], v25, v145
	s_nop 0
	v_cndmask_b32_e64 v27, v22, v246, s[50:51]
	v_cndmask_b32_e64 v25, v23, v246, s[52:53]
	v_max3_f32 v25, v26, v27, v25
	v_mov_b32_e32 v26, v24
	v_mov_b32_e32 v27, v24
	s_nop 1
	v_permlane32_swap_b32_e32 v26, v27
	v_max3_f32 v24, v24, v26, v27
	v_mov_b32_e32 v26, v25
	v_mov_b32_e32 v27, v25
	s_nop 1
	v_permlane32_swap_b32_e32 v26, v27
	v_max3_f32 v25, v25, v26, v27
	v_mov_b32_e32 v26, v24
	v_mov_b32_e32 v27, v24
	s_nop 1
	v_permlane16_swap_b32_e32 v26, v27
	v_max_f32_e32 v24, v24, v26
	v_mov_b32_e32 v26, v25
	v_mov_b32_e32 v28, v25
	v_max3_f32 v132, v128, v24, v27
	s_nop 0
	v_permlane16_swap_b32_e32 v26, v28
	v_sub_f32_e32 v24, v128, v132
	v_exp_f32_e32 v92, v24
	v_sub_f32_e32 v24, v76, v132
	v_max_f32_e32 v29, v25, v26
	v_exp_f32_e32 v24, v24
	v_sub_f32_e32 v26, v77, v132
	v_exp_f32_e32 v26, v26
	v_sub_f32_e32 v27, v78, v132
	v_exp_f32_e32 v27, v27
	v_sub_f32_e32 v30, v79, v132
	v_exp_f32_e32 v30, v30
	v_sub_f32_e32 v31, v84, v132
	v_cndmask_b32_e64 v24, v24, 0, vcc
	v_exp_f32_e32 v31, v31
	v_sub_f32_e32 v76, v85, v132
	v_add_f32_e32 v25, 0, v24
	v_cndmask_b32_e64 v26, v26, 0, s[0:1]
	v_exp_f32_e32 v76, v76
	v_sub_f32_e32 v77, v86, v132
	v_add_f32_e32 v25, v26, v25
	v_cndmask_b32_e64 v27, v27, 0, s[22:23]
	v_exp_f32_e32 v77, v77
	v_sub_f32_e32 v78, v87, v132
	v_add_f32_e32 v25, v27, v25
	v_cndmask_b32_e64 v30, v30, 0, s[24:25]
	v_exp_f32_e32 v78, v78
	v_add_f32_e32 v25, v30, v25
	v_cndmask_b32_e64 v31, v31, 0, s[26:27]
	v_add_f32_e32 v25, v31, v25
	v_cndmask_b32_e64 v76, v76, 0, s[28:29]
	v_add_f32_e32 v25, v76, v25
	v_cndmask_b32_e64 v77, v77, 0, s[30:31]
	v_add_f32_e32 v25, v77, v25
	v_cndmask_b32_e64 v78, v78, 0, s[34:35]
	v_add_f32_e32 v128, v78, v25
	v_fmac_f32_e32 v128, v129, v92
	v_max3_f32 v129, v130, v29, v28
	v_sub_f32_e32 v16, v16, v129
	v_exp_f32_e32 v16, v16
	v_sub_f32_e32 v17, v17, v129
	v_exp_f32_e32 v17, v17
	v_sub_f32_e32 v18, v18, v129
	v_exp_f32_e32 v18, v18
	v_sub_f32_e32 v19, v19, v129
	v_exp_f32_e32 v19, v19
	v_sub_f32_e32 v20, v20, v129
	v_sub_f32_e32 v28, v130, v129
	v_cndmask_b32_e64 v16, v16, 0, s[38:39]
	v_exp_f32_e32 v20, v20
	v_sub_f32_e32 v21, v21, v129
	v_cvt_pk_bf16_f32 v24, v24, v26
	v_cvt_pk_bf16_f32 v26, v31, v76
	v_exp_f32_e32 v76, v28
	v_add_f32_e32 v28, 0, v16
	v_cndmask_b32_e64 v17, v17, 0, s[40:41]
	v_exp_f32_e32 v21, v21
	v_sub_f32_e32 v22, v22, v129
	v_add_f32_e32 v28, v17, v28
	v_cndmask_b32_e64 v18, v18, 0, s[42:43]
	v_exp_f32_e32 v22, v22
	v_sub_f32_e32 v23, v23, v129
	v_add_f32_e32 v28, v18, v28
	v_cndmask_b32_e64 v19, v19, 0, s[44:45]
	v_exp_f32_e32 v23, v23
	v_add_f32_e32 v28, v19, v28
	v_cndmask_b32_e64 v20, v20, 0, s[46:47]
	v_add_f32_e32 v28, v20, v28
	v_cndmask_b32_e64 v21, v21, 0, s[48:49]
	v_add_f32_e32 v28, v21, v28
	v_cndmask_b32_e64 v22, v22, 0, s[50:51]
	v_add_f32_e32 v28, v22, v28
	v_cndmask_b32_e64 v23, v23, 0, s[52:53]
	v_cvt_pk_bf16_f32 v25, v27, v30
	v_cvt_pk_bf16_f32 v27, v77, v78
	v_add_f32_e32 v130, v23, v28
	v_cvt_pk_bf16_f32 v28, v16, v17
	v_cvt_pk_bf16_f32 v29, v18, v19
	v_pk_mul_f32 v[18:19], v[66:67], v[92:93] op_sel_hi:[1,0]
	v_pk_mul_f32 v[16:17], v[64:65], v[92:93] op_sel_hi:[1,0]
	v_pk_mul_f32 v[66:67], v[106:107], v[92:93] op_sel_hi:[1,0]
	v_pk_mul_f32 v[64:65], v[104:105], v[92:93] op_sel_hi:[1,0]
	v_cvt_pk_bf16_f32 v30, v20, v21
	v_cvt_pk_bf16_f32 v31, v22, v23
	s_waitcnt lgkmcnt(8)
	v_mfma_f32_16x16x32_bf16 v[104:107], v[138:141], v[24:27], v[64:67]
	v_fmac_f32_e32 v130, v131, v76
	v_pk_mul_f32 v[22:23], v[70:71], v[76:77] op_sel_hi:[1,0]
	v_pk_mul_f32 v[20:21], v[68:69], v[76:77] op_sel_hi:[1,0]
	v_pk_mul_f32 v[66:67], v[110:111], v[76:77] op_sel_hi:[1,0]
	v_pk_mul_f32 v[64:65], v[108:109], v[76:77] op_sel_hi:[1,0]
	v_mfma_f32_16x16x32_bf16 v[16:19], v[134:137], v[24:27], v[16:19]
	s_nop 0
	v_mfma_f32_16x16x32_bf16 v[108:111], v[138:141], v[28:31], v[64:67]
	s_nop 2
	v_mul_f32_e64 v66, v114, v92
	v_mul_f32_e64 v67, v115, v92
	v_pk_mul_f32 v[64:65], v[112:113], v[92:93] op_sel_hi:[1,0]
	v_mfma_f32_16x16x32_bf16 v[20:23], v[134:137], v[28:31], v[20:23]
	s_waitcnt lgkmcnt(6)
	v_mfma_f32_16x16x32_bf16 v[112:115], v[176:179], v[24:27], v[64:67]
	s_nop 2
	v_mul_f32_e64 v66, v118, v76
	v_mul_f32_e64 v67, v119, v76
	v_pk_mul_f32 v[64:65], v[116:117], v[76:77] op_sel_hi:[1,0]
	s_nop 1
	v_mfma_f32_16x16x32_bf16 v[116:119], v[176:179], v[28:31], v[64:67]
	s_nop 2
	v_mul_f32_e64 v66, v122, v92
	v_mul_f32_e64 v67, v123, v92
	v_pk_mul_f32 v[64:65], v[120:121], v[92:93] op_sel_hi:[1,0]
	s_waitcnt lgkmcnt(4)
	s_nop 0
	v_mfma_f32_16x16x32_bf16 v[120:123], v[188:191], v[24:27], v[64:67]
	v_mul_f32_e64 v26, v126, v76
	v_mul_f32_e64 v27, v127, v76
	v_pk_mul_f32 v[24:25], v[124:125], v[76:77] op_sel_hi:[1,0]
	v_or_b32_e32 v64, 0x70, v166
	s_nop 0
	v_mfma_f32_16x16x32_bf16 v[124:127], v[188:191], v[28:31], v[24:27]
	v_add_u32_e32 v64, s76, v64
	s_nop 0
	s_nop 0
	v_add_u32_e32 v24, s76, v196
	v_med3_i32 v24, v24, 0, s75
	v_lshl_add_u32 v24, v24, 9, v152
	global_load_dwordx4 v[76:79], v24, s[98:99]
	v_add_u32_e32 v24, s76, v168
	v_med3_i32 v24, v24, 0, s75
	v_lshl_add_u32 v24, v24, 9, v152
	global_load_dwordx4 v[84:87], v24, s[98:99]
	v_add_u32_e32 v24, s76, v193
	v_med3_i32 v24, v24, 0, s75
	v_lshl_add_u32 v24, v24, 9, v152
	global_load_dwordx4 v[92:95], v24, s[98:99]
	v_add_u32_e32 v24, s76, v194
	v_med3_i32 v24, v24, 0, s75
	v_lshl_add_u32 v24, v24, 9, v152
	global_load_dwordx4 v[100:103], v24, s[98:99]
	v_or_b32_e32 v24, 0x60, v166
	v_add_u32_e32 v24, s76, v24
	v_med3_i32 v24, v24, 0, s75
	v_med3_i32 v64, v64, 0, s75
	v_lshl_add_u32 v28, v24, 9, v158
	v_lshl_add_u32 v68, v64, 9, v158
	global_load_dwordx4 v[24:27], v28, s[100:101]
	s_nop 0
	global_load_dwordx4 v[28:31], v28, s[100:101] offset:64
	s_nop 0
	global_load_dwordx4 v[64:67], v68, s[100:101]
	s_nop 0
	global_load_dwordx4 v[68:71], v68, s[100:101] offset:64
	ds_read_b64_tr_b16 v[136:137], v169 offset:6912
	ds_read_b64_tr_b16 v[134:135], v169 offset:4608
	ds_read_b64_tr_b16 v[138:139], v169 offset:4640
	ds_read_b64_tr_b16 v[140:141], v169 offset:6944
	ds_read_b64_tr_b16 v[176:177], v169 offset:4672
	ds_read_b64_tr_b16 v[178:179], v169 offset:6976
	ds_read_b64_tr_b16 v[188:189], v169 offset:4704
	ds_read_b64_tr_b16 v[190:191], v169 offset:7008
	s_waitcnt vmcnt(15)
	ds_write_b128 v241, v[72:75]
	s_waitcnt vmcnt(14)
	ds_write_b128 v242, v[80:83]
	s_waitcnt vmcnt(13)
	ds_write_b128 v243, v[88:91]
	s_waitcnt vmcnt(12)
	ds_write_b128 v244, v[96:99]
	v_mfma_f32_16x16x32_bf16 v[72:75], v[32:35], v[4:7], 0
	v_mfma_f32_16x16x32_bf16 v[32:35], v[32:35], v[12:15], 0
	v_mfma_f32_16x16x32_bf16 v[72:75], v[36:39], v[8:11], v[72:75]
	v_mfma_f32_16x16x32_bf16 v[80:83], v[48:51], v[4:7], 0
	v_mfma_f32_16x16x32_bf16 v[32:35], v[36:39], v[0:3], v[32:35]
	v_mfma_f32_16x16x32_bf16 v[36:39], v[48:51], v[12:15], 0
	v_sub_u32_e32 v48, v197, v147
	v_add_u32_e32 v51, 1, v48
	s_nop 2
	v_max_f32_e32 v50, v72, v72
	v_cmp_gt_u32_e64 s[0:1], v51, v146
	v_cmp_gt_u32_e32 vcc, v48, v146
	v_max_f32_e32 v50, 0xf149f2ca, v50
	v_cndmask_b32_e64 v51, v73, v246, s[0:1]
	v_cndmask_b32_e32 v50, v50, v246, vcc
	v_mfma_f32_16x16x32_bf16 v[80:83], v[52:55], v[8:11], v[80:83]
	v_max_f32_e32 v50, v50, v51
	v_add_u32_e32 v51, 2, v48
	v_cmp_gt_u32_e64 s[22:23], v51, v146
	v_mfma_f32_16x16x32_bf16 v[36:39], v[52:55], v[0:3], v[36:39]
	v_add_u32_e32 v52, 3, v48
	v_cmp_gt_u32_e64 s[24:25], v52, v146
	v_cndmask_b32_e64 v51, v74, v246, s[22:23]
	v_sub_u32_e32 v49, v197, v148
	v_cndmask_b32_e64 v52, v75, v246, s[24:25]
	v_max3_f32 v50, v50, v51, v52
	v_add_u32_e32 v51, 16, v48
	v_add_u32_e32 v52, 17, v48
	v_cmp_gt_u32_e64 s[26:27], v51, v146
	v_cmp_gt_u32_e64 s[28:29], v52, v146
	v_cmp_gt_u32_e64 s[38:39], v49, v145
	v_cndmask_b32_e64 v51, v80, v246, s[26:27]
	v_cndmask_b32_e64 v52, v81, v246, s[28:29]
	v_max3_f32 v50, v50, v51, v52
	v_add_u32_e32 v51, 18, v48
	v_add_u32_e32 v48, 19, v48
	v_cmp_gt_u32_e64 s[30:31], v51, v146
	v_cmp_gt_u32_e64 s[34:35], v48, v146
	v_add_u32_e32 v52, 3, v49
	v_cndmask_b32_e64 v51, v82, v246, s[30:31]
	v_cndmask_b32_e64 v48, v83, v246, s[34:35]
	v_max3_f32 v48, v50, v51, v48
	v_add_u32_e32 v51, 1, v49
	v_max_f32_e32 v50, v32, v32
	v_cmp_gt_u32_e64 s[40:41], v51, v145
	v_max_f32_e32 v50, 0xf149f2ca, v50
	v_cndmask_b32_e64 v50, v50, v246, s[38:39]
	v_cndmask_b32_e64 v51, v33, v246, s[40:41]
	v_max_f32_e32 v50, v50, v51
	v_add_u32_e32 v51, 2, v49
	v_cmp_gt_u32_e64 s[42:43], v51, v145
	v_cmp_gt_u32_e64 s[44:45], v52, v145
	s_nop 0
	v_cndmask_b32_e64 v51, v34, v246, s[42:43]
	v_cndmask_b32_e64 v52, v35, v246, s[44:45]
	v_max3_f32 v50, v50, v51, v52
	v_add_u32_e32 v51, 16, v49
	v_add_u32_e32 v52, 17, v49
	v_cmp_gt_u32_e64 s[46:47], v51, v145
	v_cmp_gt_u32_e64 s[48:49], v52, v145
	s_nop 0
	v_cndmask_b32_e64 v51, v36, v246, s[46:47]
	v_cndmask_b32_e64 v52, v37, v246, s[48:49]
	v_max3_f32 v50, v50, v51, v52
	v_add_u32_e32 v51, 18, v49
	v_add_u32_e32 v49, 19, v49
	v_cmp_gt_u32_e64 s[50:51], v51, v145
	v_cmp_gt_u32_e64 s[52:53], v49, v145
	s_nop 0
	v_cndmask_b32_e64 v51, v38, v246, s[50:51]
	v_cndmask_b32_e64 v49, v39, v246, s[52:53]
	v_max3_f32 v49, v50, v51, v49
	v_mov_b32_e32 v50, v48
	v_mov_b32_e32 v51, v48
	s_nop 1
	v_permlane32_swap_b32_e32 v50, v51
	v_max3_f32 v48, v48, v50, v51
	v_mov_b32_e32 v50, v49
	v_mov_b32_e32 v51, v49
	s_nop 1
	v_permlane32_swap_b32_e32 v50, v51
	v_max3_f32 v49, v49, v50, v51
	v_mov_b32_e32 v50, v48
	v_mov_b32_e32 v51, v48
	s_nop 1
	v_permlane16_swap_b32_e32 v50, v51
	v_max_f32_e32 v48, v48, v50
	v_mov_b32_e32 v50, v49
	v_mov_b32_e32 v53, v49
	v_max3_f32 v131, v132, v48, v51
	s_nop 0
	v_permlane16_swap_b32_e32 v50, v53
	v_sub_f32_e32 v48, v132, v131
	v_exp_f32_e32 v52, v48
	v_sub_f32_e32 v48, v72, v131
	v_max_f32_e32 v54, v49, v50
	v_exp_f32_e32 v48, v48
	v_sub_f32_e32 v50, v73, v131
	v_exp_f32_e32 v50, v50
	v_sub_f32_e32 v51, v74, v131
	v_exp_f32_e32 v51, v51
	v_sub_f32_e32 v55, v75, v131
	v_exp_f32_e32 v55, v55
	v_sub_f32_e32 v72, v80, v131
	v_cndmask_b32_e64 v48, v48, 0, vcc
	v_exp_f32_e32 v72, v72
	v_sub_f32_e32 v73, v81, v131
	v_add_f32_e32 v49, 0, v48
	v_cndmask_b32_e64 v50, v50, 0, s[0:1]
	v_exp_f32_e32 v73, v73
	v_sub_f32_e32 v74, v82, v131
	v_add_f32_e32 v49, v50, v49
	v_cndmask_b32_e64 v51, v51, 0, s[22:23]
	v_exp_f32_e32 v74, v74
	v_sub_f32_e32 v75, v83, v131
	v_add_f32_e32 v49, v51, v49
	v_cndmask_b32_e64 v55, v55, 0, s[24:25]
	v_exp_f32_e32 v75, v75
	v_add_f32_e32 v49, v55, v49
	v_cndmask_b32_e64 v72, v72, 0, s[26:27]
	v_add_f32_e32 v49, v72, v49
	v_cndmask_b32_e64 v73, v73, 0, s[28:29]
	v_add_f32_e32 v49, v73, v49
	v_cndmask_b32_e64 v74, v74, 0, s[30:31]
	v_add_f32_e32 v49, v74, v49
	v_cndmask_b32_e64 v75, v75, 0, s[34:35]
	v_add_f32_e32 v132, v75, v49
	v_fmac_f32_e32 v132, v128, v52
	v_max3_f32 v128, v129, v54, v53
	v_sub_f32_e32 v32, v32, v128
	v_exp_f32_e32 v32, v32
	v_sub_f32_e32 v33, v33, v128
	v_exp_f32_e32 v33, v33
	v_sub_f32_e32 v34, v34, v128
	v_exp_f32_e32 v34, v34
	v_sub_f32_e32 v35, v35, v128
	v_exp_f32_e32 v35, v35
	v_sub_f32_e32 v36, v36, v128
	v_sub_f32_e32 v53, v129, v128
	v_cndmask_b32_e64 v32, v32, 0, s[38:39]
	v_exp_f32_e32 v36, v36
	v_sub_f32_e32 v37, v37, v128
	v_exp_f32_e32 v54, v53
	v_add_f32_e32 v53, 0, v32
	v_cndmask_b32_e64 v33, v33, 0, s[40:41]
	v_exp_f32_e32 v37, v37
	v_add_f32_e32 v53, v33, v53
	v_cndmask_b32_e64 v34, v34, 0, s[42:43]
	v_add_f32_e32 v53, v34, v53
	v_cndmask_b32_e64 v35, v35, 0, s[44:45]
	v_cvt_pk_bf16_f32 v49, v51, v55
	v_add_f32_e32 v53, v35, v53
	v_cndmask_b32_e64 v55, v36, 0, s[46:47]
	v_add_f32_e32 v36, v55, v53
	v_cndmask_b32_e64 v53, v37, 0, s[48:49]
	v_sub_f32_e32 v37, v38, v128
	v_exp_f32_e32 v37, v37
	v_cvt_pk_bf16_f32 v48, v48, v50
	v_cvt_pk_bf16_f32 v50, v72, v73
	v_add_f32_e32 v36, v53, v36
	v_cndmask_b32_e64 v72, v37, 0, s[50:51]
	v_sub_f32_e32 v37, v39, v128
	v_exp_f32_e32 v37, v37
	v_cvt_pk_bf16_f32 v51, v74, v75
	v_add_f32_e32 v36, v72, v36
	v_pk_mul_f32 v[18:19], v[18:19], v[52:53] op_sel_hi:[1,0]
	v_cndmask_b32_e64 v39, v37, 0, s[52:53]
	v_pk_mul_f32 v[16:17], v[16:17], v[52:53] op_sel_hi:[1,0]
	v_add_f32_e32 v129, v39, v36
	v_cvt_pk_bf16_f32 v36, v32, v33
	v_cvt_pk_bf16_f32 v37, v34, v35
	v_cvt_pk_bf16_f32 v38, v55, v53
	v_cvt_pk_bf16_f32 v39, v72, v39
	s_waitcnt lgkmcnt(10)
	v_mfma_f32_16x16x32_bf16 v[32:35], v[134:137], v[48:51], v[16:19]
	v_fmac_f32_e32 v129, v130, v54
	s_nop 1
	v_pk_mul_f32 v[18:19], v[22:23], v[54:55] op_sel_hi:[1,0]
	v_pk_mul_f32 v[16:17], v[20:21], v[54:55] op_sel_hi:[1,0]
	s_nop 1
	v_mfma_f32_16x16x32_bf16 v[96:99], v[134:137], v[36:39], v[16:19]
	s_nop 2
	v_mul_f32_e64 v18, v106, v52
	v_mul_f32_e64 v19, v107, v52
	v_pk_mul_f32 v[16:17], v[104:105], v[52:53] op_sel_hi:[1,0]
	s_waitcnt lgkmcnt(8)
	s_nop 0
	v_mfma_f32_16x16x32_bf16 v[104:107], v[138:141], v[48:51], v[16:19]
	s_nop 2
	v_mul_f32_e64 v18, v110, v54
	v_mul_f32_e64 v19, v111, v54
	v_pk_mul_f32 v[16:17], v[108:109], v[54:55] op_sel_hi:[1,0]
	s_nop 1
	v_mfma_f32_16x16x32_bf16 v[108:111], v[138:141], v[36:39], v[16:19]
	s_nop 2
	v_mul_f32_e64 v18, v114, v52
	v_mul_f32_e64 v19, v115, v52
	v_pk_mul_f32 v[16:17], v[112:113], v[52:53] op_sel_hi:[1,0]
	s_waitcnt lgkmcnt(6)
	s_nop 0
	v_mfma_f32_16x16x32_bf16 v[112:115], v[176:179], v[48:51], v[16:19]
	s_nop 2
	v_mul_f32_e64 v18, v118, v54
	v_mul_f32_e64 v19, v119, v54
	v_pk_mul_f32 v[16:17], v[116:117], v[54:55] op_sel_hi:[1,0]
	s_nop 1
	v_mfma_f32_16x16x32_bf16 v[116:119], v[176:179], v[36:39], v[16:19]
	s_nop 2
	v_mul_f32_e64 v18, v122, v52
	v_mul_f32_e64 v19, v123, v52
	v_pk_mul_f32 v[16:17], v[120:121], v[52:53] op_sel_hi:[1,0]
	s_waitcnt lgkmcnt(4)
	s_nop 0
	v_mfma_f32_16x16x32_bf16 v[120:123], v[188:191], v[48:51], v[16:19]
	v_or_b32_e32 v48, 0x90, v166
	v_add_u32_e32 v48, s76, v48
	s_nop 0
	v_pk_mul_f32 v[18:19], v[126:127], v[54:55] op_sel_hi:[1,0]
	v_pk_mul_f32 v[16:17], v[124:125], v[54:55] op_sel_hi:[1,0]
	s_nop 1
	v_mfma_f32_16x16x32_bf16 v[124:127], v[188:191], v[36:39], v[16:19]
	s_nop 2
	v_add_u32_e32 v16, 0x80, v149
	v_med3_i32 v16, v16, 0, s75
	v_lshl_add_u32 v16, v16, 9, v152
	global_load_dwordx4 v[36:39], v16, s[98:99]
	v_add_u32_e32 v16, 0x80, v150
	v_med3_i32 v16, v16, 0, s75
	v_lshl_add_u32 v16, v16, 9, v152
	global_load_dwordx4 v[72:75], v16, s[98:99]
	v_add_u32_e32 v16, 0x80, v151
	v_med3_i32 v16, v16, 0, s75
	v_lshl_add_u32 v16, v16, 9, v152
	global_load_dwordx4 v[80:83], v16, s[98:99]
	v_add_u32_e32 v16, 0x80, v252
	v_med3_i32 v16, v16, 0, s75
	v_lshl_add_u32 v16, v16, 9, v152
	global_load_dwordx4 v[88:91], v16, s[98:99]
	v_or_b32_e32 v16, 0x80, v166
	v_add_u32_e32 v16, s76, v16
	v_med3_i32 v16, v16, 0, s75
	v_med3_i32 v48, v48, 0, s75
	v_lshl_add_u32 v20, v16, 9, v158
	v_lshl_add_u32 v52, v48, 9, v158
	global_load_dwordx4 v[16:19], v20, s[100:101]
	s_nop 0
	global_load_dwordx4 v[20:23], v20, s[100:101] offset:64
	s_nop 0
	global_load_dwordx4 v[48:51], v52, s[100:101]
	s_nop 0
	global_load_dwordx4 v[52:55], v52, s[100:101] offset:64
	ds_read_b64_tr_b16 v[136:137], v169 offset:2304
	ds_read_b64_tr_b16 v[134:135], v169
	ds_read_b64_tr_b16 v[138:139], v169 offset:32
	ds_read_b64_tr_b16 v[140:141], v169 offset:2336
	ds_read_b64_tr_b16 v[188:189], v169 offset:64
	ds_read_b64_tr_b16 v[190:191], v169 offset:2368
	ds_read_b64_tr_b16 v[200:201], v169 offset:96
	ds_read_b64_tr_b16 v[202:203], v169 offset:2400
	s_waitcnt vmcnt(15)
	ds_write_b128 v241, v[76:79] offset:4608
	s_waitcnt vmcnt(14)
	ds_write_b128 v242, v[84:87] offset:4608
	s_waitcnt vmcnt(13)
	ds_write_b128 v243, v[92:95] offset:4608
	s_waitcnt vmcnt(12)
	ds_write_b128 v244, v[100:103] offset:4608
	v_mfma_f32_16x16x32_bf16 v[76:79], v[40:43], v[4:7], 0
	v_mfma_f32_16x16x32_bf16 v[40:43], v[40:43], v[12:15], 0
	v_mfma_f32_16x16x32_bf16 v[76:79], v[44:47], v[8:11], v[76:79]
	v_mfma_f32_16x16x32_bf16 v[84:87], v[56:59], v[4:7], 0
	v_mfma_f32_16x16x32_bf16 v[40:43], v[44:47], v[0:3], v[40:43]
	v_mfma_f32_16x16x32_bf16 v[44:47], v[56:59], v[12:15], 0
	v_sub_u32_e32 v56, v198, v147
	v_add_u32_e32 v59, 1, v56
	s_nop 2
	v_max_f32_e32 v58, v76, v76
	v_cmp_gt_u32_e64 s[0:1], v59, v146
	v_cmp_gt_u32_e32 vcc, v56, v146
	v_max_f32_e32 v58, 0xf149f2ca, v58
	v_cndmask_b32_e64 v59, v77, v246, s[0:1]
	v_cndmask_b32_e32 v58, v58, v246, vcc
	v_mfma_f32_16x16x32_bf16 v[84:87], v[60:63], v[8:11], v[84:87]
	v_max_f32_e32 v58, v58, v59
	v_add_u32_e32 v59, 2, v56
	v_cmp_gt_u32_e64 s[22:23], v59, v146
	v_mfma_f32_16x16x32_bf16 v[44:47], v[60:63], v[0:3], v[44:47]
	v_add_u32_e32 v60, 3, v56
	v_cmp_gt_u32_e64 s[24:25], v60, v146
	v_cndmask_b32_e64 v59, v78, v246, s[22:23]
	v_sub_u32_e32 v57, v198, v148
	v_cndmask_b32_e64 v60, v79, v246, s[24:25]
	v_max3_f32 v58, v58, v59, v60
	v_add_u32_e32 v59, 16, v56
	v_add_u32_e32 v60, 17, v56
	v_cmp_gt_u32_e64 s[26:27], v59, v146
	v_cmp_gt_u32_e64 s[28:29], v60, v146
	v_cmp_gt_u32_e64 s[38:39], v57, v145
	v_cndmask_b32_e64 v59, v84, v246, s[26:27]
	v_cndmask_b32_e64 v60, v85, v246, s[28:29]
	v_max3_f32 v58, v58, v59, v60
	v_add_u32_e32 v59, 18, v56
	v_add_u32_e32 v56, 19, v56
	v_cmp_gt_u32_e64 s[30:31], v59, v146
	v_cmp_gt_u32_e64 s[34:35], v56, v146
	v_add_u32_e32 v60, 3, v57
	v_cndmask_b32_e64 v59, v86, v246, s[30:31]
	v_cndmask_b32_e64 v56, v87, v246, s[34:35]
	v_max3_f32 v56, v58, v59, v56
	v_add_u32_e32 v59, 1, v57
	v_max_f32_e32 v58, v40, v40
	v_cmp_gt_u32_e64 s[40:41], v59, v145
	v_max_f32_e32 v58, 0xf149f2ca, v58
	v_cndmask_b32_e64 v58, v58, v246, s[38:39]
	v_cndmask_b32_e64 v59, v41, v246, s[40:41]
	v_max_f32_e32 v58, v58, v59
	v_add_u32_e32 v59, 2, v57
	v_cmp_gt_u32_e64 s[42:43], v59, v145
	v_cmp_gt_u32_e64 s[44:45], v60, v145
	s_nop 0
	v_cndmask_b32_e64 v59, v42, v246, s[42:43]
	v_cndmask_b32_e64 v60, v43, v246, s[44:45]
	v_max3_f32 v58, v58, v59, v60
	v_add_u32_e32 v59, 16, v57
	v_add_u32_e32 v60, 17, v57
	v_cmp_gt_u32_e64 s[46:47], v59, v145
	v_cmp_gt_u32_e64 s[48:49], v60, v145
	s_nop 0
	v_cndmask_b32_e64 v59, v44, v246, s[46:47]
	v_cndmask_b32_e64 v60, v45, v246, s[48:49]
	v_max3_f32 v58, v58, v59, v60
	v_add_u32_e32 v59, 18, v57
	v_add_u32_e32 v57, 19, v57
	v_cmp_gt_u32_e64 s[50:51], v59, v145
	v_cmp_gt_u32_e64 s[52:53], v57, v145
	s_nop 0
	v_cndmask_b32_e64 v59, v46, v246, s[50:51]
	v_cndmask_b32_e64 v57, v47, v246, s[52:53]
	v_max3_f32 v57, v58, v59, v57
	v_mov_b32_e32 v58, v56
	v_mov_b32_e32 v59, v56
	s_nop 1
	v_permlane32_swap_b32_e32 v58, v59
	v_max3_f32 v56, v56, v58, v59
	v_mov_b32_e32 v58, v57
	v_mov_b32_e32 v59, v57
	s_nop 1
	v_permlane32_swap_b32_e32 v58, v59
	v_max3_f32 v57, v57, v58, v59
	v_mov_b32_e32 v58, v56
	v_mov_b32_e32 v59, v56
	s_nop 1
	v_permlane16_swap_b32_e32 v58, v59
	v_max_f32_e32 v56, v56, v58
	v_mov_b32_e32 v58, v57
	v_mov_b32_e32 v61, v57
	s_nop 1
	v_permlane16_swap_b32_e32 v58, v61
	v_max_f32_e32 v62, v57, v58
	v_max3_f32 v175, v131, v56, v59
	v_sub_f32_e32 v56, v131, v175
	v_max3_f32 v177, v128, v62, v61
	v_exp_f32_e32 v60, v56
	v_sub_f32_e32 v56, v76, v175
	v_sub_f32_e32 v40, v40, v177
	v_exp_f32_e32 v56, v56
	v_sub_f32_e32 v58, v77, v175
	v_exp_f32_e32 v40, v40
	v_sub_f32_e32 v41, v41, v177
	v_exp_f32_e32 v58, v58
	v_sub_f32_e32 v59, v78, v175
	v_exp_f32_e32 v41, v41
	v_sub_f32_e32 v42, v42, v177
	v_exp_f32_e32 v59, v59
	v_sub_f32_e32 v63, v79, v175
	v_exp_f32_e32 v42, v42
	v_sub_f32_e32 v43, v43, v177
	v_exp_f32_e32 v63, v63
	v_sub_f32_e32 v76, v84, v175
	v_exp_f32_e32 v43, v43
	v_sub_f32_e32 v44, v44, v177
	v_cndmask_b32_e64 v56, v56, 0, vcc
	v_exp_f32_e32 v76, v76
	v_sub_f32_e32 v77, v85, v175
	v_sub_f32_e32 v61, v128, v177
	v_cndmask_b32_e64 v40, v40, 0, s[38:39]
	v_exp_f32_e32 v44, v44
	v_sub_f32_e32 v45, v45, v177
	v_add_f32_e32 v57, 0, v56
	v_cndmask_b32_e64 v58, v58, 0, s[0:1]
	v_exp_f32_e32 v77, v77
	v_sub_f32_e32 v78, v86, v175
	v_exp_f32_e32 v62, v61
	v_add_f32_e32 v61, 0, v40
	v_cndmask_b32_e64 v41, v41, 0, s[40:41]
	v_exp_f32_e32 v45, v45
	v_sub_f32_e32 v46, v46, v177
	v_add_f32_e32 v57, v58, v57
	v_cndmask_b32_e64 v59, v59, 0, s[22:23]
	v_exp_f32_e32 v78, v78
	v_sub_f32_e32 v79, v87, v175
	v_add_f32_e32 v61, v41, v61
	v_cndmask_b32_e64 v42, v42, 0, s[42:43]
	v_exp_f32_e32 v46, v46
	v_add_f32_e32 v57, v59, v57
	v_cndmask_b32_e64 v63, v63, 0, s[24:25]
	v_exp_f32_e32 v79, v79
	v_add_f32_e32 v61, v42, v61
	v_cndmask_b32_e64 v43, v43, 0, s[44:45]
	v_sub_f32_e32 v47, v47, v177
	v_add_f32_e32 v57, v63, v57
	v_cndmask_b32_e64 v76, v76, 0, s[26:27]
	v_add_f32_e32 v61, v43, v61
	v_cndmask_b32_e64 v44, v44, 0, s[46:47]
	v_exp_f32_e32 v47, v47
	v_add_f32_e32 v57, v76, v57
	v_cndmask_b32_e64 v77, v77, 0, s[28:29]
	v_add_f32_e32 v61, v44, v61
	v_cndmask_b32_e64 v45, v45, 0, s[48:49]
	v_add_f32_e32 v57, v77, v57
	v_cndmask_b32_e64 v78, v78, 0, s[30:31]
	v_add_f32_e32 v61, v45, v61
	v_cndmask_b32_e64 v46, v46, 0, s[50:51]
	v_add_f32_e32 v57, v78, v57
	v_cndmask_b32_e64 v79, v79, 0, s[34:35]
	v_add_f32_e32 v61, v46, v61
	v_add_f32_e32 v176, v79, v57
	v_cvt_pk_bf16_f32 v56, v56, v58
	v_cvt_pk_bf16_f32 v57, v59, v63
	v_cvt_pk_bf16_f32 v58, v76, v77
	v_cvt_pk_bf16_f32 v59, v78, v79
	v_cndmask_b32_e64 v47, v47, 0, s[52:53]
	v_pk_mul_f32 v[34:35], v[34:35], v[60:61] op_sel_hi:[1,0]
	v_pk_mul_f32 v[32:33], v[32:33], v[60:61] op_sel_hi:[1,0]
	v_add_f32_e32 v178, v47, v61
	v_cvt_pk_bf16_f32 v40, v40, v41
	v_cvt_pk_bf16_f32 v41, v42, v43
	v_cvt_pk_bf16_f32 v42, v44, v45
	v_cvt_pk_bf16_f32 v43, v46, v47
	s_waitcnt lgkmcnt(10)
	v_mfma_f32_16x16x32_bf16 v[44:47], v[134:137], v[56:59], v[32:35]
	v_fmac_f32_e32 v176, v132, v60
	v_fmac_f32_e32 v178, v129, v62
	s_nop 0
	v_pk_mul_f32 v[34:35], v[98:99], v[62:63] op_sel_hi:[1,0]
	v_pk_mul_f32 v[32:33], v[96:97], v[62:63] op_sel_hi:[1,0]
	s_nop 1
	v_mfma_f32_16x16x32_bf16 v[100:103], v[134:137], v[40:43], v[32:35]
	s_nop 2
	v_mul_f32_e64 v34, v106, v60
	v_mul_f32_e64 v35, v107, v60
	v_pk_mul_f32 v[32:33], v[104:105], v[60:61] op_sel_hi:[1,0]
	s_waitcnt lgkmcnt(8)
	s_nop 0
	v_mfma_f32_16x16x32_bf16 v[104:107], v[138:141], v[56:59], v[32:35]
	s_nop 2
	v_mul_f32_e64 v34, v110, v62
	v_mul_f32_e64 v35, v111, v62
	v_pk_mul_f32 v[32:33], v[108:109], v[62:63] op_sel_hi:[1,0]
	s_nop 1
	v_mfma_f32_16x16x32_bf16 v[108:111], v[138:141], v[40:43], v[32:35]
	s_nop 2
	v_mul_f32_e64 v34, v114, v60
	v_mul_f32_e64 v35, v115, v60
	v_pk_mul_f32 v[32:33], v[112:113], v[60:61] op_sel_hi:[1,0]
	s_waitcnt lgkmcnt(6)
	s_nop 0
	v_mfma_f32_16x16x32_bf16 v[112:115], v[188:191], v[56:59], v[32:35]
	s_nop 2
	v_mul_f32_e64 v34, v118, v62
	v_mul_f32_e64 v35, v119, v62
	v_pk_mul_f32 v[32:33], v[116:117], v[62:63] op_sel_hi:[1,0]
	s_nop 1
	v_mfma_f32_16x16x32_bf16 v[116:119], v[188:191], v[40:43], v[32:35]
	v_add_u32_e32 v188, s76, v207
	s_nop 1
	v_pk_mul_f32 v[34:35], v[122:123], v[60:61] op_sel_hi:[1,0]
	v_pk_mul_f32 v[32:33], v[120:121], v[60:61] op_sel_hi:[1,0]
	s_waitcnt lgkmcnt(4)
	s_nop 0
	v_mfma_f32_16x16x32_bf16 v[120:123], v[200:203], v[56:59], v[32:35]
	v_or_b32_e32 v56, 0xb0, v166
	v_add_u32_e32 v56, s76, v56
	s_nop 0
	v_pk_mul_f32 v[34:35], v[126:127], v[62:63] op_sel_hi:[1,0]
	v_pk_mul_f32 v[32:33], v[124:125], v[62:63] op_sel_hi:[1,0]
	s_nop 1
	v_mfma_f32_16x16x32_bf16 v[124:127], v[200:203], v[40:43], v[32:35]
	s_nop 2
	v_add_u32_e32 v32, 0xa0, v149
	v_med3_i32 v32, v32, 0, s75
	v_lshl_add_u32 v32, v32, 9, v152
	global_load_dwordx4 v[76:79], v32, s[98:99]
	v_add_u32_e32 v32, 0xa0, v150
	v_med3_i32 v32, v32, 0, s75
	v_lshl_add_u32 v32, v32, 9, v152
	global_load_dwordx4 v[84:87], v32, s[98:99]
	v_add_u32_e32 v32, 0xa0, v151
	v_med3_i32 v32, v32, 0, s75
	v_lshl_add_u32 v32, v32, 9, v152
	global_load_dwordx4 v[92:95], v32, s[98:99]
	v_add_u32_e32 v32, 0xa0, v252
	v_med3_i32 v32, v32, 0, s75
	v_lshl_add_u32 v32, v32, 9, v152
	global_load_dwordx4 v[96:99], v32, s[98:99]
	v_or_b32_e32 v32, 0xa0, v166
	v_add_u32_e32 v32, s76, v32
	v_med3_i32 v32, v32, 0, s75
	v_med3_i32 v56, v56, 0, s75
	v_lshl_add_u32 v40, v32, 9, v158
	v_lshl_add_u32 v60, v56, 9, v158
	global_load_dwordx4 v[32:35], v40, s[100:101]
	s_nop 0
	global_load_dwordx4 v[40:43], v40, s[100:101] offset:64
	s_nop 0
	global_load_dwordx4 v[56:59], v60, s[100:101]
	s_nop 0
	global_load_dwordx4 v[60:63], v60, s[100:101] offset:64
	ds_read_b64_tr_b16 v[142:143], v169 offset:6912
	ds_read_b64_tr_b16 v[140:141], v169 offset:4608
	ds_read_b64_tr_b16 v[136:137], v169 offset:4640
	ds_read_b64_tr_b16 v[138:139], v169 offset:6944
	ds_read_b64_tr_b16 v[132:133], v169 offset:4672
	ds_read_b64_tr_b16 v[134:135], v169 offset:6976
	ds_read_b64_tr_b16 v[128:129], v169 offset:4704
	ds_read_b64_tr_b16 v[130:131], v169 offset:7008
	s_waitcnt vmcnt(15)
	ds_write_b128 v241, v[36:39]
	s_waitcnt vmcnt(14)
	ds_write_b128 v242, v[72:75]
	s_waitcnt vmcnt(13)
	ds_write_b128 v243, v[80:83]
	s_waitcnt vmcnt(12)
	ds_write_b128 v244, v[88:91]
	v_mfma_f32_16x16x32_bf16 v[36:39], v[24:27], v[4:7], 0
	v_mfma_f32_16x16x32_bf16 v[24:27], v[24:27], v[12:15], 0
	v_mfma_f32_16x16x32_bf16 v[36:39], v[28:31], v[8:11], v[36:39]
	v_mfma_f32_16x16x32_bf16 v[72:75], v[64:67], v[4:7], 0
	v_mfma_f32_16x16x32_bf16 v[24:27], v[28:31], v[0:3], v[24:27]
	v_mfma_f32_16x16x32_bf16 v[28:31], v[64:67], v[12:15], 0
	v_sub_u32_e32 v64, v199, v147
	v_add_u32_e32 v67, 1, v64
	s_nop 2
	v_max_f32_e32 v66, v36, v36
	v_cmp_gt_u32_e64 s[0:1], v67, v146
	v_cmp_gt_u32_e32 vcc, v64, v146
	v_max_f32_e32 v66, 0xf149f2ca, v66
	v_cndmask_b32_e64 v67, v37, v246, s[0:1]
	v_cndmask_b32_e32 v66, v66, v246, vcc
	v_mfma_f32_16x16x32_bf16 v[72:75], v[68:71], v[8:11], v[72:75]
	v_max_f32_e32 v66, v66, v67
	v_add_u32_e32 v67, 2, v64
	v_cmp_gt_u32_e64 s[22:23], v67, v146
	v_mfma_f32_16x16x32_bf16 v[28:31], v[68:71], v[0:3], v[28:31]
	v_add_u32_e32 v68, 3, v64
	v_cmp_gt_u32_e64 s[24:25], v68, v146
	v_cndmask_b32_e64 v67, v38, v246, s[22:23]
	v_sub_u32_e32 v65, v199, v148
	v_cndmask_b32_e64 v68, v39, v246, s[24:25]
	v_max3_f32 v66, v66, v67, v68
	v_add_u32_e32 v67, 16, v64
	v_add_u32_e32 v68, 17, v64
	v_cmp_gt_u32_e64 s[26:27], v67, v146
	v_cmp_gt_u32_e64 s[28:29], v68, v146
	v_cmp_gt_u32_e64 s[38:39], v65, v145
	v_cndmask_b32_e64 v67, v72, v246, s[26:27]
	v_cndmask_b32_e64 v68, v73, v246, s[28:29]
	v_max3_f32 v66, v66, v67, v68
	v_add_u32_e32 v67, 18, v64
	v_add_u32_e32 v64, 19, v64
	v_cmp_gt_u32_e64 s[30:31], v67, v146
	v_cmp_gt_u32_e64 s[34:35], v64, v146
	v_add_u32_e32 v68, 3, v65
	v_cndmask_b32_e64 v67, v74, v246, s[30:31]
	v_cndmask_b32_e64 v64, v75, v246, s[34:35]
	v_max3_f32 v64, v66, v67, v64
	v_add_u32_e32 v67, 1, v65
	v_max_f32_e32 v66, v24, v24
	v_cmp_gt_u32_e64 s[40:41], v67, v145
	v_max_f32_e32 v66, 0xf149f2ca, v66
	v_cndmask_b32_e64 v66, v66, v246, s[38:39]
	v_cndmask_b32_e64 v67, v25, v246, s[40:41]
	v_max_f32_e32 v66, v66, v67
	v_add_u32_e32 v67, 2, v65
	v_cmp_gt_u32_e64 s[42:43], v67, v145
	v_cmp_gt_u32_e64 s[44:45], v68, v145
	s_nop 0
	v_cndmask_b32_e64 v67, v26, v246, s[42:43]
	v_cndmask_b32_e64 v68, v27, v246, s[44:45]
	v_max3_f32 v66, v66, v67, v68
	v_add_u32_e32 v67, 16, v65
	v_add_u32_e32 v68, 17, v65
	v_cmp_gt_u32_e64 s[46:47], v67, v145
	v_cmp_gt_u32_e64 s[48:49], v68, v145
	s_nop 0
	v_cndmask_b32_e64 v67, v28, v246, s[46:47]
	v_cndmask_b32_e64 v68, v29, v246, s[48:49]
	v_max3_f32 v66, v66, v67, v68
	v_add_u32_e32 v67, 18, v65
	v_add_u32_e32 v65, 19, v65
	v_cmp_gt_u32_e64 s[50:51], v67, v145
	v_cmp_gt_u32_e64 s[52:53], v65, v145
	s_nop 0
	v_cndmask_b32_e64 v67, v30, v246, s[50:51]
	v_cndmask_b32_e64 v65, v31, v246, s[52:53]
	v_max3_f32 v65, v66, v67, v65
	v_mov_b32_e32 v66, v64
	v_mov_b32_e32 v67, v64
	s_nop 1
	v_permlane32_swap_b32_e32 v66, v67
	v_max3_f32 v64, v64, v66, v67
	v_mov_b32_e32 v66, v65
	v_mov_b32_e32 v67, v65
	s_nop 1
	v_permlane32_swap_b32_e32 v66, v67
	v_max3_f32 v65, v65, v66, v67
	v_mov_b32_e32 v66, v64
	v_mov_b32_e32 v67, v64
	s_nop 1
	v_permlane16_swap_b32_e32 v66, v67
	v_max_f32_e32 v64, v64, v66
	v_max3_f32 v179, v175, v64, v67
	v_sub_f32_e32 v36, v36, v179
	v_exp_f32_e32 v36, v36
	v_sub_f32_e32 v37, v37, v179
	v_mov_b32_e32 v66, v65
	v_mov_b32_e32 v68, v65
	v_exp_f32_e32 v37, v37
	v_sub_f32_e32 v38, v38, v179
	v_permlane16_swap_b32_e32 v66, v68
	v_exp_f32_e32 v38, v38
	v_sub_f32_e32 v39, v39, v179
	v_exp_f32_e32 v39, v39
	v_sub_f32_e32 v67, v72, v179
	v_max_f32_e32 v65, v65, v66
	v_cndmask_b32_e64 v36, v36, 0, vcc
	v_exp_f32_e32 v67, v67
	v_sub_f32_e32 v69, v73, v179
	v_add_f32_e32 v66, 0, v36
	v_cndmask_b32_e64 v37, v37, 0, s[0:1]
	v_exp_f32_e32 v69, v69
	v_sub_f32_e32 v70, v74, v179
	v_max3_f32 v181, v177, v65, v68
	v_add_f32_e32 v66, v37, v66
	v_cndmask_b32_e64 v38, v38, 0, s[22:23]
	v_exp_f32_e32 v70, v70
	v_sub_f32_e32 v71, v75, v179
	v_sub_f32_e32 v24, v24, v181
	v_add_f32_e32 v66, v38, v66
	v_cndmask_b32_e64 v39, v39, 0, s[24:25]
	v_exp_f32_e32 v71, v71
	v_exp_f32_e32 v24, v24
	v_sub_f32_e32 v25, v25, v181
	v_add_f32_e32 v66, v39, v66
	v_cndmask_b32_e64 v67, v67, 0, s[26:27]
	v_exp_f32_e32 v25, v25
	v_sub_f32_e32 v26, v26, v181
	v_add_f32_e32 v66, v67, v66
	v_cndmask_b32_e64 v69, v69, 0, s[28:29]
	v_exp_f32_e32 v26, v26
	v_sub_f32_e32 v27, v27, v181
	v_add_f32_e32 v66, v69, v66
	v_cndmask_b32_e64 v70, v70, 0, s[30:31]
	v_exp_f32_e32 v27, v27
	v_sub_f32_e32 v28, v28, v181
	v_add_f32_e32 v66, v70, v66
	v_cndmask_b32_e64 v71, v71, 0, s[34:35]
	v_sub_f32_e32 v65, v177, v181
	v_cndmask_b32_e64 v24, v24, 0, s[38:39]
	v_exp_f32_e32 v28, v28
	v_sub_f32_e32 v29, v29, v181
	v_add_f32_e32 v180, v71, v66
	v_exp_f32_e32 v66, v65
	v_add_f32_e32 v65, 0, v24
	v_cndmask_b32_e64 v25, v25, 0, s[40:41]
	v_exp_f32_e32 v29, v29
	v_sub_f32_e32 v30, v30, v181
	v_add_f32_e32 v65, v25, v65
	v_cndmask_b32_e64 v26, v26, 0, s[42:43]
	v_exp_f32_e32 v30, v30
	v_sub_f32_e32 v31, v31, v181
	v_sub_f32_e32 v64, v175, v179
	v_add_f32_e32 v65, v26, v65
	v_cndmask_b32_e64 v27, v27, 0, s[44:45]
	v_exp_f32_e32 v31, v31
	v_exp_f32_e32 v64, v64
	v_add_f32_e32 v65, v27, v65
	v_cndmask_b32_e64 v28, v28, 0, s[46:47]
	v_add_f32_e32 v65, v28, v65
	v_cndmask_b32_e64 v29, v29, 0, s[48:49]
	v_add_f32_e32 v65, v29, v65
	v_cndmask_b32_e64 v30, v30, 0, s[50:51]
	v_add_f32_e32 v65, v30, v65
	v_cndmask_b32_e64 v31, v31, 0, s[52:53]
	v_cvt_pk_bf16_f32 v36, v36, v37
	v_cvt_pk_bf16_f32 v37, v38, v39
	v_cvt_pk_bf16_f32 v38, v67, v69
	v_cvt_pk_bf16_f32 v39, v70, v71
	v_add_f32_e32 v183, v31, v65
	v_cvt_pk_bf16_f32 v24, v24, v25
	v_cvt_pk_bf16_f32 v25, v26, v27
	v_cvt_pk_bf16_f32 v26, v28, v29
	v_cvt_pk_bf16_f32 v27, v30, v31
	v_pk_mul_f32 v[30:31], v[46:47], v[64:65] op_sel_hi:[1,0]
	v_pk_mul_f32 v[28:29], v[44:45], v[64:65] op_sel_hi:[1,0]
	v_fmac_f32_e32 v180, v176, v64
	v_fmac_f32_e32 v183, v178, v66
	s_waitcnt lgkmcnt(10)
	v_mfma_f32_16x16x32_bf16 v[68:71], v[140:143], v[36:39], v[28:31]
	s_nop 2
	v_mul_f32_e64 v30, v102, v66
	v_mul_f32_e64 v31, v103, v66
	v_pk_mul_f32 v[28:29], v[100:101], v[66:67] op_sel_hi:[1,0]
	s_nop 1
	v_mfma_f32_16x16x32_bf16 v[72:75], v[140:143], v[24:27], v[28:31]
	s_nop 2
	v_mul_f32_e64 v30, v106, v64
	v_mul_f32_e64 v31, v107, v64
	v_pk_mul_f32 v[28:29], v[104:105], v[64:65] op_sel_hi:[1,0]
	s_waitcnt lgkmcnt(8)
	s_nop 0
	v_mfma_f32_16x16x32_bf16 v[80:83], v[136:139], v[36:39], v[28:31]
	s_nop 2
	v_mul_f32_e64 v30, v110, v66
	v_mul_f32_e64 v31, v111, v66
	v_pk_mul_f32 v[28:29], v[108:109], v[66:67] op_sel_hi:[1,0]
	s_nop 1
	v_mfma_f32_16x16x32_bf16 v[108:111], v[136:139], v[24:27], v[28:31]
	s_nop 2
	v_mul_f32_e64 v30, v114, v64
	v_mul_f32_e64 v31, v115, v64
	v_pk_mul_f32 v[28:29], v[112:113], v[64:65] op_sel_hi:[1,0]
	s_waitcnt lgkmcnt(6)
	s_nop 0
	v_mfma_f32_16x16x32_bf16 v[112:115], v[132:135], v[36:39], v[28:31]
	s_nop 2
	v_mul_f32_e64 v30, v118, v66
	v_mul_f32_e64 v31, v119, v66
	v_pk_mul_f32 v[28:29], v[116:117], v[66:67] op_sel_hi:[1,0]
	s_nop 1
	v_mfma_f32_16x16x32_bf16 v[116:119], v[132:135], v[24:27], v[28:31]
	s_nop 2
	v_mul_f32_e64 v30, v122, v64
	v_mul_f32_e64 v31, v123, v64
	v_pk_mul_f32 v[28:29], v[120:121], v[64:65] op_sel_hi:[1,0]
	s_waitcnt lgkmcnt(4)
	s_nop 0
	v_mfma_f32_16x16x32_bf16 v[120:123], v[128:131], v[36:39], v[28:31]
	s_nop 2
	v_mul_f32_e64 v30, v126, v66
	v_mul_f32_e64 v31, v127, v66
	v_pk_mul_f32 v[28:29], v[124:125], v[66:67] op_sel_hi:[1,0]
	s_nop 1
	v_mfma_f32_16x16x32_bf16 v[124:127], v[128:131], v[24:27], v[28:31]
	v_add_u32_e32 v24, 0xc0, v149
	v_med3_i32 v24, v24, 0, s75
	v_lshl_add_u32 v24, v24, 9, v152
	global_load_dwordx4 v[64:67], v24, s[98:99]
	v_add_u32_e32 v24, 0xc0, v150
	v_med3_i32 v24, v24, 0, s75
	v_lshl_add_u32 v24, v24, 9, v152
	global_load_dwordx4 v[88:91], v24, s[98:99]
	v_add_u32_e32 v24, 0xc0, v151
	v_med3_i32 v24, v24, 0, s75
	v_lshl_add_u32 v24, v24, 9, v152
	global_load_dwordx4 v[100:103], v24, s[98:99]
	v_add_u32_e32 v24, 0xc0, v252
	v_med3_i32 v24, v24, 0, s75
	v_lshl_add_u32 v24, v24, 9, v152
	global_load_dwordx4 v[104:107], v24, s[98:99]
	v_or_b32_e32 v24, 0xc0, v166
	v_add_u32_e32 v24, s76, v24
	v_med3_i32 v24, v24, 0, s75
	v_lshl_add_u32 v24, v24, 9, v158
	global_load_dwordx4 v[36:39], v24, s[100:101]
	global_load_dwordx4 v[44:47], v24, s[100:101] offset:64
	v_or_b32_e32 v24, 0xd0, v166
	v_add_u32_e32 v24, s76, v24
	v_med3_i32 v24, v24, 0, s75
	v_lshl_add_u32 v28, v24, 9, v158
	global_load_dwordx4 v[24:27], v28, s[100:101]
	s_nop 0
	global_load_dwordx4 v[28:31], v28, s[100:101] offset:64
	ds_read_b64_tr_b16 v[142:143], v169 offset:2304
	ds_read_b64_tr_b16 v[140:141], v169
	ds_read_b64_tr_b16 v[136:137], v169 offset:32
	ds_read_b64_tr_b16 v[138:139], v169 offset:2336
	ds_read_b64_tr_b16 v[132:133], v169 offset:64
	ds_read_b64_tr_b16 v[134:135], v169 offset:2368
	ds_read_b64_tr_b16 v[128:129], v169 offset:96
	ds_read_b64_tr_b16 v[130:131], v169 offset:2400
	s_waitcnt vmcnt(15)
	ds_write_b128 v241, v[76:79] offset:4608
	s_waitcnt vmcnt(14)
	ds_write_b128 v242, v[84:87] offset:4608
	s_waitcnt vmcnt(13)
	ds_write_b128 v243, v[92:95] offset:4608
	s_waitcnt vmcnt(12)
	ds_write_b128 v244, v[96:99] offset:4608
	v_mfma_f32_16x16x32_bf16 v[76:79], v[16:19], v[4:7], 0
	v_mfma_f32_16x16x32_bf16 v[16:19], v[16:19], v[12:15], 0
	v_mfma_f32_16x16x32_bf16 v[76:79], v[20:23], v[8:11], v[76:79]
	v_mfma_f32_16x16x32_bf16 v[84:87], v[48:51], v[4:7], 0
	v_mfma_f32_16x16x32_bf16 v[16:19], v[20:23], v[0:3], v[16:19]
	v_mfma_f32_16x16x32_bf16 v[20:23], v[48:51], v[12:15], 0
	v_add_u32_e32 v49, 0xc0, v154
	v_sub_u32_e32 v48, v49, v147
	v_add_u32_e32 v51, 1, v48
	s_nop 1
	v_max_f32_e32 v50, v76, v76
	v_cmp_gt_u32_e64 s[0:1], v51, v146
	v_cmp_gt_u32_e32 vcc, v48, v146
	v_max_f32_e32 v50, 0xf149f2ca, v50
	v_cndmask_b32_e64 v51, v77, v246, s[0:1]
	v_cndmask_b32_e32 v50, v50, v246, vcc
	v_mfma_f32_16x16x32_bf16 v[84:87], v[52:55], v[8:11], v[84:87]
	v_max_f32_e32 v50, v50, v51
	v_add_u32_e32 v51, 2, v48
	v_cmp_gt_u32_e64 s[22:23], v51, v146
	v_mfma_f32_16x16x32_bf16 v[20:23], v[52:55], v[0:3], v[20:23]
	v_add_u32_e32 v52, 3, v48
	v_cmp_gt_u32_e64 s[24:25], v52, v146
	v_cndmask_b32_e64 v51, v78, v246, s[22:23]
	v_sub_u32_e32 v49, v49, v148
	v_cndmask_b32_e64 v52, v79, v246, s[24:25]
	v_max3_f32 v50, v50, v51, v52
	v_add_u32_e32 v51, 16, v48
	v_add_u32_e32 v52, 17, v48
	v_cmp_gt_u32_e64 s[26:27], v51, v146
	v_cmp_gt_u32_e64 s[28:29], v52, v146
	v_cmp_gt_u32_e64 s[38:39], v49, v145
	v_cndmask_b32_e64 v51, v84, v246, s[26:27]
	v_cndmask_b32_e64 v52, v85, v246, s[28:29]
	v_max3_f32 v50, v50, v51, v52
	v_add_u32_e32 v51, 18, v48
	v_add_u32_e32 v48, 19, v48
	v_cmp_gt_u32_e64 s[30:31], v51, v146
	v_cmp_gt_u32_e64 s[34:35], v48, v146
	v_add_u32_e32 v52, 3, v49
	v_cndmask_b32_e64 v51, v86, v246, s[30:31]
	v_cndmask_b32_e64 v48, v87, v246, s[34:35]
	v_max3_f32 v48, v50, v51, v48
	v_add_u32_e32 v51, 1, v49
	v_max_f32_e32 v50, v16, v16
	v_cmp_gt_u32_e64 s[40:41], v51, v145
	v_max_f32_e32 v50, 0xf149f2ca, v50
	v_cndmask_b32_e64 v50, v50, v246, s[38:39]
	v_cndmask_b32_e64 v51, v17, v246, s[40:41]
	v_max_f32_e32 v50, v50, v51
	v_add_u32_e32 v51, 2, v49
	v_cmp_gt_u32_e64 s[42:43], v51, v145
	v_cmp_gt_u32_e64 s[44:45], v52, v145
	s_nop 0
	v_cndmask_b32_e64 v51, v18, v246, s[42:43]
	v_cndmask_b32_e64 v52, v19, v246, s[44:45]
	v_max3_f32 v50, v50, v51, v52
	v_add_u32_e32 v51, 16, v49
	v_add_u32_e32 v52, 17, v49
	v_cmp_gt_u32_e64 s[46:47], v51, v145
	v_cmp_gt_u32_e64 s[48:49], v52, v145
	s_nop 0
	v_cndmask_b32_e64 v51, v20, v246, s[46:47]
	v_cndmask_b32_e64 v52, v21, v246, s[48:49]
	v_max3_f32 v50, v50, v51, v52
	v_add_u32_e32 v51, 18, v49
	v_add_u32_e32 v49, 19, v49
	v_cmp_gt_u32_e64 s[50:51], v51, v145
	v_cmp_gt_u32_e64 s[52:53], v49, v145
	s_nop 0
	v_cndmask_b32_e64 v51, v22, v246, s[50:51]
	v_cndmask_b32_e64 v49, v23, v246, s[52:53]
	v_max3_f32 v49, v50, v51, v49
	v_mov_b32_e32 v50, v48
	v_mov_b32_e32 v51, v48
	s_nop 1
	v_permlane32_swap_b32_e32 v50, v51
	v_max3_f32 v48, v48, v50, v51
	v_mov_b32_e32 v50, v49
	v_mov_b32_e32 v51, v49
	s_nop 1
	v_permlane32_swap_b32_e32 v50, v51
	v_max3_f32 v49, v49, v50, v51
	v_mov_b32_e32 v50, v48
	v_mov_b32_e32 v51, v48
	s_nop 1
	v_permlane16_swap_b32_e32 v50, v51
	v_max_f32_e32 v48, v48, v50
	v_mov_b32_e32 v50, v49
	v_mov_b32_e32 v53, v49
	s_nop 1
	v_permlane16_swap_b32_e32 v50, v53
	v_max_f32_e32 v54, v49, v50
	v_max3_f32 v175, v179, v48, v51
	v_sub_f32_e32 v48, v179, v175
	v_max3_f32 v177, v181, v54, v53
	v_exp_f32_e32 v52, v48
	v_sub_f32_e32 v48, v76, v175
	v_sub_f32_e32 v16, v16, v177
	v_exp_f32_e32 v48, v48
	v_sub_f32_e32 v50, v77, v175
	v_exp_f32_e32 v16, v16
	v_sub_f32_e32 v17, v17, v177
	v_exp_f32_e32 v50, v50
	v_sub_f32_e32 v51, v78, v175
	v_exp_f32_e32 v17, v17
	v_sub_f32_e32 v18, v18, v177
	v_exp_f32_e32 v51, v51
	v_sub_f32_e32 v55, v79, v175
	v_exp_f32_e32 v18, v18
	v_sub_f32_e32 v19, v19, v177
	v_exp_f32_e32 v55, v55
	v_sub_f32_e32 v76, v84, v175
	v_exp_f32_e32 v19, v19
	v_sub_f32_e32 v20, v20, v177
	v_cndmask_b32_e64 v48, v48, 0, vcc
	v_exp_f32_e32 v76, v76
	v_sub_f32_e32 v77, v85, v175
	v_sub_f32_e32 v53, v181, v177
	v_cndmask_b32_e64 v16, v16, 0, s[38:39]
	v_exp_f32_e32 v20, v20
	v_sub_f32_e32 v21, v21, v177
	v_add_f32_e32 v49, 0, v48
	v_cndmask_b32_e64 v50, v50, 0, s[0:1]
	v_exp_f32_e32 v77, v77
	v_sub_f32_e32 v78, v86, v175
	v_exp_f32_e32 v54, v53
	v_add_f32_e32 v53, 0, v16
	v_cndmask_b32_e64 v17, v17, 0, s[40:41]
	v_exp_f32_e32 v21, v21
	v_sub_f32_e32 v22, v22, v177
	v_add_f32_e32 v49, v50, v49
	v_cndmask_b32_e64 v51, v51, 0, s[22:23]
	v_exp_f32_e32 v78, v78
	v_sub_f32_e32 v79, v87, v175
	v_add_f32_e32 v53, v17, v53
	v_cndmask_b32_e64 v18, v18, 0, s[42:43]
	v_exp_f32_e32 v22, v22
	v_sub_f32_e32 v23, v23, v177
	v_add_f32_e32 v49, v51, v49
	v_cndmask_b32_e64 v55, v55, 0, s[24:25]
	v_exp_f32_e32 v79, v79
	v_add_f32_e32 v53, v18, v53
	v_cndmask_b32_e64 v19, v19, 0, s[44:45]
	v_exp_f32_e32 v23, v23
	v_add_f32_e32 v49, v55, v49
	v_cndmask_b32_e64 v76, v76, 0, s[26:27]
	v_add_f32_e32 v53, v19, v53
	v_cndmask_b32_e64 v20, v20, 0, s[46:47]
	v_add_f32_e32 v49, v76, v49
	v_cndmask_b32_e64 v77, v77, 0, s[28:29]
	v_add_f32_e32 v53, v20, v53
	v_cndmask_b32_e64 v21, v21, 0, s[48:49]
	v_add_f32_e32 v49, v77, v49
	v_cndmask_b32_e64 v78, v78, 0, s[30:31]
	v_add_f32_e32 v53, v21, v53
	v_cndmask_b32_e64 v22, v22, 0, s[50:51]
	v_add_f32_e32 v49, v78, v49
	v_cndmask_b32_e64 v79, v79, 0, s[34:35]
	v_add_f32_e32 v53, v22, v53
	v_cndmask_b32_e64 v23, v23, 0, s[52:53]
	v_add_f32_e32 v176, v79, v49
	v_cvt_pk_bf16_f32 v48, v48, v50
	v_cvt_pk_bf16_f32 v49, v51, v55
	v_cvt_pk_bf16_f32 v50, v76, v77
	v_cvt_pk_bf16_f32 v51, v78, v79
	v_add_f32_e32 v178, v23, v53
	v_cvt_pk_bf16_f32 v16, v16, v17
	v_cvt_pk_bf16_f32 v17, v18, v19
	v_cvt_pk_bf16_f32 v18, v20, v21
	v_cvt_pk_bf16_f32 v19, v22, v23
	v_pk_mul_f32 v[22:23], v[70:71], v[52:53] op_sel_hi:[1,0]
	v_pk_mul_f32 v[20:21], v[68:69], v[52:53] op_sel_hi:[1,0]
	v_fmac_f32_e32 v176, v180, v52
	v_fmac_f32_e32 v178, v183, v54
	s_waitcnt lgkmcnt(10)
	v_mfma_f32_16x16x32_bf16 v[76:79], v[140:143], v[48:51], v[20:23]
	v_add_u32_e32 v180, 0x100, v149
	v_add_u32_e32 v179, 0x100, v150
	s_nop 0
	v_pk_mul_f32 v[22:23], v[74:75], v[54:55] op_sel_hi:[1,0]
	v_pk_mul_f32 v[20:21], v[72:73], v[54:55] op_sel_hi:[1,0]
	s_nop 1
	v_mfma_f32_16x16x32_bf16 v[92:95], v[140:143], v[16:19], v[20:23]
	s_nop 2
	v_mul_f32_e64 v22, v82, v52
	v_mul_f32_e64 v23, v83, v52
	v_pk_mul_f32 v[20:21], v[80:81], v[52:53] op_sel_hi:[1,0]
	s_waitcnt lgkmcnt(8)
	s_nop 0
	v_mfma_f32_16x16x32_bf16 v[96:99], v[136:139], v[48:51], v[20:23]
	s_nop 2
	v_mul_f32_e64 v22, v110, v54
	v_mul_f32_e64 v23, v111, v54
	v_pk_mul_f32 v[20:21], v[108:109], v[54:55] op_sel_hi:[1,0]
	s_nop 1
	v_mfma_f32_16x16x32_bf16 v[108:111], v[136:139], v[16:19], v[20:23]
	s_nop 2
	v_mul_f32_e64 v22, v114, v52
	v_mul_f32_e64 v23, v115, v52
	v_pk_mul_f32 v[20:21], v[112:113], v[52:53] op_sel_hi:[1,0]
	s_waitcnt lgkmcnt(6)
	s_nop 0
	v_mfma_f32_16x16x32_bf16 v[112:115], v[132:135], v[48:51], v[20:23]
	s_nop 2
	v_mul_f32_e64 v22, v118, v54
	v_mul_f32_e64 v23, v119, v54
	v_pk_mul_f32 v[20:21], v[116:117], v[54:55] op_sel_hi:[1,0]
	s_nop 1
	v_mfma_f32_16x16x32_bf16 v[116:119], v[132:135], v[16:19], v[20:23]
	s_nop 2
	v_mul_f32_e64 v22, v122, v52
	v_mul_f32_e64 v23, v123, v52
	v_pk_mul_f32 v[20:21], v[120:121], v[52:53] op_sel_hi:[1,0]
	s_waitcnt lgkmcnt(4)
	s_nop 0
	v_mfma_f32_16x16x32_bf16 v[120:123], v[128:131], v[48:51], v[20:23]
	s_nop 2
	v_mul_f32_e64 v22, v126, v54
	v_mul_f32_e64 v23, v127, v54
	v_pk_mul_f32 v[20:21], v[124:125], v[54:55] op_sel_hi:[1,0]
	s_nop 1
	v_mfma_f32_16x16x32_bf16 v[124:127], v[128:131], v[16:19], v[20:23]
	v_add_u32_e32 v16, 0xe0, v149
	v_med3_i32 v16, v16, 0, s75
	v_lshl_add_u32 v16, v16, 9, v152
	global_load_dwordx4 v[68:71], v16, s[98:99]
	v_add_u32_e32 v16, 0xe0, v150
	v_med3_i32 v16, v16, 0, s75
	v_lshl_add_u32 v16, v16, 9, v152
	global_load_dwordx4 v[72:75], v16, s[98:99]
	v_add_u32_e32 v16, 0xe0, v151
	v_med3_i32 v16, v16, 0, s75
	v_lshl_add_u32 v16, v16, 9, v152
	global_load_dwordx4 v[80:83], v16, s[98:99]
	v_add_u32_e32 v16, 0xe0, v252
	v_med3_i32 v16, v16, 0, s75
	v_lshl_add_u32 v16, v16, 9, v152
	global_load_dwordx4 v[84:87], v16, s[98:99]
	v_or_b32_e32 v16, 0xe0, v166
	v_add_u32_e32 v16, s76, v16
	v_med3_i32 v16, v16, 0, s75
	v_lshl_add_u32 v16, v16, 9, v158
	global_load_dwordx4 v[48:51], v16, s[100:101]
	global_load_dwordx4 v[52:55], v16, s[100:101] offset:64
	v_or_b32_e32 v16, 0xf0, v166
	v_add_u32_e32 v16, s76, v16
	v_med3_i32 v16, v16, 0, s75
	v_lshl_add_u32 v20, v16, 9, v158
	global_load_dwordx4 v[16:19], v20, s[100:101]
	s_nop 0
	global_load_dwordx4 v[20:23], v20, s[100:101] offset:64
	ds_read_b64_tr_b16 v[142:143], v169 offset:6912
	ds_read_b64_tr_b16 v[140:141], v169 offset:4608
	ds_read_b64_tr_b16 v[136:137], v169 offset:4640
	ds_read_b64_tr_b16 v[138:139], v169 offset:6944
	ds_read_b64_tr_b16 v[132:133], v169 offset:4672
	ds_read_b64_tr_b16 v[134:135], v169 offset:6976
	ds_read_b64_tr_b16 v[128:129], v169 offset:4704
	ds_read_b64_tr_b16 v[130:131], v169 offset:7008
	s_waitcnt vmcnt(15)
	ds_write_b128 v241, v[64:67]
	s_waitcnt vmcnt(14)
	ds_write_b128 v242, v[88:91]
	s_waitcnt vmcnt(13)
	ds_write_b128 v243, v[100:103]
	s_waitcnt vmcnt(12)
	ds_write_b128 v244, v[104:107]
	v_mfma_f32_16x16x32_bf16 v[64:67], v[32:35], v[4:7], 0
	v_mfma_f32_16x16x32_bf16 v[32:35], v[32:35], v[12:15], 0
	v_mfma_f32_16x16x32_bf16 v[64:67], v[40:43], v[8:11], v[64:67]
	v_mfma_f32_16x16x32_bf16 v[88:91], v[56:59], v[4:7], 0
	v_mfma_f32_16x16x32_bf16 v[32:35], v[40:43], v[0:3], v[32:35]
	v_mfma_f32_16x16x32_bf16 v[40:43], v[56:59], v[12:15], 0
	v_add_u32_e32 v57, 0xe0, v154
	v_sub_u32_e32 v56, v57, v147
	v_add_u32_e32 v59, 1, v56
	s_nop 1
	v_max_f32_e32 v58, v64, v64
	v_cmp_gt_u32_e64 s[0:1], v59, v146
	v_cmp_gt_u32_e32 vcc, v56, v146
	v_max_f32_e32 v58, 0xf149f2ca, v58
	v_cndmask_b32_e64 v59, v65, v246, s[0:1]
	v_cndmask_b32_e32 v58, v58, v246, vcc
	v_mfma_f32_16x16x32_bf16 v[88:91], v[60:63], v[8:11], v[88:91]
	v_max_f32_e32 v58, v58, v59
	v_add_u32_e32 v59, 2, v56
	v_cmp_gt_u32_e64 s[22:23], v59, v146
	v_mfma_f32_16x16x32_bf16 v[40:43], v[60:63], v[0:3], v[40:43]
	v_add_u32_e32 v60, 3, v56
	v_cmp_gt_u32_e64 s[24:25], v60, v146
	v_cndmask_b32_e64 v59, v66, v246, s[22:23]
	v_sub_u32_e32 v57, v57, v148
	v_cndmask_b32_e64 v60, v67, v246, s[24:25]
	v_max3_f32 v58, v58, v59, v60
	v_add_u32_e32 v59, 16, v56
	v_add_u32_e32 v60, 17, v56
	v_cmp_gt_u32_e64 s[26:27], v59, v146
	v_cmp_gt_u32_e64 s[28:29], v60, v146
	v_cmp_gt_u32_e64 s[38:39], v57, v145
	v_cndmask_b32_e64 v59, v88, v246, s[26:27]
	v_cndmask_b32_e64 v60, v89, v246, s[28:29]
	v_max3_f32 v58, v58, v59, v60
	v_add_u32_e32 v59, 18, v56
	v_add_u32_e32 v56, 19, v56
	v_cmp_gt_u32_e64 s[30:31], v59, v146
	v_cmp_gt_u32_e64 s[34:35], v56, v146
	v_add_u32_e32 v60, 3, v57
	v_cndmask_b32_e64 v59, v90, v246, s[30:31]
	v_cndmask_b32_e64 v56, v91, v246, s[34:35]
	v_max3_f32 v56, v58, v59, v56
	v_add_u32_e32 v59, 1, v57
	v_max_f32_e32 v58, v32, v32
	v_cmp_gt_u32_e64 s[40:41], v59, v145
	v_max_f32_e32 v58, 0xf149f2ca, v58
	v_cndmask_b32_e64 v58, v58, v246, s[38:39]
	v_cndmask_b32_e64 v59, v33, v246, s[40:41]
	v_max_f32_e32 v58, v58, v59
	v_add_u32_e32 v59, 2, v57
	v_cmp_gt_u32_e64 s[42:43], v59, v145
	v_cmp_gt_u32_e64 s[44:45], v60, v145
	s_nop 0
	v_cndmask_b32_e64 v59, v34, v246, s[42:43]
	v_cndmask_b32_e64 v60, v35, v246, s[44:45]
	v_max3_f32 v58, v58, v59, v60
	v_add_u32_e32 v59, 16, v57
	v_add_u32_e32 v60, 17, v57
	v_cmp_gt_u32_e64 s[46:47], v59, v145
	v_cmp_gt_u32_e64 s[48:49], v60, v145
	s_nop 0
	v_cndmask_b32_e64 v59, v40, v246, s[46:47]
	v_cndmask_b32_e64 v60, v41, v246, s[48:49]
	v_max3_f32 v58, v58, v59, v60
	v_add_u32_e32 v59, 18, v57
	v_add_u32_e32 v57, 19, v57
	v_cmp_gt_u32_e64 s[50:51], v59, v145
	v_cmp_gt_u32_e64 s[52:53], v57, v145
	s_nop 0
	v_cndmask_b32_e64 v59, v42, v246, s[50:51]
	v_cndmask_b32_e64 v57, v43, v246, s[52:53]
	v_max3_f32 v57, v58, v59, v57
	v_mov_b32_e32 v58, v56
	v_mov_b32_e32 v59, v56
	s_nop 1
	v_permlane32_swap_b32_e32 v58, v59
	v_max3_f32 v56, v56, v58, v59
	v_mov_b32_e32 v58, v57
	v_mov_b32_e32 v59, v57
	s_nop 1
	v_permlane32_swap_b32_e32 v58, v59
	v_max3_f32 v57, v57, v58, v59
	v_mov_b32_e32 v58, v56
	v_mov_b32_e32 v59, v56
	s_nop 1
	v_permlane16_swap_b32_e32 v58, v59
	v_max_f32_e32 v56, v56, v58
	v_mov_b32_e32 v58, v57
	v_mov_b32_e32 v61, v57
	s_nop 1
	v_permlane16_swap_b32_e32 v58, v61
	v_max_f32_e32 v62, v57, v58
	v_max3_f32 v181, v175, v56, v59
	v_sub_f32_e32 v56, v175, v181
	v_max3_f32 v184, v177, v62, v61
	v_exp_f32_e32 v60, v56
	v_sub_f32_e32 v56, v64, v181
	v_sub_f32_e32 v32, v32, v184
	v_exp_f32_e32 v56, v56
	v_sub_f32_e32 v58, v65, v181
	v_exp_f32_e32 v32, v32
	v_sub_f32_e32 v33, v33, v184
	v_exp_f32_e32 v58, v58
	v_sub_f32_e32 v59, v66, v181
	v_exp_f32_e32 v33, v33
	v_sub_f32_e32 v34, v34, v184
	v_exp_f32_e32 v59, v59
	v_sub_f32_e32 v63, v67, v181
	v_exp_f32_e32 v34, v34
	v_sub_f32_e32 v35, v35, v184
	v_exp_f32_e32 v63, v63
	v_sub_f32_e32 v64, v88, v181
	v_exp_f32_e32 v35, v35
	v_sub_f32_e32 v40, v40, v184
	v_cndmask_b32_e64 v56, v56, 0, vcc
	v_exp_f32_e32 v64, v64
	v_sub_f32_e32 v65, v89, v181
	v_sub_f32_e32 v61, v177, v184
	v_cndmask_b32_e64 v32, v32, 0, s[38:39]
	v_exp_f32_e32 v40, v40
	v_sub_f32_e32 v41, v41, v184
	v_add_f32_e32 v57, 0, v56
	v_cndmask_b32_e64 v58, v58, 0, s[0:1]
	v_exp_f32_e32 v65, v65
	v_sub_f32_e32 v66, v90, v181
	v_exp_f32_e32 v62, v61
	v_add_f32_e32 v61, 0, v32
	v_cndmask_b32_e64 v33, v33, 0, s[40:41]
	v_exp_f32_e32 v41, v41
	v_sub_f32_e32 v42, v42, v184
	v_add_f32_e32 v57, v58, v57
	v_cndmask_b32_e64 v59, v59, 0, s[22:23]
	v_exp_f32_e32 v66, v66
	v_sub_f32_e32 v67, v91, v181
	v_add_f32_e32 v61, v33, v61
	v_cndmask_b32_e64 v34, v34, 0, s[42:43]
	v_exp_f32_e32 v42, v42
	v_sub_f32_e32 v43, v43, v184
	v_add_f32_e32 v57, v59, v57
	v_cndmask_b32_e64 v63, v63, 0, s[24:25]
	v_exp_f32_e32 v67, v67
	v_add_f32_e32 v61, v34, v61
	v_cndmask_b32_e64 v35, v35, 0, s[44:45]
	v_exp_f32_e32 v43, v43
	v_add_f32_e32 v57, v63, v57
	v_cndmask_b32_e64 v64, v64, 0, s[26:27]
	v_add_f32_e32 v61, v35, v61
	v_cndmask_b32_e64 v40, v40, 0, s[46:47]
	v_add_f32_e32 v57, v64, v57
	v_cndmask_b32_e64 v65, v65, 0, s[28:29]
	v_add_f32_e32 v61, v40, v61
	v_cndmask_b32_e64 v41, v41, 0, s[48:49]
	v_add_f32_e32 v57, v65, v57
	v_cndmask_b32_e64 v66, v66, 0, s[30:31]
	v_add_f32_e32 v61, v41, v61
	v_cndmask_b32_e64 v42, v42, 0, s[50:51]
	v_add_f32_e32 v57, v66, v57
	v_cndmask_b32_e64 v67, v67, 0, s[34:35]
	v_add_f32_e32 v61, v42, v61
	v_cndmask_b32_e64 v43, v43, 0, s[52:53]
	v_add_f32_e32 v183, v67, v57
	v_cvt_pk_bf16_f32 v56, v56, v58
	v_cvt_pk_bf16_f32 v57, v59, v63
	v_cvt_pk_bf16_f32 v58, v64, v65
	v_cvt_pk_bf16_f32 v59, v66, v67
	v_add_f32_e32 v185, v43, v61
	v_cvt_pk_bf16_f32 v32, v32, v33
	v_cvt_pk_bf16_f32 v33, v34, v35
	v_cvt_pk_bf16_f32 v34, v40, v41
	v_cvt_pk_bf16_f32 v35, v42, v43
	v_pk_mul_f32 v[42:43], v[78:79], v[60:61] op_sel_hi:[1,0]
	v_pk_mul_f32 v[40:41], v[76:77], v[60:61] op_sel_hi:[1,0]
	v_fmac_f32_e32 v185, v178, v62
	s_waitcnt lgkmcnt(10)
	v_mfma_f32_16x16x32_bf16 v[100:103], v[140:143], v[56:59], v[40:43]
	v_add_u32_e32 v178, 0x100, v151
	v_fmac_f32_e32 v183, v176, v60
	v_add_u32_e32 v177, 0x100, v252
	v_pk_mul_f32 v[42:43], v[94:95], v[62:63] op_sel_hi:[1,0]
	v_pk_mul_f32 v[40:41], v[92:93], v[62:63] op_sel_hi:[1,0]
	s_nop 1
	v_mfma_f32_16x16x32_bf16 v[92:95], v[140:143], v[32:35], v[40:43]
	s_nop 2
	v_mul_f32_e64 v42, v98, v60
	v_mul_f32_e64 v43, v99, v60
	v_pk_mul_f32 v[40:41], v[96:97], v[60:61] op_sel_hi:[1,0]
	s_waitcnt lgkmcnt(8)
	s_nop 0
	v_mfma_f32_16x16x32_bf16 v[104:107], v[136:139], v[56:59], v[40:43]
	s_nop 2
	v_mul_f32_e64 v42, v110, v62
	v_mul_f32_e64 v43, v111, v62
	v_pk_mul_f32 v[40:41], v[108:109], v[62:63] op_sel_hi:[1,0]
	s_nop 1
	v_mfma_f32_16x16x32_bf16 v[108:111], v[136:139], v[32:35], v[40:43]
	s_nop 2
	v_mul_f32_e64 v42, v114, v60
	v_mul_f32_e64 v43, v115, v60
	v_pk_mul_f32 v[40:41], v[112:113], v[60:61] op_sel_hi:[1,0]
	s_waitcnt lgkmcnt(6)
	s_nop 0
	v_mfma_f32_16x16x32_bf16 v[112:115], v[132:135], v[56:59], v[40:43]
	s_nop 2
	v_mul_f32_e64 v42, v118, v62
	v_mul_f32_e64 v43, v119, v62
	v_pk_mul_f32 v[40:41], v[116:117], v[62:63] op_sel_hi:[1,0]
	s_nop 1
	v_mfma_f32_16x16x32_bf16 v[116:119], v[132:135], v[32:35], v[40:43]
	s_nop 2
	v_mul_f32_e64 v42, v122, v60
	v_mul_f32_e64 v43, v123, v60
	v_pk_mul_f32 v[40:41], v[120:121], v[60:61] op_sel_hi:[1,0]
	s_waitcnt lgkmcnt(4)
	s_nop 0
	v_mfma_f32_16x16x32_bf16 v[120:123], v[128:131], v[56:59], v[40:43]
	s_nop 2
	v_mul_f32_e64 v42, v126, v62
	v_mul_f32_e64 v43, v127, v62
	v_pk_mul_f32 v[40:41], v[124:125], v[62:63] op_sel_hi:[1,0]
	s_nop 1
	v_mfma_f32_16x16x32_bf16 v[124:127], v[128:131], v[32:35], v[40:43]
	v_med3_i32 v32, v180, 0, s75
	v_lshl_add_u32 v32, v32, 9, v152
	global_load_dwordx4 v[56:59], v32, s[98:99]
	v_med3_i32 v32, v179, 0, s75
	v_lshl_add_u32 v32, v32, 9, v152
	global_load_dwordx4 v[60:63], v32, s[98:99]
	v_med3_i32 v32, v178, 0, s75
	v_lshl_add_u32 v32, v32, 9, v152
	global_load_dwordx4 v[88:91], v32, s[98:99]
	v_med3_i32 v32, v177, 0, s75
	v_lshl_add_u32 v32, v32, 9, v152
	global_load_dwordx4 v[96:99], v32, s[98:99]
	v_or_b32_e32 v32, 0x100, v166
	v_add_u32_e32 v32, s76, v32
	v_med3_i32 v32, v32, 0, s75
	v_lshl_add_u32 v32, v32, 9, v158
	global_load_dwordx4 v[76:79], v32, s[100:101]
	global_load_dwordx4 v[64:67], v32, s[100:101] offset:64
	v_or_b32_e32 v32, 0x110, v166
	v_add_u32_e32 v32, s76, v32
	v_med3_i32 v32, v32, 0, s75
	v_lshl_add_u32 v32, v32, 9, v158
	global_load_dwordx4 v[40:43], v32, s[100:101]
	s_nop 0
	global_load_dwordx4 v[32:35], v32, s[100:101] offset:64
	ds_read_b64_tr_b16 v[142:143], v169 offset:2304
	ds_read_b64_tr_b16 v[140:141], v169
	ds_read_b64_tr_b16 v[136:137], v169 offset:32
	ds_read_b64_tr_b16 v[138:139], v169 offset:2336
	ds_read_b64_tr_b16 v[132:133], v169 offset:64
	ds_read_b64_tr_b16 v[134:135], v169 offset:2368
	ds_read_b64_tr_b16 v[128:129], v169 offset:96
	ds_read_b64_tr_b16 v[130:131], v169 offset:2400
	s_waitcnt vmcnt(15)
	ds_write_b128 v241, v[68:71] offset:4608
	s_waitcnt vmcnt(14)
	ds_write_b128 v242, v[72:75] offset:4608
	s_waitcnt vmcnt(13)
	ds_write_b128 v243, v[80:83] offset:4608
	s_waitcnt vmcnt(12)
	ds_write_b128 v244, v[84:87] offset:4608
	v_mfma_f32_16x16x32_bf16 v[68:71], v[36:39], v[4:7], 0
	v_mfma_f32_16x16x32_bf16 v[72:75], v[24:27], v[4:7], 0
	v_mfma_f32_16x16x32_bf16 v[24:27], v[24:27], v[12:15], 0
	v_mfma_f32_16x16x32_bf16 v[68:71], v[44:47], v[8:11], v[68:71]
	v_mfma_f32_16x16x32_bf16 v[72:75], v[28:31], v[8:11], v[72:75]
	v_mfma_f32_16x16x32_bf16 v[24:27], v[28:31], v[0:3], v[24:27]
	v_add_u32_e32 v29, 0x100, v154
	v_sub_u32_e32 v28, v29, v147
	v_add_u32_e32 v31, 1, v28
	v_mfma_f32_16x16x32_bf16 v[36:39], v[36:39], v[12:15], 0
	s_nop 1
	v_max_f32_e32 v30, v68, v68
	v_cmp_gt_u32_e64 s[0:1], v31, v146
	v_cmp_gt_u32_e32 vcc, v28, v146
	v_max_f32_e32 v30, 0xf149f2ca, v30
	v_cndmask_b32_e64 v31, v69, v246, s[0:1]
	v_cndmask_b32_e32 v30, v30, v246, vcc
	v_mfma_f32_16x16x32_bf16 v[36:39], v[44:47], v[0:3], v[36:39]
	v_max_f32_e32 v30, v30, v31
	v_add_u32_e32 v31, 2, v28
	v_add_u32_e32 v44, 3, v28
	v_cmp_gt_u32_e64 s[22:23], v31, v146
	v_cmp_gt_u32_e64 s[24:25], v44, v146
	v_sub_u32_e32 v29, v29, v148
	v_cndmask_b32_e64 v31, v70, v246, s[22:23]
	v_cndmask_b32_e64 v44, v71, v246, s[24:25]
	v_max3_f32 v30, v30, v31, v44
	v_add_u32_e32 v31, 16, v28
	v_add_u32_e32 v44, 17, v28
	v_cmp_gt_u32_e64 s[26:27], v31, v146
	v_cmp_gt_u32_e64 s[28:29], v44, v146
	v_cmp_gt_u32_e64 s[38:39], v29, v145
	v_cndmask_b32_e64 v31, v72, v246, s[26:27]
	v_cndmask_b32_e64 v44, v73, v246, s[28:29]
	v_max3_f32 v30, v30, v31, v44
	v_add_u32_e32 v31, 18, v28
	v_add_u32_e32 v28, 19, v28
	v_cmp_gt_u32_e64 s[30:31], v31, v146
	v_cmp_gt_u32_e64 s[34:35], v28, v146
	v_add_u32_e32 v44, 3, v29
	v_cndmask_b32_e64 v31, v74, v246, s[30:31]
	v_cndmask_b32_e64 v28, v75, v246, s[34:35]
	v_max3_f32 v28, v30, v31, v28
	v_add_u32_e32 v31, 1, v29
	v_max_f32_e32 v30, v36, v36
	v_cmp_gt_u32_e64 s[40:41], v31, v145
	v_max_f32_e32 v30, 0xf149f2ca, v30
	v_cndmask_b32_e64 v30, v30, v246, s[38:39]
	v_cndmask_b32_e64 v31, v37, v246, s[40:41]
	v_max_f32_e32 v30, v30, v31
	v_add_u32_e32 v31, 2, v29
	v_cmp_gt_u32_e64 s[42:43], v31, v145
	v_cmp_gt_u32_e64 s[44:45], v44, v145
	s_nop 0
	v_cndmask_b32_e64 v31, v38, v246, s[42:43]
	v_cndmask_b32_e64 v44, v39, v246, s[44:45]
	v_max3_f32 v30, v30, v31, v44
	v_add_u32_e32 v31, 16, v29
	v_add_u32_e32 v44, 17, v29
	v_cmp_gt_u32_e64 s[46:47], v31, v145
	v_cmp_gt_u32_e64 s[48:49], v44, v145
	s_nop 0
	v_cndmask_b32_e64 v31, v24, v246, s[46:47]
	v_cndmask_b32_e64 v44, v25, v246, s[48:49]
	v_max3_f32 v30, v30, v31, v44
	v_add_u32_e32 v31, 18, v29
	v_add_u32_e32 v29, 19, v29
	v_cmp_gt_u32_e64 s[50:51], v31, v145
	v_cmp_gt_u32_e64 s[52:53], v29, v145
	s_nop 0
	v_cndmask_b32_e64 v31, v26, v246, s[50:51]
	v_cndmask_b32_e64 v29, v27, v246, s[52:53]
	v_max3_f32 v29, v30, v31, v29
	v_mov_b32_e32 v30, v28
	v_mov_b32_e32 v31, v28
	s_nop 1
	v_permlane32_swap_b32_e32 v30, v31
	v_max3_f32 v28, v28, v30, v31
	v_mov_b32_e32 v30, v29
	v_mov_b32_e32 v31, v29
	s_nop 1
	v_permlane32_swap_b32_e32 v30, v31
	v_max3_f32 v29, v29, v30, v31
	v_mov_b32_e32 v30, v28
	v_mov_b32_e32 v31, v28
	s_nop 1
	v_permlane16_swap_b32_e32 v30, v31
	v_max_f32_e32 v28, v28, v30
	v_mov_b32_e32 v30, v29
	v_mov_b32_e32 v45, v29
	v_max3_f32 v175, v181, v28, v31
	s_nop 0
	v_permlane16_swap_b32_e32 v30, v45
	v_sub_f32_e32 v28, v181, v175
	v_exp_f32_e32 v44, v28
	v_sub_f32_e32 v28, v68, v175
	v_max_f32_e32 v46, v29, v30
	v_exp_f32_e32 v28, v28
	v_sub_f32_e32 v30, v69, v175
	v_exp_f32_e32 v30, v30
	v_sub_f32_e32 v31, v70, v175
	v_exp_f32_e32 v31, v31
	v_sub_f32_e32 v47, v71, v175
	v_max3_f32 v181, v184, v46, v45
	v_exp_f32_e32 v47, v47
	v_sub_f32_e32 v68, v72, v175
	v_sub_f32_e32 v36, v36, v181
	v_cndmask_b32_e64 v28, v28, 0, vcc
	v_exp_f32_e32 v68, v68
	v_sub_f32_e32 v69, v73, v175
	v_exp_f32_e32 v36, v36
	v_sub_f32_e32 v37, v37, v181
	v_add_f32_e32 v29, 0, v28
	v_cndmask_b32_e64 v30, v30, 0, s[0:1]
	v_exp_f32_e32 v69, v69
	v_sub_f32_e32 v70, v74, v175
	v_exp_f32_e32 v37, v37
	v_sub_f32_e32 v38, v38, v181
	v_add_f32_e32 v29, v30, v29
	v_cndmask_b32_e64 v31, v31, 0, s[22:23]
	v_exp_f32_e32 v70, v70
	v_sub_f32_e32 v71, v75, v175
	v_exp_f32_e32 v38, v38
	v_sub_f32_e32 v39, v39, v181
	v_add_f32_e32 v29, v31, v29
	v_cndmask_b32_e64 v47, v47, 0, s[24:25]
	v_exp_f32_e32 v71, v71
	v_exp_f32_e32 v39, v39
	v_sub_f32_e32 v24, v24, v181
	v_add_f32_e32 v29, v47, v29
	v_cndmask_b32_e64 v68, v68, 0, s[26:27]
	v_sub_f32_e32 v45, v184, v181
	v_cndmask_b32_e64 v36, v36, 0, s[38:39]
	v_exp_f32_e32 v24, v24
	v_sub_f32_e32 v25, v25, v181
	v_add_f32_e32 v29, v68, v29
	v_cndmask_b32_e64 v69, v69, 0, s[28:29]
	v_exp_f32_e32 v46, v45
	v_add_f32_e32 v45, 0, v36
	v_cndmask_b32_e64 v37, v37, 0, s[40:41]
	v_exp_f32_e32 v25, v25
	v_add_f32_e32 v29, v69, v29
	v_cndmask_b32_e64 v70, v70, 0, s[30:31]
	v_add_f32_e32 v45, v37, v45
	v_cndmask_b32_e64 v38, v38, 0, s[42:43]
	v_add_f32_e32 v29, v70, v29
	v_cndmask_b32_e64 v71, v71, 0, s[34:35]
	v_add_f32_e32 v45, v38, v45
	v_cndmask_b32_e64 v39, v39, 0, s[44:45]
	v_add_f32_e32 v176, v71, v29
	v_cvt_pk_bf16_f32 v29, v31, v47
	v_add_f32_e32 v45, v39, v45
	v_cndmask_b32_e64 v47, v24, 0, s[46:47]
	v_add_f32_e32 v24, v47, v45
	v_cndmask_b32_e64 v45, v25, 0, s[48:49]
	v_sub_f32_e32 v25, v26, v181
	v_exp_f32_e32 v25, v25
	v_cvt_pk_bf16_f32 v28, v28, v30
	v_cvt_pk_bf16_f32 v30, v68, v69
	v_add_f32_e32 v24, v45, v24
	v_cndmask_b32_e64 v68, v25, 0, s[50:51]
	v_sub_f32_e32 v25, v27, v181
	v_exp_f32_e32 v25, v25
	v_add_f32_e32 v24, v68, v24
	v_fmac_f32_e32 v176, v183, v44
	v_cvt_pk_bf16_f32 v31, v70, v71
	v_cndmask_b32_e64 v27, v25, 0, s[52:53]
	v_add_f32_e32 v183, v27, v24
	v_cvt_pk_bf16_f32 v24, v36, v37
	v_cvt_pk_bf16_f32 v25, v38, v39
	v_pk_mul_f32 v[38:39], v[102:103], v[44:45] op_sel_hi:[1,0]
	v_pk_mul_f32 v[36:37], v[100:101], v[44:45] op_sel_hi:[1,0]
	v_cvt_pk_bf16_f32 v26, v47, v45
	v_cvt_pk_bf16_f32 v27, v68, v27
	s_waitcnt lgkmcnt(10)
	v_mfma_f32_16x16x32_bf16 v[80:83], v[140:143], v[28:31], v[36:39]
	v_fmac_f32_e32 v183, v185, v46
	v_add_u32_e32 v184, s76, v204
	v_add_u32_e32 v185, s76, v205
	v_pk_mul_f32 v[38:39], v[94:95], v[46:47] op_sel_hi:[1,0]
	v_pk_mul_f32 v[36:37], v[92:93], v[46:47] op_sel_hi:[1,0]
	s_nop 1
	v_mfma_f32_16x16x32_bf16 v[84:87], v[140:143], v[24:27], v[36:39]
	s_nop 2
	v_mul_f32_e64 v38, v106, v44
	v_mul_f32_e64 v39, v107, v44
	v_pk_mul_f32 v[36:37], v[104:105], v[44:45] op_sel_hi:[1,0]
	s_waitcnt lgkmcnt(8)
	s_nop 0
	v_mfma_f32_16x16x32_bf16 v[104:107], v[136:139], v[28:31], v[36:39]
	s_nop 2
	v_mul_f32_e64 v38, v110, v46
	v_mul_f32_e64 v39, v111, v46
	v_pk_mul_f32 v[36:37], v[108:109], v[46:47] op_sel_hi:[1,0]
	s_nop 1
	v_mfma_f32_16x16x32_bf16 v[108:111], v[136:139], v[24:27], v[36:39]
	s_nop 2
	v_mul_f32_e64 v38, v114, v44
	v_mul_f32_e64 v39, v115, v44
	v_pk_mul_f32 v[36:37], v[112:113], v[44:45] op_sel_hi:[1,0]
	s_waitcnt lgkmcnt(6)
	s_nop 0
	v_mfma_f32_16x16x32_bf16 v[112:115], v[132:135], v[28:31], v[36:39]
	s_nop 2
	v_mul_f32_e64 v38, v118, v46
	v_mul_f32_e64 v39, v119, v46
	v_pk_mul_f32 v[36:37], v[116:117], v[46:47] op_sel_hi:[1,0]
	s_nop 1
	v_mfma_f32_16x16x32_bf16 v[116:119], v[132:135], v[24:27], v[36:39]
	s_nop 2
	v_mul_f32_e64 v38, v122, v44
	v_mul_f32_e64 v39, v123, v44
	v_pk_mul_f32 v[36:37], v[120:121], v[44:45] op_sel_hi:[1,0]
	s_waitcnt lgkmcnt(4)
	s_nop 0
	v_mfma_f32_16x16x32_bf16 v[120:123], v[128:131], v[28:31], v[36:39]
	v_mul_f32_e64 v30, v126, v46
	v_mul_f32_e64 v31, v127, v46
	v_pk_mul_f32 v[28:29], v[124:125], v[46:47] op_sel_hi:[1,0]
	s_nop 1
	v_mfma_f32_16x16x32_bf16 v[124:127], v[128:131], v[24:27], v[28:31]
	v_add_u32_e32 v24, 0x120, v149
	v_med3_i32 v24, v24, 0, s75
	v_lshl_add_u32 v24, v24, 9, v152
	global_load_dwordx4 v[28:31], v24, s[98:99]
	v_add_u32_e32 v24, 0x120, v150
	v_med3_i32 v24, v24, 0, s75
	v_lshl_add_u32 v24, v24, 9, v152
	global_load_dwordx4 v[44:47], v24, s[98:99]
	v_add_u32_e32 v24, 0x120, v151
	v_med3_i32 v24, v24, 0, s75
	v_lshl_add_u32 v24, v24, 9, v152
	global_load_dwordx4 v[92:95], v24, s[98:99]
	v_add_u32_e32 v24, 0x120, v252
	v_med3_i32 v24, v24, 0, s75
	v_lshl_add_u32 v24, v24, 9, v152
	global_load_dwordx4 v[100:103], v24, s[98:99]
	v_or_b32_e32 v24, 0x120, v166
	v_add_u32_e32 v24, s76, v24
	v_med3_i32 v24, v24, 0, s75
	v_lshl_add_u32 v24, v24, 9, v158
	global_load_dwordx4 v[72:75], v24, s[100:101]
	global_load_dwordx4 v[68:71], v24, s[100:101] offset:64
	v_or_b32_e32 v24, 0x130, v166
	v_add_u32_e32 v24, s76, v24
	v_med3_i32 v24, v24, 0, s75
	v_lshl_add_u32 v24, v24, 9, v158
	global_load_dwordx4 v[36:39], v24, s[100:101]
	s_nop 0
	global_load_dwordx4 v[24:27], v24, s[100:101] offset:64
	ds_read_b64_tr_b16 v[142:143], v169 offset:6912
	ds_read_b64_tr_b16 v[140:141], v169 offset:4608
	ds_read_b64_tr_b16 v[136:137], v169 offset:4640
	ds_read_b64_tr_b16 v[138:139], v169 offset:6944
	ds_read_b64_tr_b16 v[132:133], v169 offset:4672
	ds_read_b64_tr_b16 v[134:135], v169 offset:6976
	ds_read_b64_tr_b16 v[128:129], v169 offset:4704
	ds_read_b64_tr_b16 v[130:131], v169 offset:7008
	s_waitcnt vmcnt(15)
	ds_write_b128 v241, v[56:59]
	s_waitcnt vmcnt(14)
	ds_write_b128 v242, v[60:63]
	s_waitcnt vmcnt(13)
	ds_write_b128 v243, v[88:91]
	s_waitcnt vmcnt(12)
	ds_write_b128 v244, v[96:99]
	v_mfma_f32_16x16x32_bf16 v[56:59], v[48:51], v[4:7], 0
	v_mfma_f32_16x16x32_bf16 v[60:63], v[16:19], v[4:7], 0
	v_mfma_f32_16x16x32_bf16 v[16:19], v[16:19], v[12:15], 0
	v_mfma_f32_16x16x32_bf16 v[56:59], v[52:55], v[8:11], v[56:59]
	v_mfma_f32_16x16x32_bf16 v[60:63], v[20:23], v[8:11], v[60:63]
	v_mfma_f32_16x16x32_bf16 v[16:19], v[20:23], v[0:3], v[16:19]
	v_sub_u32_e32 v20, v195, v147
	v_add_u32_e32 v23, 1, v20
	s_nop 3
	v_max_f32_e32 v22, v56, v56
	v_mfma_f32_16x16x32_bf16 v[48:51], v[48:51], v[12:15], 0
	v_cmp_gt_u32_e64 s[0:1], v23, v146
	v_cmp_gt_u32_e32 vcc, v20, v146
	v_max_f32_e32 v22, 0xf149f2ca, v22
	v_cndmask_b32_e64 v23, v57, v246, s[0:1]
	v_cndmask_b32_e32 v22, v22, v246, vcc
	v_mfma_f32_16x16x32_bf16 v[48:51], v[52:55], v[0:3], v[48:51]
	v_max_f32_e32 v22, v22, v23
	v_add_u32_e32 v23, 2, v20
	v_add_u32_e32 v52, 3, v20
	v_cmp_gt_u32_e64 s[22:23], v23, v146
	v_cmp_gt_u32_e64 s[24:25], v52, v146
	v_sub_u32_e32 v21, v195, v148
	v_cndmask_b32_e64 v23, v58, v246, s[22:23]
	v_cndmask_b32_e64 v52, v59, v246, s[24:25]
	v_max3_f32 v22, v22, v23, v52
	v_add_u32_e32 v23, 16, v20
	v_add_u32_e32 v52, 17, v20
	v_cmp_gt_u32_e64 s[26:27], v23, v146
	v_cmp_gt_u32_e64 s[28:29], v52, v146
	v_cmp_gt_u32_e64 s[38:39], v21, v145
	v_cndmask_b32_e64 v23, v60, v246, s[26:27]
	v_cndmask_b32_e64 v52, v61, v246, s[28:29]
	v_max3_f32 v22, v22, v23, v52
	v_add_u32_e32 v23, 18, v20
	v_add_u32_e32 v20, 19, v20
	v_cmp_gt_u32_e64 s[30:31], v23, v146
	v_cmp_gt_u32_e64 s[34:35], v20, v146
	v_add_u32_e32 v52, 3, v21
	v_cndmask_b32_e64 v23, v62, v246, s[30:31]
	v_cndmask_b32_e64 v20, v63, v246, s[34:35]
	v_max3_f32 v20, v22, v23, v20
	v_add_u32_e32 v23, 1, v21
	v_max_f32_e32 v22, v48, v48
	v_cmp_gt_u32_e64 s[40:41], v23, v145
	v_max_f32_e32 v22, 0xf149f2ca, v22
	v_cndmask_b32_e64 v22, v22, v246, s[38:39]
	v_cndmask_b32_e64 v23, v49, v246, s[40:41]
	v_max_f32_e32 v22, v22, v23
	v_add_u32_e32 v23, 2, v21
	v_cmp_gt_u32_e64 s[42:43], v23, v145
	v_cmp_gt_u32_e64 s[44:45], v52, v145
	s_nop 0
	v_cndmask_b32_e64 v23, v50, v246, s[42:43]
	v_cndmask_b32_e64 v52, v51, v246, s[44:45]
	v_max3_f32 v22, v22, v23, v52
	v_add_u32_e32 v23, 16, v21
	v_add_u32_e32 v52, 17, v21
	v_cmp_gt_u32_e64 s[46:47], v23, v145
	v_cmp_gt_u32_e64 s[48:49], v52, v145
	s_nop 0
	v_cndmask_b32_e64 v23, v16, v246, s[46:47]
	v_cndmask_b32_e64 v52, v17, v246, s[48:49]
	v_max3_f32 v22, v22, v23, v52
	v_add_u32_e32 v23, 18, v21
	v_add_u32_e32 v21, 19, v21
	v_cmp_gt_u32_e64 s[50:51], v23, v145
	v_cmp_gt_u32_e64 s[52:53], v21, v145
	s_nop 0
	v_cndmask_b32_e64 v23, v18, v246, s[50:51]
	v_cndmask_b32_e64 v21, v19, v246, s[52:53]
	v_max3_f32 v21, v22, v23, v21
	v_mov_b32_e32 v22, v20
	v_mov_b32_e32 v23, v20
	s_nop 1
	v_permlane32_swap_b32_e32 v22, v23
	v_max3_f32 v20, v20, v22, v23
	v_mov_b32_e32 v22, v21
	v_mov_b32_e32 v23, v21
	s_nop 1
	v_permlane32_swap_b32_e32 v22, v23
	v_max3_f32 v21, v21, v22, v23
	v_mov_b32_e32 v22, v20
	v_mov_b32_e32 v23, v20
	s_nop 1
	v_permlane16_swap_b32_e32 v22, v23
	v_max_f32_e32 v20, v20, v22
	v_max3_f32 v149, v175, v20, v23
	v_sub_f32_e32 v20, v175, v149
	v_exp_f32_e32 v88, v20
	v_sub_f32_e32 v20, v56, v149
	v_sub_f32_e32 v56, v61, v149
	v_exp_f32_e32 v56, v56
	v_exp_f32_e32 v20, v20
	v_sub_f32_e32 v23, v57, v149
	v_exp_f32_e32 v23, v23
	v_sub_f32_e32 v53, v58, v149
	v_cndmask_b32_e64 v58, v56, 0, s[28:29]
	v_sub_f32_e32 v56, v62, v149
	v_mov_b32_e32 v22, v21
	v_mov_b32_e32 v52, v21
	v_exp_f32_e32 v53, v53
	v_sub_f32_e32 v54, v59, v149
	v_exp_f32_e32 v56, v56
	v_permlane16_swap_b32_e32 v22, v52
	v_exp_f32_e32 v54, v54
	v_sub_f32_e32 v55, v60, v149
	v_cndmask_b32_e64 v20, v20, 0, vcc
	v_exp_f32_e32 v55, v55
	v_max_f32_e32 v21, v21, v22
	v_add_f32_e32 v22, 0, v20
	v_cndmask_b32_e64 v23, v23, 0, s[0:1]
	v_add_f32_e32 v22, v23, v22
	v_cndmask_b32_e64 v53, v53, 0, s[22:23]
	v_cndmask_b32_e64 v59, v56, 0, s[30:31]
	v_sub_f32_e32 v56, v63, v149
	v_add_f32_e32 v22, v53, v22
	v_cndmask_b32_e64 v54, v54, 0, s[24:25]
	v_exp_f32_e32 v56, v56
	v_add_f32_e32 v22, v54, v22
	v_cndmask_b32_e64 v55, v55, 0, s[26:27]
	v_add_f32_e32 v22, v55, v22
	v_add_f32_e32 v22, v58, v22
	v_max3_f32 v151, v181, v21, v52
	v_add_f32_e32 v22, v59, v22
	v_cndmask_b32_e64 v60, v56, 0, s[34:35]
	v_cvt_pk_bf16_f32 v56, v20, v23
	v_sub_f32_e32 v20, v181, v151
	v_add_f32_e32 v150, v60, v22
	v_cvt_pk_bf16_f32 v59, v59, v60
	v_exp_f32_e32 v60, v20
	v_sub_f32_e32 v20, v48, v151
	v_exp_f32_e32 v20, v20
	v_sub_f32_e32 v22, v49, v151
	v_exp_f32_e32 v22, v22
	v_sub_f32_e32 v23, v50, v151
	v_exp_f32_e32 v23, v23
	v_sub_f32_e32 v48, v51, v151
	v_exp_f32_e32 v48, v48
	v_sub_f32_e32 v16, v16, v151
	v_cndmask_b32_e64 v20, v20, 0, s[38:39]
	v_exp_f32_e32 v16, v16
	v_sub_f32_e32 v17, v17, v151
	v_add_f32_e32 v21, 0, v20
	v_cndmask_b32_e64 v22, v22, 0, s[40:41]
	v_exp_f32_e32 v17, v17
	v_add_f32_e32 v21, v22, v21
	v_cndmask_b32_e64 v23, v23, 0, s[42:43]
	v_add_f32_e32 v21, v23, v21
	v_cndmask_b32_e64 v48, v48, 0, s[44:45]
	v_add_f32_e32 v21, v48, v21
	v_cndmask_b32_e64 v49, v16, 0, s[46:47]
	v_add_f32_e32 v16, v49, v21
	v_cndmask_b32_e64 v21, v17, 0, s[48:49]
	v_sub_f32_e32 v17, v18, v151
	v_exp_f32_e32 v17, v17
	v_add_f32_e32 v16, v21, v16
	v_cvt_pk_bf16_f32 v18, v49, v21
	v_cvt_pk_bf16_f32 v57, v53, v54
	v_cndmask_b32_e64 v50, v17, 0, s[50:51]
	v_sub_f32_e32 v17, v19, v151
	v_exp_f32_e32 v17, v17
	v_add_f32_e32 v16, v50, v16
	v_cvt_pk_bf16_f32 v58, v55, v58
	v_fmac_f32_e32 v150, v176, v88
	v_cndmask_b32_e64 v19, v17, 0, s[52:53]
	v_add_f32_e32 v175, v19, v16
	v_cvt_pk_bf16_f32 v16, v20, v22
	v_cvt_pk_bf16_f32 v17, v23, v48
	v_cvt_pk_bf16_f32 v19, v50, v19
	v_pk_mul_f32 v[50:51], v[86:87], v[60:61] op_sel_hi:[1,0]
	v_pk_mul_f32 v[48:49], v[84:85], v[60:61] op_sel_hi:[1,0]
	v_pk_mul_f32 v[22:23], v[82:83], v[88:89] op_sel_hi:[1,0]
	v_pk_mul_f32 v[20:21], v[80:81], v[88:89] op_sel_hi:[1,0]
	s_waitcnt lgkmcnt(10)
	v_mfma_f32_16x16x32_bf16 v[52:55], v[140:143], v[16:19], v[48:51]
	v_fmac_f32_e32 v175, v183, v60
	s_nop 1
	v_pk_mul_f32 v[50:51], v[106:107], v[88:89] op_sel_hi:[1,0]
	v_pk_mul_f32 v[48:49], v[104:105], v[88:89] op_sel_hi:[1,0]
	v_mfma_f32_16x16x32_bf16 v[20:23], v[140:143], v[56:59], v[20:23]
	s_waitcnt lgkmcnt(8)
	v_mfma_f32_16x16x32_bf16 v[104:107], v[136:139], v[56:59], v[48:51]
	s_nop 2
	v_mul_f32_e64 v50, v110, v60
	v_mul_f32_e64 v51, v111, v60
	v_pk_mul_f32 v[48:49], v[108:109], v[60:61] op_sel_hi:[1,0]
	s_nop 1
	v_mfma_f32_16x16x32_bf16 v[108:111], v[136:139], v[16:19], v[48:51]
	s_nop 2
	v_mul_f32_e64 v50, v114, v88
	v_mul_f32_e64 v51, v115, v88
	v_pk_mul_f32 v[48:49], v[112:113], v[88:89] op_sel_hi:[1,0]
	s_waitcnt lgkmcnt(6)
	s_nop 0
	v_mfma_f32_16x16x32_bf16 v[112:115], v[132:135], v[56:59], v[48:51]
	s_nop 2
	v_mul_f32_e64 v50, v118, v60
	v_mul_f32_e64 v51, v119, v60
	v_pk_mul_f32 v[48:49], v[116:117], v[60:61] op_sel_hi:[1,0]
	s_nop 1
	v_mfma_f32_16x16x32_bf16 v[116:119], v[132:135], v[16:19], v[48:51]
	s_nop 2
	v_mul_f32_e64 v50, v122, v88
	v_mul_f32_e64 v51, v123, v88
	v_pk_mul_f32 v[48:49], v[120:121], v[88:89] op_sel_hi:[1,0]
	s_waitcnt lgkmcnt(4)
	s_nop 0
	v_mfma_f32_16x16x32_bf16 v[120:123], v[128:131], v[56:59], v[48:51]
	v_add_u32_e32 v56, 0xffffff00, v206
	v_add_u32_e32 v56, s76, v56
	s_nop 0
	v_pk_mul_f32 v[50:51], v[126:127], v[60:61] op_sel_hi:[1,0]
	v_pk_mul_f32 v[48:49], v[124:125], v[60:61] op_sel_hi:[1,0]
	s_nop 1
	v_mfma_f32_16x16x32_bf16 v[124:127], v[128:131], v[16:19], v[48:51]
	v_add_u32_e32 v16, 0xffffff00, v204
	v_add_u32_e32 v16, s76, v16
	s_nop 0
	v_add_u32_e32 v48, 0xffffff00, v205
	v_add_u32_e32 v48, s76, v48
	v_med3_i32 v16, v16, 0, s75
	v_med3_i32 v48, v48, 0, s75
	v_med3_i32 v56, v56, 0, s75
	v_lshl_add_u32 v56, v56, 9, v152
	global_load_dwordx4 v[88:91], v56, s[98:99]
	v_add_u32_e32 v56, 0xffffff00, v207
	v_add_u32_e32 v56, s76, v56
	v_med3_i32 v56, v56, 0, s75
	v_lshl_add_u32 v56, v56, 9, v152
	global_load_dwordx4 v[96:99], v56, s[98:99]
	v_add_u32_e32 v56, s76, v208
	v_lshl_add_u32 v16, v16, 9, v152
	v_lshl_add_u32 v48, v48, 9, v152
	v_med3_i32 v56, v56, 0, s75
	v_lshl_add_u32 v56, v56, 9, v158
	global_load_dwordx4 v[16:19], v16, s[98:99]
	s_nop 0
	global_load_dwordx4 v[48:51], v48, s[98:99]
	s_nop 0
	global_load_dwordx4 v[84:87], v56, s[100:101]
	global_load_dwordx4 v[80:83], v56, s[100:101] offset:64
	v_or_b32_e32 v56, 0xffffff40, v209
	v_add_u32_e32 v56, s76, v56
	v_med3_i32 v56, v56, 0, s75
	v_lshl_add_u32 v56, v56, 9, v158
	global_load_dwordx4 v[60:63], v56, s[100:101]
	s_nop 0
	global_load_dwordx4 v[56:59], v56, s[100:101] offset:64
	ds_read_b64_tr_b16 v[142:143], v169 offset:2304
	ds_read_b64_tr_b16 v[140:141], v169
	ds_read_b64_tr_b16 v[136:137], v169 offset:32
	ds_read_b64_tr_b16 v[138:139], v169 offset:2336
	ds_read_b64_tr_b16 v[132:133], v169 offset:64
	ds_read_b64_tr_b16 v[134:135], v169 offset:2368
	ds_read_b64_tr_b16 v[128:129], v169 offset:96
	ds_read_b64_tr_b16 v[130:131], v169 offset:2400
	s_waitcnt vmcnt(15)
	ds_write_b128 v241, v[28:31] offset:4608
	s_waitcnt vmcnt(14)
	ds_write_b128 v242, v[44:47] offset:4608
	s_waitcnt vmcnt(13)
	ds_write_b128 v243, v[92:95] offset:4608
	s_waitcnt vmcnt(12)
	ds_write_b128 v244, v[100:103] offset:4608
	v_mfma_f32_16x16x32_bf16 v[28:31], v[76:79], v[4:7], 0
	v_mfma_f32_16x16x32_bf16 v[44:47], v[40:43], v[4:7], 0
	v_mfma_f32_16x16x32_bf16 v[40:43], v[40:43], v[12:15], 0
	v_mfma_f32_16x16x32_bf16 v[28:31], v[64:67], v[8:11], v[28:31]
	v_mfma_f32_16x16x32_bf16 v[44:47], v[32:35], v[8:11], v[44:47]
	v_mfma_f32_16x16x32_bf16 v[32:35], v[32:35], v[0:3], v[40:43]
	s_nop 4
	v_sub_u32_e32 v40, v210, v147
	v_mfma_f32_16x16x32_bf16 v[76:79], v[76:79], v[12:15], 0
	v_add_u32_e32 v43, 1, v40
	v_max_f32_e32 v42, v28, v28
	v_cmp_gt_u32_e64 s[0:1], v43, v146
	v_cmp_gt_u32_e32 vcc, v40, v146
	v_max_f32_e32 v42, 0xf149f2ca, v42
	v_cndmask_b32_e64 v43, v29, v246, s[0:1]
	v_cndmask_b32_e32 v42, v42, v246, vcc
	v_mfma_f32_16x16x32_bf16 v[64:67], v[64:67], v[0:3], v[76:79]
	v_max_f32_e32 v42, v42, v43
	v_add_u32_e32 v43, 2, v40
	v_cmp_gt_u32_e64 s[22:23], v43, v146
	v_add_u32_e32 v76, 3, v40
	v_cmp_gt_u32_e64 s[24:25], v76, v146
	v_cndmask_b32_e64 v43, v30, v246, s[22:23]
	v_sub_u32_e32 v41, v210, v148
	v_cndmask_b32_e64 v76, v31, v246, s[24:25]
	v_max3_f32 v42, v42, v43, v76
	v_add_u32_e32 v43, 16, v40
	v_add_u32_e32 v76, 17, v40
	v_cmp_gt_u32_e64 s[26:27], v43, v146
	v_cmp_gt_u32_e64 s[28:29], v76, v146
	v_cmp_gt_u32_e64 s[38:39], v41, v145
	v_cndmask_b32_e64 v43, v44, v246, s[26:27]
	v_cndmask_b32_e64 v76, v45, v246, s[28:29]
	v_max3_f32 v42, v42, v43, v76
	v_add_u32_e32 v43, 18, v40
	v_add_u32_e32 v40, 19, v40
	v_cmp_gt_u32_e64 s[30:31], v43, v146
	v_cmp_gt_u32_e64 s[34:35], v40, v146
	v_add_u32_e32 v76, 3, v41
	v_cndmask_b32_e64 v43, v46, v246, s[30:31]
	v_cndmask_b32_e64 v40, v47, v246, s[34:35]
	v_max3_f32 v40, v42, v43, v40
	v_add_u32_e32 v43, 1, v41
	v_max_f32_e32 v42, v64, v64
	v_cmp_gt_u32_e64 s[40:41], v43, v145
	v_max_f32_e32 v42, 0xf149f2ca, v42
	v_cndmask_b32_e64 v42, v42, v246, s[38:39]
	v_cndmask_b32_e64 v43, v65, v246, s[40:41]
	v_max_f32_e32 v42, v42, v43
	v_add_u32_e32 v43, 2, v41
	v_cmp_gt_u32_e64 s[42:43], v43, v145
	v_cmp_gt_u32_e64 s[44:45], v76, v145
	s_nop 0
	v_cndmask_b32_e64 v43, v66, v246, s[42:43]
	v_cndmask_b32_e64 v76, v67, v246, s[44:45]
	v_max3_f32 v42, v42, v43, v76
	v_add_u32_e32 v43, 16, v41
	v_add_u32_e32 v76, 17, v41
	v_cmp_gt_u32_e64 s[46:47], v43, v145
	v_cmp_gt_u32_e64 s[48:49], v76, v145
	s_nop 0
	v_cndmask_b32_e64 v43, v32, v246, s[46:47]
	v_cndmask_b32_e64 v76, v33, v246, s[48:49]
	v_max3_f32 v42, v42, v43, v76
	v_add_u32_e32 v43, 18, v41
	v_add_u32_e32 v41, 19, v41
	v_cmp_gt_u32_e64 s[50:51], v43, v145
	v_cmp_gt_u32_e64 s[52:53], v41, v145
	s_nop 0
	v_cndmask_b32_e64 v43, v34, v246, s[50:51]
	v_cndmask_b32_e64 v41, v35, v246, s[52:53]
	v_max3_f32 v41, v42, v43, v41
	v_mov_b32_e32 v42, v40
	v_mov_b32_e32 v43, v40
	s_nop 1
	v_permlane32_swap_b32_e32 v42, v43
	v_max3_f32 v40, v40, v42, v43
	v_mov_b32_e32 v42, v41
	v_mov_b32_e32 v43, v41
	s_nop 1
	v_permlane32_swap_b32_e32 v42, v43
	v_max3_f32 v41, v41, v42, v43
	v_mov_b32_e32 v42, v40
	v_mov_b32_e32 v43, v40
	s_nop 1
	v_permlane16_swap_b32_e32 v42, v43
	v_max_f32_e32 v40, v40, v42
	v_max3_f32 v176, v149, v40, v43
	v_sub_f32_e32 v28, v28, v176
	v_mov_b32_e32 v42, v41
	v_mov_b32_e32 v77, v41
	v_exp_f32_e32 v28, v28
	v_sub_f32_e32 v29, v29, v176
	v_permlane16_swap_b32_e32 v42, v77
	v_exp_f32_e32 v29, v29
	v_sub_f32_e32 v30, v30, v176
	v_exp_f32_e32 v30, v30
	v_sub_f32_e32 v31, v31, v176
	v_max_f32_e32 v41, v41, v42
	v_exp_f32_e32 v31, v31
	v_sub_f32_e32 v42, v44, v176
	v_sub_f32_e32 v40, v149, v176
	v_cndmask_b32_e64 v28, v28, 0, vcc
	v_exp_f32_e32 v42, v42
	v_sub_f32_e32 v43, v45, v176
	v_exp_f32_e32 v76, v40
	v_add_f32_e32 v40, 0, v28
	v_cndmask_b32_e64 v29, v29, 0, s[0:1]
	v_exp_f32_e32 v43, v43
	v_sub_f32_e32 v44, v46, v176
	v_add_f32_e32 v40, v29, v40
	v_cndmask_b32_e64 v30, v30, 0, s[22:23]
	v_exp_f32_e32 v44, v44
	v_sub_f32_e32 v45, v47, v176
	v_add_f32_e32 v40, v30, v40
	v_cndmask_b32_e64 v31, v31, 0, s[24:25]
	v_exp_f32_e32 v45, v45
	v_add_f32_e32 v40, v31, v40
	v_cndmask_b32_e64 v42, v42, 0, s[26:27]
	v_add_f32_e32 v40, v42, v40
	v_cndmask_b32_e64 v43, v43, 0, s[28:29]
	v_add_f32_e32 v40, v43, v40
	v_cndmask_b32_e64 v44, v44, 0, s[30:31]
	v_add_f32_e32 v40, v44, v40
	v_cndmask_b32_e64 v45, v45, 0, s[34:35]
	v_add_f32_e32 v149, v45, v40
	v_fmac_f32_e32 v149, v150, v76
	v_max3_f32 v150, v151, v41, v77
	v_sub_f32_e32 v40, v151, v150
	v_cvt_pk_bf16_f32 v28, v28, v29
	v_cvt_pk_bf16_f32 v29, v30, v31
	v_cvt_pk_bf16_f32 v31, v44, v45
	v_exp_f32_e32 v44, v40
	v_sub_f32_e32 v40, v64, v150
	v_cvt_pk_bf16_f32 v30, v42, v43
	v_exp_f32_e32 v40, v40
	v_sub_f32_e32 v42, v65, v150
	v_exp_f32_e32 v42, v42
	v_sub_f32_e32 v43, v66, v150
	v_exp_f32_e32 v43, v43
	v_sub_f32_e32 v45, v67, v150
	v_exp_f32_e32 v45, v45
	v_sub_f32_e32 v32, v32, v150
	v_cndmask_b32_e64 v40, v40, 0, s[38:39]
	v_exp_f32_e32 v32, v32
	v_sub_f32_e32 v33, v33, v150
	v_add_f32_e32 v41, 0, v40
	v_cndmask_b32_e64 v42, v42, 0, s[40:41]
	v_exp_f32_e32 v33, v33
	v_add_f32_e32 v41, v42, v41
	v_cndmask_b32_e64 v43, v43, 0, s[42:43]
	v_add_f32_e32 v41, v43, v41
	v_cndmask_b32_e64 v45, v45, 0, s[44:45]
	v_add_f32_e32 v41, v45, v41
	v_cndmask_b32_e64 v46, v32, 0, s[46:47]
	v_add_f32_e32 v32, v46, v41
	v_cndmask_b32_e64 v41, v33, 0, s[48:49]
	v_sub_f32_e32 v33, v34, v150
	v_exp_f32_e32 v33, v33
	v_add_f32_e32 v32, v41, v32
	v_pk_mul_f32 v[22:23], v[22:23], v[76:77] op_sel_hi:[1,0]
	v_pk_mul_f32 v[20:21], v[20:21], v[76:77] op_sel_hi:[1,0]
	v_cndmask_b32_e64 v47, v33, 0, s[50:51]
	v_sub_f32_e32 v33, v35, v150
	v_exp_f32_e32 v33, v33
	v_add_f32_e32 v32, v47, v32
	v_cvt_pk_bf16_f32 v34, v46, v41
	v_cndmask_b32_e64 v35, v33, 0, s[52:53]
	v_add_f32_e32 v151, v35, v32
	v_cvt_pk_bf16_f32 v32, v40, v42
	v_cvt_pk_bf16_f32 v33, v43, v45
	v_cvt_pk_bf16_f32 v35, v47, v35
	s_waitcnt lgkmcnt(10)
	v_mfma_f32_16x16x32_bf16 v[40:43], v[140:143], v[28:31], v[20:23]
	v_fmac_f32_e32 v151, v175, v44
	s_nop 1
	v_pk_mul_f32 v[22:23], v[54:55], v[44:45] op_sel_hi:[1,0]
	v_pk_mul_f32 v[20:21], v[52:53], v[44:45] op_sel_hi:[1,0]
	s_nop 1
	v_mfma_f32_16x16x32_bf16 v[92:95], v[140:143], v[32:35], v[20:23]
	s_nop 2
	v_mul_f32_e64 v22, v106, v76
	v_mul_f32_e64 v23, v107, v76
	v_pk_mul_f32 v[20:21], v[104:105], v[76:77] op_sel_hi:[1,0]
	s_waitcnt lgkmcnt(8)
	s_nop 0
	v_mfma_f32_16x16x32_bf16 v[104:107], v[136:139], v[28:31], v[20:23]
	s_nop 2
	v_mul_f32_e64 v22, v110, v44
	v_mul_f32_e64 v23, v111, v44
	v_pk_mul_f32 v[20:21], v[108:109], v[44:45] op_sel_hi:[1,0]
	s_nop 1
	v_mfma_f32_16x16x32_bf16 v[108:111], v[136:139], v[32:35], v[20:23]
	s_nop 2
	v_mul_f32_e64 v22, v114, v76
	v_mul_f32_e64 v23, v115, v76
	v_pk_mul_f32 v[20:21], v[112:113], v[76:77] op_sel_hi:[1,0]
	s_waitcnt lgkmcnt(6)
	s_nop 0
	v_mfma_f32_16x16x32_bf16 v[112:115], v[132:135], v[28:31], v[20:23]
	s_nop 2
	v_mul_f32_e64 v22, v118, v44
	v_mul_f32_e64 v23, v119, v44
	v_pk_mul_f32 v[20:21], v[116:117], v[44:45] op_sel_hi:[1,0]
	s_nop 1
	v_mfma_f32_16x16x32_bf16 v[116:119], v[132:135], v[32:35], v[20:23]
	s_nop 2
	v_mul_f32_e64 v22, v122, v76
	v_mul_f32_e64 v23, v123, v76
	v_pk_mul_f32 v[20:21], v[120:121], v[76:77] op_sel_hi:[1,0]
	s_waitcnt lgkmcnt(4)
	s_nop 0
	v_mfma_f32_16x16x32_bf16 v[120:123], v[128:131], v[28:31], v[20:23]
	s_nop 2
	v_mul_f32_e64 v22, v126, v44
	v_mul_f32_e64 v23, v127, v44
	v_pk_mul_f32 v[20:21], v[124:125], v[44:45] op_sel_hi:[1,0]
	s_nop 1
	v_mfma_f32_16x16x32_bf16 v[124:127], v[128:131], v[32:35], v[20:23]
	s_nop 2
	v_add_u32_e32 v20, 0xffffff80, v204
	v_add_u32_e32 v20, s76, v20
	v_med3_i32 v20, v20, 0, s75
	v_lshl_add_u32 v20, v20, 9, v152
	global_load_dwordx4 v[32:35], v20, s[98:99]
	v_add_u32_e32 v20, 0xffffff80, v205
	v_add_u32_e32 v20, s76, v20
	v_med3_i32 v20, v20, 0, s75
	v_lshl_add_u32 v20, v20, 9, v152
	global_load_dwordx4 v[64:67], v20, s[98:99]
	v_add_u32_e32 v20, 0xffffff80, v206
	v_add_u32_e32 v20, s76, v20
	v_med3_i32 v20, v20, 0, s75
	v_lshl_add_u32 v20, v20, 9, v152
	global_load_dwordx4 v[76:79], v20, s[98:99]
	v_add_u32_e32 v20, 0xffffff80, v207
	v_add_u32_e32 v20, s76, v20
	v_med3_i32 v20, v20, 0, s75
	v_lshl_add_u32 v20, v20, 9, v152
	global_load_dwordx4 v[100:103], v20, s[98:99]
	v_or_b32_e32 v20, 0xffffff80, v209
	v_add_u32_e32 v20, s76, v20
	v_med3_i32 v20, v20, 0, s75
	v_lshl_add_u32 v20, v20, 9, v158
	global_load_dwordx4 v[52:55], v20, s[100:101]
	global_load_dwordx4 v[44:47], v20, s[100:101] offset:64
	v_add_u32_e32 v20, s76, v211
	v_med3_i32 v20, v20, 0, s75
	v_lshl_add_u32 v20, v20, 9, v158
	global_load_dwordx4 v[28:31], v20, s[100:101]
	s_nop 0
	global_load_dwordx4 v[20:23], v20, s[100:101] offset:64
	ds_read_b64_tr_b16 v[142:143], v169 offset:6912
	ds_read_b64_tr_b16 v[140:141], v169 offset:4608
	ds_read_b64_tr_b16 v[136:137], v169 offset:4640
	ds_read_b64_tr_b16 v[138:139], v169 offset:6944
	ds_read_b64_tr_b16 v[132:133], v169 offset:4672
	ds_read_b64_tr_b16 v[134:135], v169 offset:6976
	ds_read_b64_tr_b16 v[128:129], v169 offset:4704
	ds_read_b64_tr_b16 v[130:131], v169 offset:7008
	s_waitcnt vmcnt(13)
	ds_write_b128 v241, v[16:19]
	s_waitcnt vmcnt(12)
	ds_write_b128 v242, v[48:51]
	ds_write_b128 v243, v[88:91]
	ds_write_b128 v244, v[96:99]
	v_mfma_f32_16x16x32_bf16 v[16:19], v[72:75], v[4:7], 0
	v_mfma_f32_16x16x32_bf16 v[48:51], v[36:39], v[4:7], 0
	v_mfma_f32_16x16x32_bf16 v[36:39], v[36:39], v[12:15], 0
	v_mfma_f32_16x16x32_bf16 v[16:19], v[68:71], v[8:11], v[16:19]
	v_mfma_f32_16x16x32_bf16 v[48:51], v[24:27], v[8:11], v[48:51]
	v_mfma_f32_16x16x32_bf16 v[24:27], v[24:27], v[0:3], v[36:39]
	s_nop 4
	v_sub_u32_e32 v36, v212, v147
	v_mfma_f32_16x16x32_bf16 v[72:75], v[72:75], v[12:15], 0
	v_add_u32_e32 v39, 1, v36
	v_max_f32_e32 v38, v16, v16
	v_cmp_gt_u32_e64 s[0:1], v39, v146
	v_cmp_gt_u32_e32 vcc, v36, v146
	v_max_f32_e32 v38, 0xf149f2ca, v38
	v_cndmask_b32_e64 v39, v17, v246, s[0:1]
	v_cndmask_b32_e32 v38, v38, v246, vcc
	v_mfma_f32_16x16x32_bf16 v[68:71], v[68:71], v[0:3], v[72:75]
	v_max_f32_e32 v38, v38, v39
	v_add_u32_e32 v39, 2, v36
	v_cmp_gt_u32_e64 s[22:23], v39, v146
	v_add_u32_e32 v72, 3, v36
	v_cmp_gt_u32_e64 s[24:25], v72, v146
	v_cndmask_b32_e64 v39, v18, v246, s[22:23]
	v_sub_u32_e32 v37, v212, v148
	v_cndmask_b32_e64 v72, v19, v246, s[24:25]
	v_max3_f32 v38, v38, v39, v72
	v_add_u32_e32 v39, 16, v36
	v_add_u32_e32 v72, 17, v36
	v_cmp_gt_u32_e64 s[26:27], v39, v146
	v_cmp_gt_u32_e64 s[28:29], v72, v146
	v_cmp_gt_u32_e64 s[38:39], v37, v145
	v_cndmask_b32_e64 v39, v48, v246, s[26:27]
	v_cndmask_b32_e64 v72, v49, v246, s[28:29]
	v_max3_f32 v38, v38, v39, v72
	v_add_u32_e32 v39, 18, v36
	v_add_u32_e32 v36, 19, v36
	v_cmp_gt_u32_e64 s[30:31], v39, v146
	v_cmp_gt_u32_e64 s[34:35], v36, v146
	v_add_u32_e32 v72, 3, v37
	v_cndmask_b32_e64 v39, v50, v246, s[30:31]
	v_cndmask_b32_e64 v36, v51, v246, s[34:35]
	v_max3_f32 v36, v38, v39, v36
	v_add_u32_e32 v39, 1, v37
	v_max_f32_e32 v38, v68, v68
	v_cmp_gt_u32_e64 s[40:41], v39, v145
	v_max_f32_e32 v38, 0xf149f2ca, v38
	v_cndmask_b32_e64 v38, v38, v246, s[38:39]
	v_cndmask_b32_e64 v39, v69, v246, s[40:41]
	v_max_f32_e32 v38, v38, v39
	v_add_u32_e32 v39, 2, v37
	v_cmp_gt_u32_e64 s[42:43], v39, v145
	v_cmp_gt_u32_e64 s[44:45], v72, v145
	s_nop 0
	v_cndmask_b32_e64 v39, v70, v246, s[42:43]
	v_cndmask_b32_e64 v72, v71, v246, s[44:45]
	v_max3_f32 v38, v38, v39, v72
	v_add_u32_e32 v39, 16, v37
	v_add_u32_e32 v72, 17, v37
	v_cmp_gt_u32_e64 s[46:47], v39, v145
	v_cmp_gt_u32_e64 s[48:49], v72, v145
	s_nop 0
	v_cndmask_b32_e64 v39, v24, v246, s[46:47]
	v_cndmask_b32_e64 v72, v25, v246, s[48:49]
	v_max3_f32 v38, v38, v39, v72
	v_add_u32_e32 v39, 18, v37
	v_add_u32_e32 v37, 19, v37
	v_cmp_gt_u32_e64 s[50:51], v39, v145
	v_cmp_gt_u32_e64 s[52:53], v37, v145
	s_nop 0
	v_cndmask_b32_e64 v39, v26, v246, s[50:51]
	v_cndmask_b32_e64 v37, v27, v246, s[52:53]
	v_max3_f32 v37, v38, v39, v37
	v_mov_b32_e32 v38, v36
	v_mov_b32_e32 v39, v36
	s_nop 1
	v_permlane32_swap_b32_e32 v38, v39
	v_max3_f32 v36, v36, v38, v39
	v_mov_b32_e32 v38, v37
	v_mov_b32_e32 v39, v37
	s_nop 1
	v_permlane32_swap_b32_e32 v38, v39
	v_max3_f32 v37, v37, v38, v39
	v_mov_b32_e32 v38, v36
	v_mov_b32_e32 v39, v36
	s_nop 1
	v_permlane16_swap_b32_e32 v38, v39
	v_max_f32_e32 v36, v36, v38
	v_max3_f32 v145, v176, v36, v39
	v_sub_f32_e32 v16, v16, v145
	v_mov_b32_e32 v38, v37
	v_mov_b32_e32 v72, v37
	v_exp_f32_e32 v16, v16
	v_sub_f32_e32 v17, v17, v145
	v_permlane16_swap_b32_e32 v38, v72
	v_exp_f32_e32 v17, v17
	v_sub_f32_e32 v18, v18, v145
	v_exp_f32_e32 v18, v18
	v_sub_f32_e32 v19, v19, v145
	v_max_f32_e32 v37, v37, v38
	v_exp_f32_e32 v19, v19
	v_sub_f32_e32 v38, v48, v145
	v_sub_f32_e32 v36, v176, v145
	v_cndmask_b32_e64 v16, v16, 0, vcc
	v_exp_f32_e32 v38, v38
	v_sub_f32_e32 v39, v49, v145
	v_exp_f32_e32 v88, v36
	v_add_f32_e32 v36, 0, v16
	v_cndmask_b32_e64 v17, v17, 0, s[0:1]
	v_exp_f32_e32 v39, v39
	v_sub_f32_e32 v48, v50, v145
	v_add_f32_e32 v36, v17, v36
	v_cndmask_b32_e64 v18, v18, 0, s[22:23]
	v_exp_f32_e32 v48, v48
	v_sub_f32_e32 v49, v51, v145
	v_add_f32_e32 v36, v18, v36
	v_cndmask_b32_e64 v19, v19, 0, s[24:25]
	v_exp_f32_e32 v49, v49
	v_add_f32_e32 v36, v19, v36
	v_cndmask_b32_e64 v38, v38, 0, s[26:27]
	v_add_f32_e32 v36, v38, v36
	v_cndmask_b32_e64 v39, v39, 0, s[28:29]
	v_add_f32_e32 v36, v39, v36
	v_cndmask_b32_e64 v48, v48, 0, s[30:31]
	v_add_f32_e32 v36, v48, v36
	v_cndmask_b32_e64 v49, v49, 0, s[34:35]
	v_max3_f32 v147, v150, v37, v72
	v_add_f32_e32 v146, v49, v36
	v_sub_f32_e32 v36, v150, v147
	v_cvt_pk_bf16_f32 v16, v16, v17
	v_cvt_pk_bf16_f32 v17, v18, v19
	v_cvt_pk_bf16_f32 v19, v48, v49
	v_exp_f32_e32 v48, v36
	v_sub_f32_e32 v36, v68, v147
	v_cvt_pk_bf16_f32 v18, v38, v39
	v_exp_f32_e32 v36, v36
	v_sub_f32_e32 v38, v69, v147
	v_exp_f32_e32 v38, v38
	v_sub_f32_e32 v39, v70, v147
	v_exp_f32_e32 v39, v39
	v_sub_f32_e32 v49, v71, v147
	v_exp_f32_e32 v49, v49
	v_sub_f32_e32 v24, v24, v147
	v_cndmask_b32_e64 v36, v36, 0, s[38:39]
	v_exp_f32_e32 v24, v24
	v_sub_f32_e32 v25, v25, v147
	v_add_f32_e32 v37, 0, v36
	v_cndmask_b32_e64 v38, v38, 0, s[40:41]
	v_exp_f32_e32 v25, v25
	v_add_f32_e32 v37, v38, v37
	v_cndmask_b32_e64 v39, v39, 0, s[42:43]
	v_add_f32_e32 v37, v39, v37
	v_cndmask_b32_e64 v49, v49, 0, s[44:45]
	v_add_f32_e32 v37, v49, v37
	v_cndmask_b32_e64 v50, v24, 0, s[46:47]
	v_add_f32_e32 v24, v50, v37
	v_cndmask_b32_e64 v37, v25, 0, s[48:49]
	v_sub_f32_e32 v25, v26, v147
	v_exp_f32_e32 v25, v25
	v_add_f32_e32 v24, v37, v24
	v_cvt_pk_bf16_f32 v26, v50, v37
	v_cmp_lt_i32_e32 vcc, -1, v184
	v_cndmask_b32_e64 v51, v25, 0, s[50:51]
	v_sub_f32_e32 v25, v27, v147
	v_exp_f32_e32 v25, v25
	v_add_f32_e32 v24, v51, v24
	v_fmac_f32_e32 v146, v149, v88
	s_add_i32 s0, s76, 0xffffff00
	v_cndmask_b32_e64 v27, v25, 0, s[52:53]
	v_add_f32_e32 v183, v27, v24
	v_cvt_pk_bf16_f32 v24, v36, v38
	v_cvt_pk_bf16_f32 v25, v39, v49
	v_cvt_pk_bf16_f32 v27, v51, v27
	v_pk_mul_f32 v[38:39], v[42:43], v[88:89] op_sel_hi:[1,0]
	v_pk_mul_f32 v[36:37], v[40:41], v[88:89] op_sel_hi:[1,0]
	v_pk_mul_f32 v[42:43], v[94:95], v[48:49] op_sel_hi:[1,0]
	v_pk_mul_f32 v[40:41], v[92:93], v[48:49] op_sel_hi:[1,0]
	s_waitcnt lgkmcnt(10)
	v_mfma_f32_16x16x32_bf16 v[36:39], v[140:143], v[16:19], v[36:39]
	v_fmac_f32_e32 v183, v151, v48
	s_min_i32 s1, s0, 0
	s_sub_i32 s1, 3, s1
	v_mfma_f32_16x16x32_bf16 v[68:71], v[140:143], v[24:27], v[40:43]
	s_ashr_i32 s1, s1, 2
	s_sub_i32 s22, 0x200, s76
	s_sub_i32 s0, s75, s0
	v_pk_mul_f32 v[42:43], v[106:107], v[88:89] op_sel_hi:[1,0]
	v_pk_mul_f32 v[40:41], v[104:105], v[88:89] op_sel_hi:[1,0]
	s_ashr_i32 s0, s0, 2
	s_cmp_lt_i32 s76, 0
	s_waitcnt lgkmcnt(8)
	v_mfma_f32_16x16x32_bf16 v[72:75], v[136:139], v[16:19], v[40:43]
	s_nop 2
	v_mul_f32_e64 v42, v110, v48
	v_mul_f32_e64 v43, v111, v48
	v_pk_mul_f32 v[40:41], v[108:109], v[48:49] op_sel_hi:[1,0]
	s_nop 1
	v_mfma_f32_16x16x32_bf16 v[104:107], v[136:139], v[24:27], v[40:43]
	s_nop 2
	v_mul_f32_e64 v42, v114, v88
	v_mul_f32_e64 v43, v115, v88
	v_pk_mul_f32 v[40:41], v[112:113], v[88:89] op_sel_hi:[1,0]
	s_waitcnt lgkmcnt(6)
	s_nop 0
	v_mfma_f32_16x16x32_bf16 v[108:111], v[132:135], v[16:19], v[40:43]
	s_nop 2
	v_mul_f32_e64 v42, v118, v48
	v_mul_f32_e64 v43, v119, v48
	v_pk_mul_f32 v[40:41], v[116:117], v[48:49] op_sel_hi:[1,0]
	s_nop 1
	v_mfma_f32_16x16x32_bf16 v[112:115], v[132:135], v[24:27], v[40:43]
	s_nop 2
	v_mul_f32_e64 v42, v122, v88
	v_mul_f32_e64 v43, v123, v88
	v_pk_mul_f32 v[40:41], v[120:121], v[88:89] op_sel_hi:[1,0]
	s_waitcnt lgkmcnt(4)
	s_nop 0
	v_mfma_f32_16x16x32_bf16 v[116:119], v[128:131], v[16:19], v[40:43]
	v_mul_f32_e64 v18, v126, v48
	v_mul_f32_e64 v19, v127, v48
	v_pk_mul_f32 v[16:17], v[124:125], v[48:49] op_sel_hi:[1,0]
	s_nop 1
	v_mfma_f32_16x16x32_bf16 v[128:131], v[128:131], v[24:27], v[16:19]
	s_nop 2
	v_min_i32_e32 v16, s75, v184
	v_cndmask_b32_e32 v16, 0, v16, vcc
	v_lshl_add_u32 v16, v16, 9, v152
	global_load_dwordx4 v[88:91], v16, s[98:99]
	v_med3_i32 v16, v185, 0, s75
	v_lshl_add_u32 v16, v16, 9, v152
	global_load_dwordx4 v[92:95], v16, s[98:99]
	v_med3_i32 v16, v186, 0, s75
	v_lshl_add_u32 v16, v16, 9, v152
	global_load_dwordx4 v[120:123], v16, s[98:99]
	v_med3_i32 v16, v188, 0, s75
	v_lshl_add_u32 v16, v16, 9, v152
	global_load_dwordx4 v[124:127], v16, s[98:99]
	v_add_u32_e32 v16, s76, v209
	v_med3_i32 v16, v16, 0, s75
	v_lshl_add_u32 v16, v16, 9, v158
	global_load_dwordx4 v[48:51], v16, s[100:101]
	global_load_dwordx4 v[40:43], v16, s[100:101] offset:64
	v_or_b32_e32 v16, 64, v209
	v_add_u32_e32 v16, s76, v16
	v_med3_i32 v16, v16, 0, s75
	v_lshl_add_u32 v16, v16, 9, v158
	global_load_dwordx4 v[24:27], v16, s[100:101]
	s_nop 0
	global_load_dwordx4 v[16:19], v16, s[100:101] offset:64
	ds_read_b64_tr_b16 v[98:99], v169 offset:2304
	ds_read_b64_tr_b16 v[96:97], v169
	ds_read_b64_tr_b16 v[140:141], v169 offset:32
	ds_read_b64_tr_b16 v[142:143], v169 offset:2336
	ds_read_b64_tr_b16 v[136:137], v169 offset:64
	ds_read_b64_tr_b16 v[138:139], v169 offset:2368
	ds_read_b64_tr_b16 v[132:133], v169 offset:96
	ds_read_b64_tr_b16 v[134:135], v169 offset:2400
	s_waitcnt vmcnt(15)
	ds_write_b128 v241, v[32:35] offset:4608
	s_waitcnt vmcnt(14)
	ds_write_b128 v242, v[64:67] offset:4608
	s_waitcnt vmcnt(13)
	ds_write_b128 v243, v[76:79] offset:4608
	s_waitcnt vmcnt(12)
	ds_write_b128 v244, v[100:103] offset:4608
	v_mfma_f32_16x16x32_bf16 v[64:67], v[60:63], v[4:7], 0
	v_mfma_f32_16x16x32_bf16 v[60:63], v[60:63], v[12:15], 0
	v_mfma_f32_16x16x32_bf16 v[32:35], v[84:87], v[4:7], 0
	v_mfma_f32_16x16x32_bf16 v[64:67], v[56:59], v[8:11], v[64:67]
	v_mfma_f32_16x16x32_bf16 v[56:59], v[56:59], v[0:3], v[60:63]
	s_nop 4
	v_ashrrev_i32_e32 v60, 2, v250
	v_max_i32_e32 v176, s1, v60
	v_add_u32_e32 v60, s22, v251
	v_ashrrev_i32_e32 v60, 2, v60
	v_min3_i32 v60, v60, s0, v247
	v_mfma_f32_16x16x32_bf16 v[32:35], v[80:83], v[8:11], v[32:35]
	v_sub_u32_e32 v175, v60, v176
	v_ashrrev_i32_e32 v60, 2, v249
	v_max_i32_e32 v181, s1, v60
	v_add_u32_e32 v60, s22, v144
	v_sub_u32_e32 v61, v154, v176
	v_ashrrev_i32_e32 v60, 2, v60
	v_mfma_f32_16x16x32_bf16 v[76:79], v[84:87], v[12:15], 0
	v_min3_i32 v60, v60, s0, v247
	v_add_u32_e32 v63, 1, v61
	v_sub_u32_e32 v252, v60, v181
	v_max_f32_e32 v60, v32, v32
	v_cmp_gt_u32_e64 s[0:1], v63, v175
	v_cmp_gt_u32_e32 vcc, v61, v175
	v_max_f32_e32 v60, 0xf149f2ca, v60
	v_cndmask_b32_e64 v63, v33, v246, s[0:1]
	v_cndmask_b32_e32 v60, v60, v246, vcc
	v_mfma_f32_16x16x32_bf16 v[76:79], v[80:83], v[0:3], v[76:79]
	v_max_f32_e32 v60, v60, v63
	v_add_u32_e32 v63, 2, v61
	v_add_u32_e32 v80, 3, v61
	v_cmp_gt_u32_e64 s[22:23], v63, v175
	v_cmp_gt_u32_e64 s[24:25], v80, v175
	v_sub_u32_e32 v62, v154, v181
	v_cndmask_b32_e64 v63, v34, v246, s[22:23]
	v_cndmask_b32_e64 v80, v35, v246, s[24:25]
	v_max3_f32 v60, v60, v63, v80
	v_add_u32_e32 v63, 16, v61
	v_add_u32_e32 v80, 17, v61
	v_cmp_gt_u32_e64 s[26:27], v63, v175
	v_cmp_gt_u32_e64 s[28:29], v80, v175
	v_cmp_gt_u32_e64 s[38:39], v62, v252
	v_cndmask_b32_e64 v63, v64, v246, s[26:27]
	v_cndmask_b32_e64 v80, v65, v246, s[28:29]
	v_max3_f32 v60, v60, v63, v80
	v_add_u32_e32 v63, 18, v61
	v_add_u32_e32 v61, 19, v61
	v_cmp_gt_u32_e64 s[30:31], v63, v175
	v_cmp_gt_u32_e64 s[34:35], v61, v175
	v_add_u32_e32 v80, 3, v62
	v_cndmask_b32_e64 v63, v66, v246, s[30:31]
	v_cndmask_b32_e64 v61, v67, v246, s[34:35]
	v_max3_f32 v60, v60, v63, v61
	v_add_u32_e32 v63, 1, v62
	v_max_f32_e32 v61, v76, v76
	v_cmp_gt_u32_e64 s[40:41], v63, v252
	v_max_f32_e32 v61, 0xf149f2ca, v61
	v_cndmask_b32_e64 v61, v61, v246, s[38:39]
	v_cndmask_b32_e64 v63, v77, v246, s[40:41]
	v_max_f32_e32 v61, v61, v63
	v_add_u32_e32 v63, 2, v62
	v_cmp_gt_u32_e64 s[42:43], v63, v252
	v_cmp_gt_u32_e64 s[44:45], v80, v252
	s_nop 0
	v_cndmask_b32_e64 v63, v78, v246, s[42:43]
	v_cndmask_b32_e64 v80, v79, v246, s[44:45]
	v_max3_f32 v61, v61, v63, v80
	v_add_u32_e32 v63, 16, v62
	v_add_u32_e32 v80, 17, v62
	v_cmp_gt_u32_e64 s[46:47], v63, v252
	v_cmp_gt_u32_e64 s[48:49], v80, v252
	s_nop 0
	v_cndmask_b32_e64 v63, v56, v246, s[46:47]
	v_cndmask_b32_e64 v80, v57, v246, s[48:49]
	v_max3_f32 v61, v61, v63, v80
	v_add_u32_e32 v63, 18, v62
	v_add_u32_e32 v62, 19, v62
	v_cmp_gt_u32_e64 s[50:51], v63, v252
	v_cmp_gt_u32_e64 s[52:53], v62, v252
	s_nop 0
	v_cndmask_b32_e64 v63, v58, v246, s[50:51]
	v_cndmask_b32_e64 v62, v59, v246, s[52:53]
	v_max3_f32 v61, v61, v63, v62
	v_mov_b32_e32 v62, v60
	v_mov_b32_e32 v63, v60
	s_nop 1
	v_permlane32_swap_b32_e32 v62, v63
	v_max3_f32 v60, v60, v62, v63
	v_mov_b32_e32 v62, v61
	v_mov_b32_e32 v63, v61
	s_nop 1
	v_permlane32_swap_b32_e32 v62, v63
	v_max3_f32 v61, v61, v62, v63
	v_mov_b32_e32 v62, v60
	v_mov_b32_e32 v63, v60
	s_nop 1
	v_permlane16_swap_b32_e32 v62, v63
	v_max_f32_e32 v60, v60, v62
	v_max3_f32 v148, v145, v60, v63
	v_sub_f32_e32 v32, v32, v148
	v_exp_f32_e32 v32, v32
	v_sub_f32_e32 v33, v33, v148
	v_exp_f32_e32 v33, v33
	v_sub_f32_e32 v34, v34, v148
	v_mov_b32_e32 v62, v61
	v_mov_b32_e32 v80, v61
	v_exp_f32_e32 v34, v34
	v_sub_f32_e32 v35, v35, v148
	v_permlane16_swap_b32_e32 v62, v80
	v_exp_f32_e32 v35, v35
	v_sub_f32_e32 v63, v64, v148
	v_cndmask_b32_e64 v32, v32, 0, vcc
	v_exp_f32_e32 v63, v63
	v_sub_f32_e32 v64, v65, v148
	v_max_f32_e32 v61, v61, v62
	v_add_f32_e32 v62, 0, v32
	v_cndmask_b32_e64 v33, v33, 0, s[0:1]
	v_exp_f32_e32 v64, v64
	v_sub_f32_e32 v65, v66, v148
	v_add_f32_e32 v62, v33, v62
	v_cndmask_b32_e64 v34, v34, 0, s[22:23]
	v_exp_f32_e32 v65, v65
	v_sub_f32_e32 v66, v67, v148
	v_add_f32_e32 v62, v34, v62
	v_cndmask_b32_e64 v35, v35, 0, s[24:25]
	v_exp_f32_e32 v66, v66
	v_add_f32_e32 v62, v35, v62
	v_cndmask_b32_e64 v63, v63, 0, s[26:27]
	v_add_f32_e32 v62, v63, v62
	v_cndmask_b32_e64 v64, v64, 0, s[28:29]
	v_add_f32_e32 v62, v64, v62
	v_cndmask_b32_e64 v65, v65, 0, s[30:31]
	v_max3_f32 v150, v147, v61, v80
	v_add_f32_e32 v62, v65, v62
	v_cndmask_b32_e64 v66, v66, 0, s[34:35]
	v_sub_f32_e32 v61, v147, v150
	v_add_f32_e32 v149, v66, v62
	v_exp_f32_e32 v62, v61
	v_sub_f32_e32 v61, v76, v150
	v_cvt_pk_bf16_f32 v32, v32, v33
	v_cvt_pk_bf16_f32 v33, v34, v35
	v_cvt_pk_bf16_f32 v34, v63, v64
	v_exp_f32_e32 v61, v61
	v_sub_f32_e32 v64, v77, v150
	v_cvt_pk_bf16_f32 v35, v65, v66
	v_exp_f32_e32 v64, v64
	v_sub_f32_e32 v65, v78, v150
	v_exp_f32_e32 v65, v65
	v_sub_f32_e32 v66, v79, v150
	v_exp_f32_e32 v66, v66
	v_sub_f32_e32 v56, v56, v150
	v_cndmask_b32_e64 v61, v61, 0, s[38:39]
	v_exp_f32_e32 v56, v56
	v_sub_f32_e32 v57, v57, v150
	v_add_f32_e32 v63, 0, v61
	v_cndmask_b32_e64 v64, v64, 0, s[40:41]
	v_exp_f32_e32 v57, v57
	v_add_f32_e32 v63, v64, v63
	v_cndmask_b32_e64 v65, v65, 0, s[42:43]
	v_add_f32_e32 v63, v65, v63
	v_cndmask_b32_e64 v66, v66, 0, s[44:45]
	v_add_f32_e32 v63, v66, v63
	v_cndmask_b32_e64 v67, v56, 0, s[46:47]
	v_add_f32_e32 v56, v67, v63
	v_cndmask_b32_e64 v63, v57, 0, s[48:49]
	v_sub_f32_e32 v57, v58, v150
	v_exp_f32_e32 v57, v57
	v_sub_f32_e32 v60, v145, v148
	v_exp_f32_e32 v60, v60
	v_add_f32_e32 v56, v63, v56
	v_cndmask_b32_e64 v76, v57, 0, s[50:51]
	v_sub_f32_e32 v57, v59, v150
	v_exp_f32_e32 v57, v57
	v_add_f32_e32 v56, v76, v56
	v_pk_mul_f32 v[38:39], v[38:39], v[60:61] op_sel_hi:[1,0]
	v_pk_mul_f32 v[36:37], v[36:37], v[60:61] op_sel_hi:[1,0]
	v_cndmask_b32_e64 v59, v57, 0, s[52:53]
	v_add_f32_e32 v151, v59, v56
	v_cvt_pk_bf16_f32 v56, v61, v64
	v_cvt_pk_bf16_f32 v57, v65, v66
	v_cvt_pk_bf16_f32 v58, v67, v63
	v_cvt_pk_bf16_f32 v59, v76, v59
	s_waitcnt lgkmcnt(10)
	v_mfma_f32_16x16x32_bf16 v[80:83], v[96:99], v[32:35], v[36:39]
	v_fmac_f32_e32 v149, v146, v60
	v_fmac_f32_e32 v151, v183, v62
	s_nop 0
	v_pk_mul_f32 v[38:39], v[70:71], v[62:63] op_sel_hi:[1,0]
	v_pk_mul_f32 v[36:37], v[68:69], v[62:63] op_sel_hi:[1,0]
	s_nop 1
	v_mfma_f32_16x16x32_bf16 v[84:87], v[96:99], v[56:59], v[36:39]
	s_nop 2
	v_mul_f32_e64 v38, v74, v60
	v_mul_f32_e64 v39, v75, v60
	v_pk_mul_f32 v[36:37], v[72:73], v[60:61] op_sel_hi:[1,0]
	s_waitcnt lgkmcnt(8)
	s_nop 0
	v_mfma_f32_16x16x32_bf16 v[96:99], v[140:143], v[32:35], v[36:39]
	s_nop 2
	v_mul_f32_e64 v38, v106, v62
	v_mul_f32_e64 v39, v107, v62
	v_pk_mul_f32 v[36:37], v[104:105], v[62:63] op_sel_hi:[1,0]
	s_nop 1
	v_mfma_f32_16x16x32_bf16 v[100:103], v[140:143], v[56:59], v[36:39]
	s_nop 2
	v_mul_f32_e64 v38, v110, v60
	v_mul_f32_e64 v39, v111, v60
	v_pk_mul_f32 v[36:37], v[108:109], v[60:61] op_sel_hi:[1,0]
	s_waitcnt lgkmcnt(6)
	s_nop 0
	v_mfma_f32_16x16x32_bf16 v[104:107], v[136:139], v[32:35], v[36:39]
	s_nop 2
	v_mul_f32_e64 v38, v114, v62
	v_mul_f32_e64 v39, v115, v62
	v_pk_mul_f32 v[36:37], v[112:113], v[62:63] op_sel_hi:[1,0]
	s_nop 1
	v_mfma_f32_16x16x32_bf16 v[108:111], v[136:139], v[56:59], v[36:39]
	s_nop 2
	v_mul_f32_e64 v38, v118, v60
	v_mul_f32_e64 v39, v119, v60
	v_pk_mul_f32 v[36:37], v[116:117], v[60:61] op_sel_hi:[1,0]
	s_waitcnt lgkmcnt(4)
	s_nop 0
	v_mfma_f32_16x16x32_bf16 v[112:115], v[132:135], v[32:35], v[36:39]
	v_mul_f32_e64 v34, v130, v62
	v_mul_f32_e64 v35, v131, v62
	v_pk_mul_f32 v[32:33], v[128:129], v[62:63] op_sel_hi:[1,0]
	s_nop 1
	v_mfma_f32_16x16x32_bf16 v[116:119], v[132:135], v[56:59], v[32:35]
	s_nop 2
	v_add_u32_e32 v32, 0x80, v184
	v_med3_i32 v32, v32, 0, s75
	v_lshl_add_u32 v32, v32, 9, v152
	global_load_dwordx4 v[64:67], v32, s[98:99]
	v_add_u32_e32 v32, 0x80, v185
	v_med3_i32 v32, v32, 0, s75
	v_lshl_add_u32 v32, v32, 9, v152
	global_load_dwordx4 v[68:71], v32, s[98:99]
	v_add_u32_e32 v32, 0x80, v186
	v_med3_i32 v32, v32, 0, s75
	v_lshl_add_u32 v32, v32, 9, v152
	global_load_dwordx4 v[72:75], v32, s[98:99]
	v_add_u32_e32 v32, 0x80, v188
	v_med3_i32 v32, v32, 0, s75
	v_lshl_add_u32 v32, v32, 9, v152
	global_load_dwordx4 v[76:79], v32, s[98:99]
	v_or_b32_e32 v32, 0x80, v209
	v_add_u32_e32 v32, s76, v32
	v_med3_i32 v32, v32, 0, s75
	v_lshl_add_u32 v32, v32, 9, v158
	global_load_dwordx4 v[60:63], v32, s[100:101]
	global_load_dwordx4 v[56:59], v32, s[100:101] offset:64
	v_or_b32_e32 v32, 0xc0, v209
	v_add_u32_e32 v32, s76, v32
	v_med3_i32 v32, v32, 0, s75
	v_lshl_add_u32 v32, v32, 9, v158
	global_load_dwordx4 v[36:39], v32, s[100:101]
	s_nop 0
	global_load_dwordx4 v[32:35], v32, s[100:101] offset:64
	ds_read_b64_tr_b16 v[134:135], v169 offset:6912
	ds_read_b64_tr_b16 v[132:133], v169 offset:4608
	ds_read_b64_tr_b16 v[128:129], v169 offset:4640
	ds_read_b64_tr_b16 v[130:131], v169 offset:6944
	ds_read_b64_tr_b16 v[136:137], v169 offset:4672
	ds_read_b64_tr_b16 v[138:139], v169 offset:6976
	ds_read_b64_tr_b16 v[144:145], v169 offset:4704
	ds_read_b64_tr_b16 v[146:147], v169 offset:7008
	s_waitcnt vmcnt(15)
	ds_write_b128 v241, v[88:91]
	s_waitcnt vmcnt(14)
	ds_write_b128 v242, v[92:95]
	s_waitcnt vmcnt(13)
	ds_write_b128 v243, v[120:123]
	s_waitcnt vmcnt(12)
	ds_write_b128 v244, v[124:127]
	v_mfma_f32_16x16x32_bf16 v[88:91], v[52:55], v[4:7], 0
	v_mfma_f32_16x16x32_bf16 v[92:95], v[28:31], v[4:7], 0
	v_mfma_f32_16x16x32_bf16 v[28:31], v[28:31], v[12:15], 0
	v_mfma_f32_16x16x32_bf16 v[88:91], v[44:47], v[8:11], v[88:91]
	v_mfma_f32_16x16x32_bf16 v[92:95], v[20:23], v[8:11], v[92:95]
	v_mfma_f32_16x16x32_bf16 v[20:23], v[20:23], v[0:3], v[28:31]
	s_nop 4
	v_sub_u32_e32 v28, v187, v176
	v_mfma_f32_16x16x32_bf16 v[52:55], v[52:55], v[12:15], 0
	v_add_u32_e32 v31, 1, v28
	v_max_f32_e32 v30, v88, v88
	v_cmp_gt_u32_e64 s[0:1], v31, v175
	v_cmp_gt_u32_e32 vcc, v28, v175
	v_max_f32_e32 v30, 0xf149f2ca, v30
	v_cndmask_b32_e64 v31, v89, v246, s[0:1]
	v_cndmask_b32_e32 v30, v30, v246, vcc
	v_mfma_f32_16x16x32_bf16 v[44:47], v[44:47], v[0:3], v[52:55]
	v_max_f32_e32 v30, v30, v31
	v_add_u32_e32 v31, 2, v28
	v_cmp_gt_u32_e64 s[22:23], v31, v175
	v_add_u32_e32 v52, 3, v28
	v_cmp_gt_u32_e64 s[24:25], v52, v175
	v_cndmask_b32_e64 v31, v90, v246, s[22:23]
	v_sub_u32_e32 v29, v187, v181
	v_cndmask_b32_e64 v52, v91, v246, s[24:25]
	v_max3_f32 v30, v30, v31, v52
	v_add_u32_e32 v31, 16, v28
	v_add_u32_e32 v52, 17, v28
	v_cmp_gt_u32_e64 s[26:27], v31, v175
	v_cmp_gt_u32_e64 s[28:29], v52, v175
	v_cmp_gt_u32_e64 s[38:39], v29, v252
	v_cndmask_b32_e64 v31, v92, v246, s[26:27]
	v_cndmask_b32_e64 v52, v93, v246, s[28:29]
	v_max3_f32 v30, v30, v31, v52
	v_add_u32_e32 v31, 18, v28
	v_add_u32_e32 v28, 19, v28
	v_cmp_gt_u32_e64 s[30:31], v31, v175
	v_cmp_gt_u32_e64 s[34:35], v28, v175
	v_add_u32_e32 v52, 3, v29
	v_cndmask_b32_e64 v31, v94, v246, s[30:31]
	v_cndmask_b32_e64 v28, v95, v246, s[34:35]
	v_max3_f32 v28, v30, v31, v28
	v_add_u32_e32 v31, 1, v29
	v_max_f32_e32 v30, v44, v44
	v_cmp_gt_u32_e64 s[40:41], v31, v252
	v_max_f32_e32 v30, 0xf149f2ca, v30
	v_cndmask_b32_e64 v30, v30, v246, s[38:39]
	v_cndmask_b32_e64 v31, v45, v246, s[40:41]
	v_max_f32_e32 v30, v30, v31
	v_add_u32_e32 v31, 2, v29
	v_cmp_gt_u32_e64 s[42:43], v31, v252
	v_cmp_gt_u32_e64 s[44:45], v52, v252
	s_nop 0
	v_cndmask_b32_e64 v31, v46, v246, s[42:43]
	v_cndmask_b32_e64 v52, v47, v246, s[44:45]
	v_max3_f32 v30, v30, v31, v52
	v_add_u32_e32 v31, 16, v29
	v_add_u32_e32 v52, 17, v29
	v_cmp_gt_u32_e64 s[46:47], v31, v252
	v_cmp_gt_u32_e64 s[48:49], v52, v252
	s_nop 0
	v_cndmask_b32_e64 v31, v20, v246, s[46:47]
	v_cndmask_b32_e64 v52, v21, v246, s[48:49]
	v_max3_f32 v30, v30, v31, v52
	v_add_u32_e32 v31, 18, v29
	v_add_u32_e32 v29, 19, v29
	v_cmp_gt_u32_e64 s[50:51], v31, v252
	v_cmp_gt_u32_e64 s[52:53], v29, v252
	s_nop 0
	v_cndmask_b32_e64 v31, v22, v246, s[50:51]
	v_cndmask_b32_e64 v29, v23, v246, s[52:53]
	v_max3_f32 v29, v30, v31, v29
	v_mov_b32_e32 v30, v28
	v_mov_b32_e32 v31, v28
	s_nop 1
	v_permlane32_swap_b32_e32 v30, v31
	v_max3_f32 v28, v28, v30, v31
	v_mov_b32_e32 v30, v29
	v_mov_b32_e32 v31, v29
	s_nop 1
	v_permlane32_swap_b32_e32 v30, v31
	v_max3_f32 v29, v29, v30, v31
	v_mov_b32_e32 v30, v28
	v_mov_b32_e32 v31, v28
	s_nop 1
	v_permlane16_swap_b32_e32 v30, v31
	v_max_f32_e32 v28, v28, v30
	v_mov_b32_e32 v30, v29
	v_mov_b32_e32 v53, v29
	v_max3_f32 v183, v148, v28, v31
	s_nop 0
	v_permlane16_swap_b32_e32 v30, v53
	v_sub_f32_e32 v28, v148, v183
	v_exp_f32_e32 v52, v28
	v_sub_f32_e32 v28, v88, v183
	v_max_f32_e32 v54, v29, v30
	v_exp_f32_e32 v28, v28
	v_sub_f32_e32 v30, v89, v183
	v_exp_f32_e32 v30, v30
	v_sub_f32_e32 v31, v90, v183
	v_exp_f32_e32 v31, v31
	v_sub_f32_e32 v55, v91, v183
	v_max3_f32 v185, v150, v54, v53
	v_exp_f32_e32 v55, v55
	v_sub_f32_e32 v88, v92, v183
	v_sub_f32_e32 v44, v44, v185
	v_cndmask_b32_e64 v28, v28, 0, vcc
	v_exp_f32_e32 v88, v88
	v_sub_f32_e32 v89, v93, v183
	v_exp_f32_e32 v44, v44
	v_sub_f32_e32 v45, v45, v185
	v_add_f32_e32 v29, 0, v28
	v_cndmask_b32_e64 v30, v30, 0, s[0:1]
	v_exp_f32_e32 v89, v89
	v_sub_f32_e32 v90, v94, v183
	v_exp_f32_e32 v45, v45
	v_sub_f32_e32 v46, v46, v185
	v_add_f32_e32 v29, v30, v29
	v_cndmask_b32_e64 v31, v31, 0, s[22:23]
	v_exp_f32_e32 v90, v90
	v_sub_f32_e32 v91, v95, v183
	v_exp_f32_e32 v46, v46
	v_sub_f32_e32 v47, v47, v185
	v_add_f32_e32 v29, v31, v29
	v_cndmask_b32_e64 v55, v55, 0, s[24:25]
	v_exp_f32_e32 v91, v91
	v_exp_f32_e32 v47, v47
	v_sub_f32_e32 v20, v20, v185
	v_add_f32_e32 v29, v55, v29
	v_cndmask_b32_e64 v88, v88, 0, s[26:27]
	v_sub_f32_e32 v53, v150, v185
	v_cndmask_b32_e64 v44, v44, 0, s[38:39]
	v_exp_f32_e32 v20, v20
	v_sub_f32_e32 v21, v21, v185
	v_add_f32_e32 v29, v88, v29
	v_cndmask_b32_e64 v89, v89, 0, s[28:29]
	v_exp_f32_e32 v54, v53
	v_add_f32_e32 v53, 0, v44
	v_cndmask_b32_e64 v45, v45, 0, s[40:41]
	v_exp_f32_e32 v21, v21
	v_add_f32_e32 v29, v89, v29
	v_cndmask_b32_e64 v90, v90, 0, s[30:31]
	v_add_f32_e32 v53, v45, v53
	v_cndmask_b32_e64 v46, v46, 0, s[42:43]
	v_add_f32_e32 v29, v90, v29
	v_cndmask_b32_e64 v91, v91, 0, s[34:35]
	v_add_f32_e32 v53, v46, v53
	v_cndmask_b32_e64 v47, v47, 0, s[44:45]
	v_add_f32_e32 v184, v91, v29
	v_cvt_pk_bf16_f32 v29, v31, v55
	v_add_f32_e32 v53, v47, v53
	v_cndmask_b32_e64 v55, v20, 0, s[46:47]
	v_add_f32_e32 v20, v55, v53
	v_cndmask_b32_e64 v53, v21, 0, s[48:49]
	v_sub_f32_e32 v21, v22, v185
	v_exp_f32_e32 v21, v21
	v_cvt_pk_bf16_f32 v28, v28, v30
	v_cvt_pk_bf16_f32 v30, v88, v89
	v_add_f32_e32 v20, v53, v20
	v_cndmask_b32_e64 v88, v21, 0, s[50:51]
	v_sub_f32_e32 v21, v23, v185
	v_exp_f32_e32 v21, v21
	v_add_f32_e32 v20, v88, v20
	v_cvt_pk_bf16_f32 v31, v90, v91
	v_cvt_pk_bf16_f32 v22, v55, v53
	v_cndmask_b32_e64 v23, v21, 0, s[52:53]
	v_add_f32_e32 v186, v23, v20
	v_cvt_pk_bf16_f32 v20, v44, v45
	v_cvt_pk_bf16_f32 v21, v46, v47
	v_pk_mul_f32 v[46:47], v[82:83], v[52:53] op_sel_hi:[1,0]
	v_pk_mul_f32 v[44:45], v[80:81], v[52:53] op_sel_hi:[1,0]
	v_cvt_pk_bf16_f32 v23, v88, v23
	v_fmac_f32_e32 v184, v149, v52
	s_waitcnt lgkmcnt(10)
	v_mfma_f32_16x16x32_bf16 v[120:123], v[132:135], v[28:31], v[44:47]
	v_fmac_f32_e32 v186, v151, v54
	s_nop 1
	v_pk_mul_f32 v[46:47], v[86:87], v[54:55] op_sel_hi:[1,0]
	v_pk_mul_f32 v[44:45], v[84:85], v[54:55] op_sel_hi:[1,0]
	s_nop 1
	v_mfma_f32_16x16x32_bf16 v[124:127], v[132:135], v[20:23], v[44:47]
	s_nop 2
	v_mul_f32_e64 v46, v98, v52
	v_mul_f32_e64 v47, v99, v52
	v_pk_mul_f32 v[44:45], v[96:97], v[52:53] op_sel_hi:[1,0]
	s_waitcnt lgkmcnt(8)
	s_nop 0
	v_mfma_f32_16x16x32_bf16 v[96:99], v[128:131], v[28:31], v[44:47]
	s_nop 2
	v_mul_f32_e64 v46, v102, v54
	v_mul_f32_e64 v47, v103, v54
	v_pk_mul_f32 v[44:45], v[100:101], v[54:55] op_sel_hi:[1,0]
	s_nop 1
	v_mfma_f32_16x16x32_bf16 v[128:131], v[128:131], v[20:23], v[44:47]
	s_nop 2
	v_mul_f32_e64 v46, v106, v52
	v_mul_f32_e64 v47, v107, v52
	v_pk_mul_f32 v[44:45], v[104:105], v[52:53] op_sel_hi:[1,0]
	s_waitcnt lgkmcnt(6)
	s_nop 0
	v_mfma_f32_16x16x32_bf16 v[132:135], v[136:139], v[28:31], v[44:47]
	s_nop 2
	v_mul_f32_e64 v46, v110, v54
	v_mul_f32_e64 v47, v111, v54
	v_pk_mul_f32 v[44:45], v[108:109], v[54:55] op_sel_hi:[1,0]
	s_nop 1
	v_mfma_f32_16x16x32_bf16 v[136:139], v[136:139], v[20:23], v[44:47]
	s_nop 2
	v_mul_f32_e64 v46, v114, v52
	v_mul_f32_e64 v47, v115, v52
	v_pk_mul_f32 v[44:45], v[112:113], v[52:53] op_sel_hi:[1,0]
	s_waitcnt lgkmcnt(4)
	s_nop 0
	v_mfma_f32_16x16x32_bf16 v[140:143], v[144:147], v[28:31], v[44:47]
	v_mul_f32_e64 v30, v118, v54
	v_mul_f32_e64 v31, v119, v54
	v_pk_mul_f32 v[28:29], v[116:117], v[54:55] op_sel_hi:[1,0]
	s_nop 1
	v_mfma_f32_16x16x32_bf16 v[144:147], v[144:147], v[20:23], v[28:31]
	v_lshl_add_u32 v20, v155, 1, v155
	v_add_u32_e32 v20, v180, v20
	v_med3_i32 v20, v20, 0, s75
	v_lshl_add_u32 v20, v20, 9, v152
	global_load_dwordx4 v[80:83], v20, s[98:99]
	v_lshl_add_u32 v20, v172, 1, v172
	v_add_u32_e32 v20, v179, v20
	v_med3_i32 v20, v20, 0, s75
	v_lshl_add_u32 v20, v20, 9, v152
	global_load_dwordx4 v[84:87], v20, s[98:99]
	v_lshl_add_u32 v20, v173, 1, v173
	v_add_u32_e32 v20, v178, v20
	v_med3_i32 v20, v20, 0, s75
	v_lshl_add_u32 v20, v20, 9, v152
	global_load_dwordx4 v[88:91], v20, s[98:99]
	v_lshl_add_u32 v20, v182, 1, v182
	v_add_u32_e32 v20, v177, v20
	v_med3_i32 v20, v20, 0, s75
	v_lshl_add_u32 v20, v20, 9, v152
	global_load_dwordx4 v[92:95], v20, s[98:99]
	v_or_b32_e32 v20, 0x100, v209
	v_add_u32_e32 v20, s76, v20
	v_med3_i32 v20, v20, 0, s75
	v_lshl_add_u32 v20, v20, 9, v158
	global_load_dwordx4 v[52:55], v20, s[100:101]
	global_load_dwordx4 v[44:47], v20, s[100:101] offset:64
	v_or_b32_e32 v20, 0x140, v209
	v_add_u32_e32 v20, s76, v20
	v_med3_i32 v20, v20, 0, s75
	v_lshl_add_u32 v20, v20, 9, v158
	global_load_dwordx4 v[28:31], v20, s[100:101]
	s_nop 0
	global_load_dwordx4 v[20:23], v20, s[100:101] offset:64
	ds_read_b64_tr_b16 v[102:103], v169 offset:2304
	ds_read_b64_tr_b16 v[100:101], v169
	ds_read_b64_tr_b16 v[108:109], v169 offset:32
	ds_read_b64_tr_b16 v[110:111], v169 offset:2336
	ds_read_b64_tr_b16 v[116:117], v169 offset:64
	ds_read_b64_tr_b16 v[118:119], v169 offset:2368
	ds_read_b64_tr_b16 v[148:149], v169 offset:96
	ds_read_b64_tr_b16 v[150:151], v169 offset:2400
	s_waitcnt vmcnt(15)
	ds_write_b128 v241, v[64:67] offset:4608
	s_waitcnt vmcnt(14)
	ds_write_b128 v242, v[68:71] offset:4608
	s_waitcnt vmcnt(13)
	ds_write_b128 v243, v[72:75] offset:4608
	s_waitcnt vmcnt(12)
	ds_write_b128 v244, v[76:79] offset:4608
	v_mfma_f32_16x16x32_bf16 v[64:67], v[48:51], v[4:7], 0
	v_mfma_f32_16x16x32_bf16 v[68:71], v[24:27], v[4:7], 0
	v_mfma_f32_16x16x32_bf16 v[24:27], v[24:27], v[12:15], 0
	v_mfma_f32_16x16x32_bf16 v[64:67], v[40:43], v[8:11], v[64:67]
	v_mfma_f32_16x16x32_bf16 v[68:71], v[16:19], v[8:11], v[68:71]
	v_mfma_f32_16x16x32_bf16 v[16:19], v[16:19], v[0:3], v[24:27]
	s_nop 4
	v_sub_u32_e32 v24, v192, v176
	v_mfma_f32_16x16x32_bf16 v[48:51], v[48:51], v[12:15], 0
	v_add_u32_e32 v27, 1, v24
	v_max_f32_e32 v26, v64, v64
	v_cmp_gt_u32_e64 s[0:1], v27, v175
	v_cmp_gt_u32_e32 vcc, v24, v175
	v_max_f32_e32 v26, 0xf149f2ca, v26
	v_cndmask_b32_e64 v27, v65, v246, s[0:1]
	v_cndmask_b32_e32 v26, v26, v246, vcc
	v_mfma_f32_16x16x32_bf16 v[40:43], v[40:43], v[0:3], v[48:51]
	v_max_f32_e32 v26, v26, v27
	v_add_u32_e32 v27, 2, v24
	v_cmp_gt_u32_e64 s[22:23], v27, v175
	v_add_u32_e32 v48, 3, v24
	v_cmp_gt_u32_e64 s[24:25], v48, v175
	v_cndmask_b32_e64 v27, v66, v246, s[22:23]
	v_sub_u32_e32 v25, v192, v181
	v_cndmask_b32_e64 v48, v67, v246, s[24:25]
	v_max3_f32 v26, v26, v27, v48
	v_add_u32_e32 v27, 16, v24
	v_add_u32_e32 v48, 17, v24
	v_cmp_gt_u32_e64 s[26:27], v27, v175
	v_cmp_gt_u32_e64 s[28:29], v48, v175
	v_cmp_gt_u32_e64 s[38:39], v25, v252
	v_cndmask_b32_e64 v27, v68, v246, s[26:27]
	v_cndmask_b32_e64 v48, v69, v246, s[28:29]
	v_max3_f32 v26, v26, v27, v48
	v_add_u32_e32 v27, 18, v24
	v_add_u32_e32 v24, 19, v24
	v_cmp_gt_u32_e64 s[30:31], v27, v175
	v_cmp_gt_u32_e64 s[34:35], v24, v175
	v_add_u32_e32 v48, 3, v25
	v_cndmask_b32_e64 v27, v70, v246, s[30:31]
	v_cndmask_b32_e64 v24, v71, v246, s[34:35]
	v_max3_f32 v24, v26, v27, v24
	v_add_u32_e32 v27, 1, v25
	v_max_f32_e32 v26, v40, v40
	v_cmp_gt_u32_e64 s[40:41], v27, v252
	v_max_f32_e32 v26, 0xf149f2ca, v26
	v_cndmask_b32_e64 v26, v26, v246, s[38:39]
	v_cndmask_b32_e64 v27, v41, v246, s[40:41]
	v_max_f32_e32 v26, v26, v27
	v_add_u32_e32 v27, 2, v25
	v_cmp_gt_u32_e64 s[42:43], v27, v252
	v_cmp_gt_u32_e64 s[44:45], v48, v252
	s_nop 0
	v_cndmask_b32_e64 v27, v42, v246, s[42:43]
	v_cndmask_b32_e64 v48, v43, v246, s[44:45]
	v_max3_f32 v26, v26, v27, v48
	v_add_u32_e32 v27, 16, v25
	v_add_u32_e32 v48, 17, v25
	v_cmp_gt_u32_e64 s[46:47], v27, v252
	v_cmp_gt_u32_e64 s[48:49], v48, v252
	s_nop 0
	v_cndmask_b32_e64 v27, v16, v246, s[46:47]
	v_cndmask_b32_e64 v48, v17, v246, s[48:49]
	v_max3_f32 v26, v26, v27, v48
	v_add_u32_e32 v27, 18, v25
	v_add_u32_e32 v25, 19, v25
	v_cmp_gt_u32_e64 s[50:51], v27, v252
	v_cmp_gt_u32_e64 s[52:53], v25, v252
	s_nop 0
	v_cndmask_b32_e64 v27, v18, v246, s[50:51]
	v_cndmask_b32_e64 v25, v19, v246, s[52:53]
	v_max3_f32 v25, v26, v27, v25
	v_mov_b32_e32 v26, v24
	v_mov_b32_e32 v27, v24
	s_nop 1
	v_permlane32_swap_b32_e32 v26, v27
	v_max3_f32 v24, v24, v26, v27
	v_mov_b32_e32 v26, v25
	v_mov_b32_e32 v27, v25
	s_nop 1
	v_permlane32_swap_b32_e32 v26, v27
	v_max3_f32 v25, v25, v26, v27
	v_mov_b32_e32 v26, v24
	v_mov_b32_e32 v27, v24
	s_nop 1
	v_permlane16_swap_b32_e32 v26, v27
	v_max_f32_e32 v24, v24, v26
	v_max3_f32 v177, v183, v24, v27
	v_sub_f32_e32 v48, v66, v177
	v_exp_f32_e32 v48, v48
	v_sub_f32_e32 v24, v183, v177
	v_exp_f32_e32 v72, v24
	v_sub_f32_e32 v24, v64, v177
	v_cndmask_b32_e64 v49, v48, 0, s[22:23]
	v_sub_f32_e32 v48, v67, v177
	v_exp_f32_e32 v48, v48
	v_exp_f32_e32 v24, v24
	v_sub_f32_e32 v27, v65, v177
	v_exp_f32_e32 v27, v27
	v_cndmask_b32_e64 v50, v48, 0, s[24:25]
	v_sub_f32_e32 v48, v68, v177
	v_exp_f32_e32 v48, v48
	v_mov_b32_e32 v26, v25
	v_mov_b32_e32 v73, v25
	s_nop 1
	v_permlane16_swap_b32_e32 v26, v73
	v_cndmask_b32_e64 v51, v48, 0, s[26:27]
	v_sub_f32_e32 v48, v69, v177
	v_exp_f32_e32 v48, v48
	v_cndmask_b32_e64 v24, v24, 0, vcc
	v_max_f32_e32 v25, v25, v26
	v_cndmask_b32_e64 v64, v48, 0, s[28:29]
	v_sub_f32_e32 v48, v70, v177
	v_exp_f32_e32 v48, v48
	v_add_f32_e32 v26, 0, v24
	v_cndmask_b32_e64 v27, v27, 0, s[0:1]
	v_add_f32_e32 v26, v27, v26
	v_cndmask_b32_e64 v65, v48, 0, s[30:31]
	v_sub_f32_e32 v48, v71, v177
	v_exp_f32_e32 v48, v48
	v_add_f32_e32 v26, v49, v26
	v_add_f32_e32 v26, v50, v26
	v_add_f32_e32 v26, v51, v26
	v_max3_f32 v179, v185, v25, v73
	v_add_f32_e32 v26, v64, v26
	v_cndmask_b32_e64 v66, v48, 0, s[34:35]
	v_cvt_pk_bf16_f32 v48, v24, v27
	v_sub_f32_e32 v24, v185, v179
	v_add_f32_e32 v26, v65, v26
	v_cvt_pk_bf16_f32 v49, v49, v50
	v_cvt_pk_bf16_f32 v50, v51, v64
	v_exp_f32_e32 v64, v24
	v_sub_f32_e32 v24, v40, v179
	v_add_f32_e32 v178, v66, v26
	v_exp_f32_e32 v24, v24
	v_sub_f32_e32 v26, v41, v179
	v_exp_f32_e32 v26, v26
	v_sub_f32_e32 v27, v42, v179
	v_exp_f32_e32 v27, v27
	v_sub_f32_e32 v40, v43, v179
	v_exp_f32_e32 v40, v40
	v_sub_f32_e32 v16, v16, v179
	v_cndmask_b32_e64 v24, v24, 0, s[38:39]
	v_exp_f32_e32 v16, v16
	v_sub_f32_e32 v17, v17, v179
	v_add_f32_e32 v25, 0, v24
	v_cndmask_b32_e64 v26, v26, 0, s[40:41]
	v_exp_f32_e32 v17, v17
	v_add_f32_e32 v25, v26, v25
	v_cndmask_b32_e64 v27, v27, 0, s[42:43]
	v_add_f32_e32 v25, v27, v25
	v_cndmask_b32_e64 v40, v40, 0, s[44:45]
	v_add_f32_e32 v25, v40, v25
	v_cndmask_b32_e64 v41, v16, 0, s[46:47]
	v_add_f32_e32 v16, v41, v25
	v_cndmask_b32_e64 v25, v17, 0, s[48:49]
	v_sub_f32_e32 v17, v18, v179
	v_exp_f32_e32 v17, v17
	v_add_f32_e32 v16, v25, v16
	v_cvt_pk_bf16_f32 v51, v65, v66
	v_cvt_pk_bf16_f32 v18, v41, v25
	v_cndmask_b32_e64 v42, v17, 0, s[50:51]
	v_sub_f32_e32 v17, v19, v179
	v_exp_f32_e32 v17, v17
	v_add_f32_e32 v16, v42, v16
	v_fmac_f32_e32 v178, v184, v72
	v_cndmask_b32_e64 v19, v17, 0, s[52:53]
	v_add_f32_e32 v180, v19, v16
	v_cvt_pk_bf16_f32 v16, v24, v26
	v_cvt_pk_bf16_f32 v17, v27, v40
	v_cvt_pk_bf16_f32 v19, v42, v19
	v_pk_mul_f32 v[26:27], v[122:123], v[72:73] op_sel_hi:[1,0]
	v_pk_mul_f32 v[24:25], v[120:121], v[72:73] op_sel_hi:[1,0]
	v_pk_mul_f32 v[42:43], v[126:127], v[64:65] op_sel_hi:[1,0]
	v_pk_mul_f32 v[40:41], v[124:125], v[64:65] op_sel_hi:[1,0]
	s_waitcnt lgkmcnt(10)
	v_mfma_f32_16x16x32_bf16 v[24:27], v[100:103], v[48:51], v[24:27]
	v_fmac_f32_e32 v180, v186, v64
	v_mfma_f32_16x16x32_bf16 v[100:103], v[100:103], v[16:19], v[40:43]
	s_nop 2
	v_mul_f32_e64 v42, v98, v72
	v_mul_f32_e64 v43, v99, v72
	v_pk_mul_f32 v[40:41], v[96:97], v[72:73] op_sel_hi:[1,0]
	s_waitcnt lgkmcnt(8)
	s_nop 0
	v_mfma_f32_16x16x32_bf16 v[104:107], v[108:111], v[48:51], v[40:43]
	s_nop 2
	v_mul_f32_e64 v42, v130, v64
	v_mul_f32_e64 v43, v131, v64
	v_pk_mul_f32 v[40:41], v[128:129], v[64:65] op_sel_hi:[1,0]
	s_nop 1
	v_mfma_f32_16x16x32_bf16 v[108:111], v[108:111], v[16:19], v[40:43]
	s_nop 2
	v_mul_f32_e64 v42, v134, v72
	v_mul_f32_e64 v43, v135, v72
	v_pk_mul_f32 v[40:41], v[132:133], v[72:73] op_sel_hi:[1,0]
	s_waitcnt lgkmcnt(6)
	s_nop 0
	v_mfma_f32_16x16x32_bf16 v[112:115], v[116:119], v[48:51], v[40:43]
	s_nop 2
	v_mul_f32_e64 v42, v138, v64
	v_mul_f32_e64 v43, v139, v64
	v_pk_mul_f32 v[40:41], v[136:137], v[64:65] op_sel_hi:[1,0]
	s_nop 1
	v_mfma_f32_16x16x32_bf16 v[116:119], v[116:119], v[16:19], v[40:43]
	s_nop 2
	v_mul_f32_e64 v42, v142, v72
	v_mul_f32_e64 v43, v143, v72
	v_pk_mul_f32 v[40:41], v[140:141], v[72:73] op_sel_hi:[1,0]
	s_waitcnt lgkmcnt(4)
	s_nop 0
	v_mfma_f32_16x16x32_bf16 v[120:123], v[148:151], v[48:51], v[40:43]
	s_nop 2
	v_mul_f32_e64 v42, v146, v64
	v_mul_f32_e64 v43, v147, v64
	v_pk_mul_f32 v[40:41], v[144:145], v[64:65] op_sel_hi:[1,0]
	s_nop 1
	v_mfma_f32_16x16x32_bf16 v[124:127], v[148:151], v[16:19], v[40:43]
	v_lshlrev_b32_e32 v16, 2, v196
	v_add_u32_e32 v16, s76, v16
	v_med3_i32 v16, v16, 0, s75
	v_lshl_add_u32 v16, v16, 9, v152
	global_load_dwordx4 v[68:71], v16, s[98:99]
	v_lshlrev_b32_e32 v16, 2, v168
	v_add_u32_e32 v16, s76, v16
	v_med3_i32 v16, v16, 0, s75
	v_lshl_add_u32 v16, v16, 9, v152
	global_load_dwordx4 v[72:75], v16, s[98:99]
	v_lshlrev_b32_e32 v16, 2, v193
	v_add_u32_e32 v16, s76, v16
	v_med3_i32 v16, v16, 0, s75
	v_lshl_add_u32 v16, v16, 9, v152
	global_load_dwordx4 v[76:79], v16, s[98:99]
	v_lshlrev_b32_e32 v16, 2, v194
	v_add_u32_e32 v16, s76, v16
	v_med3_i32 v16, v16, 0, s75
	v_lshl_add_u32 v16, v16, 9, v152
	global_load_dwordx4 v[96:99], v16, s[98:99]
	v_or_b32_e32 v16, 0x180, v209
	v_add_u32_e32 v16, s76, v16
	v_med3_i32 v16, v16, 0, s75
	v_lshl_add_u32 v16, v16, 9, v158
	global_load_dwordx4 v[64:67], v16, s[100:101]
	global_load_dwordx4 v[48:51], v16, s[100:101] offset:64
	v_or_b32_e32 v16, 0x1c0, v209
	v_add_u32_e32 v16, s76, v16
	v_med3_i32 v16, v16, 0, s75
	v_lshl_add_u32 v16, v16, 9, v158
	global_load_dwordx4 v[40:43], v16, s[100:101]
	s_nop 0
	global_load_dwordx4 v[16:19], v16, s[100:101] offset:64
	ds_read_b64_tr_b16 v[142:143], v169 offset:6912
	ds_read_b64_tr_b16 v[140:141], v169 offset:4608
	ds_read_b64_tr_b16 v[136:137], v169 offset:4640
	ds_read_b64_tr_b16 v[138:139], v169 offset:6944
	ds_read_b64_tr_b16 v[132:133], v169 offset:4672
	ds_read_b64_tr_b16 v[134:135], v169 offset:6976
	ds_read_b64_tr_b16 v[128:129], v169 offset:4704
	ds_read_b64_tr_b16 v[130:131], v169 offset:7008
	s_waitcnt vmcnt(15)
	ds_write_b128 v241, v[80:83]
	s_waitcnt vmcnt(14)
	ds_write_b128 v242, v[84:87]
	s_waitcnt vmcnt(13)
	ds_write_b128 v243, v[88:91]
	s_waitcnt vmcnt(12)
	ds_write_b128 v244, v[92:95]
	v_mfma_f32_16x16x32_bf16 v[80:83], v[60:63], v[4:7], 0
	v_mfma_f32_16x16x32_bf16 v[84:87], v[36:39], v[4:7], 0
	v_mfma_f32_16x16x32_bf16 v[36:39], v[36:39], v[12:15], 0
	v_mfma_f32_16x16x32_bf16 v[80:83], v[56:59], v[8:11], v[80:83]
	v_mfma_f32_16x16x32_bf16 v[84:87], v[32:35], v[8:11], v[84:87]
	v_mfma_f32_16x16x32_bf16 v[32:35], v[32:35], v[0:3], v[36:39]
	s_nop 4
	v_sub_u32_e32 v36, v197, v176
	v_mfma_f32_16x16x32_bf16 v[60:63], v[60:63], v[12:15], 0
	v_add_u32_e32 v39, 1, v36
	v_max_f32_e32 v38, v80, v80
	v_cmp_gt_u32_e64 s[0:1], v39, v175
	v_cmp_gt_u32_e32 vcc, v36, v175
	v_max_f32_e32 v38, 0xf149f2ca, v38
	v_cndmask_b32_e64 v39, v81, v246, s[0:1]
	v_cndmask_b32_e32 v38, v38, v246, vcc
	v_mfma_f32_16x16x32_bf16 v[56:59], v[56:59], v[0:3], v[60:63]
	v_max_f32_e32 v38, v38, v39
	v_add_u32_e32 v39, 2, v36
	v_cmp_gt_u32_e64 s[22:23], v39, v175
	v_add_u32_e32 v60, 3, v36
	v_cmp_gt_u32_e64 s[24:25], v60, v175
	v_cndmask_b32_e64 v39, v82, v246, s[22:23]
	v_sub_u32_e32 v37, v197, v181
	v_cndmask_b32_e64 v60, v83, v246, s[24:25]
	v_max3_f32 v38, v38, v39, v60
	v_add_u32_e32 v39, 16, v36
	v_add_u32_e32 v60, 17, v36
	v_cmp_gt_u32_e64 s[26:27], v39, v175
	v_cmp_gt_u32_e64 s[28:29], v60, v175
	v_cmp_gt_u32_e64 s[38:39], v37, v252
	v_cndmask_b32_e64 v39, v84, v246, s[26:27]
	v_cndmask_b32_e64 v60, v85, v246, s[28:29]
	v_max3_f32 v38, v38, v39, v60
	v_add_u32_e32 v39, 18, v36
	v_add_u32_e32 v36, 19, v36
	v_cmp_gt_u32_e64 s[30:31], v39, v175
	v_cmp_gt_u32_e64 s[34:35], v36, v175
	v_add_u32_e32 v60, 3, v37
	v_cndmask_b32_e64 v39, v86, v246, s[30:31]
	v_cndmask_b32_e64 v36, v87, v246, s[34:35]
	v_max3_f32 v36, v38, v39, v36
	v_add_u32_e32 v39, 1, v37
	v_max_f32_e32 v38, v56, v56
	v_cmp_gt_u32_e64 s[40:41], v39, v252
	v_max_f32_e32 v38, 0xf149f2ca, v38
	v_cndmask_b32_e64 v38, v38, v246, s[38:39]
	v_cndmask_b32_e64 v39, v57, v246, s[40:41]
	v_max_f32_e32 v38, v38, v39
	v_add_u32_e32 v39, 2, v37
	v_cmp_gt_u32_e64 s[42:43], v39, v252
	v_cmp_gt_u32_e64 s[44:45], v60, v252
	s_nop 0
	v_cndmask_b32_e64 v39, v58, v246, s[42:43]
	v_cndmask_b32_e64 v60, v59, v246, s[44:45]
	v_max3_f32 v38, v38, v39, v60
	v_add_u32_e32 v39, 16, v37
	v_add_u32_e32 v60, 17, v37
	v_cmp_gt_u32_e64 s[46:47], v39, v252
	v_cmp_gt_u32_e64 s[48:49], v60, v252
	s_nop 0
	v_cndmask_b32_e64 v39, v32, v246, s[46:47]
	v_cndmask_b32_e64 v60, v33, v246, s[48:49]
	v_max3_f32 v38, v38, v39, v60
	v_add_u32_e32 v39, 18, v37
	v_add_u32_e32 v37, 19, v37
	v_cmp_gt_u32_e64 s[50:51], v39, v252
	v_cmp_gt_u32_e64 s[52:53], v37, v252
	s_nop 0
	v_cndmask_b32_e64 v39, v34, v246, s[50:51]
	v_cndmask_b32_e64 v37, v35, v246, s[52:53]
	v_max3_f32 v37, v38, v39, v37
	v_mov_b32_e32 v38, v36
	v_mov_b32_e32 v39, v36
	s_nop 1
	v_permlane32_swap_b32_e32 v38, v39
	v_max3_f32 v36, v36, v38, v39
	v_mov_b32_e32 v38, v37
	v_mov_b32_e32 v39, v37
	s_nop 1
	v_permlane32_swap_b32_e32 v38, v39
	v_max3_f32 v37, v37, v38, v39
	v_mov_b32_e32 v38, v36
	v_mov_b32_e32 v39, v36
	s_nop 1
	v_permlane16_swap_b32_e32 v38, v39
	v_max_f32_e32 v36, v36, v38
	v_mov_b32_e32 v38, v37
	v_mov_b32_e32 v61, v37
	v_max3_f32 v144, v177, v36, v39
	s_nop 0
	v_permlane16_swap_b32_e32 v38, v61
	v_sub_f32_e32 v36, v177, v144
	v_exp_f32_e32 v60, v36
	v_sub_f32_e32 v36, v80, v144
	v_max_f32_e32 v62, v37, v38
	v_exp_f32_e32 v36, v36
	v_sub_f32_e32 v38, v81, v144
	v_exp_f32_e32 v38, v38
	v_sub_f32_e32 v39, v82, v144
	v_exp_f32_e32 v39, v39
	v_sub_f32_e32 v63, v83, v144
	v_max3_f32 v146, v179, v62, v61
	v_exp_f32_e32 v63, v63
	v_sub_f32_e32 v80, v84, v144
	v_sub_f32_e32 v56, v56, v146
	v_cndmask_b32_e64 v36, v36, 0, vcc
	v_exp_f32_e32 v80, v80
	v_sub_f32_e32 v81, v85, v144
	v_exp_f32_e32 v56, v56
	v_sub_f32_e32 v57, v57, v146
	v_add_f32_e32 v37, 0, v36
	v_cndmask_b32_e64 v38, v38, 0, s[0:1]
	v_exp_f32_e32 v81, v81
	v_sub_f32_e32 v82, v86, v144
	v_exp_f32_e32 v57, v57
	v_sub_f32_e32 v58, v58, v146
	v_add_f32_e32 v37, v38, v37
	v_cndmask_b32_e64 v39, v39, 0, s[22:23]
	v_exp_f32_e32 v82, v82
	v_sub_f32_e32 v83, v87, v144
	v_exp_f32_e32 v58, v58
	v_sub_f32_e32 v59, v59, v146
	v_add_f32_e32 v37, v39, v37
	v_cndmask_b32_e64 v63, v63, 0, s[24:25]
	v_exp_f32_e32 v83, v83
	v_exp_f32_e32 v59, v59
	v_sub_f32_e32 v32, v32, v146
	v_add_f32_e32 v37, v63, v37
	v_cndmask_b32_e64 v80, v80, 0, s[26:27]
	v_sub_f32_e32 v61, v179, v146
	v_cndmask_b32_e64 v56, v56, 0, s[38:39]
	v_exp_f32_e32 v32, v32
	v_sub_f32_e32 v33, v33, v146
	v_add_f32_e32 v37, v80, v37
	v_cndmask_b32_e64 v81, v81, 0, s[28:29]
	v_exp_f32_e32 v62, v61
	v_add_f32_e32 v61, 0, v56
	v_cndmask_b32_e64 v57, v57, 0, s[40:41]
	v_exp_f32_e32 v33, v33
	v_add_f32_e32 v37, v81, v37
	v_cndmask_b32_e64 v82, v82, 0, s[30:31]
	v_add_f32_e32 v61, v57, v61
	v_cndmask_b32_e64 v58, v58, 0, s[42:43]
	v_add_f32_e32 v37, v82, v37
	v_cndmask_b32_e64 v83, v83, 0, s[34:35]
	v_add_f32_e32 v61, v58, v61
	v_cndmask_b32_e64 v59, v59, 0, s[44:45]
	v_add_f32_e32 v145, v83, v37
	v_cvt_pk_bf16_f32 v37, v39, v63
	v_add_f32_e32 v61, v59, v61
	v_cndmask_b32_e64 v63, v32, 0, s[46:47]
	v_add_f32_e32 v32, v63, v61
	v_cndmask_b32_e64 v61, v33, 0, s[48:49]
	v_sub_f32_e32 v33, v34, v146
	v_exp_f32_e32 v33, v33
	v_cvt_pk_bf16_f32 v36, v36, v38
	v_cvt_pk_bf16_f32 v38, v80, v81
	v_add_f32_e32 v32, v61, v32
	v_cndmask_b32_e64 v80, v33, 0, s[50:51]
	v_sub_f32_e32 v33, v35, v146
	v_exp_f32_e32 v33, v33
	v_cvt_pk_bf16_f32 v39, v82, v83
	v_add_f32_e32 v32, v80, v32
	v_pk_mul_f32 v[26:27], v[26:27], v[60:61] op_sel_hi:[1,0]
	v_cndmask_b32_e64 v35, v33, 0, s[52:53]
	v_pk_mul_f32 v[24:25], v[24:25], v[60:61] op_sel_hi:[1,0]
	v_add_f32_e32 v147, v35, v32
	v_cvt_pk_bf16_f32 v32, v56, v57
	v_cvt_pk_bf16_f32 v33, v58, v59
	v_cvt_pk_bf16_f32 v34, v63, v61
	v_cvt_pk_bf16_f32 v35, v80, v35
	s_waitcnt lgkmcnt(10)
	v_mfma_f32_16x16x32_bf16 v[92:95], v[140:143], v[36:39], v[24:27]
	v_fmac_f32_e32 v145, v178, v60
	v_fmac_f32_e32 v147, v180, v62
	s_nop 0
	v_pk_mul_f32 v[26:27], v[102:103], v[62:63] op_sel_hi:[1,0]
	v_pk_mul_f32 v[24:25], v[100:101], v[62:63] op_sel_hi:[1,0]
	s_nop 1
	v_mfma_f32_16x16x32_bf16 v[100:103], v[140:143], v[32:35], v[24:27]
	s_nop 2
	v_mul_f32_e64 v26, v106, v60
	v_mul_f32_e64 v27, v107, v60
	v_pk_mul_f32 v[24:25], v[104:105], v[60:61] op_sel_hi:[1,0]
	s_waitcnt lgkmcnt(8)
	s_nop 0
	v_mfma_f32_16x16x32_bf16 v[104:107], v[136:139], v[36:39], v[24:27]
	s_nop 2
	v_mul_f32_e64 v26, v110, v62
	v_mul_f32_e64 v27, v111, v62
	v_pk_mul_f32 v[24:25], v[108:109], v[62:63] op_sel_hi:[1,0]
	s_nop 1
	v_mfma_f32_16x16x32_bf16 v[108:111], v[136:139], v[32:35], v[24:27]
	s_nop 2
	v_mul_f32_e64 v26, v114, v60
	v_mul_f32_e64 v27, v115, v60
	v_pk_mul_f32 v[24:25], v[112:113], v[60:61] op_sel_hi:[1,0]
	s_waitcnt lgkmcnt(6)
	s_nop 0
	v_mfma_f32_16x16x32_bf16 v[112:115], v[132:135], v[36:39], v[24:27]
	s_nop 2
	v_mul_f32_e64 v26, v118, v62
	v_mul_f32_e64 v27, v119, v62
	v_pk_mul_f32 v[24:25], v[116:117], v[62:63] op_sel_hi:[1,0]
	s_nop 1
	v_mfma_f32_16x16x32_bf16 v[116:119], v[132:135], v[32:35], v[24:27]
	s_nop 2
	v_mul_f32_e64 v26, v122, v60
	v_mul_f32_e64 v27, v123, v60
	v_pk_mul_f32 v[24:25], v[120:121], v[60:61] op_sel_hi:[1,0]
	s_waitcnt lgkmcnt(4)
	s_nop 0
	v_mfma_f32_16x16x32_bf16 v[120:123], v[128:131], v[36:39], v[24:27]
	s_nop 2
	v_mul_f32_e64 v26, v126, v62
	v_mul_f32_e64 v27, v127, v62
	v_pk_mul_f32 v[24:25], v[124:125], v[62:63] op_sel_hi:[1,0]
	s_nop 1
	v_mfma_f32_16x16x32_bf16 v[124:127], v[128:131], v[32:35], v[24:27]
	s_nop 2
	v_add_u32_e32 v24, s76, v214
	v_med3_i32 v24, v24, 0, s75
	v_lshl_add_u32 v24, v24, 9, v152
	global_load_dwordx4 v[60:63], v24, s[98:99]
	v_add_u32_e32 v24, s76, v216
	v_med3_i32 v24, v24, 0, s75
	v_lshl_add_u32 v24, v24, 9, v152
	global_load_dwordx4 v[80:83], v24, s[98:99]
	v_add_u32_e32 v24, s76, v218
	v_med3_i32 v24, v24, 0, s75
	v_lshl_add_u32 v24, v24, 9, v152
	global_load_dwordx4 v[84:87], v24, s[98:99]
	v_add_u32_e32 v24, s76, v220
	v_med3_i32 v24, v24, 0, s75
	v_lshl_add_u32 v24, v24, 9, v152
	global_load_dwordx4 v[88:91], v24, s[98:99]
	v_add_u32_e32 v24, s76, v221
	v_med3_i32 v24, v24, 0, s75
	v_lshl_add_u32 v24, v24, 9, v158
	global_load_dwordx4 v[56:59], v24, s[100:101]
	global_load_dwordx4 v[36:39], v24, s[100:101] offset:64
	v_or_b32_e32 v24, 0x100, v221
	v_add_u32_e32 v24, s76, v24
	v_med3_i32 v24, v24, 0, s75
	v_lshl_add_u32 v24, v24, 9, v158
	global_load_dwordx4 v[32:35], v24, s[100:101]
	s_nop 0
	global_load_dwordx4 v[24:27], v24, s[100:101] offset:64
	ds_read_b64_tr_b16 v[142:143], v169 offset:2304
	ds_read_b64_tr_b16 v[140:141], v169
	ds_read_b64_tr_b16 v[136:137], v169 offset:32
	ds_read_b64_tr_b16 v[138:139], v169 offset:2336
	ds_read_b64_tr_b16 v[132:133], v169 offset:64
	ds_read_b64_tr_b16 v[134:135], v169 offset:2368
	ds_read_b64_tr_b16 v[128:129], v169 offset:96
	ds_read_b64_tr_b16 v[130:131], v169 offset:2400
	s_waitcnt vmcnt(15)
	ds_write_b128 v241, v[68:71] offset:4608
	s_waitcnt vmcnt(14)
	ds_write_b128 v242, v[72:75] offset:4608
	s_waitcnt vmcnt(13)
	ds_write_b128 v243, v[76:79] offset:4608
	s_waitcnt vmcnt(12)
	ds_write_b128 v244, v[96:99] offset:4608
	v_mfma_f32_16x16x32_bf16 v[68:71], v[52:55], v[4:7], 0
	v_mfma_f32_16x16x32_bf16 v[72:75], v[28:31], v[4:7], 0
	v_mfma_f32_16x16x32_bf16 v[28:31], v[28:31], v[12:15], 0
	v_mfma_f32_16x16x32_bf16 v[68:71], v[44:47], v[8:11], v[68:71]
	v_mfma_f32_16x16x32_bf16 v[72:75], v[20:23], v[8:11], v[72:75]
	v_mfma_f32_16x16x32_bf16 v[20:23], v[20:23], v[0:3], v[28:31]
	s_nop 4
	v_sub_u32_e32 v28, v198, v176
	v_mfma_f32_16x16x32_bf16 v[52:55], v[52:55], v[12:15], 0
	v_add_u32_e32 v31, 1, v28
	v_max_f32_e32 v30, v68, v68
	v_cmp_gt_u32_e64 s[0:1], v31, v175
	v_cmp_gt_u32_e32 vcc, v28, v175
	v_max_f32_e32 v30, 0xf149f2ca, v30
	v_cndmask_b32_e64 v31, v69, v246, s[0:1]
	v_cndmask_b32_e32 v30, v30, v246, vcc
	v_mfma_f32_16x16x32_bf16 v[44:47], v[44:47], v[0:3], v[52:55]
	v_max_f32_e32 v30, v30, v31
	v_add_u32_e32 v31, 2, v28
	v_cmp_gt_u32_e64 s[22:23], v31, v175
	v_add_u32_e32 v52, 3, v28
	v_cmp_gt_u32_e64 s[24:25], v52, v175
	v_cndmask_b32_e64 v31, v70, v246, s[22:23]
	v_sub_u32_e32 v29, v198, v181
	v_cndmask_b32_e64 v52, v71, v246, s[24:25]
	v_max3_f32 v30, v30, v31, v52
	v_add_u32_e32 v31, 16, v28
	v_add_u32_e32 v52, 17, v28
	v_cmp_gt_u32_e64 s[26:27], v31, v175
	v_cmp_gt_u32_e64 s[28:29], v52, v175
	v_cmp_gt_u32_e64 s[38:39], v29, v252
	v_cndmask_b32_e64 v31, v72, v246, s[26:27]
	v_cndmask_b32_e64 v52, v73, v246, s[28:29]
	v_max3_f32 v30, v30, v31, v52
	v_add_u32_e32 v31, 18, v28
	v_add_u32_e32 v28, 19, v28
	v_cmp_gt_u32_e64 s[30:31], v31, v175
	v_cmp_gt_u32_e64 s[34:35], v28, v175
	v_add_u32_e32 v52, 3, v29
	v_cndmask_b32_e64 v31, v74, v246, s[30:31]
	v_cndmask_b32_e64 v28, v75, v246, s[34:35]
	v_max3_f32 v28, v30, v31, v28
	v_add_u32_e32 v31, 1, v29
	v_max_f32_e32 v30, v44, v44
	v_cmp_gt_u32_e64 s[40:41], v31, v252
	v_max_f32_e32 v30, 0xf149f2ca, v30
	v_cndmask_b32_e64 v30, v30, v246, s[38:39]
	v_cndmask_b32_e64 v31, v45, v246, s[40:41]
	v_max_f32_e32 v30, v30, v31
	v_add_u32_e32 v31, 2, v29
	v_cmp_gt_u32_e64 s[42:43], v31, v252
	v_cmp_gt_u32_e64 s[44:45], v52, v252
	s_nop 0
	v_cndmask_b32_e64 v31, v46, v246, s[42:43]
	v_cndmask_b32_e64 v52, v47, v246, s[44:45]
	v_max3_f32 v30, v30, v31, v52
	v_add_u32_e32 v31, 16, v29
	v_add_u32_e32 v52, 17, v29
	v_cmp_gt_u32_e64 s[46:47], v31, v252
	v_cmp_gt_u32_e64 s[48:49], v52, v252
	s_nop 0
	v_cndmask_b32_e64 v31, v20, v246, s[46:47]
	v_cndmask_b32_e64 v52, v21, v246, s[48:49]
	v_max3_f32 v30, v30, v31, v52
	v_add_u32_e32 v31, 18, v29
	v_add_u32_e32 v29, 19, v29
	v_cmp_gt_u32_e64 s[50:51], v31, v252
	v_cmp_gt_u32_e64 s[52:53], v29, v252
	s_nop 0
	v_cndmask_b32_e64 v31, v22, v246, s[50:51]
	v_cndmask_b32_e64 v29, v23, v246, s[52:53]
	v_max3_f32 v29, v30, v31, v29
	v_mov_b32_e32 v30, v28
	v_mov_b32_e32 v31, v28
	s_nop 1
	v_permlane32_swap_b32_e32 v30, v31
	v_max3_f32 v28, v28, v30, v31
	v_mov_b32_e32 v30, v29
	v_mov_b32_e32 v31, v29
	s_nop 1
	v_permlane32_swap_b32_e32 v30, v31
	v_max3_f32 v29, v29, v30, v31
	v_mov_b32_e32 v30, v28
	v_mov_b32_e32 v31, v28
	s_nop 1
	v_permlane16_swap_b32_e32 v30, v31
	v_max_f32_e32 v28, v28, v30
	v_mov_b32_e32 v30, v29
	v_mov_b32_e32 v53, v29
	v_max3_f32 v148, v144, v28, v31
	s_nop 0
	v_permlane16_swap_b32_e32 v30, v53
	v_sub_f32_e32 v28, v144, v148
	v_exp_f32_e32 v52, v28
	v_sub_f32_e32 v28, v68, v148
	v_max_f32_e32 v54, v29, v30
	v_exp_f32_e32 v28, v28
	v_sub_f32_e32 v30, v69, v148
	v_exp_f32_e32 v30, v30
	v_sub_f32_e32 v31, v70, v148
	v_exp_f32_e32 v31, v31
	v_sub_f32_e32 v55, v71, v148
	v_max3_f32 v149, v146, v54, v53
	v_exp_f32_e32 v55, v55
	v_sub_f32_e32 v68, v72, v148
	v_sub_f32_e32 v44, v44, v149
	v_cndmask_b32_e64 v28, v28, 0, vcc
	v_exp_f32_e32 v68, v68
	v_sub_f32_e32 v69, v73, v148
	v_exp_f32_e32 v44, v44
	v_sub_f32_e32 v45, v45, v149
	v_add_f32_e32 v29, 0, v28
	v_cndmask_b32_e64 v30, v30, 0, s[0:1]
	v_exp_f32_e32 v69, v69
	v_sub_f32_e32 v70, v74, v148
	v_exp_f32_e32 v45, v45
	v_sub_f32_e32 v46, v46, v149
	v_add_f32_e32 v29, v30, v29
	v_cndmask_b32_e64 v31, v31, 0, s[22:23]
	v_exp_f32_e32 v70, v70
	v_sub_f32_e32 v71, v75, v148
	v_exp_f32_e32 v46, v46
	v_sub_f32_e32 v47, v47, v149
	v_add_f32_e32 v29, v31, v29
	v_cndmask_b32_e64 v55, v55, 0, s[24:25]
	v_exp_f32_e32 v71, v71
	v_exp_f32_e32 v47, v47
	v_sub_f32_e32 v20, v20, v149
	v_add_f32_e32 v29, v55, v29
	v_cndmask_b32_e64 v68, v68, 0, s[26:27]
	v_sub_f32_e32 v53, v146, v149
	v_cndmask_b32_e64 v44, v44, 0, s[38:39]
	v_exp_f32_e32 v20, v20
	v_sub_f32_e32 v21, v21, v149
	v_add_f32_e32 v29, v68, v29
	v_cndmask_b32_e64 v69, v69, 0, s[28:29]
	v_exp_f32_e32 v54, v53
	v_add_f32_e32 v53, 0, v44
	v_cndmask_b32_e64 v45, v45, 0, s[40:41]
	v_exp_f32_e32 v21, v21
	v_add_f32_e32 v29, v69, v29
	v_cndmask_b32_e64 v70, v70, 0, s[30:31]
	v_add_f32_e32 v53, v45, v53
	v_cndmask_b32_e64 v46, v46, 0, s[42:43]
	v_add_f32_e32 v29, v70, v29
	v_cndmask_b32_e64 v71, v71, 0, s[34:35]
	v_add_f32_e32 v53, v46, v53
	v_cndmask_b32_e64 v47, v47, 0, s[44:45]
	v_add_f32_e32 v144, v71, v29
	v_cvt_pk_bf16_f32 v29, v31, v55
	v_add_f32_e32 v53, v47, v53
	v_cndmask_b32_e64 v55, v20, 0, s[46:47]
	v_add_f32_e32 v20, v55, v53
	v_cndmask_b32_e64 v53, v21, 0, s[48:49]
	v_sub_f32_e32 v21, v22, v149
	v_exp_f32_e32 v21, v21
	v_cvt_pk_bf16_f32 v28, v28, v30
	v_cvt_pk_bf16_f32 v30, v68, v69
	v_add_f32_e32 v20, v53, v20
	v_cndmask_b32_e64 v68, v21, 0, s[50:51]
	v_sub_f32_e32 v21, v23, v149
	v_exp_f32_e32 v21, v21
	v_add_f32_e32 v20, v68, v20
	v_fmac_f32_e32 v144, v145, v52
	v_cvt_pk_bf16_f32 v31, v70, v71
	v_cndmask_b32_e64 v23, v21, 0, s[52:53]
	v_add_f32_e32 v145, v23, v20
	v_cvt_pk_bf16_f32 v20, v44, v45
	v_cvt_pk_bf16_f32 v21, v46, v47
	v_pk_mul_f32 v[46:47], v[94:95], v[52:53] op_sel_hi:[1,0]
	v_pk_mul_f32 v[44:45], v[92:93], v[52:53] op_sel_hi:[1,0]
	v_cvt_pk_bf16_f32 v22, v55, v53
	v_cvt_pk_bf16_f32 v23, v68, v23
	s_waitcnt lgkmcnt(10)
	v_mfma_f32_16x16x32_bf16 v[96:99], v[140:143], v[28:31], v[44:47]
	v_fmac_f32_e32 v145, v147, v54
	s_nop 1
	v_pk_mul_f32 v[46:47], v[102:103], v[54:55] op_sel_hi:[1,0]
	v_pk_mul_f32 v[44:45], v[100:101], v[54:55] op_sel_hi:[1,0]
	s_nop 1
	v_mfma_f32_16x16x32_bf16 v[100:103], v[140:143], v[20:23], v[44:47]
	s_nop 2
	v_mul_f32_e64 v46, v106, v52
	v_mul_f32_e64 v47, v107, v52
	v_pk_mul_f32 v[44:45], v[104:105], v[52:53] op_sel_hi:[1,0]
	s_waitcnt lgkmcnt(8)
	s_nop 0
	v_mfma_f32_16x16x32_bf16 v[104:107], v[136:139], v[28:31], v[44:47]
	s_nop 2
	v_mul_f32_e64 v46, v110, v54
	v_mul_f32_e64 v47, v111, v54
	v_pk_mul_f32 v[44:45], v[108:109], v[54:55] op_sel_hi:[1,0]
	s_nop 1
	v_mfma_f32_16x16x32_bf16 v[108:111], v[136:139], v[20:23], v[44:47]
	s_nop 2
	v_mul_f32_e64 v46, v114, v52
	v_mul_f32_e64 v47, v115, v52
	v_pk_mul_f32 v[44:45], v[112:113], v[52:53] op_sel_hi:[1,0]
	s_waitcnt lgkmcnt(6)
	s_nop 0
	v_mfma_f32_16x16x32_bf16 v[112:115], v[132:135], v[28:31], v[44:47]
	s_nop 2
	v_mul_f32_e64 v46, v118, v54
	v_mul_f32_e64 v47, v119, v54
	v_pk_mul_f32 v[44:45], v[116:117], v[54:55] op_sel_hi:[1,0]
	s_nop 1
	v_mfma_f32_16x16x32_bf16 v[116:119], v[132:135], v[20:23], v[44:47]
	s_nop 2
	v_mul_f32_e64 v46, v122, v52
	v_mul_f32_e64 v47, v123, v52
	v_pk_mul_f32 v[44:45], v[120:121], v[52:53] op_sel_hi:[1,0]
	s_waitcnt lgkmcnt(4)
	s_nop 0
	v_mfma_f32_16x16x32_bf16 v[120:123], v[128:131], v[28:31], v[44:47]
	v_mul_f32_e64 v30, v126, v54
	v_mul_f32_e64 v31, v127, v54
	v_pk_mul_f32 v[28:29], v[124:125], v[54:55] op_sel_hi:[1,0]
	s_nop 1
	v_mfma_f32_16x16x32_bf16 v[124:127], v[128:131], v[20:23], v[28:31]
	v_add_u32_e32 v20, s76, v222
	v_med3_i32 v20, v20, 0, s75
	v_lshl_add_u32 v20, v20, 9, v152
	global_load_dwordx4 v[68:71], v20, s[98:99]
	v_add_u32_e32 v20, s76, v223
	v_med3_i32 v20, v20, 0, s75
	v_lshl_add_u32 v20, v20, 9, v152
	global_load_dwordx4 v[72:75], v20, s[98:99]
	v_add_u32_e32 v20, s76, v224
	v_med3_i32 v20, v20, 0, s75
	v_lshl_add_u32 v20, v20, 9, v152
	global_load_dwordx4 v[76:79], v20, s[98:99]
	v_add_u32_e32 v20, s76, v225
	v_med3_i32 v20, v20, 0, s75
	v_lshl_add_u32 v20, v20, 9, v152
	global_load_dwordx4 v[92:95], v20, s[98:99]
	v_add_u32_e32 v20, s76, v226
	v_med3_i32 v20, v20, 0, s75
	v_lshl_add_u32 v20, v20, 9, v158
	global_load_dwordx4 v[52:55], v20, s[100:101]
	global_load_dwordx4 v[44:47], v20, s[100:101] offset:64
	v_add_u32_e32 v20, s76, v227
	v_med3_i32 v20, v20, 0, s75
	v_lshl_add_u32 v20, v20, 9, v158
	global_load_dwordx4 v[28:31], v20, s[100:101]
	s_nop 0
	global_load_dwordx4 v[20:23], v20, s[100:101] offset:64
	ds_read_b64_tr_b16 v[142:143], v169 offset:6912
	ds_read_b64_tr_b16 v[140:141], v169 offset:4608
	ds_read_b64_tr_b16 v[136:137], v169 offset:4640
	ds_read_b64_tr_b16 v[138:139], v169 offset:6944
	ds_read_b64_tr_b16 v[132:133], v169 offset:4672
	ds_read_b64_tr_b16 v[134:135], v169 offset:6976
	ds_read_b64_tr_b16 v[128:129], v169 offset:4704
	ds_read_b64_tr_b16 v[130:131], v169 offset:7008
	s_waitcnt vmcnt(15)
	ds_write_b128 v241, v[60:63]
	s_waitcnt vmcnt(14)
	ds_write_b128 v242, v[80:83]
	s_waitcnt vmcnt(13)
	ds_write_b128 v243, v[84:87]
	s_waitcnt vmcnt(12)
	ds_write_b128 v244, v[88:91]
	v_mfma_f32_16x16x32_bf16 v[60:63], v[64:67], v[4:7], 0
	v_mfma_f32_16x16x32_bf16 v[80:83], v[40:43], v[4:7], 0
	v_mfma_f32_16x16x32_bf16 v[40:43], v[40:43], v[12:15], 0
	v_mfma_f32_16x16x32_bf16 v[60:63], v[48:51], v[8:11], v[60:63]
	v_mfma_f32_16x16x32_bf16 v[80:83], v[16:19], v[8:11], v[80:83]
	v_mfma_f32_16x16x32_bf16 v[16:19], v[16:19], v[0:3], v[40:43]
	s_nop 4
	v_sub_u32_e32 v40, v199, v176
	v_mfma_f32_16x16x32_bf16 v[64:67], v[64:67], v[12:15], 0
	v_add_u32_e32 v43, 1, v40
	v_max_f32_e32 v42, v60, v60
	v_cmp_gt_u32_e64 s[0:1], v43, v175
	v_cmp_gt_u32_e32 vcc, v40, v175
	v_max_f32_e32 v42, 0xf149f2ca, v42
	v_cndmask_b32_e64 v43, v61, v246, s[0:1]
	v_cndmask_b32_e32 v42, v42, v246, vcc
	v_mfma_f32_16x16x32_bf16 v[48:51], v[48:51], v[0:3], v[64:67]
	v_max_f32_e32 v42, v42, v43
	v_add_u32_e32 v43, 2, v40
	v_cmp_gt_u32_e64 s[22:23], v43, v175
	v_add_u32_e32 v64, 3, v40
	v_cmp_gt_u32_e64 s[24:25], v64, v175
	v_cndmask_b32_e64 v43, v62, v246, s[22:23]
	v_sub_u32_e32 v41, v199, v181
	v_cndmask_b32_e64 v64, v63, v246, s[24:25]
	v_max3_f32 v42, v42, v43, v64
	v_add_u32_e32 v43, 16, v40
	v_add_u32_e32 v64, 17, v40
	v_cmp_gt_u32_e64 s[26:27], v43, v175
	v_cmp_gt_u32_e64 s[28:29], v64, v175
	v_cmp_gt_u32_e64 s[38:39], v41, v252
	v_cndmask_b32_e64 v43, v80, v246, s[26:27]
	v_cndmask_b32_e64 v64, v81, v246, s[28:29]
	v_max3_f32 v42, v42, v43, v64
	v_add_u32_e32 v43, 18, v40
	v_add_u32_e32 v40, 19, v40
	v_cmp_gt_u32_e64 s[30:31], v43, v175
	v_cmp_gt_u32_e64 s[34:35], v40, v175
	v_add_u32_e32 v64, 3, v41
	v_cndmask_b32_e64 v43, v82, v246, s[30:31]
	v_cndmask_b32_e64 v40, v83, v246, s[34:35]
	v_max3_f32 v40, v42, v43, v40
	v_add_u32_e32 v43, 1, v41
	v_max_f32_e32 v42, v48, v48
	v_cmp_gt_u32_e64 s[40:41], v43, v252
	v_max_f32_e32 v42, 0xf149f2ca, v42
	v_cndmask_b32_e64 v42, v42, v246, s[38:39]
	v_cndmask_b32_e64 v43, v49, v246, s[40:41]
	v_max_f32_e32 v42, v42, v43
	v_add_u32_e32 v43, 2, v41
	v_cmp_gt_u32_e64 s[42:43], v43, v252
	v_cmp_gt_u32_e64 s[44:45], v64, v252
	s_nop 0
	v_cndmask_b32_e64 v43, v50, v246, s[42:43]
	v_cndmask_b32_e64 v64, v51, v246, s[44:45]
	v_max3_f32 v42, v42, v43, v64
	v_add_u32_e32 v43, 16, v41
	v_add_u32_e32 v64, 17, v41
	v_cmp_gt_u32_e64 s[46:47], v43, v252
	v_cmp_gt_u32_e64 s[48:49], v64, v252
	s_nop 0
	v_cndmask_b32_e64 v43, v16, v246, s[46:47]
	v_cndmask_b32_e64 v64, v17, v246, s[48:49]
	v_max3_f32 v42, v42, v43, v64
	v_add_u32_e32 v43, 18, v41
	v_add_u32_e32 v41, 19, v41
	v_cmp_gt_u32_e64 s[50:51], v43, v252
	v_cmp_gt_u32_e64 s[52:53], v41, v252
	s_nop 0
	v_cndmask_b32_e64 v43, v18, v246, s[50:51]
	v_cndmask_b32_e64 v41, v19, v246, s[52:53]
	v_max3_f32 v41, v42, v43, v41
	v_mov_b32_e32 v42, v40
	v_mov_b32_e32 v43, v40
	s_nop 1
	v_permlane32_swap_b32_e32 v42, v43
	v_max3_f32 v40, v40, v42, v43
	v_mov_b32_e32 v42, v41
	v_mov_b32_e32 v43, v41
	s_nop 1
	v_permlane32_swap_b32_e32 v42, v43
	v_max3_f32 v41, v41, v42, v43
	v_mov_b32_e32 v42, v40
	v_mov_b32_e32 v43, v40
	s_nop 1
	v_permlane16_swap_b32_e32 v42, v43
	v_max_f32_e32 v40, v40, v42
	v_max3_f32 v147, v148, v40, v43
	v_sub_f32_e32 v40, v148, v147
	v_exp_f32_e32 v84, v40
	v_sub_f32_e32 v40, v60, v147
	v_exp_f32_e32 v40, v40
	v_mov_b32_e32 v42, v41
	v_mov_b32_e32 v64, v41
	s_nop 1
	v_permlane16_swap_b32_e32 v42, v64
	v_cndmask_b32_e64 v85, v40, 0, vcc
	v_sub_f32_e32 v40, v61, v147
	v_exp_f32_e32 v40, v40
	v_max_f32_e32 v65, v41, v42
	v_max3_f32 v146, v149, v65, v64
	v_cndmask_b32_e64 v61, v40, 0, s[0:1]
	v_sub_f32_e32 v40, v62, v147
	v_exp_f32_e32 v40, v40
	v_sub_f32_e32 v48, v48, v146
	v_sub_f32_e32 v16, v16, v146
	v_exp_f32_e32 v48, v48
	v_cndmask_b32_e64 v62, v40, 0, s[22:23]
	v_sub_f32_e32 v40, v63, v147
	v_exp_f32_e32 v40, v40
	v_exp_f32_e32 v16, v16
	v_cndmask_b32_e64 v86, v48, 0, s[38:39]
	v_sub_f32_e32 v48, v49, v146
	v_cndmask_b32_e64 v63, v40, 0, s[24:25]
	v_sub_f32_e32 v40, v80, v147
	v_exp_f32_e32 v40, v40
	v_cndmask_b32_e64 v90, v16, 0, s[46:47]
	v_sub_f32_e32 v16, v17, v146
	v_exp_f32_e32 v48, v48
	v_cndmask_b32_e64 v80, v40, 0, s[26:27]
	v_sub_f32_e32 v40, v81, v147
	v_exp_f32_e32 v40, v40
	v_exp_f32_e32 v16, v16
	v_cndmask_b32_e64 v87, v48, 0, s[40:41]
	v_sub_f32_e32 v48, v50, v146
	v_cndmask_b32_e64 v81, v40, 0, s[28:29]
	v_sub_f32_e32 v40, v82, v147
	v_exp_f32_e32 v40, v40
	v_cndmask_b32_e64 v91, v16, 0, s[48:49]
	v_sub_f32_e32 v16, v18, v146
	v_exp_f32_e32 v48, v48
	v_exp_f32_e32 v16, v16
	v_cndmask_b32_e64 v82, v40, 0, s[30:31]
	v_sub_f32_e32 v40, v83, v147
	v_exp_f32_e32 v40, v40
	v_cndmask_b32_e64 v88, v48, 0, s[42:43]
	v_sub_f32_e32 v48, v51, v146
	v_cndmask_b32_e64 v148, v16, 0, s[50:51]
	v_sub_f32_e32 v16, v19, v146
	v_sub_f32_e32 v60, v149, v146
	v_exp_f32_e32 v48, v48
	v_exp_f32_e32 v16, v16
	v_exp_f32_e32 v60, v60
	v_cndmask_b32_e64 v83, v40, 0, s[34:35]
	v_cvt_pk_bf16_f32 v40, v85, v61
	v_cvt_pk_bf16_f32 v41, v62, v63
	v_cvt_pk_bf16_f32 v42, v80, v81
	v_cvt_pk_bf16_f32 v43, v82, v83
	v_cndmask_b32_e64 v89, v48, 0, s[44:45]
	v_cndmask_b32_e64 v149, v16, 0, s[52:53]
	v_pk_mul_f32 v[50:51], v[98:99], v[84:85] op_sel_hi:[1,0]
	v_pk_mul_f32 v[48:49], v[96:97], v[84:85] op_sel_hi:[1,0]
	v_cvt_pk_bf16_f32 v16, v86, v87
	v_cvt_pk_bf16_f32 v17, v88, v89
	v_cvt_pk_bf16_f32 v18, v90, v91
	v_cvt_pk_bf16_f32 v19, v148, v149
	s_waitcnt lgkmcnt(10)
	v_mfma_f32_16x16x32_bf16 v[64:67], v[140:143], v[40:43], v[48:51]
	s_cselect_b64 s[38:39], -1, 0
	s_add_i32 s0, s76, 0xfffffc00
	s_min_i32 s1, s0, 0
	v_pk_mul_f32 v[50:51], v[102:103], v[60:61] op_sel_hi:[1,0]
	v_pk_mul_f32 v[48:49], v[100:101], v[60:61] op_sel_hi:[1,0]
	s_sub_i32 s1, 15, s1
	s_ashr_i32 s1, s1, 4
	v_mfma_f32_16x16x32_bf16 v[100:103], v[140:143], v[16:19], v[48:51]
	s_sub_i32 s0, s75, s0
	s_ashr_i32 s0, s0, 4
	s_or_b32 s40, s76, 8
	v_pk_mul_f32 v[50:51], v[106:107], v[84:85] op_sel_hi:[1,0]
	v_pk_mul_f32 v[48:49], v[104:105], v[84:85] op_sel_hi:[1,0]
	s_lshl_b32 s56, s56, 7
	s_add_i32 s71, s71, s78
	s_waitcnt lgkmcnt(8)
	v_mfma_f32_16x16x32_bf16 v[104:107], v[136:139], v[40:43], v[48:51]
	s_nop 2
	v_mul_f32_e64 v50, v110, v60
	v_mul_f32_e64 v51, v111, v60
	v_pk_mul_f32 v[48:49], v[108:109], v[60:61] op_sel_hi:[1,0]
	s_nop 1
	v_mfma_f32_16x16x32_bf16 v[108:111], v[136:139], v[16:19], v[48:51]
	s_nop 2
	v_mul_f32_e64 v50, v114, v84
	v_mul_f32_e64 v51, v115, v84
	v_pk_mul_f32 v[48:49], v[112:113], v[84:85] op_sel_hi:[1,0]
	s_waitcnt lgkmcnt(6)
	s_nop 0
	v_mfma_f32_16x16x32_bf16 v[112:115], v[132:135], v[40:43], v[48:51]
	s_nop 2
	v_mul_f32_e64 v50, v118, v60
	v_mul_f32_e64 v51, v119, v60
	v_pk_mul_f32 v[48:49], v[116:117], v[60:61] op_sel_hi:[1,0]
	s_nop 1
	v_mfma_f32_16x16x32_bf16 v[116:119], v[132:135], v[16:19], v[48:51]
	s_nop 2
	v_mul_f32_e64 v50, v122, v84
	v_mul_f32_e64 v51, v123, v84
	v_pk_mul_f32 v[48:49], v[120:121], v[84:85] op_sel_hi:[1,0]
	s_waitcnt lgkmcnt(4)
	s_nop 0
	v_mfma_f32_16x16x32_bf16 v[120:123], v[128:131], v[40:43], v[48:51]
	v_mul_f32_e64 v42, v126, v60
	v_mul_f32_e64 v43, v127, v60
	v_pk_mul_f32 v[40:41], v[124:125], v[60:61] op_sel_hi:[1,0]
	s_nop 1
	v_mfma_f32_16x16x32_bf16 v[124:127], v[128:131], v[16:19], v[40:43]
	v_add_f32_e32 v16, 0, v86
	v_add_f32_e32 v16, v87, v16
	v_add_f32_e32 v16, v88, v16
	v_add_f32_e32 v16, v89, v16
	v_add_f32_e32 v16, v90, v16
	v_add_f32_e32 v16, v91, v16
	v_add_f32_e32 v16, v148, v16
	v_add_f32_e32 v151, v149, v16
	v_add_f32_e32 v16, 0, v85
	v_add_f32_e32 v16, v61, v16
	v_add_f32_e32 v16, v62, v16
	v_add_f32_e32 v16, v63, v16
	v_add_f32_e32 v16, v80, v16
	v_add_f32_e32 v16, v81, v16
	v_add_f32_e32 v16, v82, v16
	v_fmac_f32_e32 v151, v145, v60
	v_add_f32_e32 v145, v83, v16
	v_add_u32_e32 v16, s76, v213
	v_fmac_f32_e32 v145, v144, v84
	v_ashrrev_i32_e32 v148, 4, v250
	v_med3_i32 v16, v16, 0, s75
	v_lshl_add_u32 v16, v16, 9, v152
	global_load_dwordx4 v[80:83], v16, s[98:99]
	v_add_u32_e32 v16, s76, v215
	v_max_i32_e32 v150, s1, v148
	s_nop 0
	v_med3_i32 v16, v16, 0, s75
	v_lshl_add_u32 v16, v16, 9, v152
	global_load_dwordx4 v[84:87], v16, s[98:99]
	v_add_u32_e32 v16, s76, v217
	v_med3_i32 v16, v16, 0, s75
	v_lshl_add_u32 v16, v16, 9, v152
	global_load_dwordx4 v[88:91], v16, s[98:99]
	v_add_u32_e32 v16, s76, v219
	v_med3_i32 v16, v16, 0, s75
	v_lshl_add_u32 v16, v16, 9, v152
	global_load_dwordx4 v[96:99], v16, s[98:99]
	v_min_i32_e32 v16, s75, v251
	v_cndmask_b32_e64 v16, v16, 0, s[38:39]
	v_lshl_add_u32 v16, v16, 9, v158
	global_load_dwordx4 v[48:51], v16, s[100:101]
	global_load_dwordx4 v[60:63], v16, s[100:101] offset:64
	v_add_u32_e32 v16, s76, v228
	v_med3_i32 v16, v16, 0, s75
	v_lshl_add_u32 v16, v16, 9, v158
	global_load_dwordx4 v[40:43], v16, s[100:101]
	s_nop 0
	global_load_dwordx4 v[16:19], v16, s[100:101] offset:64
	ds_read_b64_tr_b16 v[142:143], v169 offset:2304
	ds_read_b64_tr_b16 v[140:141], v169
	ds_read_b64_tr_b16 v[136:137], v169 offset:32
	ds_read_b64_tr_b16 v[138:139], v169 offset:2336
	ds_read_b64_tr_b16 v[132:133], v169 offset:64
	ds_read_b64_tr_b16 v[134:135], v169 offset:2368
	ds_read_b64_tr_b16 v[128:129], v169 offset:96
	ds_read_b64_tr_b16 v[130:131], v169 offset:2400
	s_waitcnt vmcnt(15)
	ds_write_b128 v241, v[68:71] offset:4608
	s_waitcnt vmcnt(14)
	ds_write_b128 v242, v[72:75] offset:4608
	s_waitcnt vmcnt(13)
	ds_write_b128 v243, v[76:79] offset:4608
	s_waitcnt vmcnt(12)
	ds_write_b128 v244, v[92:95] offset:4608
	v_mfma_f32_16x16x32_bf16 v[72:75], v[32:35], v[4:7], 0
	v_mfma_f32_16x16x32_bf16 v[32:35], v[32:35], v[12:15], 0
	v_mfma_f32_16x16x32_bf16 v[68:71], v[56:59], v[4:7], 0
	v_mfma_f32_16x16x32_bf16 v[72:75], v[24:27], v[8:11], v[72:75]
	v_mfma_f32_16x16x32_bf16 v[24:27], v[24:27], v[0:3], v[32:35]
	v_mfma_f32_16x16x32_bf16 v[68:71], v[36:39], v[8:11], v[68:71]
	v_mfma_f32_16x16x32_bf16 v[56:59], v[56:59], v[12:15], 0
	s_nop 5
	v_add_u32_e32 v25, 0x800, v250
	v_ashrrev_i32_e32 v25, 4, v25
	v_min3_i32 v25, v25, s0, v248
	v_sub_u32_e32 v26, v154, v150
	v_sub_u32_e32 v149, v25, v150
	v_add_u32_e32 v27, 1, v26
	v_max_f32_e32 v25, v68, v68
	v_cmp_gt_u32_e64 s[0:1], v27, v149
	v_cmp_gt_u32_e32 vcc, v26, v149
	v_max_f32_e32 v25, 0xf149f2ca, v25
	v_cndmask_b32_e64 v27, v69, v246, s[0:1]
	v_cndmask_b32_e32 v25, v25, v246, vcc
	v_max_f32_e32 v25, v25, v27
	v_add_u32_e32 v27, 2, v26
	v_add_u32_e32 v32, 3, v26
	v_cmp_gt_u32_e64 s[22:23], v27, v149
	v_cmp_gt_u32_e64 s[24:25], v32, v149
	v_mfma_f32_16x16x32_bf16 v[36:39], v[36:39], v[0:3], v[56:59]
	v_cndmask_b32_e64 v27, v70, v246, s[22:23]
	v_cndmask_b32_e64 v32, v71, v246, s[24:25]
	v_max3_f32 v25, v25, v27, v32
	v_add_u32_e32 v27, 16, v26
	v_add_u32_e32 v32, 17, v26
	v_cmp_gt_u32_e64 s[26:27], v27, v149
	v_cmp_gt_u32_e64 s[28:29], v32, v149
	s_nop 0
	v_cndmask_b32_e64 v27, v72, v246, s[26:27]
	v_cndmask_b32_e64 v32, v73, v246, s[28:29]
	v_max3_f32 v25, v25, v27, v32
	v_add_u32_e32 v27, 18, v26
	v_add_u32_e32 v26, 19, v26
	v_cmp_gt_u32_e64 s[30:31], v27, v149
	v_cmp_gt_u32_e64 s[34:35], v26, v149
	s_nop 0
	v_cndmask_b32_e64 v27, v74, v246, s[30:31]
	v_cndmask_b32_e64 v26, v75, v246, s[34:35]
	v_max3_f32 v25, v25, v27, v26
	v_max_f32_e32 v26, v36, v36
	v_max_f32_e32 v26, 0xf149f2ca, v26
	v_cndmask_b32_e64 v26, v246, v26, s[36:37]
	v_cndmask_b32_e64 v27, v246, v24, s[4:5]
	v_max3_f32 v26, v26, v27, s73
	v_mov_b32_e32 v27, v25
	v_mov_b32_e32 v32, v25
	s_nop 1
	v_permlane32_swap_b32_e32 v27, v32
	v_max3_f32 v25, v25, v27, v32
	v_mov_b32_e32 v27, v26
	v_mov_b32_e32 v32, v26
	s_nop 1
	v_permlane32_swap_b32_e32 v27, v32
	v_max3_f32 v26, v26, v27, v32
	v_mov_b32_e32 v27, v25
	v_mov_b32_e32 v32, v25
	s_nop 1
	v_permlane16_swap_b32_e32 v27, v32
	v_max_f32_e32 v25, v25, v27
	v_max3_f32 v144, v147, v25, v32
	v_sub_f32_e32 v25, v147, v144
	v_exp_f32_e32 v56, v25
	v_sub_f32_e32 v25, v68, v144
	v_exp_f32_e32 v25, v25
	v_sub_f32_e32 v32, v69, v144
	v_exp_f32_e32 v32, v32
	v_sub_f32_e32 v33, v70, v144
	v_mov_b32_e32 v27, v26
	v_mov_b32_e32 v37, v26
	v_exp_f32_e32 v33, v33
	v_sub_f32_e32 v34, v71, v144
	v_permlane16_swap_b32_e32 v27, v37
	v_exp_f32_e32 v34, v34
	v_sub_f32_e32 v35, v72, v144
	v_cndmask_b32_e64 v25, v25, 0, vcc
	v_exp_f32_e32 v35, v35
	v_sub_f32_e32 v38, v73, v144
	v_max_f32_e32 v26, v26, v27
	v_add_f32_e32 v27, 0, v25
	v_cndmask_b32_e64 v32, v32, 0, s[0:1]
	v_exp_f32_e32 v38, v38
	v_sub_f32_e32 v39, v74, v144
	v_add_f32_e32 v27, v32, v27
	v_cndmask_b32_e64 v33, v33, 0, s[22:23]
	v_exp_f32_e32 v39, v39
	v_sub_f32_e32 v57, v75, v144
	v_add_f32_e32 v27, v33, v27
	v_cndmask_b32_e64 v34, v34, 0, s[24:25]
	v_exp_f32_e32 v57, v57
	v_add_f32_e32 v27, v34, v27
	v_cndmask_b32_e64 v35, v35, 0, s[26:27]
	v_add_f32_e32 v27, v35, v27
	v_cndmask_b32_e64 v38, v38, 0, s[28:29]
	v_add_f32_e32 v27, v38, v27
	v_cndmask_b32_e64 v39, v39, 0, s[30:31]
	v_add_f32_e32 v27, v39, v27
	v_cndmask_b32_e64 v57, v57, 0, s[34:35]
	v_add_f32_e32 v147, v57, v27
	v_fmac_f32_e32 v147, v145, v56
	v_max3_f32 v145, v146, v26, v37
	v_cvt_pk_bf16_f32 v32, v25, v32
	v_sub_f32_e32 v25, v146, v145
	v_exp_f32_e32 v58, v25
	v_sub_f32_e32 v25, v36, v145
	v_exp_f32_e32 v25, v25
	v_sub_f32_e32 v24, v24, v145
	v_exp_f32_e32 v24, v24
	v_cvt_pk_bf16_f32 v33, v33, v34
	v_cndmask_b32_e64 v25, 0, v25, s[36:37]
	v_cvt_pk_bf16_f32 v34, v35, v38
	v_cvt_pk_bf16_f32 v35, v39, v57
	v_add_f32_e32 v26, 0, v25
	v_cndmask_b32_e64 v27, 0, v24, s[4:5]
	v_pk_mul_f32 v[38:39], v[66:67], v[56:57] op_sel_hi:[1,0]
	v_pk_mul_f32 v[36:37], v[64:65], v[56:57] op_sel_hi:[1,0]
	v_add_f32_e32 v146, v27, v26
	v_cvt_pk_bf16_f32 v24, v25, 0
	v_cvt_pk_bf16_f32 v26, v27, 0
	v_mov_b32_e32 v25, v153
	v_mov_b32_e32 v27, v153
	s_waitcnt lgkmcnt(10)
	v_mfma_f32_16x16x32_bf16 v[76:79], v[140:143], v[32:35], v[36:39]
	v_fmac_f32_e32 v146, v151, v58
	s_nop 1
	v_pk_mul_f32 v[38:39], v[102:103], v[58:59] op_sel_hi:[1,0]
	v_pk_mul_f32 v[36:37], v[100:101], v[58:59] op_sel_hi:[1,0]
	s_nop 1
	v_mfma_f32_16x16x32_bf16 v[100:103], v[140:143], v[24:27], v[36:39]
	s_nop 2
	v_mul_f32_e64 v38, v106, v56
	v_mul_f32_e64 v39, v107, v56
	v_pk_mul_f32 v[36:37], v[104:105], v[56:57] op_sel_hi:[1,0]
	s_waitcnt lgkmcnt(8)
	s_nop 0
	v_mfma_f32_16x16x32_bf16 v[104:107], v[136:139], v[32:35], v[36:39]
	s_nop 2
	v_mul_f32_e64 v38, v110, v58
	v_mul_f32_e64 v39, v111, v58
	v_pk_mul_f32 v[36:37], v[108:109], v[58:59] op_sel_hi:[1,0]
	s_nop 1
	v_mfma_f32_16x16x32_bf16 v[108:111], v[136:139], v[24:27], v[36:39]
	s_nop 2
	v_mul_f32_e64 v38, v114, v56
	v_mul_f32_e64 v39, v115, v56
	v_pk_mul_f32 v[36:37], v[112:113], v[56:57] op_sel_hi:[1,0]
	s_waitcnt lgkmcnt(6)
	s_nop 0
	v_mfma_f32_16x16x32_bf16 v[112:115], v[132:135], v[32:35], v[36:39]
	s_nop 2
	v_mul_f32_e64 v38, v118, v58
	v_mul_f32_e64 v39, v119, v58
	v_pk_mul_f32 v[36:37], v[116:117], v[58:59] op_sel_hi:[1,0]
	s_nop 1
	v_mfma_f32_16x16x32_bf16 v[116:119], v[132:135], v[24:27], v[36:39]
	s_nop 2
	v_mul_f32_e64 v38, v122, v56
	v_mul_f32_e64 v39, v123, v56
	v_pk_mul_f32 v[36:37], v[120:121], v[56:57] op_sel_hi:[1,0]
	v_add_u32_e32 v56, s76, v232
	s_waitcnt lgkmcnt(4)
	v_mfma_f32_16x16x32_bf16 v[120:123], v[128:131], v[32:35], v[36:39]
	v_mul_f32_e64 v34, v126, v58
	v_mul_f32_e64 v35, v127, v58
	v_pk_mul_f32 v[32:33], v[124:125], v[58:59] op_sel_hi:[1,0]
	v_add_u32_e32 v36, s76, v231
	s_nop 0
	v_mfma_f32_16x16x32_bf16 v[124:127], v[128:131], v[24:27], v[32:35]
	v_add_u32_e32 v24, s76, v229
	s_nop 1
	v_add_u32_e32 v32, s76, v230
	v_med3_i32 v24, v24, 0, s75
	v_med3_i32 v32, v32, 0, s75
	v_med3_i32 v36, v36, 0, s75
	v_med3_i32 v56, v56, 0, s75
	v_lshl_add_u32 v36, v36, 9, v152
	v_lshl_add_u32 v56, v56, 9, v152
	global_load_dwordx4 v[36:39], v36, s[98:99]
	global_load_dwordx4 v[92:95], v56, s[98:99]
	v_add_u32_e32 v56, s76, v233
	v_med3_i32 v56, v56, 0, s75
	v_lshl_add_u32 v24, v24, 9, v152
	v_lshl_add_u32 v32, v32, 9, v152
	v_lshl_add_u32 v56, v56, 9, v158
	global_load_dwordx4 v[24:27], v24, s[98:99]
	s_nop 0
	global_load_dwordx4 v[32:35], v32, s[98:99]
	s_nop 0
	global_load_dwordx4 v[72:75], v56, s[100:101]
	global_load_dwordx4 v[68:71], v56, s[100:101] offset:64
	v_add_u32_e32 v56, s76, v234
	v_med3_i32 v56, v56, 0, s75
	v_lshl_add_u32 v56, v56, 9, v158
	global_load_dwordx4 v[64:67], v56, s[100:101]
	s_nop 0
	global_load_dwordx4 v[56:59], v56, s[100:101] offset:64
	ds_read_b64_tr_b16 v[142:143], v169 offset:6912
	ds_read_b64_tr_b16 v[140:141], v169 offset:4608
	ds_read_b64_tr_b16 v[136:137], v169 offset:4640
	ds_read_b64_tr_b16 v[138:139], v169 offset:6944
	ds_read_b64_tr_b16 v[132:133], v169 offset:4672
	ds_read_b64_tr_b16 v[134:135], v169 offset:6976
	ds_read_b64_tr_b16 v[128:129], v169 offset:4704
	ds_read_b64_tr_b16 v[130:131], v169 offset:7008
	s_waitcnt vmcnt(15)
	ds_write_b128 v241, v[80:83]
	s_waitcnt vmcnt(14)
	ds_write_b128 v242, v[84:87]
	s_waitcnt vmcnt(13)
	ds_write_b128 v243, v[88:91]
	s_waitcnt vmcnt(12)
	ds_write_b128 v244, v[96:99]
	v_mfma_f32_16x16x32_bf16 v[80:83], v[52:55], v[4:7], 0
	v_mfma_f32_16x16x32_bf16 v[84:87], v[28:31], v[4:7], 0
	v_mfma_f32_16x16x32_bf16 v[28:31], v[28:31], v[12:15], 0
	v_mfma_f32_16x16x32_bf16 v[80:83], v[44:47], v[8:11], v[80:83]
	v_mfma_f32_16x16x32_bf16 v[84:87], v[20:23], v[8:11], v[84:87]
	v_mfma_f32_16x16x32_bf16 v[20:23], v[20:23], v[0:3], v[28:31]
	v_mfma_f32_16x16x32_bf16 v[52:55], v[52:55], v[12:15], 0
	v_mfma_f32_16x16x32_bf16 v[44:47], v[44:47], v[0:3], v[52:55]
	s_nop 5
	v_sub_u32_e32 v21, v187, v150
	v_add_u32_e32 v23, 1, v21
	v_max_f32_e32 v22, v80, v80
	v_cmp_gt_u32_e64 s[0:1], v23, v149
	v_cmp_gt_u32_e32 vcc, v21, v149
	v_max_f32_e32 v22, 0xf149f2ca, v22
	v_cndmask_b32_e64 v23, v81, v246, s[0:1]
	v_cndmask_b32_e32 v22, v22, v246, vcc
	v_max_f32_e32 v22, v22, v23
	v_add_u32_e32 v23, 2, v21
	v_add_u32_e32 v28, 3, v21
	v_cmp_gt_u32_e64 s[22:23], v23, v149
	v_cmp_gt_u32_e64 s[24:25], v28, v149
	s_nop 0
	v_cndmask_b32_e64 v23, v82, v246, s[22:23]
	v_cndmask_b32_e64 v28, v83, v246, s[24:25]
	v_max3_f32 v22, v22, v23, v28
	v_add_u32_e32 v23, 16, v21
	v_add_u32_e32 v28, 17, v21
	v_cmp_gt_u32_e64 s[26:27], v23, v149
	v_cmp_gt_u32_e64 s[28:29], v28, v149
	s_nop 0
	v_cndmask_b32_e64 v23, v84, v246, s[26:27]
	v_cndmask_b32_e64 v28, v85, v246, s[28:29]
	v_max3_f32 v22, v22, v23, v28
	v_add_u32_e32 v23, 18, v21
	v_add_u32_e32 v21, 19, v21
	v_cmp_gt_u32_e64 s[30:31], v23, v149
	v_cmp_gt_u32_e64 s[34:35], v21, v149
	s_nop 0
	v_cndmask_b32_e64 v23, v86, v246, s[30:31]
	v_cndmask_b32_e64 v21, v87, v246, s[34:35]
	v_max3_f32 v21, v22, v23, v21
	v_max_f32_e32 v22, v44, v44
	v_max_f32_e32 v22, 0xf149f2ca, v22
	v_cndmask_b32_e64 v22, v246, v22, s[6:7]
	v_cndmask_b32_e64 v23, v246, v20, s[8:9]
	v_max3_f32 v22, v22, v23, s73
	v_mov_b32_e32 v23, v21
	v_mov_b32_e32 v28, v21
	s_nop 1
	v_permlane32_swap_b32_e32 v23, v28
	v_max3_f32 v21, v21, v23, v28
	v_mov_b32_e32 v23, v22
	v_mov_b32_e32 v28, v22
	s_nop 1
	v_permlane32_swap_b32_e32 v23, v28
	v_max3_f32 v22, v22, v23, v28
	v_mov_b32_e32 v23, v21
	v_mov_b32_e32 v28, v21
	s_nop 1
	v_permlane16_swap_b32_e32 v23, v28
	v_max_f32_e32 v21, v21, v23
	v_max3_f32 v175, v144, v21, v28
	v_sub_f32_e32 v21, v144, v175
	v_exp_f32_e32 v144, v21
	v_sub_f32_e32 v21, v80, v175
	v_sub_f32_e32 v28, v81, v175
	v_mov_b32_e32 v23, v22
	v_mov_b32_e32 v29, v22
	v_exp_f32_e32 v21, v21
	v_exp_f32_e32 v28, v28
	v_permlane16_swap_b32_e32 v23, v29
	v_sub_f32_e32 v30, v82, v175
	v_exp_f32_e32 v30, v30
	v_sub_f32_e32 v31, v83, v175
	v_max_f32_e32 v22, v22, v23
	v_exp_f32_e32 v31, v31
	v_sub_f32_e32 v45, v84, v175
	v_cndmask_b32_e64 v21, v21, 0, vcc
	v_cndmask_b32_e64 v28, v28, 0, s[0:1]
	v_exp_f32_e32 v45, v45
	v_sub_f32_e32 v46, v85, v175
	v_max3_f32 v176, v145, v22, v29
	v_add_f32_e32 v23, 0, v21
	v_exp_f32_e32 v46, v46
	v_sub_f32_e32 v47, v86, v175
	v_cvt_pk_bf16_f32 v80, v21, v28
	v_sub_f32_e32 v21, v145, v176
	v_add_f32_e32 v23, v28, v23
	v_cndmask_b32_e64 v30, v30, 0, s[22:23]
	v_exp_f32_e32 v47, v47
	v_sub_f32_e32 v52, v87, v175
	v_exp_f32_e32 v84, v21
	v_sub_f32_e32 v21, v44, v176
	v_add_f32_e32 v23, v30, v23
	v_cndmask_b32_e64 v31, v31, 0, s[24:25]
	v_exp_f32_e32 v52, v52
	v_exp_f32_e32 v21, v21
	v_sub_f32_e32 v20, v20, v176
	v_add_f32_e32 v23, v31, v23
	v_cndmask_b32_e64 v45, v45, 0, s[26:27]
	v_exp_f32_e32 v20, v20
	v_add_f32_e32 v23, v45, v23
	v_cndmask_b32_e64 v46, v46, 0, s[28:29]
	v_add_f32_e32 v23, v46, v23
	v_cndmask_b32_e64 v47, v47, 0, s[30:31]
	v_add_f32_e32 v23, v47, v23
	v_cndmask_b32_e64 v52, v52, 0, s[34:35]
	v_cndmask_b32_e64 v21, 0, v21, s[6:7]
	v_add_f32_e32 v151, v52, v23
	v_add_f32_e32 v22, 0, v21
	v_cndmask_b32_e64 v23, 0, v20, s[8:9]
	v_fmac_f32_e32 v151, v147, v144
	v_cvt_pk_bf16_f32 v81, v30, v31
	v_add_f32_e32 v147, v23, v22
	v_cvt_pk_bf16_f32 v20, v21, 0
	v_cvt_pk_bf16_f32 v22, v23, 0
	v_mov_b32_e32 v21, v153
	v_mov_b32_e32 v23, v153
	v_pk_mul_f32 v[30:31], v[78:79], v[144:145] op_sel_hi:[1,0]
	v_pk_mul_f32 v[28:29], v[76:77], v[144:145] op_sel_hi:[1,0]
	v_pk_mul_f32 v[78:79], v[110:111], v[84:85] op_sel_hi:[1,0]
	v_pk_mul_f32 v[76:77], v[108:109], v[84:85] op_sel_hi:[1,0]
	v_cvt_pk_bf16_f32 v82, v45, v46
	v_cvt_pk_bf16_f32 v83, v47, v52
	s_waitcnt lgkmcnt(8)
	v_mfma_f32_16x16x32_bf16 v[88:91], v[136:139], v[20:23], v[76:79]
	v_mul_f32_e64 v46, v102, v84
	v_mul_f32_e64 v47, v103, v84
	v_pk_mul_f32 v[44:45], v[100:101], v[84:85] op_sel_hi:[1,0]
	v_pk_mul_f32 v[54:55], v[106:107], v[144:145] op_sel_hi:[1,0]
	v_pk_mul_f32 v[78:79], v[114:115], v[144:145] op_sel_hi:[1,0]
	v_pk_mul_f32 v[76:77], v[112:113], v[144:145] op_sel_hi:[1,0]
	v_pk_mul_f32 v[52:53], v[104:105], v[144:145] op_sel_hi:[1,0]
	v_mfma_f32_16x16x32_bf16 v[44:47], v[140:143], v[20:23], v[44:47]
	v_fmac_f32_e32 v147, v146, v84
	s_waitcnt lgkmcnt(6)
	v_mfma_f32_16x16x32_bf16 v[96:99], v[132:135], v[80:83], v[76:79]
	s_nop 2
	v_mul_f32_e64 v78, v118, v84
	v_mul_f32_e64 v79, v119, v84
	v_pk_mul_f32 v[76:77], v[116:117], v[84:85] op_sel_hi:[1,0]
	v_mfma_f32_16x16x32_bf16 v[28:31], v[140:143], v[80:83], v[28:31]
	s_nop 0
	v_mfma_f32_16x16x32_bf16 v[100:103], v[132:135], v[20:23], v[76:79]
	s_nop 2
	v_mul_f32_e64 v78, v122, v144
	v_mul_f32_e64 v79, v123, v144
	v_pk_mul_f32 v[76:77], v[120:121], v[144:145] op_sel_hi:[1,0]
	v_mfma_f32_16x16x32_bf16 v[52:55], v[136:139], v[80:83], v[52:55]
	s_waitcnt lgkmcnt(4)
	v_mfma_f32_16x16x32_bf16 v[104:107], v[128:131], v[80:83], v[76:79]
	s_nop 2
	v_mul_f32_e64 v78, v126, v84
	v_mul_f32_e64 v79, v127, v84
	v_pk_mul_f32 v[76:77], v[124:125], v[84:85] op_sel_hi:[1,0]
	s_nop 1
	v_mfma_f32_16x16x32_bf16 v[108:111], v[128:131], v[20:23], v[76:79]
	v_add_u32_e32 v20, s76, v235
	v_med3_i32 v20, v20, 0, s75
	v_lshl_add_u32 v20, v20, 9, v152
	global_load_dwordx4 v[112:115], v20, s[98:99]
	v_add_u32_e32 v20, s76, v236
	v_med3_i32 v20, v20, 0, s75
	v_lshl_add_u32 v20, v20, 9, v152
	global_load_dwordx4 v[116:119], v20, s[98:99]
	v_add_u32_e32 v20, s76, v237
	v_med3_i32 v20, v20, 0, s75
	v_lshl_add_u32 v20, v20, 9, v152
	global_load_dwordx4 v[120:123], v20, s[98:99]
	v_add_u32_e32 v20, s76, v238
	v_med3_i32 v20, v20, 0, s75
	v_lshl_add_u32 v20, v20, 9, v152
	global_load_dwordx4 v[124:127], v20, s[98:99]
	v_add_u32_e32 v20, s76, v239
	v_med3_i32 v20, v20, 0, s75
	v_lshl_add_u32 v20, v20, 9, v158
	global_load_dwordx4 v[84:87], v20, s[100:101]
	global_load_dwordx4 v[80:83], v20, s[100:101] offset:64
	v_add_u32_e32 v20, s76, v240
	s_addk_i32 s76, 0xfc08
	s_nop 0
	v_med3_i32 v20, v20, 0, s75
	v_lshl_add_u32 v20, v20, 9, v158
	global_load_dwordx4 v[76:79], v20, s[100:101]
	s_nop 0
	global_load_dwordx4 v[20:23], v20, s[100:101] offset:64
	ds_read_b64_tr_b16 v[142:143], v169 offset:2304
	ds_read_b64_tr_b16 v[140:141], v169
	ds_read_b64_tr_b16 v[136:137], v169 offset:32
	ds_read_b64_tr_b16 v[138:139], v169 offset:2336
	ds_read_b64_tr_b16 v[132:133], v169 offset:64
	ds_read_b64_tr_b16 v[134:135], v169 offset:2368
	ds_read_b64_tr_b16 v[128:129], v169 offset:96
	ds_read_b64_tr_b16 v[130:131], v169 offset:2400
	s_waitcnt vmcnt(13)
	ds_write_b128 v241, v[24:27] offset:4608
	s_waitcnt vmcnt(12)
	ds_write_b128 v242, v[32:35] offset:4608
	ds_write_b128 v243, v[36:39] offset:4608
	ds_write_b128 v244, v[92:95] offset:4608
	v_mfma_f32_16x16x32_bf16 v[36:39], v[48:51], v[12:15], 0
	v_mfma_f32_16x16x32_bf16 v[24:27], v[48:51], v[4:7], 0
	v_mfma_f32_16x16x32_bf16 v[36:39], v[60:63], v[0:3], v[36:39]
	v_mfma_f32_16x16x32_bf16 v[32:35], v[40:43], v[4:7], 0
	v_mfma_f32_16x16x32_bf16 v[38:41], v[40:43], v[12:15], 0
	v_mfma_f32_16x16x32_bf16 v[24:27], v[60:63], v[8:11], v[24:27]
	v_mfma_f32_16x16x32_bf16 v[32:35], v[16:19], v[8:11], v[32:35]
	v_mfma_f32_16x16x32_bf16 v[16:19], v[16:19], v[0:3], v[38:41]
	s_nop 7
	v_sub_u32_e32 v17, v192, v150
	v_add_u32_e32 v19, 1, v17
	v_max_f32_e32 v18, v24, v24
	v_cmp_gt_u32_e64 s[0:1], v19, v149
	v_cmp_gt_u32_e32 vcc, v17, v149
	v_max_f32_e32 v18, 0xf149f2ca, v18
	v_cndmask_b32_e64 v19, v25, v246, s[0:1]
	v_cndmask_b32_e32 v18, v18, v246, vcc
	v_max_f32_e32 v18, v18, v19
	v_add_u32_e32 v19, 2, v17
	v_add_u32_e32 v37, 3, v17
	v_cmp_gt_u32_e64 s[22:23], v19, v149
	v_cmp_gt_u32_e64 s[24:25], v37, v149
	s_nop 0
	v_cndmask_b32_e64 v19, v26, v246, s[22:23]
	v_cndmask_b32_e64 v37, v27, v246, s[24:25]
	v_max3_f32 v18, v18, v19, v37
	v_add_u32_e32 v19, 16, v17
	v_add_u32_e32 v37, 17, v17
	v_cmp_gt_u32_e64 s[26:27], v19, v149
	v_cmp_gt_u32_e64 s[28:29], v37, v149
	s_nop 0
	v_cndmask_b32_e64 v19, v32, v246, s[26:27]
	v_cndmask_b32_e64 v37, v33, v246, s[28:29]
	v_max3_f32 v18, v18, v19, v37
	v_add_u32_e32 v19, 18, v17
	v_add_u32_e32 v17, 19, v17
	v_cmp_gt_u32_e64 s[30:31], v19, v149
	v_cmp_gt_u32_e64 s[34:35], v17, v149
	s_nop 0
	v_cndmask_b32_e64 v19, v34, v246, s[30:31]
	v_cndmask_b32_e64 v17, v35, v246, s[34:35]
	v_max3_f32 v17, v18, v19, v17
	v_max_f32_e32 v18, v36, v36
	v_max_f32_e32 v18, 0xf149f2ca, v18
	v_cndmask_b32_e64 v18, v246, v18, s[10:11]
	v_cndmask_b32_e64 v19, v246, v16, s[12:13]
	v_max3_f32 v18, v18, v19, s73
	v_mov_b32_e32 v19, v17
	v_mov_b32_e32 v37, v17
	s_nop 1
	v_permlane32_swap_b32_e32 v19, v37
	v_max3_f32 v17, v17, v19, v37
	v_mov_b32_e32 v19, v18
	v_mov_b32_e32 v37, v18
	s_nop 1
	v_permlane32_swap_b32_e32 v19, v37
	v_max3_f32 v18, v18, v19, v37
	v_mov_b32_e32 v19, v17
	v_mov_b32_e32 v37, v17
	s_nop 1
	v_permlane16_swap_b32_e32 v19, v37
	v_max_f32_e32 v17, v17, v19
	v_max3_f32 v145, v175, v17, v37
	v_sub_f32_e32 v17, v175, v145
	v_exp_f32_e32 v38, v17
	v_sub_f32_e32 v17, v24, v145
	v_exp_f32_e32 v17, v17
	v_mov_b32_e32 v19, v18
	v_mov_b32_e32 v39, v18
	s_nop 1
	v_permlane16_swap_b32_e32 v19, v39
	v_cndmask_b32_e64 v37, v17, 0, vcc
	v_sub_f32_e32 v17, v25, v145
	v_exp_f32_e32 v17, v17
	v_max_f32_e32 v18, v18, v19
	v_max3_f32 v144, v176, v18, v39
	v_cndmask_b32_e64 v60, v17, 0, s[0:1]
	v_sub_f32_e32 v17, v26, v145
	v_exp_f32_e32 v17, v17
	v_sub_f32_e32 v16, v16, v144
	v_exp_f32_e32 v16, v16
	v_cvt_pk_bf16_f32 v24, v37, v60
	v_cndmask_b32_e64 v61, v17, 0, s[22:23]
	v_sub_f32_e32 v17, v27, v145
	v_exp_f32_e32 v17, v17
	v_cndmask_b32_e64 v39, 0, v16, s[12:13]
	v_pk_mul_f32 v[30:31], v[30:31], v[38:39] op_sel_hi:[1,0]
	v_pk_mul_f32 v[28:29], v[28:29], v[38:39] op_sel_hi:[1,0]
	v_cndmask_b32_e64 v62, v17, 0, s[24:25]
	v_sub_f32_e32 v17, v32, v145
	v_exp_f32_e32 v17, v17
	v_cvt_pk_bf16_f32 v25, v61, v62
	v_cvt_pk_bf16_f32 v18, v39, 0
	v_mov_b32_e32 v19, v153
	v_cndmask_b32_e64 v63, v17, 0, s[26:27]
	v_sub_f32_e32 v17, v33, v145
	v_exp_f32_e32 v17, v17
	s_nop 0
	v_cndmask_b32_e64 v33, v17, 0, s[28:29]
	v_sub_f32_e32 v17, v34, v145
	v_exp_f32_e32 v17, v17
	v_cvt_pk_bf16_f32 v26, v63, v33
	v_cndmask_b32_e64 v34, v17, 0, s[30:31]
	v_sub_f32_e32 v17, v35, v145
	v_exp_f32_e32 v17, v17
	s_nop 0
	v_cndmask_b32_e64 v35, v17, 0, s[34:35]
	v_sub_f32_e32 v17, v176, v144
	v_exp_f32_e32 v32, v17
	v_sub_f32_e32 v17, v36, v144
	v_exp_f32_e32 v17, v17
	v_cvt_pk_bf16_f32 v27, v34, v35
	v_cndmask_b32_e64 v36, 0, v17, s[10:11]
	v_cvt_pk_bf16_f32 v16, v36, 0
	v_mov_b32_e32 v17, v153
	s_waitcnt lgkmcnt(10)
	v_mfma_f32_16x16x32_bf16 v[40:43], v[140:143], v[24:27], v[28:31]
	s_nop 2
	v_mul_f32_e64 v30, v46, v32
	v_mul_f32_e64 v31, v47, v32
	v_pk_mul_f32 v[28:29], v[44:45], v[32:33] op_sel_hi:[1,0]
	s_nop 1
	v_mfma_f32_16x16x32_bf16 v[44:47], v[140:143], v[16:19], v[28:31]
	s_nop 2
	v_mul_f32_e64 v30, v54, v38
	v_mul_f32_e64 v31, v55, v38
	v_pk_mul_f32 v[28:29], v[52:53], v[38:39] op_sel_hi:[1,0]
	s_waitcnt lgkmcnt(8)
	s_nop 0
	v_mfma_f32_16x16x32_bf16 v[48:51], v[136:139], v[24:27], v[28:31]
	s_nop 2
	v_mul_f32_e64 v30, v90, v32
	v_mul_f32_e64 v31, v91, v32
	v_pk_mul_f32 v[28:29], v[88:89], v[32:33] op_sel_hi:[1,0]
	s_nop 1
	v_mfma_f32_16x16x32_bf16 v[52:55], v[136:139], v[16:19], v[28:31]
	s_nop 2
	v_mul_f32_e64 v30, v98, v38
	v_mul_f32_e64 v31, v99, v38
	v_pk_mul_f32 v[28:29], v[96:97], v[38:39] op_sel_hi:[1,0]
	s_waitcnt lgkmcnt(6)
	s_nop 0
	v_mfma_f32_16x16x32_bf16 v[88:91], v[132:135], v[24:27], v[28:31]
	s_nop 2
	v_mul_f32_e64 v30, v102, v32
	v_mul_f32_e64 v31, v103, v32
	v_pk_mul_f32 v[28:29], v[100:101], v[32:33] op_sel_hi:[1,0]
	s_nop 1
	v_mfma_f32_16x16x32_bf16 v[100:103], v[132:135], v[16:19], v[28:31]
	s_nop 2
	v_mul_f32_e64 v30, v106, v38
	v_mul_f32_e64 v31, v107, v38
	v_pk_mul_f32 v[28:29], v[104:105], v[38:39] op_sel_hi:[1,0]
	s_waitcnt lgkmcnt(4)
	s_nop 0
	v_mfma_f32_16x16x32_bf16 v[104:107], v[128:131], v[24:27], v[28:31]
	v_mul_f32_e64 v26, v110, v32
	v_mul_f32_e64 v27, v111, v32
	v_pk_mul_f32 v[24:25], v[108:109], v[32:33] op_sel_hi:[1,0]
	s_nop 1
	v_mfma_f32_16x16x32_bf16 v[108:111], v[128:131], v[16:19], v[24:27]
	v_add_f32_e32 v16, 0, v36
	v_add_f32_e32 v146, v39, v16
	v_add_f32_e32 v16, 0, v37
	v_add_f32_e32 v16, v60, v16
	v_add_f32_e32 v16, v61, v16
	v_add_f32_e32 v16, v62, v16
	v_add_f32_e32 v16, v63, v16
	v_add_f32_e32 v16, v33, v16
	v_add_f32_e32 v16, v34, v16
	v_fmac_f32_e32 v146, v147, v32
	v_add_f32_e32 v147, v35, v16
	v_add_u32_e32 v16, s40, v214
	v_add_u32_e32 v24, s40, v216
	v_med3_i32 v16, v16, 0, s75
	v_med3_i32 v24, v24, 0, s75
	v_lshl_add_u32 v16, v16, 9, v152
	v_lshl_add_u32 v24, v24, 9, v152
	global_load_dwordx4 v[16:19], v16, s[98:99]
	v_or_b32_e32 v32, 0xfffffd00, v167
	global_load_dwordx4 v[60:63], v24, s[98:99]
	v_add_u32_e32 v24, s40, v218
	v_add_u32_e32 v32, s40, v32
	v_med3_i32 v24, v24, 0, s75
	v_lshl_add_u32 v24, v24, 9, v152
	global_load_dwordx4 v[92:95], v24, s[98:99]
	v_add_u32_e32 v24, s40, v220
	v_fmac_f32_e32 v147, v151, v38
	s_nop 0
	v_med3_i32 v24, v24, 0, s75
	v_lshl_add_u32 v24, v24, 9, v152
	global_load_dwordx4 v[96:99], v24, s[98:99]
	v_add_u32_e32 v24, s40, v221
	v_med3_i32 v24, v24, 0, s75
	v_med3_i32 v32, v32, 0, s75
	v_lshl_add_u32 v28, v24, 9, v158
	v_lshl_add_u32 v36, v32, 9, v158
	global_load_dwordx4 v[24:27], v28, s[100:101]
	s_nop 0
	global_load_dwordx4 v[28:31], v28, s[100:101] offset:64
	s_nop 0
	global_load_dwordx4 v[32:35], v36, s[100:101]
	s_nop 0
	global_load_dwordx4 v[36:39], v36, s[100:101] offset:64
	ds_read_b64_tr_b16 v[142:143], v169 offset:6912
	ds_read_b64_tr_b16 v[140:141], v169 offset:4608
	ds_read_b64_tr_b16 v[132:133], v169 offset:4640
	ds_read_b64_tr_b16 v[134:135], v169 offset:6944
	ds_read_b64_tr_b16 v[128:129], v169 offset:4672
	ds_read_b64_tr_b16 v[130:131], v169 offset:6976
	ds_read_b64_tr_b16 v[136:137], v169 offset:4704
	ds_read_b64_tr_b16 v[138:139], v169 offset:7008
	s_waitcnt vmcnt(15)
	ds_write_b128 v241, v[112:115]
	s_waitcnt vmcnt(14)
	ds_write_b128 v242, v[116:119]
	s_waitcnt vmcnt(13)
	ds_write_b128 v243, v[120:123]
	s_waitcnt vmcnt(12)
	ds_write_b128 v244, v[124:127]
	v_mfma_f32_16x16x32_bf16 v[112:115], v[72:75], v[4:7], 0
	v_mfma_f32_16x16x32_bf16 v[116:119], v[64:67], v[4:7], 0
	v_mfma_f32_16x16x32_bf16 v[64:67], v[64:67], v[12:15], 0
	v_mfma_f32_16x16x32_bf16 v[112:115], v[68:71], v[8:11], v[112:115]
	v_mfma_f32_16x16x32_bf16 v[116:119], v[56:59], v[8:11], v[116:119]
	v_mfma_f32_16x16x32_bf16 v[56:59], v[56:59], v[0:3], v[64:67]
	v_mfma_f32_16x16x32_bf16 v[72:75], v[72:75], v[12:15], 0
	v_mfma_f32_16x16x32_bf16 v[68:71], v[68:71], v[0:3], v[72:75]
	s_nop 5
	v_sub_u32_e32 v57, v197, v150
	v_add_u32_e32 v59, 1, v57
	v_max_f32_e32 v58, v112, v112
	v_cmp_gt_u32_e64 s[0:1], v59, v149
	v_cmp_gt_u32_e32 vcc, v57, v149
	v_max_f32_e32 v58, 0xf149f2ca, v58
	v_cndmask_b32_e64 v59, v113, v246, s[0:1]
	v_cndmask_b32_e32 v58, v58, v246, vcc
	v_max_f32_e32 v58, v58, v59
	v_add_u32_e32 v59, 2, v57
	v_add_u32_e32 v64, 3, v57
	v_cmp_gt_u32_e64 s[22:23], v59, v149
	v_cmp_gt_u32_e64 s[24:25], v64, v149
	s_nop 0
	v_cndmask_b32_e64 v59, v114, v246, s[22:23]
	v_cndmask_b32_e64 v64, v115, v246, s[24:25]
	v_max3_f32 v58, v58, v59, v64
	v_add_u32_e32 v59, 16, v57
	v_add_u32_e32 v64, 17, v57
	v_cmp_gt_u32_e64 s[26:27], v59, v149
	v_cmp_gt_u32_e64 s[28:29], v64, v149
	s_nop 0
	v_cndmask_b32_e64 v59, v116, v246, s[26:27]
	v_cndmask_b32_e64 v64, v117, v246, s[28:29]
	v_max3_f32 v58, v58, v59, v64
	v_add_u32_e32 v59, 18, v57
	v_add_u32_e32 v57, 19, v57
	v_cmp_gt_u32_e64 s[30:31], v59, v149
	v_cmp_gt_u32_e64 s[34:35], v57, v149
	s_nop 0
	v_cndmask_b32_e64 v59, v118, v246, s[30:31]
	v_cndmask_b32_e64 v57, v119, v246, s[34:35]
	v_max3_f32 v57, v58, v59, v57
	v_max_f32_e32 v58, v68, v68
	v_max_f32_e32 v58, 0xf149f2ca, v58
	v_cndmask_b32_e64 v58, v246, v58, s[14:15]
	v_cndmask_b32_e64 v59, v246, v56, s[16:17]
	v_max3_f32 v58, v58, v59, s73
	v_mov_b32_e32 v59, v57
	v_mov_b32_e32 v64, v57
	s_nop 1
	v_permlane32_swap_b32_e32 v59, v64
	v_max3_f32 v57, v57, v59, v64
	v_mov_b32_e32 v59, v58
	v_mov_b32_e32 v64, v58
	s_nop 1
	v_permlane32_swap_b32_e32 v59, v64
	v_max3_f32 v58, v58, v59, v64
	v_mov_b32_e32 v59, v57
	v_mov_b32_e32 v64, v57
	s_nop 1
	v_permlane16_swap_b32_e32 v59, v64
	v_max_f32_e32 v57, v57, v59
	v_max3_f32 v175, v145, v57, v64
	v_sub_f32_e32 v57, v145, v175
	v_exp_f32_e32 v72, v57
	v_sub_f32_e32 v57, v112, v175
	v_exp_f32_e32 v57, v57
	v_sub_f32_e32 v64, v113, v175
	v_mov_b32_e32 v59, v58
	v_mov_b32_e32 v69, v58
	v_exp_f32_e32 v64, v64
	s_nop 0
	v_permlane16_swap_b32_e32 v59, v69
	v_sub_f32_e32 v65, v114, v175
	v_max_f32_e32 v58, v58, v59
	v_cndmask_b32_e64 v57, v57, 0, vcc
	v_exp_f32_e32 v65, v65
	v_sub_f32_e32 v66, v115, v175
	v_add_f32_e32 v59, 0, v57
	v_cndmask_b32_e64 v64, v64, 0, s[0:1]
	v_exp_f32_e32 v66, v66
	v_sub_f32_e32 v67, v116, v175
	v_max3_f32 v177, v144, v58, v69
	v_add_f32_e32 v59, v64, v59
	v_exp_f32_e32 v67, v67
	v_sub_f32_e32 v70, v117, v175
	v_cvt_pk_bf16_f32 v64, v57, v64
	v_sub_f32_e32 v57, v144, v177
	v_exp_f32_e32 v70, v70
	v_sub_f32_e32 v71, v118, v175
	v_sub_f32_e32 v73, v119, v175
	v_exp_f32_e32 v74, v57
	v_sub_f32_e32 v57, v68, v177
	v_cndmask_b32_e64 v65, v65, 0, s[22:23]
	v_exp_f32_e32 v71, v71
	v_exp_f32_e32 v73, v73
	v_exp_f32_e32 v57, v57
	v_sub_f32_e32 v56, v56, v177
	v_add_f32_e32 v59, v65, v59
	v_cndmask_b32_e64 v66, v66, 0, s[24:25]
	v_exp_f32_e32 v56, v56
	v_add_f32_e32 v59, v66, v59
	v_cndmask_b32_e64 v67, v67, 0, s[26:27]
	v_add_f32_e32 v59, v67, v59
	v_cndmask_b32_e64 v70, v70, 0, s[28:29]
	v_add_f32_e32 v59, v70, v59
	v_cndmask_b32_e64 v71, v71, 0, s[30:31]
	v_cndmask_b32_e64 v73, v73, 0, s[34:35]
	v_cndmask_b32_e64 v57, 0, v57, s[14:15]
	v_add_f32_e32 v59, v71, v59
	v_cvt_pk_bf16_f32 v65, v65, v66
	v_cvt_pk_bf16_f32 v66, v67, v70
	v_cvt_pk_bf16_f32 v67, v71, v73
	v_add_f32_e32 v58, 0, v57
	v_cndmask_b32_e64 v56, 0, v56, s[16:17]
	v_pk_mul_f32 v[42:43], v[42:43], v[72:73] op_sel_hi:[1,0]
	v_pk_mul_f32 v[40:41], v[40:41], v[72:73] op_sel_hi:[1,0]
	v_add_f32_e32 v176, v73, v59
	v_add_f32_e32 v178, v56, v58
	v_cvt_pk_bf16_f32 v68, v57, 0
	v_cvt_pk_bf16_f32 v70, v56, 0
	v_mov_b32_e32 v69, v153
	v_mov_b32_e32 v71, v153
	s_waitcnt lgkmcnt(10)
	v_mfma_f32_16x16x32_bf16 v[56:59], v[140:143], v[64:67], v[40:43]
	v_fmac_f32_e32 v176, v147, v72
	v_fmac_f32_e32 v178, v146, v74
	s_nop 0
	v_pk_mul_f32 v[42:43], v[46:47], v[74:75] op_sel_hi:[1,0]
	v_pk_mul_f32 v[40:41], v[44:45], v[74:75] op_sel_hi:[1,0]
	s_nop 1
	v_mfma_f32_16x16x32_bf16 v[112:115], v[140:143], v[68:71], v[40:43]
	s_nop 2
	v_mul_f32_e64 v42, v50, v72
	v_mul_f32_e64 v43, v51, v72
	v_pk_mul_f32 v[40:41], v[48:49], v[72:73] op_sel_hi:[1,0]
	v_add_u32_e32 v48, s40, v227
	v_min_i32_e32 v49, s75, v48
	s_waitcnt lgkmcnt(8)
	v_mfma_f32_16x16x32_bf16 v[116:119], v[132:135], v[64:67], v[40:43]
	s_nop 2
	v_mul_f32_e64 v42, v54, v74
	v_mul_f32_e64 v43, v55, v74
	v_pk_mul_f32 v[40:41], v[52:53], v[74:75] op_sel_hi:[1,0]
	s_nop 1
	v_mfma_f32_16x16x32_bf16 v[120:123], v[132:135], v[68:71], v[40:43]
	s_nop 2
	v_mul_f32_e64 v42, v90, v72
	v_mul_f32_e64 v43, v91, v72
	v_pk_mul_f32 v[40:41], v[88:89], v[72:73] op_sel_hi:[1,0]
	s_waitcnt lgkmcnt(6)
	s_nop 0
	v_mfma_f32_16x16x32_bf16 v[124:127], v[128:131], v[64:67], v[40:43]
	s_nop 2
	v_mul_f32_e64 v42, v102, v74
	v_mul_f32_e64 v43, v103, v74
	v_pk_mul_f32 v[40:41], v[100:101], v[74:75] op_sel_hi:[1,0]
	s_nop 1
	v_mfma_f32_16x16x32_bf16 v[128:131], v[128:131], v[68:71], v[40:43]
	s_nop 2
	v_mul_f32_e64 v42, v106, v72
	v_mul_f32_e64 v43, v107, v72
	v_pk_mul_f32 v[40:41], v[104:105], v[72:73] op_sel_hi:[1,0]
	s_waitcnt lgkmcnt(4)
	s_nop 0
	v_mfma_f32_16x16x32_bf16 v[132:135], v[136:139], v[64:67], v[40:43]
	s_nop 2
	v_mul_f32_e64 v42, v110, v74
	v_mul_f32_e64 v43, v111, v74
	v_pk_mul_f32 v[40:41], v[108:109], v[74:75] op_sel_hi:[1,0]
	s_nop 1
	v_mfma_f32_16x16x32_bf16 v[136:139], v[136:139], v[68:71], v[40:43]
	s_nop 2
	v_add_u32_e32 v40, s40, v222
	v_med3_i32 v40, v40, 0, s75
	v_lshl_add_u32 v40, v40, 9, v152
	global_load_dwordx4 v[64:67], v40, s[98:99]
	v_add_u32_e32 v40, s40, v223
	v_med3_i32 v40, v40, 0, s75
	v_lshl_add_u32 v40, v40, 9, v152
	global_load_dwordx4 v[68:71], v40, s[98:99]
	v_add_u32_e32 v40, s40, v224
	v_med3_i32 v40, v40, 0, s75
	v_lshl_add_u32 v40, v40, 9, v152
	global_load_dwordx4 v[72:75], v40, s[98:99]
	v_add_u32_e32 v40, s40, v225
	v_med3_i32 v40, v40, 0, s75
	v_lshl_add_u32 v40, v40, 9, v152
	global_load_dwordx4 v[88:91], v40, s[98:99]
	v_add_u32_e32 v40, s40, v226
	v_med3_i32 v40, v40, 0, s75
	v_cmp_lt_i32_e32 vcc, -1, v48
	s_nop 1
	v_cndmask_b32_e32 v48, 0, v49, vcc
	v_lshl_add_u32 v44, v40, 9, v158
	v_lshl_add_u32 v52, v48, 9, v158
	global_load_dwordx4 v[40:43], v44, s[100:101]
	s_nop 0
	global_load_dwordx4 v[44:47], v44, s[100:101] offset:64
	s_nop 0
	global_load_dwordx4 v[48:51], v52, s[100:101]
	s_nop 0
	global_load_dwordx4 v[52:55], v52, s[100:101] offset:64
	ds_read_b64_tr_b16 v[102:103], v169 offset:2304
	ds_read_b64_tr_b16 v[100:101], v169
	ds_read_b64_tr_b16 v[108:109], v169 offset:32
	ds_read_b64_tr_b16 v[110:111], v169 offset:2336
	ds_read_b64_tr_b16 v[144:145], v169 offset:64
	ds_read_b64_tr_b16 v[146:147], v169 offset:2368
	ds_read_b64_tr_b16 v[140:141], v169 offset:96
	ds_read_b64_tr_b16 v[142:143], v169 offset:2400
	s_waitcnt vmcnt(15)
	ds_write_b128 v241, v[16:19] offset:4608
	s_waitcnt vmcnt(14)
	ds_write_b128 v242, v[60:63] offset:4608
	s_waitcnt vmcnt(13)
	ds_write_b128 v243, v[92:95] offset:4608
	s_waitcnt vmcnt(12)
	ds_write_b128 v244, v[96:99] offset:4608
	v_mfma_f32_16x16x32_bf16 v[16:19], v[84:87], v[4:7], 0
	v_mfma_f32_16x16x32_bf16 v[60:63], v[76:79], v[4:7], 0
	v_mfma_f32_16x16x32_bf16 v[76:79], v[76:79], v[12:15], 0
	v_mfma_f32_16x16x32_bf16 v[16:19], v[80:83], v[8:11], v[16:19]
	v_mfma_f32_16x16x32_bf16 v[60:63], v[20:23], v[8:11], v[60:63]
	v_mfma_f32_16x16x32_bf16 v[20:23], v[20:23], v[0:3], v[76:79]
	v_mfma_f32_16x16x32_bf16 v[84:87], v[84:87], v[12:15], 0
	v_mfma_f32_16x16x32_bf16 v[80:83], v[80:83], v[0:3], v[84:87]
	s_nop 5
	v_sub_u32_e32 v21, v198, v150
	v_add_u32_e32 v23, 1, v21
	v_max_f32_e32 v22, v16, v16
	v_cmp_gt_u32_e64 s[0:1], v23, v149
	v_cmp_gt_u32_e32 vcc, v21, v149
	v_max_f32_e32 v22, 0xf149f2ca, v22
	v_cndmask_b32_e64 v23, v17, v246, s[0:1]
	v_cndmask_b32_e32 v22, v22, v246, vcc
	v_max_f32_e32 v22, v22, v23
	v_add_u32_e32 v23, 2, v21
	v_add_u32_e32 v76, 3, v21
	v_cmp_gt_u32_e64 s[22:23], v23, v149
	v_cmp_gt_u32_e64 s[24:25], v76, v149
	s_nop 0
	v_cndmask_b32_e64 v23, v18, v246, s[22:23]
	v_cndmask_b32_e64 v76, v19, v246, s[24:25]
	v_max3_f32 v22, v22, v23, v76
	v_add_u32_e32 v23, 16, v21
	v_add_u32_e32 v76, 17, v21
	v_cmp_gt_u32_e64 s[26:27], v23, v149
	v_cmp_gt_u32_e64 s[28:29], v76, v149
	s_nop 0
	v_cndmask_b32_e64 v23, v60, v246, s[26:27]
	v_cndmask_b32_e64 v76, v61, v246, s[28:29]
	v_max3_f32 v22, v22, v23, v76
	v_add_u32_e32 v23, 18, v21
	v_add_u32_e32 v21, 19, v21
	v_cmp_gt_u32_e64 s[30:31], v23, v149
	v_cmp_gt_u32_e64 s[34:35], v21, v149
	s_nop 0
	v_cndmask_b32_e64 v23, v62, v246, s[30:31]
	v_cndmask_b32_e64 v21, v63, v246, s[34:35]
	v_max3_f32 v21, v22, v23, v21
	v_max_f32_e32 v22, v80, v80
	v_max_f32_e32 v22, 0xf149f2ca, v22
	v_cndmask_b32_e64 v22, v246, v22, s[18:19]
	v_cndmask_b32_e64 v23, v246, v20, s[20:21]
	v_max3_f32 v22, v22, v23, s73
	v_mov_b32_e32 v23, v21
	v_mov_b32_e32 v76, v21
	s_nop 1
	v_permlane32_swap_b32_e32 v23, v76
	v_max3_f32 v21, v21, v23, v76
	v_mov_b32_e32 v23, v22
	v_mov_b32_e32 v76, v22
	s_nop 1
	v_permlane32_swap_b32_e32 v23, v76
	v_max3_f32 v22, v22, v23, v76
	v_mov_b32_e32 v23, v21
	v_mov_b32_e32 v76, v21
	s_nop 1
	v_permlane16_swap_b32_e32 v23, v76
	v_max_f32_e32 v21, v21, v23
	v_max3_f32 v151, v175, v21, v76
	v_sub_f32_e32 v16, v16, v151
	v_mov_b32_e32 v23, v22
	v_mov_b32_e32 v77, v22
	v_exp_f32_e32 v16, v16
	v_sub_f32_e32 v17, v17, v151
	v_permlane16_swap_b32_e32 v23, v77
	v_exp_f32_e32 v17, v17
	v_sub_f32_e32 v18, v18, v151
	v_exp_f32_e32 v18, v18
	v_sub_f32_e32 v19, v19, v151
	v_max_f32_e32 v22, v22, v23
	v_exp_f32_e32 v19, v19
	v_sub_f32_e32 v23, v60, v151
	v_sub_f32_e32 v21, v175, v151
	v_cndmask_b32_e64 v16, v16, 0, vcc
	v_exp_f32_e32 v23, v23
	v_sub_f32_e32 v60, v61, v151
	v_exp_f32_e32 v76, v21
	v_add_f32_e32 v21, 0, v16
	v_cndmask_b32_e64 v17, v17, 0, s[0:1]
	v_exp_f32_e32 v60, v60
	v_sub_f32_e32 v61, v62, v151
	v_add_f32_e32 v21, v17, v21
	v_cndmask_b32_e64 v18, v18, 0, s[22:23]
	v_exp_f32_e32 v61, v61
	v_sub_f32_e32 v62, v63, v151
	v_add_f32_e32 v21, v18, v21
	v_cndmask_b32_e64 v19, v19, 0, s[24:25]
	v_exp_f32_e32 v62, v62
	v_add_f32_e32 v21, v19, v21
	v_cndmask_b32_e64 v23, v23, 0, s[26:27]
	v_add_f32_e32 v21, v23, v21
	v_cndmask_b32_e64 v60, v60, 0, s[28:29]
	v_add_f32_e32 v21, v60, v21
	v_cndmask_b32_e64 v61, v61, 0, s[30:31]
	v_add_f32_e32 v21, v61, v21
	v_cndmask_b32_e64 v62, v62, 0, s[34:35]
	v_max3_f32 v175, v177, v22, v77
	v_add_f32_e32 v149, v62, v21
	v_sub_f32_e32 v21, v177, v175
	v_cvt_pk_bf16_f32 v16, v16, v17
	v_cvt_pk_bf16_f32 v17, v18, v19
	v_cvt_pk_bf16_f32 v18, v23, v60
	v_exp_f32_e32 v60, v21
	v_sub_f32_e32 v21, v80, v175
	v_exp_f32_e32 v21, v21
	v_sub_f32_e32 v20, v20, v175
	v_exp_f32_e32 v20, v20
	v_cvt_pk_bf16_f32 v19, v61, v62
	v_cndmask_b32_e64 v21, 0, v21, s[18:19]
	v_add_f32_e32 v22, 0, v21
	v_cndmask_b32_e64 v23, 0, v20, s[20:21]
	v_pk_mul_f32 v[58:59], v[58:59], v[76:77] op_sel_hi:[1,0]
	v_pk_mul_f32 v[56:57], v[56:57], v[76:77] op_sel_hi:[1,0]
	v_add_f32_e32 v150, v23, v22
	v_cvt_pk_bf16_f32 v20, v21, 0
	v_cvt_pk_bf16_f32 v22, v23, 0
	v_mov_b32_e32 v21, v153
	v_mov_b32_e32 v23, v153
	s_waitcnt lgkmcnt(10)
	v_mfma_f32_16x16x32_bf16 v[96:99], v[100:103], v[16:19], v[56:59]
	v_fmac_f32_e32 v149, v176, v76
	v_fmac_f32_e32 v150, v178, v60
	s_min_i32 s0, s76, 0
	v_pk_mul_f32 v[58:59], v[114:115], v[60:61] op_sel_hi:[1,0]
	v_pk_mul_f32 v[56:57], v[112:113], v[60:61] op_sel_hi:[1,0]
	s_sub_i32 s0, 15, s0
	s_sub_i32 s1, s75, s76
	v_mfma_f32_16x16x32_bf16 v[100:103], v[100:103], v[20:23], v[56:59]
	s_ashr_i32 s0, s0, 4
	s_ashr_i32 s1, s1, 4
	s_cmpk_lt_i32 s71, 0x3000
	v_pk_mul_f32 v[58:59], v[118:119], v[76:77] op_sel_hi:[1,0]
	v_pk_mul_f32 v[56:57], v[116:117], v[76:77] op_sel_hi:[1,0]
	s_waitcnt lgkmcnt(8)
	s_nop 0
	v_mfma_f32_16x16x32_bf16 v[104:107], v[108:111], v[16:19], v[56:59]
	s_nop 2
	v_mul_f32_e64 v58, v122, v60
	v_mul_f32_e64 v59, v123, v60
	v_pk_mul_f32 v[56:57], v[120:121], v[60:61] op_sel_hi:[1,0]
	s_nop 1
	v_mfma_f32_16x16x32_bf16 v[108:111], v[108:111], v[20:23], v[56:59]
	s_nop 2
	v_mul_f32_e64 v58, v126, v76
	v_mul_f32_e64 v59, v127, v76
	v_pk_mul_f32 v[56:57], v[124:125], v[76:77] op_sel_hi:[1,0]
	s_waitcnt lgkmcnt(6)
	s_nop 0
	v_mfma_f32_16x16x32_bf16 v[112:115], v[144:147], v[16:19], v[56:59]
	s_nop 2
	v_mul_f32_e64 v58, v130, v60
	v_mul_f32_e64 v59, v131, v60
	v_pk_mul_f32 v[56:57], v[128:129], v[60:61] op_sel_hi:[1,0]
	s_nop 1
	v_mfma_f32_16x16x32_bf16 v[116:119], v[144:147], v[20:23], v[56:59]
	v_max_i32_e32 v145, s0, v148
	s_nop 1
	v_pk_mul_f32 v[58:59], v[134:135], v[76:77] op_sel_hi:[1,0]
	v_pk_mul_f32 v[56:57], v[132:133], v[76:77] op_sel_hi:[1,0]
	s_waitcnt lgkmcnt(4)
	s_nop 0
	v_mfma_f32_16x16x32_bf16 v[120:123], v[140:143], v[16:19], v[56:59]
	v_mul_f32_e64 v18, v138, v60
	v_mul_f32_e64 v19, v139, v60
	v_pk_mul_f32 v[16:17], v[136:137], v[60:61] op_sel_hi:[1,0]
	v_add_u32_e32 v56, s40, v228
	s_nop 0
	v_mfma_f32_16x16x32_bf16 v[124:127], v[140:143], v[20:23], v[16:19]
	s_nop 1
	s_nop 0
	v_add_u32_e32 v16, s40, v213
	v_med3_i32 v16, v16, 0, s75
	v_lshl_add_u32 v16, v16, 9, v152
	global_load_dwordx4 v[76:79], v16, s[98:99]
	v_add_u32_e32 v16, s40, v215
	v_med3_i32 v16, v16, 0, s75
	v_lshl_add_u32 v16, v16, 9, v152
	global_load_dwordx4 v[80:83], v16, s[98:99]
	v_add_u32_e32 v16, s40, v217
	v_med3_i32 v16, v16, 0, s75
	v_lshl_add_u32 v16, v16, 9, v152
	global_load_dwordx4 v[84:87], v16, s[98:99]
	v_add_u32_e32 v16, s40, v219
	v_med3_i32 v16, v16, 0, s75
	v_lshl_add_u32 v16, v16, 9, v152
	global_load_dwordx4 v[92:95], v16, s[98:99]
	v_or_b32_e32 v16, s40, v167
	v_min_i32_e32 v16, s75, v16
	v_cndmask_b32_e64 v16, v16, 0, s[38:39]
	v_med3_i32 v56, v56, 0, s75
	v_lshl_add_u32 v20, v16, 9, v158
	v_lshl_add_u32 v60, v56, 9, v158
	global_load_dwordx4 v[16:19], v20, s[100:101]
	s_nop 0
	global_load_dwordx4 v[20:23], v20, s[100:101] offset:64
	s_nop 0
	global_load_dwordx4 v[56:59], v60, s[100:101]
	s_nop 0
	global_load_dwordx4 v[60:63], v60, s[100:101] offset:64
	ds_read_b64_tr_b16 v[132:133], v169 offset:6912
	ds_read_b64_tr_b16 v[130:131], v169 offset:4608
	ds_read_b64_tr_b16 v[134:135], v169 offset:4640
	ds_read_b64_tr_b16 v[136:137], v169 offset:6944
	ds_read_b64_tr_b16 v[138:139], v169 offset:4672
	ds_read_b64_tr_b16 v[140:141], v169 offset:6976
	ds_read_b64_tr_b16 v[176:177], v169 offset:4704
	ds_read_b64_tr_b16 v[178:179], v169 offset:7008
	s_waitcnt vmcnt(15)
	ds_write_b128 v241, v[64:67]
	s_waitcnt vmcnt(14)
	ds_write_b128 v242, v[68:71]
	s_waitcnt vmcnt(13)
	ds_write_b128 v243, v[72:75]
	s_waitcnt vmcnt(12)
	ds_write_b128 v244, v[88:91]
	v_mfma_f32_16x16x32_bf16 v[64:67], v[24:27], v[4:7], 0
	v_mfma_f32_16x16x32_bf16 v[64:67], v[28:31], v[8:11], v[64:67]
	v_mfma_f32_16x16x32_bf16 v[24:27], v[24:27], v[12:15], 0
	v_mfma_f32_16x16x32_bf16 v[66:69], v[32:35], v[4:7], 0
	v_mfma_f32_16x16x32_bf16 v[24:27], v[28:31], v[0:3], v[24:27]
	v_mfma_f32_16x16x32_bf16 v[28:31], v[32:35], v[12:15], 0
	v_add_u32_e32 v32, 0x7f8, v249
	v_ashrrev_i32_e32 v32, 4, v32
	v_min3_i32 v32, v32, s1, v248
	v_mfma_f32_16x16x32_bf16 v[66:69], v[36:39], v[8:11], v[66:69]
	v_sub_u32_e32 v144, v32, v145
	v_max_f32_e32 v32, v64, v64
	v_sub_u32_e32 v33, v154, v145
	v_max_f32_e32 v32, 0xf149f2ca, v32
	v_cndmask_b32_e64 v32, v246, v32, s[36:37]
	s_nop 2
	v_cndmask_b32_e64 v34, v246, v66, s[4:5]
	v_add_u32_e32 v35, 1, v33
	v_max3_f32 v32, v32, v34, s73
	v_max_f32_e32 v34, v24, v24
	v_cmp_gt_u32_e64 s[0:1], v35, v144
	v_cmp_gt_u32_e32 vcc, v33, v144
	v_max_f32_e32 v34, 0xf149f2ca, v34
	v_cndmask_b32_e64 v35, v25, v246, s[0:1]
	v_cndmask_b32_e32 v34, v34, v246, vcc
	v_mfma_f32_16x16x32_bf16 v[28:31], v[36:39], v[0:3], v[28:31]
	v_max_f32_e32 v34, v34, v35
	v_add_u32_e32 v35, 2, v33
	v_add_u32_e32 v36, 3, v33
	v_cmp_gt_u32_e64 s[22:23], v35, v144
	v_cmp_gt_u32_e64 s[24:25], v36, v144
	s_nop 0
	v_cndmask_b32_e64 v35, v26, v246, s[22:23]
	v_cndmask_b32_e64 v36, v27, v246, s[24:25]
	v_max3_f32 v34, v34, v35, v36
	v_add_u32_e32 v35, 16, v33
	v_add_u32_e32 v36, 17, v33
	v_cmp_gt_u32_e64 s[26:27], v35, v144
	v_cmp_gt_u32_e64 s[28:29], v36, v144
	s_nop 0
	v_cndmask_b32_e64 v35, v28, v246, s[26:27]
	v_cndmask_b32_e64 v36, v29, v246, s[28:29]
	v_max3_f32 v34, v34, v35, v36
	v_add_u32_e32 v35, 18, v33
	v_add_u32_e32 v33, 19, v33
	v_cmp_gt_u32_e64 s[30:31], v35, v144
	v_cmp_gt_u32_e64 s[34:35], v33, v144
	s_nop 0
	v_cndmask_b32_e64 v35, v30, v246, s[30:31]
	v_cndmask_b32_e64 v33, v31, v246, s[34:35]
	v_max3_f32 v33, v34, v35, v33
	v_mov_b32_e32 v34, v32
	v_mov_b32_e32 v35, v32
	s_nop 1
	v_permlane32_swap_b32_e32 v34, v35
	v_max3_f32 v32, v32, v34, v35
	v_mov_b32_e32 v34, v33
	v_mov_b32_e32 v35, v33
	s_nop 1
	v_permlane32_swap_b32_e32 v34, v35
	v_max3_f32 v33, v33, v34, v35
	v_mov_b32_e32 v34, v32
	v_mov_b32_e32 v35, v32
	s_nop 1
	v_permlane16_swap_b32_e32 v34, v35
	v_max_f32_e32 v32, v32, v34
	v_mov_b32_e32 v34, v33
	v_mov_b32_e32 v37, v33
	s_nop 1
	v_permlane16_swap_b32_e32 v34, v37
	v_max_f32_e32 v38, v33, v34
	v_max3_f32 v128, v175, v38, v37
	v_sub_f32_e32 v24, v24, v128
	v_exp_f32_e32 v24, v24
	v_sub_f32_e32 v37, v175, v128
	v_exp_f32_e32 v38, v37
	v_max3_f32 v129, v151, v32, v35
	v_cndmask_b32_e64 v37, v24, 0, vcc
	v_sub_f32_e32 v24, v25, v128
	v_exp_f32_e32 v24, v24
	v_sub_f32_e32 v32, v151, v129
	v_exp_f32_e32 v36, v32
	v_sub_f32_e32 v32, v64, v129
	v_cndmask_b32_e64 v65, v24, 0, s[0:1]
	v_sub_f32_e32 v24, v26, v128
	v_exp_f32_e32 v32, v32
	v_exp_f32_e32 v24, v24
	v_mov_b32_e32 v33, v153
	v_mov_b32_e32 v35, v153
	v_cndmask_b32_e64 v39, 0, v32, s[36:37]
	v_sub_f32_e32 v32, v66, v129
	v_cndmask_b32_e64 v66, v24, 0, s[22:23]
	v_sub_f32_e32 v24, v27, v128
	v_exp_f32_e32 v24, v24
	v_exp_f32_e32 v32, v32
	v_cndmask_b32_e64 v67, v24, 0, s[24:25]
	v_sub_f32_e32 v24, v28, v128
	v_exp_f32_e32 v24, v24
	v_cndmask_b32_e64 v64, 0, v32, s[4:5]
	v_cvt_pk_bf16_f32 v32, v39, 0
	v_cvt_pk_bf16_f32 v34, v64, 0
	v_cndmask_b32_e64 v68, v24, 0, s[26:27]
	v_sub_f32_e32 v24, v29, v128
	v_exp_f32_e32 v24, v24
	v_pk_mul_f32 v[28:29], v[96:97], v[36:37] op_sel_hi:[1,0]
	v_cvt_pk_bf16_f32 v25, v66, v67
	v_cndmask_b32_e64 v69, v24, 0, s[28:29]
	v_sub_f32_e32 v24, v30, v128
	v_exp_f32_e32 v24, v24
	v_cvt_pk_bf16_f32 v26, v68, v69
	v_cndmask_b32_e64 v70, v24, 0, s[30:31]
	v_sub_f32_e32 v24, v31, v128
	v_exp_f32_e32 v24, v24
	v_pk_mul_f32 v[30:31], v[98:99], v[36:37] op_sel_hi:[1,0]
	v_cndmask_b32_e64 v71, v24, 0, s[34:35]
	v_cvt_pk_bf16_f32 v24, v37, v65
	v_cvt_pk_bf16_f32 v27, v70, v71
	s_waitcnt lgkmcnt(10)
	v_mfma_f32_16x16x32_bf16 v[96:99], v[130:133], v[32:35], v[28:31]
	s_nop 2
	v_mul_f32_e64 v30, v102, v38
	v_mul_f32_e64 v31, v103, v38
	v_pk_mul_f32 v[28:29], v[100:101], v[38:39] op_sel_hi:[1,0]
	s_nop 1
	v_mfma_f32_16x16x32_bf16 v[100:103], v[130:133], v[24:27], v[28:31]
	s_nop 2
	v_mul_f32_e64 v30, v106, v36
	v_mul_f32_e64 v31, v107, v36
	v_pk_mul_f32 v[28:29], v[104:105], v[36:37] op_sel_hi:[1,0]
	s_waitcnt lgkmcnt(8)
	s_nop 0
	v_mfma_f32_16x16x32_bf16 v[104:107], v[134:137], v[32:35], v[28:31]
	s_nop 2
	v_mul_f32_e64 v30, v110, v38
	v_mul_f32_e64 v31, v111, v38
	v_pk_mul_f32 v[28:29], v[108:109], v[38:39] op_sel_hi:[1,0]
	s_nop 1
	v_mfma_f32_16x16x32_bf16 v[108:111], v[134:137], v[24:27], v[28:31]
	s_nop 2
	v_mul_f32_e64 v30, v114, v36
	v_mul_f32_e64 v31, v115, v36
	v_pk_mul_f32 v[28:29], v[112:113], v[36:37] op_sel_hi:[1,0]
	s_waitcnt lgkmcnt(6)
	s_nop 0
	v_mfma_f32_16x16x32_bf16 v[112:115], v[138:141], v[32:35], v[28:31]
	s_nop 2
	v_mul_f32_e64 v30, v118, v38
	v_mul_f32_e64 v31, v119, v38
	v_pk_mul_f32 v[28:29], v[116:117], v[38:39] op_sel_hi:[1,0]
	s_nop 1
	v_mfma_f32_16x16x32_bf16 v[116:119], v[138:141], v[24:27], v[28:31]
	s_nop 2
	v_mul_f32_e64 v30, v122, v36
	v_mul_f32_e64 v31, v123, v36
	v_pk_mul_f32 v[28:29], v[120:121], v[36:37] op_sel_hi:[1,0]
	s_waitcnt lgkmcnt(4)
	s_nop 0
	v_mfma_f32_16x16x32_bf16 v[120:123], v[176:179], v[32:35], v[28:31]
	v_add_u32_e32 v32, s40, v234
	s_nop 0
	s_nop 0
	v_pk_mul_f32 v[30:31], v[126:127], v[38:39] op_sel_hi:[1,0]
	v_pk_mul_f32 v[28:29], v[124:125], v[38:39] op_sel_hi:[1,0]
	s_nop 1
	v_mfma_f32_16x16x32_bf16 v[124:127], v[176:179], v[24:27], v[28:31]
	v_add_f32_e32 v24, 0, v37
	v_add_f32_e32 v24, v65, v24
	v_add_f32_e32 v24, v66, v24
	v_add_f32_e32 v24, v67, v24
	v_add_f32_e32 v24, v68, v24
	v_add_f32_e32 v24, v69, v24
	v_add_f32_e32 v24, v70, v24
	v_add_f32_e32 v130, v71, v24
	v_add_f32_e32 v24, 0, v39
	v_add_f32_e32 v131, v64, v24
	v_add_u32_e32 v24, s40, v229
	v_fmac_f32_e32 v131, v149, v36
	v_fmac_f32_e32 v130, v150, v38
	v_med3_i32 v24, v24, 0, s75
	v_lshl_add_u32 v24, v24, 9, v152
	global_load_dwordx4 v[64:67], v24, s[98:99]
	v_add_u32_e32 v24, s40, v230
	v_med3_i32 v24, v24, 0, s75
	v_lshl_add_u32 v24, v24, 9, v152
	global_load_dwordx4 v[68:71], v24, s[98:99]
	v_add_u32_e32 v24, s40, v231
	v_med3_i32 v24, v24, 0, s75
	v_lshl_add_u32 v24, v24, 9, v152
	global_load_dwordx4 v[72:75], v24, s[98:99]
	v_add_u32_e32 v24, s40, v232
	v_med3_i32 v24, v24, 0, s75
	v_lshl_add_u32 v24, v24, 9, v152
	global_load_dwordx4 v[88:91], v24, s[98:99]
	v_add_u32_e32 v24, s40, v233
	v_med3_i32 v24, v24, 0, s75
	v_med3_i32 v32, v32, 0, s75
	v_lshl_add_u32 v28, v24, 9, v158
	v_lshl_add_u32 v36, v32, 9, v158
	global_load_dwordx4 v[24:27], v28, s[100:101]
	s_nop 0
	global_load_dwordx4 v[28:31], v28, s[100:101] offset:64
	s_nop 0
	global_load_dwordx4 v[32:35], v36, s[100:101]
	s_nop 0
	global_load_dwordx4 v[36:39], v36, s[100:101] offset:64
	ds_read_b64_tr_b16 v[134:135], v169 offset:2304
	ds_read_b64_tr_b16 v[132:133], v169
	ds_read_b64_tr_b16 v[136:137], v169 offset:32
	ds_read_b64_tr_b16 v[138:139], v169 offset:2336
	ds_read_b64_tr_b16 v[140:141], v169 offset:64
	ds_read_b64_tr_b16 v[142:143], v169 offset:2368
	ds_read_b64_tr_b16 v[176:177], v169 offset:96
	ds_read_b64_tr_b16 v[178:179], v169 offset:2400
	s_waitcnt vmcnt(15)
	ds_write_b128 v241, v[76:79] offset:4608
	s_waitcnt vmcnt(14)
	ds_write_b128 v242, v[80:83] offset:4608
	s_waitcnt vmcnt(13)
	ds_write_b128 v243, v[84:87] offset:4608
	s_waitcnt vmcnt(12)
	ds_write_b128 v244, v[92:95] offset:4608
	v_mfma_f32_16x16x32_bf16 v[76:79], v[40:43], v[4:7], 0
	v_mfma_f32_16x16x32_bf16 v[76:79], v[44:47], v[8:11], v[76:79]
	v_mfma_f32_16x16x32_bf16 v[78:81], v[48:51], v[4:7], 0
	v_mfma_f32_16x16x32_bf16 v[40:43], v[40:43], v[12:15], 0
	s_nop 5
	v_mov_b32_e32 v77, v153
	v_mfma_f32_16x16x32_bf16 v[78:81], v[52:55], v[8:11], v[78:81]
	v_mfma_f32_16x16x32_bf16 v[40:43], v[44:47], v[0:3], v[40:43]
	v_mfma_f32_16x16x32_bf16 v[44:47], v[48:51], v[12:15], 0
	v_max_f32_e32 v49, v76, v76
	v_sub_u32_e32 v48, v187, v145
	v_max_f32_e32 v49, 0xf149f2ca, v49
	v_cndmask_b32_e64 v49, v246, v49, s[6:7]
	s_nop 1
	v_cndmask_b32_e64 v50, v246, v78, s[8:9]
	v_add_u32_e32 v51, 1, v48
	v_max3_f32 v49, v49, v50, s73
	v_max_f32_e32 v50, v40, v40
	v_cmp_gt_u32_e64 s[0:1], v51, v144
	v_cmp_gt_u32_e32 vcc, v48, v144
	v_max_f32_e32 v50, 0xf149f2ca, v50
	v_cndmask_b32_e64 v51, v41, v246, s[0:1]
	v_cndmask_b32_e32 v50, v50, v246, vcc
	v_mfma_f32_16x16x32_bf16 v[44:47], v[52:55], v[0:3], v[44:47]
	v_max_f32_e32 v50, v50, v51
	v_add_u32_e32 v51, 2, v48
	v_add_u32_e32 v52, 3, v48
	v_cmp_gt_u32_e64 s[22:23], v51, v144
	v_cmp_gt_u32_e64 s[24:25], v52, v144
	v_mov_b32_e32 v79, v153
	v_cndmask_b32_e64 v51, v42, v246, s[22:23]
	v_cndmask_b32_e64 v52, v43, v246, s[24:25]
	v_max3_f32 v50, v50, v51, v52
	v_add_u32_e32 v51, 16, v48
	v_add_u32_e32 v52, 17, v48
	v_cmp_gt_u32_e64 s[26:27], v51, v144
	v_cmp_gt_u32_e64 s[28:29], v52, v144
	s_nop 0
	v_cndmask_b32_e64 v51, v44, v246, s[26:27]
	v_cndmask_b32_e64 v52, v45, v246, s[28:29]
	v_max3_f32 v50, v50, v51, v52
	v_add_u32_e32 v51, 18, v48
	v_add_u32_e32 v48, 19, v48
	v_cmp_gt_u32_e64 s[30:31], v51, v144
	v_cmp_gt_u32_e64 s[34:35], v48, v144
	s_nop 0
	v_cndmask_b32_e64 v51, v46, v246, s[30:31]
	v_cndmask_b32_e64 v48, v47, v246, s[34:35]
	v_max3_f32 v48, v50, v51, v48
	v_mov_b32_e32 v50, v49
	v_mov_b32_e32 v51, v49
	s_nop 1
	v_permlane32_swap_b32_e32 v50, v51
	v_max3_f32 v49, v49, v50, v51
	v_mov_b32_e32 v50, v48
	v_mov_b32_e32 v51, v48
	s_nop 1
	v_permlane32_swap_b32_e32 v50, v51
	v_max3_f32 v48, v48, v50, v51
	v_mov_b32_e32 v50, v49
	v_mov_b32_e32 v51, v49
	s_nop 1
	v_permlane16_swap_b32_e32 v50, v51
	v_max_f32_e32 v49, v49, v50
	v_mov_b32_e32 v50, v48
	v_mov_b32_e32 v52, v48
	s_nop 1
	v_permlane16_swap_b32_e32 v50, v52
	v_max_f32_e32 v48, v48, v50
	v_max3_f32 v148, v128, v48, v52
	v_sub_f32_e32 v40, v40, v148
	v_exp_f32_e32 v40, v40
	v_sub_f32_e32 v41, v41, v148
	v_exp_f32_e32 v41, v41
	v_sub_f32_e32 v42, v42, v148
	v_exp_f32_e32 v42, v42
	v_sub_f32_e32 v43, v43, v148
	v_exp_f32_e32 v43, v43
	v_sub_f32_e32 v44, v44, v148
	v_max3_f32 v146, v129, v49, v51
	v_sub_f32_e32 v48, v128, v148
	v_cndmask_b32_e64 v40, v40, 0, vcc
	v_exp_f32_e32 v44, v44
	v_sub_f32_e32 v45, v45, v148
	v_sub_f32_e32 v49, v129, v146
	v_exp_f32_e32 v86, v48
	v_add_f32_e32 v48, 0, v40
	v_cndmask_b32_e64 v41, v41, 0, s[0:1]
	v_exp_f32_e32 v45, v45
	v_sub_f32_e32 v46, v46, v148
	v_sub_f32_e32 v47, v47, v148
	v_exp_f32_e32 v84, v49
	v_sub_f32_e32 v49, v76, v146
	v_sub_f32_e32 v51, v78, v146
	v_add_f32_e32 v48, v41, v48
	v_cndmask_b32_e64 v42, v42, 0, s[22:23]
	v_exp_f32_e32 v46, v46
	v_exp_f32_e32 v47, v47
	v_exp_f32_e32 v49, v49
	v_exp_f32_e32 v51, v51
	v_add_f32_e32 v48, v42, v48
	v_cndmask_b32_e64 v43, v43, 0, s[24:25]
	v_add_f32_e32 v48, v43, v48
	v_cndmask_b32_e64 v44, v44, 0, s[26:27]
	v_add_f32_e32 v48, v44, v48
	v_cndmask_b32_e64 v45, v45, 0, s[28:29]
	v_add_f32_e32 v48, v45, v48
	v_cndmask_b32_e64 v46, v46, 0, s[30:31]
	v_cndmask_b32_e64 v47, v47, 0, s[34:35]
	v_cndmask_b32_e64 v49, 0, v49, s[6:7]
	v_cndmask_b32_e64 v51, 0, v51, s[8:9]
	v_add_f32_e32 v48, v46, v48
	v_cvt_pk_bf16_f32 v40, v40, v41
	v_cvt_pk_bf16_f32 v41, v42, v43
	v_cvt_pk_bf16_f32 v42, v44, v45
	v_cvt_pk_bf16_f32 v43, v46, v47
	v_pk_mul_f32 v[82:83], v[110:111], v[86:87] op_sel_hi:[1,0]
	v_pk_mul_f32 v[80:81], v[108:109], v[86:87] op_sel_hi:[1,0]
	v_add_f32_e32 v50, 0, v49
	v_cvt_pk_bf16_f32 v76, v49, 0
	v_cvt_pk_bf16_f32 v78, v51, 0
	v_add_f32_e32 v149, v47, v48
	v_pk_mul_f32 v[46:47], v[98:99], v[84:85] op_sel_hi:[1,0]
	v_pk_mul_f32 v[44:45], v[96:97], v[84:85] op_sel_hi:[1,0]
	s_waitcnt lgkmcnt(8)
	v_mfma_f32_16x16x32_bf16 v[96:99], v[136:139], v[40:43], v[80:83]
	v_add_f32_e32 v147, v51, v50
	v_pk_mul_f32 v[50:51], v[102:103], v[86:87] op_sel_hi:[1,0]
	v_pk_mul_f32 v[48:49], v[100:101], v[86:87] op_sel_hi:[1,0]
	v_pk_mul_f32 v[82:83], v[114:115], v[84:85] op_sel_hi:[1,0]
	v_pk_mul_f32 v[80:81], v[112:113], v[84:85] op_sel_hi:[1,0]
	v_pk_mul_f32 v[54:55], v[106:107], v[84:85] op_sel_hi:[1,0]
	v_pk_mul_f32 v[52:53], v[104:105], v[84:85] op_sel_hi:[1,0]
	s_waitcnt lgkmcnt(6)
	v_mfma_f32_16x16x32_bf16 v[100:103], v[140:143], v[76:79], v[80:83]
	v_fmac_f32_e32 v147, v131, v84
	v_fmac_f32_e32 v149, v130, v86
	s_nop 0
	v_pk_mul_f32 v[82:83], v[118:119], v[86:87] op_sel_hi:[1,0]
	v_pk_mul_f32 v[80:81], v[116:117], v[86:87] op_sel_hi:[1,0]
	v_mfma_f32_16x16x32_bf16 v[44:47], v[132:135], v[76:79], v[44:47]
	s_nop 0
	v_mfma_f32_16x16x32_bf16 v[104:107], v[140:143], v[40:43], v[80:83]
	s_nop 2
	v_mul_f32_e64 v82, v122, v84
	v_mul_f32_e64 v83, v123, v84
	v_pk_mul_f32 v[80:81], v[120:121], v[84:85] op_sel_hi:[1,0]
	v_mfma_f32_16x16x32_bf16 v[52:55], v[136:139], v[76:79], v[52:55]
	v_add_u32_e32 v84, s40, v240
	s_waitcnt lgkmcnt(4)
	v_mfma_f32_16x16x32_bf16 v[108:111], v[176:179], v[76:79], v[80:83]
	v_mul_f32_e64 v78, v126, v86
	v_mul_f32_e64 v79, v127, v86
	v_pk_mul_f32 v[76:77], v[124:125], v[86:87] op_sel_hi:[1,0]
	v_mfma_f32_16x16x32_bf16 v[48:51], v[132:135], v[40:43], v[48:51]
	s_nop 0
	v_mfma_f32_16x16x32_bf16 v[112:115], v[176:179], v[40:43], v[76:79]
	v_add_u32_e32 v40, s40, v235
	s_nop 1
	v_add_u32_e32 v76, s40, v236
	v_med3_i32 v40, v40, 0, s75
	v_med3_i32 v76, v76, 0, s75
	v_lshl_add_u32 v40, v40, 9, v152
	v_lshl_add_u32 v76, v76, 9, v152
	global_load_dwordx4 v[40:43], v40, s[98:99]
	s_nop 0
	global_load_dwordx4 v[116:119], v76, s[98:99]
	v_add_u32_e32 v76, s40, v237
	v_med3_i32 v76, v76, 0, s75
	v_lshl_add_u32 v76, v76, 9, v152
	global_load_dwordx4 v[120:123], v76, s[98:99]
	v_add_u32_e32 v76, s40, v238
	v_med3_i32 v76, v76, 0, s75
	v_lshl_add_u32 v76, v76, 9, v152
	global_load_dwordx4 v[124:127], v76, s[98:99]
	v_add_u32_e32 v76, s40, v239
	v_med3_i32 v76, v76, 0, s75
	v_med3_i32 v84, v84, 0, s75
	v_lshl_add_u32 v80, v76, 9, v158
	v_lshl_add_u32 v84, v84, 9, v158
	global_load_dwordx4 v[76:79], v80, s[100:101]
	s_nop 0
	global_load_dwordx4 v[80:83], v80, s[100:101] offset:64
	s_nop 0
	global_load_dwordx4 v[92:95], v84, s[100:101]
	s_nop 0
	global_load_dwordx4 v[84:87], v84, s[100:101] offset:64
	ds_read_b64_tr_b16 v[142:143], v169 offset:6912
	ds_read_b64_tr_b16 v[140:141], v169 offset:4608
	ds_read_b64_tr_b16 v[136:137], v169 offset:4640
	ds_read_b64_tr_b16 v[138:139], v169 offset:6944
	ds_read_b64_tr_b16 v[132:133], v169 offset:4672
	ds_read_b64_tr_b16 v[134:135], v169 offset:6976
	ds_read_b64_tr_b16 v[128:129], v169 offset:4704
	ds_read_b64_tr_b16 v[130:131], v169 offset:7008
	s_waitcnt vmcnt(15)
	ds_write_b128 v241, v[64:67]
	s_waitcnt vmcnt(14)
	ds_write_b128 v242, v[68:71]
	s_waitcnt vmcnt(13)
	ds_write_b128 v243, v[72:75]
	s_waitcnt vmcnt(12)
	ds_write_b128 v244, v[88:91]
	v_mfma_f32_16x16x32_bf16 v[64:67], v[16:19], v[4:7], 0
	v_mfma_f32_16x16x32_bf16 v[64:67], v[20:23], v[8:11], v[64:67]
	v_mfma_f32_16x16x32_bf16 v[66:69], v[56:59], v[4:7], 0
	v_mfma_f32_16x16x32_bf16 v[16:19], v[16:19], v[12:15], 0
	v_mfma_f32_16x16x32_bf16 v[66:69], v[60:63], v[8:11], v[66:69]
	v_mfma_f32_16x16x32_bf16 v[16:19], v[20:23], v[0:3], v[16:19]
	v_mfma_f32_16x16x32_bf16 v[20:23], v[56:59], v[12:15], 0
	s_nop 2
	v_max_f32_e32 v57, v64, v64
	v_sub_u32_e32 v56, v192, v145
	v_max_f32_e32 v57, 0xf149f2ca, v57
	v_cndmask_b32_e64 v57, v246, v57, s[10:11]
	v_cndmask_b32_e64 v58, v246, v66, s[12:13]
	v_add_u32_e32 v59, 1, v56
	v_max3_f32 v57, v57, v58, s73
	v_max_f32_e32 v58, v16, v16
	v_cmp_gt_u32_e64 s[0:1], v59, v144
	v_cmp_gt_u32_e32 vcc, v56, v144
	v_max_f32_e32 v58, 0xf149f2ca, v58
	v_cndmask_b32_e64 v59, v17, v246, s[0:1]
	v_cndmask_b32_e32 v58, v58, v246, vcc
	v_mfma_f32_16x16x32_bf16 v[20:23], v[60:63], v[0:3], v[20:23]
	v_max_f32_e32 v58, v58, v59
	v_add_u32_e32 v59, 2, v56
	v_add_u32_e32 v60, 3, v56
	v_cmp_gt_u32_e64 s[22:23], v59, v144
	v_cmp_gt_u32_e64 s[24:25], v60, v144
	v_mov_b32_e32 v61, v153
	v_cndmask_b32_e64 v59, v18, v246, s[22:23]
	v_cndmask_b32_e64 v60, v19, v246, s[24:25]
	v_max3_f32 v58, v58, v59, v60
	v_add_u32_e32 v59, 16, v56
	v_add_u32_e32 v60, 17, v56
	v_cmp_gt_u32_e64 s[26:27], v59, v144
	v_cmp_gt_u32_e64 s[28:29], v60, v144
	v_mov_b32_e32 v63, v153
	v_cndmask_b32_e64 v59, v20, v246, s[26:27]
	v_cndmask_b32_e64 v60, v21, v246, s[28:29]
	v_max3_f32 v58, v58, v59, v60
	v_add_u32_e32 v59, 18, v56
	v_add_u32_e32 v56, 19, v56
	v_cmp_gt_u32_e64 s[30:31], v59, v144
	v_cmp_gt_u32_e64 s[34:35], v56, v144
	s_nop 0
	v_cndmask_b32_e64 v59, v22, v246, s[30:31]
	v_cndmask_b32_e64 v56, v23, v246, s[34:35]
	v_max3_f32 v56, v58, v59, v56
	v_mov_b32_e32 v58, v57
	v_mov_b32_e32 v59, v57
	s_nop 1
	v_permlane32_swap_b32_e32 v58, v59
	v_max3_f32 v57, v57, v58, v59
	v_mov_b32_e32 v58, v56
	v_mov_b32_e32 v59, v56
	s_nop 1
	v_permlane32_swap_b32_e32 v58, v59
	v_max3_f32 v56, v56, v58, v59
	v_mov_b32_e32 v58, v57
	v_mov_b32_e32 v59, v57
	s_nop 1
	v_permlane16_swap_b32_e32 v58, v59
	v_max_f32_e32 v57, v57, v58
	v_mov_b32_e32 v58, v56
	v_mov_b32_e32 v65, v56
	s_nop 1
	v_permlane16_swap_b32_e32 v58, v65
	v_max_f32_e32 v56, v56, v58
	v_max3_f32 v151, v148, v56, v65
	v_sub_f32_e32 v16, v16, v151
	v_exp_f32_e32 v16, v16
	v_sub_f32_e32 v17, v17, v151
	v_max3_f32 v150, v146, v57, v59
	v_exp_f32_e32 v17, v17
	v_sub_f32_e32 v18, v18, v151
	v_sub_f32_e32 v57, v146, v150
	v_exp_f32_e32 v18, v18
	v_sub_f32_e32 v19, v19, v151
	v_exp_f32_e32 v68, v57
	v_sub_f32_e32 v57, v64, v150
	v_exp_f32_e32 v19, v19
	v_sub_f32_e32 v20, v20, v151
	v_exp_f32_e32 v57, v57
	v_sub_f32_e32 v59, v66, v150
	v_sub_f32_e32 v56, v148, v151
	v_cndmask_b32_e64 v16, v16, 0, vcc
	v_exp_f32_e32 v20, v20
	v_sub_f32_e32 v21, v21, v151
	v_exp_f32_e32 v59, v59
	v_exp_f32_e32 v72, v56
	v_add_f32_e32 v56, 0, v16
	v_cndmask_b32_e64 v17, v17, 0, s[0:1]
	v_exp_f32_e32 v21, v21
	v_sub_f32_e32 v22, v22, v151
	v_add_f32_e32 v56, v17, v56
	v_cndmask_b32_e64 v18, v18, 0, s[22:23]
	v_exp_f32_e32 v22, v22
	v_sub_f32_e32 v23, v23, v151
	v_add_f32_e32 v56, v18, v56
	v_cndmask_b32_e64 v19, v19, 0, s[24:25]
	v_exp_f32_e32 v23, v23
	v_cndmask_b32_e64 v57, 0, v57, s[10:11]
	v_add_f32_e32 v56, v19, v56
	v_cndmask_b32_e64 v20, v20, 0, s[26:27]
	v_add_f32_e32 v58, 0, v57
	v_cndmask_b32_e64 v59, 0, v59, s[12:13]
	v_add_f32_e32 v56, v20, v56
	v_cndmask_b32_e64 v21, v21, 0, s[28:29]
	v_add_f32_e32 v146, v59, v58
	v_add_f32_e32 v56, v21, v56
	v_cndmask_b32_e64 v22, v22, 0, s[30:31]
	v_fmac_f32_e32 v146, v147, v68
	v_cvt_pk_bf16_f32 v60, v57, 0
	v_cvt_pk_bf16_f32 v62, v59, 0
	v_add_f32_e32 v56, v22, v56
	v_cndmask_b32_e64 v23, v23, 0, s[34:35]
	v_cvt_pk_bf16_f32 v64, v16, v17
	v_cvt_pk_bf16_f32 v65, v18, v19
	v_pk_mul_f32 v[18:19], v[46:47], v[68:69] op_sel_hi:[1,0]
	v_pk_mul_f32 v[16:17], v[44:45], v[68:69] op_sel_hi:[1,0]
	v_pk_mul_f32 v[46:47], v[54:55], v[68:69] op_sel_hi:[1,0]
	v_pk_mul_f32 v[44:45], v[52:53], v[68:69] op_sel_hi:[1,0]
	v_pk_mul_f32 v[54:55], v[102:103], v[68:69] op_sel_hi:[1,0]
	v_pk_mul_f32 v[52:53], v[100:101], v[68:69] op_sel_hi:[1,0]
	v_pk_mul_f32 v[70:71], v[110:111], v[68:69] op_sel_hi:[1,0]
	v_pk_mul_f32 v[68:69], v[108:109], v[68:69] op_sel_hi:[1,0]
	v_add_f32_e32 v147, v23, v56
	v_cvt_pk_bf16_f32 v66, v20, v21
	v_cvt_pk_bf16_f32 v67, v22, v23
	s_waitcnt lgkmcnt(10)
	v_mfma_f32_16x16x32_bf16 v[16:19], v[140:143], v[60:63], v[16:19]
	v_mul_f32_e64 v22, v50, v72
	v_mul_f32_e64 v23, v51, v72
	v_pk_mul_f32 v[20:21], v[48:49], v[72:73] op_sel_hi:[1,0]
	v_pk_mul_f32 v[50:51], v[98:99], v[72:73] op_sel_hi:[1,0]
	s_waitcnt lgkmcnt(8)
	v_mfma_f32_16x16x32_bf16 v[44:47], v[136:139], v[60:63], v[44:47]
	v_mul_f32_e64 v48, v96, v72
	v_mul_f32_e64 v49, v97, v72
	v_pk_mul_f32 v[58:59], v[106:107], v[72:73] op_sel_hi:[1,0]
	v_pk_mul_f32 v[56:57], v[104:105], v[72:73] op_sel_hi:[1,0]
	s_waitcnt lgkmcnt(6)
	v_mfma_f32_16x16x32_bf16 v[52:55], v[132:135], v[60:63], v[52:55]
	v_fmac_f32_e32 v147, v149, v72
	s_waitcnt lgkmcnt(4)
	v_mfma_f32_16x16x32_bf16 v[60:63], v[128:131], v[60:63], v[68:71]
	s_nop 2
	v_mul_f32_e64 v70, v114, v72
	v_mul_f32_e64 v71, v115, v72
	v_pk_mul_f32 v[68:69], v[112:113], v[72:73] op_sel_hi:[1,0]
	v_mfma_f32_16x16x32_bf16 v[20:23], v[140:143], v[64:67], v[20:23]
	v_mfma_f32_16x16x32_bf16 v[48:51], v[136:139], v[64:67], v[48:51]
	v_mfma_f32_16x16x32_bf16 v[56:59], v[132:135], v[64:67], v[56:59]
	v_mfma_f32_16x16x32_bf16 v[64:67], v[128:131], v[64:67], v[68:71]
	ds_read_b64_tr_b16 v[98:99], v169 offset:2304
	ds_read_b64_tr_b16 v[96:97], v169
	ds_read_b64_tr_b16 v[88:89], v169 offset:32
	ds_read_b64_tr_b16 v[90:91], v169 offset:2336
	ds_read_b64_tr_b16 v[72:73], v169 offset:64
	ds_read_b64_tr_b16 v[74:75], v169 offset:2368
	ds_read_b64_tr_b16 v[68:69], v169 offset:96
	ds_read_b64_tr_b16 v[70:71], v169 offset:2400
	s_waitcnt vmcnt(7)
	ds_write_b128 v241, v[40:43] offset:4608
	s_waitcnt vmcnt(6)
	ds_write_b128 v242, v[116:119] offset:4608
	s_waitcnt vmcnt(5)
	ds_write_b128 v243, v[120:123] offset:4608
	s_waitcnt vmcnt(4)
	ds_write_b128 v244, v[124:127] offset:4608
	v_mfma_f32_16x16x32_bf16 v[40:43], v[24:27], v[4:7], 0
	v_mfma_f32_16x16x32_bf16 v[100:103], v[32:35], v[4:7], 0
	v_mfma_f32_16x16x32_bf16 v[24:27], v[24:27], v[12:15], 0
	v_mfma_f32_16x16x32_bf16 v[40:43], v[28:31], v[8:11], v[40:43]
	v_mfma_f32_16x16x32_bf16 v[100:103], v[36:39], v[8:11], v[100:103]
	v_mfma_f32_16x16x32_bf16 v[24:27], v[28:31], v[0:3], v[24:27]
	s_nop 5
	v_mov_b32_e32 v41, v153
	v_mov_b32_e32 v43, v153
	v_mfma_f32_16x16x32_bf16 v[28:31], v[32:35], v[12:15], 0
	v_max_f32_e32 v33, v40, v40
	v_sub_u32_e32 v32, v197, v145
	v_max_f32_e32 v33, 0xf149f2ca, v33
	v_cndmask_b32_e64 v33, v246, v33, s[14:15]
	v_cndmask_b32_e64 v34, v246, v100, s[16:17]
	v_add_u32_e32 v35, 1, v32
	v_max3_f32 v33, v33, v34, s73
	v_max_f32_e32 v34, v24, v24
	v_cmp_gt_u32_e64 s[0:1], v35, v144
	v_cmp_gt_u32_e32 vcc, v32, v144
	v_max_f32_e32 v34, 0xf149f2ca, v34
	v_cndmask_b32_e64 v35, v25, v246, s[0:1]
	v_cndmask_b32_e32 v34, v34, v246, vcc
	v_mfma_f32_16x16x32_bf16 v[28:31], v[36:39], v[0:3], v[28:31]
	v_max_f32_e32 v34, v34, v35
	v_add_u32_e32 v35, 2, v32
	v_add_u32_e32 v36, 3, v32
	v_cmp_gt_u32_e64 s[22:23], v35, v144
	v_cmp_gt_u32_e64 s[24:25], v36, v144
	s_nop 0
	v_cndmask_b32_e64 v35, v26, v246, s[22:23]
	v_cndmask_b32_e64 v36, v27, v246, s[24:25]
	v_max3_f32 v34, v34, v35, v36
	v_add_u32_e32 v35, 16, v32
	v_add_u32_e32 v36, 17, v32
	v_cmp_gt_u32_e64 s[26:27], v35, v144
	v_cmp_gt_u32_e64 s[28:29], v36, v144
	s_nop 0
	v_cndmask_b32_e64 v35, v28, v246, s[26:27]
	v_cndmask_b32_e64 v36, v29, v246, s[28:29]
	v_max3_f32 v34, v34, v35, v36
	v_add_u32_e32 v35, 18, v32
	v_add_u32_e32 v32, 19, v32
	v_cmp_gt_u32_e64 s[30:31], v35, v144
	v_cmp_gt_u32_e64 s[34:35], v32, v144
	s_nop 0
	v_cndmask_b32_e64 v35, v30, v246, s[30:31]
	v_cndmask_b32_e64 v32, v31, v246, s[34:35]
	v_max3_f32 v32, v34, v35, v32
	v_mov_b32_e32 v34, v33
	v_mov_b32_e32 v35, v33
	s_nop 1
	v_permlane32_swap_b32_e32 v34, v35
	v_max3_f32 v33, v33, v34, v35
	v_mov_b32_e32 v34, v32
	v_mov_b32_e32 v35, v32
	s_nop 1
	v_permlane32_swap_b32_e32 v34, v35
	v_max3_f32 v32, v32, v34, v35
	v_mov_b32_e32 v34, v33
	v_mov_b32_e32 v35, v33
	s_nop 1
	v_permlane16_swap_b32_e32 v34, v35
	v_max_f32_e32 v33, v33, v34
	v_max3_f32 v101, v150, v33, v35
	v_sub_f32_e32 v33, v150, v101
	v_exp_f32_e32 v106, v33
	v_sub_f32_e32 v33, v40, v101
	v_mov_b32_e32 v34, v32
	v_mov_b32_e32 v36, v32
	v_exp_f32_e32 v33, v33
	s_nop 0
	v_permlane16_swap_b32_e32 v34, v36
	v_max_f32_e32 v32, v32, v34
	v_cndmask_b32_e64 v107, 0, v33, s[14:15]
	v_sub_f32_e32 v33, v100, v101
	v_max3_f32 v100, v151, v32, v36
	v_sub_f32_e32 v24, v24, v100
	v_exp_f32_e32 v24, v24
	v_exp_f32_e32 v33, v33
	v_sub_f32_e32 v32, v151, v100
	v_exp_f32_e32 v108, v32
	v_cndmask_b32_e64 v110, v24, 0, vcc
	v_sub_f32_e32 v24, v25, v100
	v_exp_f32_e32 v24, v24
	v_cndmask_b32_e64 v109, 0, v33, s[16:17]
	v_cvt_pk_bf16_f32 v40, v107, 0
	v_cvt_pk_bf16_f32 v42, v109, 0
	v_cndmask_b32_e64 v111, v24, 0, s[0:1]
	v_sub_f32_e32 v24, v26, v100
	v_exp_f32_e32 v24, v24
	v_pk_mul_f32 v[18:19], v[18:19], v[106:107] op_sel_hi:[1,0]
	v_pk_mul_f32 v[16:17], v[16:17], v[106:107] op_sel_hi:[1,0]
	v_pk_mul_f32 v[34:35], v[54:55], v[106:107] op_sel_hi:[1,0]
	v_cndmask_b32_e64 v112, v24, 0, s[22:23]
	v_sub_f32_e32 v24, v27, v100
	v_exp_f32_e32 v24, v24
	v_pk_mul_f32 v[26:27], v[46:47], v[106:107] op_sel_hi:[1,0]
	v_pk_mul_f32 v[32:33], v[52:53], v[106:107] op_sel_hi:[1,0]
	v_pk_mul_f32 v[46:47], v[62:63], v[106:107] op_sel_hi:[1,0]
	v_cndmask_b32_e64 v113, v24, 0, s[24:25]
	v_sub_f32_e32 v24, v28, v100
	v_exp_f32_e32 v24, v24
	s_waitcnt lgkmcnt(10)
	v_mfma_f32_16x16x32_bf16 v[16:19], v[96:99], v[40:43], v[16:19]
	v_cvt_pk_bf16_f32 v102, v110, v111
	v_cvt_pk_bf16_f32 v103, v112, v113
	v_cndmask_b32_e64 v114, v24, 0, s[26:27]
	v_sub_f32_e32 v24, v29, v100
	v_exp_f32_e32 v24, v24
	s_waitcnt lgkmcnt(6)
	v_mfma_f32_16x16x32_bf16 v[32:35], v[72:75], v[40:43], v[32:35]
	v_mul_f32_e64 v28, v48, v108
	v_mul_f32_e64 v29, v49, v108
	v_add_f32_e32 v48, 0, v110
	v_cndmask_b32_e64 v115, v24, 0, s[28:29]
	v_sub_f32_e32 v24, v30, v100
	v_exp_f32_e32 v24, v24
	v_add_f32_e32 v48, v111, v48
	v_add_f32_e32 v48, v112, v48
	v_add_f32_e32 v48, v113, v48
	v_cndmask_b32_e64 v116, v24, 0, s[30:31]
	v_sub_f32_e32 v24, v31, v100
	v_exp_f32_e32 v24, v24
	v_add_f32_e32 v48, v114, v48
	v_add_f32_e32 v48, v115, v48
	v_cvt_pk_bf16_f32 v104, v114, v115
	v_cndmask_b32_e64 v117, v24, 0, s[34:35]
	v_pk_mul_f32 v[24:25], v[44:45], v[106:107] op_sel_hi:[1,0]
	v_pk_mul_f32 v[44:45], v[60:61], v[106:107] op_sel_hi:[1,0]
	v_cvt_pk_bf16_f32 v105, v116, v117
	v_mfma_f32_16x16x32_bf16 v[24:27], v[88:91], v[40:43], v[24:27]
	v_add_f32_e32 v48, v116, v48
	v_pk_mul_f32 v[38:39], v[58:59], v[108:109] op_sel_hi:[1,0]
	v_pk_mul_f32 v[36:37], v[56:57], v[108:109] op_sel_hi:[1,0]
	s_waitcnt lgkmcnt(4)
	v_mfma_f32_16x16x32_bf16 v[40:43], v[68:71], v[40:43], v[44:47]
	v_mul_f32_e64 v30, v50, v108
	v_mul_f32_e64 v31, v51, v108
	v_pk_mul_f32 v[22:23], v[22:23], v[108:109] op_sel_hi:[1,0]
	v_pk_mul_f32 v[20:21], v[20:21], v[108:109] op_sel_hi:[1,0]
	v_pk_mul_f32 v[46:47], v[66:67], v[108:109] op_sel_hi:[1,0]
	v_pk_mul_f32 v[44:45], v[64:65], v[108:109] op_sel_hi:[1,0]
	s_waitcnt vmcnt(3)
	v_mfma_f32_16x16x32_bf16 v[64:67], v[76:79], v[4:7], 0
	s_waitcnt vmcnt(1)
	v_mfma_f32_16x16x32_bf16 v[4:7], v[92:95], v[4:7], 0
	v_mfma_f32_16x16x32_bf16 v[64:67], v[80:83], v[8:11], v[64:67]
	s_waitcnt vmcnt(0)
	v_mfma_f32_16x16x32_bf16 v[8:11], v[84:87], v[8:11], v[4:7]
	v_mfma_f32_16x16x32_bf16 v[4:7], v[76:79], v[12:15], 0
	v_mfma_f32_16x16x32_bf16 v[10:13], v[92:95], v[12:15], 0
	s_nop 5
	v_sub_u32_e32 v9, v198, v145
	v_cmp_gt_u32_e64 s[34:35], v9, v144
	v_mov_b32_e32 v15, v153
	v_mfma_f32_16x16x32_bf16 v[4:7], v[80:83], v[0:3], v[4:7]
	v_mfma_f32_16x16x32_bf16 v[0:3], v[84:87], v[0:3], v[10:13]
	s_nop 2
	v_max_f32_e32 v10, v64, v64
	v_max_f32_e32 v10, 0xf149f2ca, v10
	v_cndmask_b32_e64 v10, v246, v10, s[18:19]
	v_cndmask_b32_e64 v11, v246, v8, s[20:21]
	v_add_u32_e32 v12, 1, v9
	v_max3_f32 v10, v10, v11, s73
	v_max_f32_e32 v11, v4, v4
	v_cmp_gt_u32_e64 s[30:31], v12, v144
	v_max_f32_e32 v11, 0xf149f2ca, v11
	v_cndmask_b32_e64 v11, v11, v246, s[34:35]
	v_cndmask_b32_e64 v12, v5, v246, s[30:31]
	v_max_f32_e32 v11, v11, v12
	v_add_u32_e32 v12, 2, v9
	v_add_u32_e32 v13, 3, v9
	v_cmp_gt_u32_e64 s[28:29], v12, v144
	v_cmp_gt_u32_e64 s[26:27], v13, v144
	v_mfma_f32_16x16x32_bf16 v[44:47], v[68:71], v[102:105], v[44:47]
	v_cndmask_b32_e64 v12, v6, v246, s[28:29]
	v_cndmask_b32_e64 v13, v7, v246, s[26:27]
	v_max3_f32 v11, v11, v12, v13
	v_add_u32_e32 v12, 16, v9
	v_add_u32_e32 v13, 17, v9
	v_cmp_gt_u32_e64 s[24:25], v12, v144
	v_cmp_gt_u32_e64 s[22:23], v13, v144
	v_add_f32_e32 v68, v117, v48
	v_cndmask_b32_e64 v12, v0, v246, s[24:25]
	v_cndmask_b32_e64 v13, v1, v246, s[22:23]
	v_max3_f32 v11, v11, v12, v13
	v_add_u32_e32 v12, 18, v9
	v_add_u32_e32 v9, 19, v9
	v_cmp_gt_u32_e64 s[0:1], v12, v144
	v_cmp_gt_u32_e32 vcc, v9, v144
	v_add_f32_e32 v48, 0, v107
	v_cndmask_b32_e64 v12, v2, v246, s[0:1]
	v_cndmask_b32_e32 v9, v3, v246, vcc
	v_max3_f32 v9, v11, v12, v9
	v_mov_b32_e32 v11, v10
	v_mov_b32_e32 v12, v10
	s_nop 1
	v_permlane32_swap_b32_e32 v11, v12
	v_max3_f32 v10, v10, v11, v12
	v_mov_b32_e32 v11, v9
	v_mov_b32_e32 v12, v9
	s_nop 1
	v_permlane32_swap_b32_e32 v11, v12
	v_max3_f32 v9, v9, v11, v12
	v_mov_b32_e32 v11, v10
	v_mov_b32_e32 v12, v10
	s_nop 1
	v_permlane16_swap_b32_e32 v11, v12
	v_max_f32_e32 v10, v10, v11
	v_mov_b32_e32 v11, v9
	v_mov_b32_e32 v67, v9
	s_nop 1
	v_permlane16_swap_b32_e32 v11, v67
	v_max3_f32 v10, v101, v10, v12
	v_max_f32_e32 v9, v9, v11
	v_sub_f32_e32 v11, v101, v10
	v_exp_f32_e32 v66, v11
	v_sub_f32_e32 v11, v64, v10
	v_exp_f32_e32 v11, v11
	v_sub_f32_e32 v8, v8, v10
	v_exp_f32_e32 v8, v8
	v_add_f32_e32 v69, v109, v48
	v_cndmask_b32_e64 v11, 0, v11, s[18:19]
	v_add_f32_e32 v12, 0, v11
	v_cndmask_b32_e64 v8, 0, v8, s[20:21]
	v_fmac_f32_e32 v69, v146, v106
	v_add_f32_e32 v65, v8, v12
	v_cvt_pk_bf16_f32 v14, v8, 0
	v_max3_f32 v8, v100, v9, v67
	v_fmac_f32_e32 v65, v69, v66
	v_sub_f32_e32 v4, v4, v8
	v_cvt_pk_bf16_f32 v12, v11, 0
	v_exp_f32_e32 v4, v4
	v_sub_f32_e32 v5, v5, v8
	v_pk_mul_f32 v[10:11], v[34:35], v[66:67] op_sel_hi:[1,0]
	ds_bpermute_b32 v34, v170, v65
	v_exp_f32_e32 v5, v5
	v_sub_f32_e32 v6, v6, v8
	v_exp_f32_e32 v6, v6
	v_sub_f32_e32 v7, v7, v8
	v_exp_f32_e32 v7, v7
	v_sub_f32_e32 v0, v0, v8
	v_sub_f32_e32 v9, v100, v8
	v_cndmask_b32_e64 v4, v4, 0, s[34:35]
	v_exp_f32_e32 v0, v0
	v_sub_f32_e32 v1, v1, v8
	v_mfma_f32_16x16x32_bf16 v[36:39], v[72:75], v[102:105], v[36:39]
	v_exp_f32_e32 v72, v9
	v_add_f32_e32 v9, 0, v4
	v_cndmask_b32_e64 v5, v5, 0, s[30:31]
	v_exp_f32_e32 v1, v1
	v_sub_f32_e32 v2, v2, v8
	s_waitcnt lgkmcnt(0)
	v_add_f32_e32 v34, v65, v34
	v_add_f32_e32 v9, v5, v9
	v_cndmask_b32_e64 v6, v6, 0, s[28:29]
	v_exp_f32_e32 v2, v2
	v_sub_f32_e32 v3, v3, v8
	ds_bpermute_b32 v35, v171, v34
	v_add_f32_e32 v9, v6, v9
	v_cndmask_b32_e64 v7, v7, 0, s[26:27]
	v_exp_f32_e32 v3, v3
	v_add_f32_e32 v9, v7, v9
	v_cndmask_b32_e64 v0, v0, 0, s[24:25]
	v_add_f32_e32 v9, v0, v9
	v_cndmask_b32_e64 v1, v1, 0, s[22:23]
	ds_read_b64_tr_b16 v[62:63], v169 offset:6912
	ds_read_b64_tr_b16 v[60:61], v169 offset:4608
	ds_read_b64_tr_b16 v[56:57], v169 offset:4640
	ds_read_b64_tr_b16 v[58:59], v169 offset:6944
	ds_read_b64_tr_b16 v[52:53], v169 offset:4672
	ds_read_b64_tr_b16 v[54:55], v169 offset:6976
	ds_read_b64_tr_b16 v[48:49], v169 offset:4704
	ds_read_b64_tr_b16 v[50:51], v169 offset:7008
	v_add_f32_e32 v9, v1, v9
	v_cndmask_b32_e64 v2, v2, 0, s[0:1]
	v_add_f32_e32 v9, v2, v9
	v_cndmask_b32_e64 v3, v3, 0, vcc
	s_waitcnt lgkmcnt(8)
	v_add_f32_e32 v34, v34, v35
	v_fmac_f32_e32 v68, v147, v108
	v_mov_b32_e32 v13, v153
	v_add_f32_e32 v64, v3, v9
	v_pk_mul_f32 v[8:9], v[32:33], v[66:67] op_sel_hi:[1,0]
	v_div_scale_f32 v35, s[0:1], v34, v34, 1.0
	v_fmac_f32_e32 v64, v68, v72
	v_cvt_pk_bf16_f32 v68, v4, v5
	v_cvt_pk_bf16_f32 v69, v6, v7
	v_pk_mul_f32 v[6:7], v[26:27], v[66:67] op_sel_hi:[1,0]
	v_pk_mul_f32 v[4:5], v[24:25], v[66:67] op_sel_hi:[1,0]
	s_waitcnt lgkmcnt(2)
	v_mfma_f32_16x16x32_bf16 v[24:27], v[52:55], v[12:15], v[8:11]
	v_cvt_pk_bf16_f32 v70, v0, v1
	v_cvt_pk_bf16_f32 v71, v2, v3
	v_pk_mul_f32 v[2:3], v[18:19], v[66:67] op_sel_hi:[1,0]
	v_pk_mul_f32 v[8:9], v[36:37], v[72:73] op_sel_hi:[1,0]
	v_rcp_f32_e32 v36, v35
	v_mfma_f32_16x16x32_bf16 v[20:23], v[96:99], v[102:105], v[20:23]
	v_mul_f32_e64 v10, v38, v72
	v_mul_f32_e64 v11, v39, v72
	v_pk_mul_f32 v[0:1], v[16:17], v[66:67] op_sel_hi:[1,0]
	v_fma_f32 v37, -v35, v36, 1.0
	v_fmac_f32_e32 v36, v37, v36
	v_div_scale_f32 v37, vcc, 1.0, v34, 1.0
	v_mul_f32_e32 v38, v37, v36
	v_fma_f32 v39, -v35, v38, v37
	v_mfma_f32_16x16x32_bf16 v[16:19], v[60:63], v[12:15], v[0:3]
	v_fmac_f32_e32 v38, v39, v36
	v_fma_f32 v35, -v35, v38, v37
	v_div_fmas_f32 v35, v35, v36, v38
	v_mfma_f32_16x16x32_bf16 v[28:31], v[88:91], v[102:105], v[28:31]
	v_mul_f32_e64 v2, v22, v72
	v_mul_f32_e64 v3, v23, v72
	v_pk_mul_f32 v[0:1], v[20:21], v[72:73] op_sel_hi:[1,0]
	v_div_fixup_f32 v34, v35, v34, 1.0
	v_mfma_f32_16x16x32_bf16 v[20:23], v[56:59], v[12:15], v[4:7]
	v_lshl_add_u64 v[32:33], v[156:157], 0, s[56:57]
	v_lshlrev_b64 v[36:37], 11, v[162:163]
	v_pk_mul_f32 v[16:17], v[16:17], v[34:35] op_sel_hi:[1,0]
	v_pk_mul_f32 v[18:19], v[18:19], v[34:35] op_sel_hi:[1,0]
	v_pk_mul_f32 v[6:7], v[30:31], v[72:73] op_sel_hi:[1,0]
	v_pk_mul_f32 v[4:5], v[28:29], v[72:73] op_sel_hi:[1,0]
	v_pk_mul_f32 v[30:31], v[42:43], v[66:67] op_sel_hi:[1,0]
	v_pk_mul_f32 v[28:29], v[40:41], v[66:67] op_sel_hi:[1,0]
	v_lshl_add_u64 v[36:37], v[32:33], 0, v[36:37]
	v_cvt_pk_bf16_f32 v16, v16, v17
	v_cvt_pk_bf16_f32 v17, v18, v19
	s_waitcnt lgkmcnt(0)
	v_mfma_f32_16x16x32_bf16 v[28:31], v[48:51], v[12:15], v[28:31]
	global_store_dwordx2 v[36:37], v[16:17], off
	v_pk_mul_f32 v[16:17], v[20:21], v[34:35] op_sel_hi:[1,0]
	v_pk_mul_f32 v[18:19], v[22:23], v[34:35] op_sel_hi:[1,0]
	v_cvt_pk_bf16_f32 v16, v16, v17
	v_cvt_pk_bf16_f32 v17, v18, v19
	global_store_dwordx2 v[36:37], v[16:17], off offset:32
	v_pk_mul_f32 v[16:17], v[24:25], v[34:35] op_sel_hi:[1,0]
	v_pk_mul_f32 v[18:19], v[26:27], v[34:35] op_sel_hi:[1,0]
	v_cvt_pk_bf16_f32 v16, v16, v17
	v_cvt_pk_bf16_f32 v17, v18, v19
	global_store_dwordx2 v[36:37], v[16:17], off offset:64
	v_pk_mul_f32 v[16:17], v[28:29], v[34:35] op_sel_hi:[1,0]
	v_pk_mul_f32 v[18:19], v[30:31], v[34:35] op_sel_hi:[1,0]
	v_cvt_pk_bf16_f32 v16, v16, v17
	v_cvt_pk_bf16_f32 v17, v18, v19
	global_store_dwordx2 v[36:37], v[16:17], off offset:96
	ds_bpermute_b32 v16, v170, v64
	v_mfma_f32_16x16x32_bf16 v[0:3], v[60:63], v[68:71], v[0:3]
	v_mul_f32_e64 v14, v46, v72
	v_mul_f32_e64 v15, v47, v72
	v_pk_mul_f32 v[12:13], v[44:45], v[72:73] op_sel_hi:[1,0]
	s_waitcnt lgkmcnt(0)
	v_add_f32_e32 v16, v64, v16
	ds_bpermute_b32 v17, v171, v16
	v_mfma_f32_16x16x32_bf16 v[4:7], v[56:59], v[68:71], v[4:7]
	s_waitcnt lgkmcnt(0)
	v_add_f32_e32 v16, v16, v17
	v_div_scale_f32 v17, s[0:1], v16, v16, 1.0
	v_rcp_f32_e32 v18, v17
	v_mfma_f32_16x16x32_bf16 v[8:11], v[52:55], v[68:71], v[8:11]
	v_fma_f32 v19, -v17, v18, 1.0
	v_fmac_f32_e32 v18, v19, v18
	v_div_scale_f32 v19, vcc, 1.0, v16, 1.0
	v_mul_f32_e32 v20, v19, v18
	v_fma_f32 v21, -v17, v20, v19
	v_fmac_f32_e32 v20, v21, v18
	v_fma_f32 v17, -v17, v20, v19
	v_div_fmas_f32 v17, v17, v18, v20
	v_div_fixup_f32 v16, v17, v16, 1.0
	v_lshlrev_b64 v[18:19], 11, v[160:161]
	v_pk_mul_f32 v[0:1], v[0:1], v[16:17] op_sel_hi:[1,0]
	v_pk_mul_f32 v[2:3], v[2:3], v[16:17] op_sel_hi:[1,0]
	v_lshl_add_u64 v[18:19], v[32:33], 0, v[18:19]
	v_cvt_pk_bf16_f32 v0, v0, v1
	v_cvt_pk_bf16_f32 v1, v2, v3
	v_mfma_f32_16x16x32_bf16 v[12:15], v[48:51], v[68:71], v[12:15]
	global_store_dwordx2 v[18:19], v[0:1], off
	v_pk_mul_f32 v[0:1], v[4:5], v[16:17] op_sel_hi:[1,0]
	v_pk_mul_f32 v[2:3], v[6:7], v[16:17] op_sel_hi:[1,0]
	v_cvt_pk_bf16_f32 v0, v0, v1
	v_cvt_pk_bf16_f32 v1, v2, v3
	global_store_dwordx2 v[18:19], v[0:1], off offset:32
	v_pk_mul_f32 v[0:1], v[8:9], v[16:17] op_sel_hi:[1,0]
	v_pk_mul_f32 v[2:3], v[10:11], v[16:17] op_sel_hi:[1,0]
	v_cvt_pk_bf16_f32 v0, v0, v1
	v_cvt_pk_bf16_f32 v1, v2, v3
	global_store_dwordx2 v[18:19], v[0:1], off offset:64
	v_pk_mul_f32 v[0:1], v[12:13], v[16:17] op_sel_hi:[1,0]
	v_pk_mul_f32 v[2:3], v[14:15], v[16:17] op_sel_hi:[1,0]
	v_cvt_pk_bf16_f32 v0, v0, v1
	v_cvt_pk_bf16_f32 v1, v2, v3
	global_store_dwordx2 v[18:19], v[0:1], off offset:96
	s_cbranch_scc1 .LBB0_246
	s_mov_b32 s76, s79
	v_readlane_b32 s72, v253, 43
	v_xor_b32_e32 v240, 32, v174
	v_xor_b32_e32 v241, 16, v174
	v_xor_b32_e32 v242, 8, v174
	v_xor_b32_e32 v243, 4, v174
	v_xor_b32_e32 v244, 2, v174
	v_xor_b32_e32 v245, 1, v174
	v_and_b32_e32 v246, 64, v174

	.amdhsa_kernel _Z14fwd_megakernel6Params
		.amdhsa_group_segment_fixed_size 0
		.amdhsa_private_segment_fixed_size 0
		.amdhsa_kernarg_size 416
		.amdhsa_user_sgpr_count 2
		.amdhsa_user_sgpr_dispatch_ptr 0
		.amdhsa_user_sgpr_queue_ptr 0
		.amdhsa_user_sgpr_kernarg_segment_ptr 1
		.amdhsa_user_sgpr_dispatch_id 0
		.amdhsa_user_sgpr_kernarg_preload_length 0
		.amdhsa_user_sgpr_kernarg_preload_offset 0
		.amdhsa_user_sgpr_private_segment_size 0
		.amdhsa_uses_dynamic_stack 0
		.amdhsa_enable_private_segment 0
		.amdhsa_system_sgpr_workgroup_id_x 1
		.amdhsa_system_sgpr_workgroup_id_y 0
		.amdhsa_system_sgpr_workgroup_id_z 0
		.amdhsa_system_sgpr_workgroup_info 0
		.amdhsa_system_vgpr_workitem_id 2
		.amdhsa_next_free_vgpr 256
		.amdhsa_next_free_sgpr 102
		.amdhsa_accum_offset 256
		.amdhsa_reserve_vcc 1
		.amdhsa_float_round_mode_32 0
		.amdhsa_float_round_mode_16_64 0
		.amdhsa_float_denorm_mode_32 3
		.amdhsa_float_denorm_mode_16_64 3
		.amdhsa_dx10_clamp 1
		.amdhsa_ieee_mode 1
		.amdhsa_fp16_overflow 0
		.amdhsa_tg_split 0
		.amdhsa_exception_fp_ieee_invalid_op 0
		.amdhsa_exception_fp_denorm_src 0
		.amdhsa_exception_fp_ieee_div_zero 0
		.amdhsa_exception_fp_ieee_overflow 0
		.amdhsa_exception_fp_ieee_underflow 0
		.amdhsa_exception_fp_ieee_inexact 0
		.amdhsa_exception_int_div_zero 0
	.end_amdhsa_kernel

amdhsa.kernels:
  - .agpr_count:     0
    .args:
      - .offset:         0
        .size:           160
        .value_kind:     by_value
      - .offset:         160
        .size:           4
        .value_kind:     hidden_block_count_x
      - .offset:         164
        .size:           4
        .value_kind:     hidden_block_count_y
      - .offset:         168
        .size:           4
        .value_kind:     hidden_block_count_z
      - .offset:         172
        .size:           2
        .value_kind:     hidden_group_size_x
      - .offset:         174
        .size:           2
        .value_kind:     hidden_group_size_y
      - .offset:         176
        .size:           2
        .value_kind:     hidden_group_size_z
      - .offset:         178
        .size:           2
        .value_kind:     hidden_remainder_x
      - .offset:         180
        .size:           2
        .value_kind:     hidden_remainder_y
      - .offset:         182
        .size:           2
        .value_kind:     hidden_remainder_z
      - .offset:         200
        .size:           8
        .value_kind:     hidden_global_offset_x
      - .offset:         208
        .size:           8
        .value_kind:     hidden_global_offset_y
      - .offset:         216
        .size:           8
        .value_kind:     hidden_global_offset_z
      - .offset:         224
        .size:           2
        .value_kind:     hidden_grid_dims
      - .offset:         248
        .size:           8
        .value_kind:     hidden_multigrid_sync_arg
      - .offset:         280
        .size:           4
        .value_kind:     hidden_dynamic_lds_size
    .group_segment_fixed_size: 0
    .kernarg_segment_align: 8
    .kernarg_segment_size: 416
    .language:       OpenCL C
    .language_version:
      - 2
      - 0
    .max_flat_workgroup_size: 512
    .name:           _Z14fwd_megakernel6Params
    .private_segment_fixed_size: 0
    .sgpr_count:     108
    .sgpr_spill_count: 185
    .symbol:         _Z14fwd_megakernel6Params.kd
    .uniform_work_group_size: 1
    .uses_dynamic_stack: false
    .vgpr_count:     256
    .vgpr_spill_count: 0
    .wavefront_size: 64
